# all 16-byte global stores made write-through (sc1) so the grid barrier's L2 write-back has less dirty data
# baseline (speedup 1.0000x reference)
; __device__ __forceinline__ unsigned pk2(float lo, float hi) { const f32x2 v = {lo, hi}; const hwbf16x2 b = __builtin_convertvector(v, hwbf16x2); return __builtin_bit_cast(unsigned, b); }
; __device__ __forceinline__ void xpose_write(const XDesc& d, int tile, const float* scr, int tid) {
;     const int ntn = d.Npad / 64, kb = tile / ntn, nb = tile % ntn, k0 = kb * 64, n0 = nb * 64;
;     const int nl = tid >> 3, kc = (tid & 7) * 8, n = n0 + nl;
;     const int orow = d.rowoff + (d.mode == 1 ? ((n % DFF) * 2 + n / DFF) : n);
;     const float* s = scr + kc * 65 + nl;
;     u32x4 o; o.x = pk2(s[0], s[65]); o.y = pk2(s[2 * 65], s[3 * 65]); o.z = pk2(s[4 * 65], s[5 * 65]); o.w = pk2(s[6 * 65], s[7 * 65]);
;     *(u32x4*)(d.WT + (size_t)orow * d.ldo + d.koff + k0 + kc) = o;
; }
; __device__ __forceinline__ void p0_prep(const Args& a, unsigned char* lds, int tid) {
;     ...
;             xpose_write(d, r, scr, tid);
;             __syncthreads();
;             d = dn; r = rn; it = itn;
.LBB0_60:
	ds_read2_b32 v[12:13], v22 offset1:65
	ds_read2_b32 v[14:15], v22 offset0:130 offset1:195
	v_add_u32_e32 v11, 0x400, v22
	ds_read2_b32 v[16:17], v11 offset0:4 offset1:69
	ds_read2_b32 v[24:25], v11 offset0:134 offset1:199
	v_add_u32_e32 v26, s4, v10
	s_lshl_b32 s0, s0, 6
	s_waitcnt lgkmcnt(2)
	v_cvt_pk_bf16_f32 v11, v14, v15
	v_mad_i64_i32 v[14:15], s[2:3], v26, s30, 0
	v_lshl_add_u64 v[14:15], v[14:15], 1, s[12:13]
	s_ashr_i32 s9, s8, 31
	v_lshl_add_u64 v[14:15], s[8:9], 1, v[14:15]
	s_ashr_i32 s1, s0, 31
	v_lshl_add_u64 v[14:15], s[0:1], 1, v[14:15]
	v_cvt_pk_bf16_f32 v10, v12, v13
	s_waitcnt lgkmcnt(1)
	v_cvt_pk_bf16_f32 v12, v16, v17
	s_waitcnt lgkmcnt(0)
	v_cvt_pk_bf16_f32 v13, v24, v25
	v_lshl_add_u64 v[14:15], v[14:15], 0, v[20:21]
	global_store_dwordx4 v[14:15], v[10:13], off sc1
	s_waitcnt vmcnt(1)
	v_mov_b64_e32 v[16:17], v[8:9]
	s_andn2_b64 vcc, exec, s[20:21]
	s_mov_b32 s5, s34
	v_mov_b64_e32 v[14:15], v[6:7]
	v_mov_b64_e32 v[12:13], v[4:5]
	v_mov_b64_e32 v[10:11], v[2:3]
	s_mov_b32 s31, s36
	s_mov_b32 s9, s39
	s_mov_b64 s[12:13], s[22:23]
	s_mov_b32 s30, s37
	s_mov_b32 s8, s35
	s_mov_b32 s4, s14
	s_barrier
	s_cbranch_vccz .LBB0_124

; __device__ __forceinline__ unsigned pk2(float lo, float hi) { const f32x2 v = {lo, hi}; const hwbf16x2 b = __builtin_convertvector(v, hwbf16x2); return __builtin_bit_cast(unsigned, b); }
; __device__ __forceinline__ void p0_prep(const Args& a, unsigned char* lds, int tid) {
;     ...
;         for (int idx = bid * NTHREADS + tid; idx < (LORA_K / 8) * 3072; idx += G * NTHREADS) {
;             const int kg = idx / 3072, n = idx % 3072, blk = n >> 10, nn = n & 1023;
;             float v[8];
; #pragma unroll
;             for (int j = 0; j < 8; ++j) { const int k = kg * 8 + j; float x = 0.f;
;                 if (blk == 0) { if (k < 64) x = a.in[I_W2][(size_t)k * D + nn]; }
;                 else if (blk == 1) { if (k >= 64 && k < 128) x = a.in[I_A2][(size_t)(k - 64) * D + nn]; }
;                 else { if (k >= 128 && k < 288) x = a.in[I_G2][(size_t)(k - 128) * D + nn]; }
;                 v[j] = x; }
;             u32x4 o; o.x = pk2(v[0], v[1]); o.y = pk2(v[2], v[3]); o.z = pk2(v[4], v[5]); o.w = pk2(v[6], v[7]);
;             *(u32x4*)(WL + (size_t)n * LORA_K + kg * 8) = o;
;         }
.LBB0_127:
	s_or_b64 exec, exec, s[0:1]
	v_mad_u64_u32 v[12:13], s[0:1], v14, s31, v[2:3]
	v_readlane_b32 s0, v248, 52
	v_ashrrev_i32_e32 v13, 31, v12
	v_readlane_b32 s1, v248, 53
	v_add_u32_e32 v3, s24, v3
	s_waitcnt vmcnt(0)
	v_cvt_pk_bf16_f32 v8, v7, v16
	v_lshl_add_u64 v[12:13], v[12:13], 1, s[0:1]
	v_ashrrev_i32_e32 v7, 31, v6
	v_cmp_lt_i32_e32 vcc, s33, v3
	v_cvt_pk_bf16_f32 v9, v17, v19
	v_cvt_pk_bf16_f32 v10, v20, v21
	v_cvt_pk_bf16_f32 v11, v22, v4
	v_lshl_add_u64 v[6:7], v[6:7], 1, v[12:13]
	s_or_b64 s[12:13], vcc, s[12:13]
	v_add_u32_e32 v2, s25, v2
	global_store_dwordx4 v[6:7], v[8:11], off sc1
	s_andn2_b64 exec, exec, s[12:13]
	s_cbranch_execz .LBB0_239

; __device__ __forceinline__ unsigned cvt_pk_bf16(float lo, float hi) { unsigned r; asm volatile("v_cvt_pk_bf16_f32 %0, %1, %2" : "=v"(r) : "v"(lo), "v"(hi)); return r; }
;     __device__ __forceinline__ void operator()(const f32x4 (&acc)[2][2][4][2], const Unit& u, int wr, int wc, int fr, int fq) const {
;         const int row0 = u.pm * BM + wr * 64 + fr, col0 = u.pn * BM + wc * 32 + 4 * fq;
;         const float* gp = gate + (size_t)(u.pm >> 4) * NMOD;
;         f32x4 gv[2][2], sv[2][2];
; #pragma unroll
;         for (int bj = 0; bj < 2; ++bj)
; #pragma unroll
;             for (int n = 0; n < 2; ++n) { gv[bj][n] = *(const f32x4*)(gp + col0 + bj * HALF + n * 16) * (HALFSC ? 0.5f : 1.0f);
;                 if (FOLD) sv[bj][n] = *(const f32x4*)(scn + (size_t)(u.pm >> 4) * NMOD + col0 + bj * HALF + n * 16) + 1.0f; }
; #pragma unroll
;         for (int ai = 0; ai < 2; ++ai)
; #pragma unroll
;             for (int m = 0; m < 4; ++m) { const int row = row0 + ai * HALF + m * 16; const size_t off = (size_t)row * D + col0;
;                 float ssq = 0.f;
; #pragma unroll
;                 for (int bj = 0; bj < 2; ++bj)
; #pragma unroll
;                     for (int n = 0; n < 2; ++n) { const f32x4 bs = *(const f32x4*)(base + off + bj * HALF + n * 16);
;                         const f32x4 o = bs + gv[bj][n] * acc[ai][bj][m][n];
;                         *(f32x4*)(out + off + bj * HALF + n * 16) = o;
;                         if (FOLD) { ssq += (o.x * o.x + o.y * o.y) + (o.z * o.z + o.w * o.w); const f32x4 q = o * sv[bj][n];
;                             u32x2 w; w.x = cvt_pk_bf16(q.x, q.y); w.y = cvt_pk_bf16(q.z, q.w); *(u32x2*)(U2 + off + bj * HALF + n * 16) = w; } }
;                 if (FOLD) { ssq += __shfl_xor(ssq, 16); ssq += __shfl_xor(ssq, 32);
;                     if (fq == 0) part[(size_t)row * 16 + (u.pn & 3) * 4 + wc] = ssq; } }
.LBB0_427:
	s_ashr_i32 s36, s61, 4
	v_lshl_or_b32 v144, s22, 8, v169
	s_mul_i32 s39, s36, 0x9000
	v_lshl_add_u32 v146, s61, 8, v166
	s_mul_hi_i32 s38, s36, 0x9000
	s_add_u32 s36, s46, s39
	v_ashrrev_i32_e32 v145, 31, v144
	v_ashrrev_i32_e32 v147, 31, v146
	s_addc_u32 s37, s47, s38
	v_lshlrev_b64 v[156:157], 2, v[144:145]
	v_lshlrev_b64 v[152:153], 10, v[146:147]
	v_lshl_add_u64 v[158:159], s[36:37], 0, v[156:157]
	s_add_u32 s36, s48, s39
	v_lshl_add_u64 v[160:161], v[152:153], 0, v[144:145]
	v_readlane_b32 s72, v248, 11
	s_addc_u32 s37, s49, s38
	v_lshlrev_b64 v[186:187], 2, v[160:161]
	v_readlane_b32 s73, v248, 12
	global_load_dwordx4 v[148:151], v[158:159], off
	v_lshl_add_u64 v[156:157], s[36:37], 0, v[156:157]
	v_lshl_add_u64 v[208:209], s[72:73], 0, v[186:187]
	global_load_dwordx4 v[152:155], v[208:209], off
	global_load_dwordx4 v[162:165], v[156:157], off
	v_readlane_b32 s74, v248, 13
	v_readlane_b32 s75, v248, 14
	v_readlane_b32 s76, v248, 15
	v_readlane_b32 s77, v248, 16
	v_readlane_b32 s78, v248, 17
	v_readlane_b32 s79, v248, 18
	v_readlane_b32 s72, v248, 0
	v_readlane_b32 s36, v249, 43
	global_load_dwordx4 v[174:177], v[158:159], off offset:64
	global_load_dwordx4 v[178:181], v[158:159], off offset:512
	global_load_dwordx4 v[182:185], v[158:159], off offset:576
	v_readlane_b32 s78, v248, 6
	v_readlane_b32 s79, v248, 7
	v_readlane_b32 s37, v249, 44
	s_lshl_b32 s22, s22, 2
	v_lshl_add_u64 v[212:213], s[78:79], 0, v[186:187]
	global_load_dwordx4 v[186:189], v[156:157], off offset:64
	global_load_dwordx4 v[190:193], v[156:157], off offset:512
	global_load_dwordx4 v[194:197], v[156:157], off offset:576
	global_load_dwordx4 v[236:239], v[208:209], off offset:64
	global_load_dwordx4 v[240:243], v[208:209], off offset:512
	global_load_dwordx4 v[244:247], v[208:209], off offset:576
	v_lshl_add_u64 v[210:211], v[160:161], 1, s[36:37]
	s_and_b32 s38, s22, 12
	v_readlane_b32 s80, v248, 19
	v_readlane_b32 s81, v248, 20
	v_readlane_b32 s82, v248, 21
	v_readlane_b32 s83, v248, 22
	v_readlane_b32 s84, v248, 23
	v_readlane_b32 s85, v248, 24
	v_readlane_b32 s86, v248, 25
	v_readlane_b32 s87, v248, 26
	v_readlane_b32 s73, v248, 1
	v_readlane_b32 s74, v248, 2
	v_readlane_b32 s75, v248, 3
	v_readlane_b32 s76, v248, 4
	v_readlane_b32 s77, v248, 5
	s_waitcnt vmcnt(3)
	v_pk_mul_f32 v[158:159], v[148:149], 0.5 op_sel_hi:[1,0]
	v_pk_mul_f32 v[156:157], v[150:151], 0.5 op_sel_hi:[1,0]
	v_pk_fma_f32 v[198:199], v[124:125], v[158:159], v[152:153]
	v_pk_add_f32 v[162:163], v[162:163], 1.0 op_sel_hi:[1,0]
	v_pk_fma_f32 v[200:201], v[126:127], v[156:157], v[154:155]
	v_pk_add_f32 v[160:161], v[164:165], 1.0 op_sel_hi:[1,0]
	v_pk_mul_f32 v[126:127], v[162:163], v[198:199]
	global_store_dwordx4 v[212:213], v[198:201], off sc1
	v_pk_mul_f32 v[124:125], v[160:161], v[200:201]
	v_cvt_pk_bf16_f32 v126, v126, v127
	v_pk_mul_f32 v[150:151], v[174:175], 0.5 op_sel_hi:[1,0]
	v_cvt_pk_bf16_f32 v127, v124, v125
	global_store_dwordx2 v[210:211], v[126:127], off
	v_pk_mul_f32 v[154:155], v[176:177], 0.5 op_sel_hi:[1,0]
	v_pk_mul_f32 v[152:153], v[180:181], 0.5 op_sel_hi:[1,0]
	v_pk_add_f32 v[126:127], v[186:187], 1.0 op_sel_hi:[1,0]
	v_pk_add_f32 v[124:125], v[188:189], 1.0 op_sel_hi:[1,0]
	v_pk_mul_f32 v[148:149], v[178:179], 0.5 op_sel_hi:[1,0]
	v_mul_f32_e32 v164, v199, v199
	v_fmac_f32_e32 v164, v198, v198
	s_waitcnt vmcnt(4)
	v_pk_fma_f32 v[186:187], v[120:121], v[150:151], v[236:237]
	v_pk_fma_f32 v[188:189], v[122:123], v[154:155], v[238:239]
	v_pk_mul_f32 v[122:123], v[126:127], v[186:187]
	global_store_dwordx4 v[212:213], v[186:189], off offset:64 sc1
	v_pk_mul_f32 v[120:121], v[124:125], v[188:189]
	v_cvt_pk_bf16_f32 v122, v122, v123
	v_mul_f32_e32 v180, v189, v189
	v_cvt_pk_bf16_f32 v123, v120, v121
	global_store_dwordx2 v[210:211], v[122:123], off offset:32
	v_pk_add_f32 v[122:123], v[190:191], 1.0 op_sel_hi:[1,0]
	v_pk_add_f32 v[120:121], v[192:193], 1.0 op_sel_hi:[1,0]
	v_fmac_f32_e32 v180, v188, v188
	s_waitcnt vmcnt(5)
	v_pk_fma_f32 v[178:179], v[118:119], v[152:153], v[242:243]
	v_pk_fma_f32 v[176:177], v[116:117], v[148:149], v[240:241]
	global_store_dwordx4 v[212:213], v[176:179], off offset:512 sc1
	v_pk_mul_f32 v[118:119], v[122:123], v[176:177]
	v_pk_mul_f32 v[116:117], v[120:121], v[178:179]
	v_cvt_pk_bf16_f32 v118, v118, v119
	v_mul_f32_e32 v175, v201, v201
	v_cvt_pk_bf16_f32 v119, v116, v117
	global_store_dwordx2 v[210:211], v[118:119], off offset:256
	v_fmac_f32_e32 v175, v200, v200
	v_and_b32_e32 v117, 64, v173
	v_add_f32_e32 v164, v164, v175
	v_mul_f32_e32 v175, v187, v187
	v_xor_b32_e32 v116, 16, v173
	v_add_u32_e32 v117, 64, v117
	v_fmac_f32_e32 v175, v186, v186
	v_xor_b32_e32 v118, 32, v173
	v_cmp_lt_i32_e32 vcc, v116, v117
	v_add_f32_e32 v175, v175, v180
	v_add_f32_e32 v164, v164, v175
	v_cndmask_b32_e32 v116, v173, v116, vcc
	v_cmp_lt_i32_e32 vcc, v118, v117
	v_mul_f32_e32 v175, v177, v177
	v_mul_f32_e32 v177, v179, v179
	v_cndmask_b32_e32 v165, v173, v118, vcc
	v_lshlrev_b32_e32 v174, 2, v116
	v_pk_mul_f32 v[118:119], v[184:185], 0.5 op_sel_hi:[1,0]
	v_pk_mul_f32 v[116:117], v[182:183], 0.5 op_sel_hi:[1,0]
	v_fmac_f32_e32 v175, v176, v176
	v_fmac_f32_e32 v177, v178, v178
	v_add_f32_e32 v175, v175, v177
	v_add_f32_e32 v164, v164, v175
	s_waitcnt vmcnt(6)
	v_pk_fma_f32 v[178:179], v[114:115], v[118:119], v[246:247]
	v_pk_fma_f32 v[176:177], v[112:113], v[116:117], v[244:245]
	v_mul_f32_e32 v113, v179, v179
	v_mul_f32_e32 v112, v177, v177
	v_fmac_f32_e32 v112, v176, v176
	v_fmac_f32_e32 v113, v178, v178
	v_add_f32_e32 v112, v112, v113
	v_add_f32_e32 v164, v164, v112
	ds_bpermute_b32 v175, v174, v164
	v_pk_add_f32 v[112:113], v[194:195], 1.0 op_sel_hi:[1,0]
	v_pk_add_f32 v[114:115], v[196:197], 1.0 op_sel_hi:[1,0]
	global_store_dwordx4 v[212:213], v[176:179], off offset:576 sc1
	s_waitcnt lgkmcnt(0)
	v_add_f32_e32 v164, v164, v175
	v_lshlrev_b32_e32 v175, 2, v165
	ds_bpermute_b32 v165, v175, v164
	v_pk_mul_f32 v[176:177], v[112:113], v[176:177]
	v_pk_mul_f32 v[178:179], v[114:115], v[178:179]
	v_cvt_pk_bf16_f32 v176, v176, v177
	s_nop 0
	v_cvt_pk_bf16_f32 v177, v178, v179
	global_store_dwordx2 v[210:211], v[176:177], off offset:288
	s_and_saveexec_b64 s[36:37], s[0:1]
	s_cbranch_execz .LBB0_429
	v_readlane_b32 s40, v249, 31
	s_waitcnt lgkmcnt(0)
	v_add_f32_e32 v176, v164, v165
	v_lshlrev_b64 v[164:165], 6, v[146:147]
	v_readlane_b32 s41, v249, 32
	s_lshl_b32 s22, s38, 2
	s_nop 0
	v_lshl_add_u64 v[164:165], s[40:41], 0, v[164:165]
	v_lshl_add_u64 v[164:165], v[164:165], 0, s[22:23]
	s_lshl_b32 s22, s50, 2
	v_lshl_add_u64 v[164:165], v[164:165], 0, s[22:23]
	global_store_dword v[164:165], v176, off
; __device__ __forceinline__ unsigned cvt_pk_bf16(float lo, float hi) { unsigned r; asm volatile("v_cvt_pk_bf16_f32 %0, %1, %2" : "=v"(r) : "v"(lo), "v"(hi)); return r; }
;     __device__ __forceinline__ void operator()(const f32x4 (&acc)[2][2][4][2], const Unit& u, int wr, int wc, int fr, int fq) const {
;     ...
;         for (int ai = 0; ai < 2; ++ai)
; #pragma unroll
;             for (int m = 0; m < 4; ++m) { const int row = row0 + ai * HALF + m * 16; const size_t off = (size_t)row * D + col0;
;                 float ssq = 0.f;
; #pragma unroll
;                 for (int bj = 0; bj < 2; ++bj)
; #pragma unroll
;                     for (int n = 0; n < 2; ++n) { const f32x4 bs = *(const f32x4*)(base + off + bj * HALF + n * 16);
;                         const f32x4 o = bs + gv[bj][n] * acc[ai][bj][m][n];
;                         *(f32x4*)(out + off + bj * HALF + n * 16) = o;
;                         if (FOLD) { ssq += (o.x * o.x + o.y * o.y) + (o.z * o.z + o.w * o.w); const f32x4 q = o * sv[bj][n];
;                             u32x2 w; w.x = cvt_pk_bf16(q.x, q.y); w.y = cvt_pk_bf16(q.z, q.w); *(u32x2*)(U2 + off + bj * HALF + n * 16) = w; } }
;                 if (FOLD) { ssq += __shfl_xor(ssq, 16); ssq += __shfl_xor(ssq, 32);
;                     if (fq == 0) part[(size_t)row * 16 + (u.pn & 3) * 4 + wc] = ssq; } }
.LBB0_429:
	s_or_b64 exec, exec, s[36:37]
	v_or_b32_e32 v164, 16, v146
	s_waitcnt lgkmcnt(0)
	v_ashrrev_i32_e32 v165, 31, v164
	v_lshlrev_b64 v[176:177], 10, v[164:165]
	v_lshl_add_u64 v[180:181], v[176:177], 0, v[144:145]
	v_readlane_b32 s72, v248, 11
	v_lshlrev_b64 v[182:183], 2, v[180:181]
	v_readlane_b32 s73, v248, 12
	v_readlane_b32 s74, v248, 13
	v_readlane_b32 s75, v248, 14
	v_lshl_add_u64 v[184:185], s[72:73], 0, v[182:183]
	global_load_dwordx4 v[236:239], v[184:185], off
	global_load_dwordx4 v[240:243], v[184:185], off offset:64
	global_load_dwordx4 v[244:247], v[184:185], off offset:512
	global_load_dwordx4 v[176:179], v[184:185], off offset:576
	v_readlane_b32 s76, v248, 15
	v_readlane_b32 s77, v248, 16
	v_readlane_b32 s78, v248, 17
	v_readlane_b32 s79, v248, 18
	v_readlane_b32 s36, v249, 43
	v_readlane_b32 s72, v248, 0
	v_readlane_b32 s37, v249, 44
	v_readlane_b32 s78, v248, 6
	v_readlane_b32 s79, v248, 7
	v_lshl_add_u64 v[180:181], v[180:181], 1, s[36:37]
	v_readlane_b32 s80, v248, 19
	v_lshl_add_u64 v[182:183], s[78:79], 0, v[182:183]
	v_readlane_b32 s81, v248, 20
	v_readlane_b32 s82, v248, 21
	v_readlane_b32 s83, v248, 22
	v_readlane_b32 s84, v248, 23
	v_readlane_b32 s85, v248, 24
	v_readlane_b32 s86, v248, 25
	v_readlane_b32 s87, v248, 26
	v_readlane_b32 s73, v248, 1
	v_readlane_b32 s74, v248, 2
	v_readlane_b32 s75, v248, 3
	v_readlane_b32 s76, v248, 4
	v_readlane_b32 s77, v248, 5
	s_waitcnt vmcnt(3)
	v_pk_fma_f32 v[108:109], v[108:109], v[158:159], v[236:237]
	v_pk_fma_f32 v[110:111], v[110:111], v[156:157], v[238:239]
	v_pk_mul_f32 v[238:239], v[162:163], v[108:109]
	global_store_dwordx4 v[182:183], v[108:111], off sc1
	v_pk_mul_f32 v[236:237], v[160:161], v[110:111]
	v_cvt_pk_bf16_f32 v238, v238, v239
	s_nop 0
	v_cvt_pk_bf16_f32 v239, v236, v237
	global_store_dwordx2 v[180:181], v[238:239], off
	v_mul_f32_e32 v109, v109, v109
	v_mul_f32_e32 v111, v111, v111
	v_fmac_f32_e32 v109, v108, v108
	v_fmac_f32_e32 v111, v110, v110
	v_add_f32_e32 v108, v109, v111
	s_waitcnt vmcnt(4)
	v_pk_fma_f32 v[104:105], v[104:105], v[150:151], v[240:241]
	v_pk_fma_f32 v[106:107], v[106:107], v[154:155], v[242:243]
	v_pk_mul_f32 v[242:243], v[126:127], v[104:105]
	global_store_dwordx4 v[182:183], v[104:107], off offset:64 sc1
	v_pk_mul_f32 v[240:241], v[124:125], v[106:107]
	v_cvt_pk_bf16_f32 v242, v242, v243
	s_nop 0
	v_cvt_pk_bf16_f32 v243, v240, v241
	global_store_dwordx2 v[180:181], v[242:243], off offset:32
	v_mul_f32_e32 v105, v105, v105
	v_mul_f32_e32 v107, v107, v107
	v_fmac_f32_e32 v105, v104, v104
	v_fmac_f32_e32 v107, v106, v106
	v_add_f32_e32 v104, v105, v107
	v_add_f32_e32 v104, v108, v104
	s_waitcnt vmcnt(5)
	v_pk_fma_f32 v[100:101], v[100:101], v[148:149], v[244:245]
	v_pk_fma_f32 v[102:103], v[102:103], v[152:153], v[246:247]
	v_pk_mul_f32 v[246:247], v[122:123], v[100:101]
	global_store_dwordx4 v[182:183], v[100:103], off offset:512 sc1
	v_pk_mul_f32 v[244:245], v[120:121], v[102:103]
	v_cvt_pk_bf16_f32 v246, v246, v247
	s_nop 0
	v_cvt_pk_bf16_f32 v247, v244, v245
	global_store_dwordx2 v[180:181], v[246:247], off offset:256
	v_mul_f32_e32 v101, v101, v101
	v_mul_f32_e32 v103, v103, v103
	v_fmac_f32_e32 v101, v100, v100
	v_fmac_f32_e32 v103, v102, v102
	v_add_f32_e32 v100, v101, v103
	v_add_f32_e32 v102, v104, v100
	s_waitcnt vmcnt(6)
	v_pk_fma_f32 v[100:101], v[98:99], v[118:119], v[178:179]
	v_pk_fma_f32 v[98:99], v[96:97], v[116:117], v[176:177]
	v_mul_f32_e32 v97, v101, v101
	v_mul_f32_e32 v96, v99, v99
	v_fmac_f32_e32 v96, v98, v98
	v_fmac_f32_e32 v97, v100, v100
	v_add_f32_e32 v96, v96, v97
	v_add_f32_e32 v96, v102, v96
	ds_bpermute_b32 v97, v174, v96
	global_store_dwordx4 v[182:183], v[98:101], off offset:576 sc1
	s_waitcnt lgkmcnt(0)
	v_add_f32_e32 v96, v96, v97
	ds_bpermute_b32 v97, v175, v96
	v_pk_mul_f32 v[98:99], v[112:113], v[98:99]
	v_pk_mul_f32 v[100:101], v[114:115], v[100:101]
	v_cvt_pk_bf16_f32 v98, v98, v99
	s_nop 0
	v_cvt_pk_bf16_f32 v99, v100, v101
	global_store_dwordx2 v[180:181], v[98:99], off offset:288
	s_and_saveexec_b64 s[36:37], s[0:1]
	s_cbranch_execz .LBB0_431
	v_readlane_b32 s40, v249, 31
	s_waitcnt lgkmcnt(0)
	v_add_f32_e32 v98, v96, v97
	v_lshlrev_b64 v[96:97], 6, v[164:165]
	v_readlane_b32 s41, v249, 32
	s_lshl_b32 s22, s38, 2
	s_nop 0
	v_lshl_add_u64 v[96:97], s[40:41], 0, v[96:97]
	v_lshl_add_u64 v[96:97], v[96:97], 0, s[22:23]
	s_lshl_b32 s22, s50, 2
	v_lshl_add_u64 v[96:97], v[96:97], 0, s[22:23]
	global_store_dword v[96:97], v98, off
; __device__ __forceinline__ unsigned cvt_pk_bf16(float lo, float hi) { unsigned r; asm volatile("v_cvt_pk_bf16_f32 %0, %1, %2" : "=v"(r) : "v"(lo), "v"(hi)); return r; }
;     __device__ __forceinline__ void operator()(const f32x4 (&acc)[2][2][4][2], const Unit& u, int wr, int wc, int fr, int fq) const {
;     ...
;         for (int ai = 0; ai < 2; ++ai)
; #pragma unroll
;             for (int m = 0; m < 4; ++m) { const int row = row0 + ai * HALF + m * 16; const size_t off = (size_t)row * D + col0;
;                 float ssq = 0.f;
; #pragma unroll
;                 for (int bj = 0; bj < 2; ++bj)
; #pragma unroll
;                     for (int n = 0; n < 2; ++n) { const f32x4 bs = *(const f32x4*)(base + off + bj * HALF + n * 16);
;                         const f32x4 o = bs + gv[bj][n] * acc[ai][bj][m][n];
;                         *(f32x4*)(out + off + bj * HALF + n * 16) = o;
;                         if (FOLD) { ssq += (o.x * o.x + o.y * o.y) + (o.z * o.z + o.w * o.w); const f32x4 q = o * sv[bj][n];
;                             u32x2 w; w.x = cvt_pk_bf16(q.x, q.y); w.y = cvt_pk_bf16(q.z, q.w); *(u32x2*)(U2 + off + bj * HALF + n * 16) = w; } }
;                 if (FOLD) { ssq += __shfl_xor(ssq, 16); ssq += __shfl_xor(ssq, 32);
;                     if (fq == 0) part[(size_t)row * 16 + (u.pn & 3) * 4 + wc] = ssq; } }
.LBB0_431:
	s_or_b64 exec, exec, s[36:37]
	v_or_b32_e32 v96, 32, v146
	s_waitcnt lgkmcnt(0)
	v_ashrrev_i32_e32 v97, 31, v96
	v_lshlrev_b64 v[98:99], 10, v[96:97]
	v_lshl_add_u64 v[102:103], v[98:99], 0, v[144:145]
	v_readlane_b32 s72, v248, 11
	v_lshlrev_b64 v[104:105], 2, v[102:103]
	v_readlane_b32 s73, v248, 12
	v_readlane_b32 s74, v248, 13
	v_readlane_b32 s75, v248, 14
	v_lshl_add_u64 v[106:107], s[72:73], 0, v[104:105]
	global_load_dwordx4 v[236:239], v[106:107], off
	global_load_dwordx4 v[240:243], v[106:107], off offset:64
	global_load_dwordx4 v[244:247], v[106:107], off offset:512
	global_load_dwordx4 v[98:101], v[106:107], off offset:576
	v_readlane_b32 s76, v248, 15
	v_readlane_b32 s77, v248, 16
	v_readlane_b32 s78, v248, 17
	v_readlane_b32 s79, v248, 18
	v_readlane_b32 s36, v249, 43
	v_readlane_b32 s72, v248, 0
	v_readlane_b32 s37, v249, 44
	v_readlane_b32 s78, v248, 6
	v_readlane_b32 s79, v248, 7
	v_lshl_add_u64 v[102:103], v[102:103], 1, s[36:37]
	v_readlane_b32 s80, v248, 19
	v_lshl_add_u64 v[104:105], s[78:79], 0, v[104:105]
	v_readlane_b32 s81, v248, 20
	v_readlane_b32 s82, v248, 21
	v_readlane_b32 s83, v248, 22
	v_readlane_b32 s84, v248, 23
	v_readlane_b32 s85, v248, 24
	v_readlane_b32 s86, v248, 25
	v_readlane_b32 s87, v248, 26
	v_readlane_b32 s73, v248, 1
	v_readlane_b32 s74, v248, 2
	v_readlane_b32 s75, v248, 3
	v_readlane_b32 s76, v248, 4
	v_readlane_b32 s77, v248, 5
	s_waitcnt vmcnt(3)
	v_pk_fma_f32 v[92:93], v[92:93], v[158:159], v[236:237]
	v_pk_fma_f32 v[94:95], v[94:95], v[156:157], v[238:239]
	v_pk_mul_f32 v[238:239], v[162:163], v[92:93]
	global_store_dwordx4 v[104:105], v[92:95], off sc1
	v_pk_mul_f32 v[236:237], v[160:161], v[94:95]
	v_cvt_pk_bf16_f32 v238, v238, v239
	s_nop 0
	v_cvt_pk_bf16_f32 v239, v236, v237
	global_store_dwordx2 v[102:103], v[238:239], off
	v_mul_f32_e32 v93, v93, v93
	v_mul_f32_e32 v95, v95, v95
	v_fmac_f32_e32 v93, v92, v92
	v_fmac_f32_e32 v95, v94, v94
	v_add_f32_e32 v92, v93, v95
	s_waitcnt vmcnt(4)
	v_pk_fma_f32 v[88:89], v[88:89], v[150:151], v[240:241]
	v_pk_fma_f32 v[90:91], v[90:91], v[154:155], v[242:243]
	v_pk_mul_f32 v[242:243], v[126:127], v[88:89]
	global_store_dwordx4 v[104:105], v[88:91], off offset:64 sc1
	v_pk_mul_f32 v[240:241], v[124:125], v[90:91]
	v_cvt_pk_bf16_f32 v242, v242, v243
	s_nop 0
	v_cvt_pk_bf16_f32 v243, v240, v241
	global_store_dwordx2 v[102:103], v[242:243], off offset:32
	v_mul_f32_e32 v89, v89, v89
	v_mul_f32_e32 v91, v91, v91
	v_fmac_f32_e32 v89, v88, v88
	v_fmac_f32_e32 v91, v90, v90
	v_add_f32_e32 v88, v89, v91
	v_add_f32_e32 v88, v92, v88
	s_waitcnt vmcnt(5)
	v_pk_fma_f32 v[84:85], v[84:85], v[148:149], v[244:245]
	v_pk_fma_f32 v[86:87], v[86:87], v[152:153], v[246:247]
	v_pk_mul_f32 v[246:247], v[122:123], v[84:85]
	global_store_dwordx4 v[104:105], v[84:87], off offset:512 sc1
	v_pk_mul_f32 v[244:245], v[120:121], v[86:87]
	v_cvt_pk_bf16_f32 v246, v246, v247
	s_nop 0
	v_cvt_pk_bf16_f32 v247, v244, v245
	global_store_dwordx2 v[102:103], v[246:247], off offset:256
	v_mul_f32_e32 v85, v85, v85
	v_mul_f32_e32 v87, v87, v87
	v_fmac_f32_e32 v85, v84, v84
	v_fmac_f32_e32 v87, v86, v86
	v_add_f32_e32 v84, v85, v87
	v_add_f32_e32 v86, v88, v84
	s_waitcnt vmcnt(6)
	v_pk_fma_f32 v[84:85], v[82:83], v[118:119], v[100:101]
	v_pk_fma_f32 v[82:83], v[80:81], v[116:117], v[98:99]
	v_mul_f32_e32 v81, v85, v85
	v_mul_f32_e32 v80, v83, v83
	v_fmac_f32_e32 v80, v82, v82
	v_fmac_f32_e32 v81, v84, v84
	v_add_f32_e32 v80, v80, v81
	v_add_f32_e32 v80, v86, v80
	ds_bpermute_b32 v81, v174, v80
	global_store_dwordx4 v[104:105], v[82:85], off offset:576 sc1
	s_waitcnt lgkmcnt(0)
	v_add_f32_e32 v80, v80, v81
	ds_bpermute_b32 v81, v175, v80
	v_pk_mul_f32 v[82:83], v[112:113], v[82:83]
	v_pk_mul_f32 v[84:85], v[114:115], v[84:85]
	v_cvt_pk_bf16_f32 v82, v82, v83
	s_nop 0
	v_cvt_pk_bf16_f32 v83, v84, v85
	global_store_dwordx2 v[102:103], v[82:83], off offset:288
	s_and_saveexec_b64 s[36:37], s[0:1]
	s_cbranch_execz .LBB0_433
	v_readlane_b32 s40, v249, 31
	s_waitcnt lgkmcnt(0)
	v_add_f32_e32 v82, v80, v81
	v_lshlrev_b64 v[80:81], 6, v[96:97]
	v_readlane_b32 s41, v249, 32
	s_lshl_b32 s22, s38, 2
	s_nop 0
	v_lshl_add_u64 v[80:81], s[40:41], 0, v[80:81]
	v_lshl_add_u64 v[80:81], v[80:81], 0, s[22:23]
	s_lshl_b32 s22, s50, 2
	v_lshl_add_u64 v[80:81], v[80:81], 0, s[22:23]
	global_store_dword v[80:81], v82, off
; __device__ __forceinline__ unsigned cvt_pk_bf16(float lo, float hi) { unsigned r; asm volatile("v_cvt_pk_bf16_f32 %0, %1, %2" : "=v"(r) : "v"(lo), "v"(hi)); return r; }
;     __device__ __forceinline__ void operator()(const f32x4 (&acc)[2][2][4][2], const Unit& u, int wr, int wc, int fr, int fq) const {
;     ...
;         for (int ai = 0; ai < 2; ++ai)
; #pragma unroll
;             for (int m = 0; m < 4; ++m) { const int row = row0 + ai * HALF + m * 16; const size_t off = (size_t)row * D + col0;
;                 float ssq = 0.f;
; #pragma unroll
;                 for (int bj = 0; bj < 2; ++bj)
; #pragma unroll
;                     for (int n = 0; n < 2; ++n) { const f32x4 bs = *(const f32x4*)(base + off + bj * HALF + n * 16);
;                         const f32x4 o = bs + gv[bj][n] * acc[ai][bj][m][n];
;                         *(f32x4*)(out + off + bj * HALF + n * 16) = o;
;                         if (FOLD) { ssq += (o.x * o.x + o.y * o.y) + (o.z * o.z + o.w * o.w); const f32x4 q = o * sv[bj][n];
;                             u32x2 w; w.x = cvt_pk_bf16(q.x, q.y); w.y = cvt_pk_bf16(q.z, q.w); *(u32x2*)(U2 + off + bj * HALF + n * 16) = w; } }
;                 if (FOLD) { ssq += __shfl_xor(ssq, 16); ssq += __shfl_xor(ssq, 32);
;                     if (fq == 0) part[(size_t)row * 16 + (u.pn & 3) * 4 + wc] = ssq; } }
.LBB0_433:
	s_or_b64 exec, exec, s[36:37]
	v_or_b32_e32 v80, 48, v146
	s_waitcnt lgkmcnt(0)
	v_ashrrev_i32_e32 v81, 31, v80
	v_lshlrev_b64 v[82:83], 10, v[80:81]
	v_lshl_add_u64 v[86:87], v[82:83], 0, v[144:145]
	v_readlane_b32 s72, v248, 11
	v_lshlrev_b64 v[88:89], 2, v[86:87]
	v_readlane_b32 s73, v248, 12
	v_readlane_b32 s74, v248, 13
	v_readlane_b32 s75, v248, 14
	v_lshl_add_u64 v[90:91], s[72:73], 0, v[88:89]
	global_load_dwordx4 v[236:239], v[90:91], off
	global_load_dwordx4 v[240:243], v[90:91], off offset:64
	global_load_dwordx4 v[244:247], v[90:91], off offset:512
	global_load_dwordx4 v[82:85], v[90:91], off offset:576
	v_readlane_b32 s76, v248, 15
	v_readlane_b32 s77, v248, 16
	v_readlane_b32 s78, v248, 17
	v_readlane_b32 s79, v248, 18
	v_readlane_b32 s36, v249, 43
	v_readlane_b32 s72, v248, 0
	v_readlane_b32 s37, v249, 44
	v_readlane_b32 s78, v248, 6
	v_readlane_b32 s79, v248, 7
	v_lshl_add_u64 v[86:87], v[86:87], 1, s[36:37]
	v_readlane_b32 s80, v248, 19
	v_lshl_add_u64 v[88:89], s[78:79], 0, v[88:89]
	v_readlane_b32 s81, v248, 20
	v_readlane_b32 s82, v248, 21
	v_readlane_b32 s83, v248, 22
	v_readlane_b32 s84, v248, 23
	v_readlane_b32 s85, v248, 24
	v_readlane_b32 s86, v248, 25
	v_readlane_b32 s87, v248, 26
	v_readlane_b32 s73, v248, 1
	v_readlane_b32 s74, v248, 2
	v_readlane_b32 s75, v248, 3
	v_readlane_b32 s76, v248, 4
	v_readlane_b32 s77, v248, 5
	s_waitcnt vmcnt(3)
	v_pk_fma_f32 v[76:77], v[76:77], v[158:159], v[236:237]
	v_pk_fma_f32 v[78:79], v[78:79], v[156:157], v[238:239]
	v_pk_mul_f32 v[238:239], v[162:163], v[76:77]
	global_store_dwordx4 v[88:89], v[76:79], off sc1
	v_pk_mul_f32 v[236:237], v[160:161], v[78:79]
	v_cvt_pk_bf16_f32 v238, v238, v239
	s_nop 0
	v_cvt_pk_bf16_f32 v239, v236, v237
	global_store_dwordx2 v[86:87], v[238:239], off
	v_mul_f32_e32 v77, v77, v77
	v_mul_f32_e32 v79, v79, v79
	v_fmac_f32_e32 v77, v76, v76
	v_fmac_f32_e32 v79, v78, v78
	v_add_f32_e32 v76, v77, v79
	s_waitcnt vmcnt(4)
	v_pk_fma_f32 v[72:73], v[72:73], v[150:151], v[240:241]
	v_pk_fma_f32 v[74:75], v[74:75], v[154:155], v[242:243]
	v_pk_mul_f32 v[242:243], v[126:127], v[72:73]
	global_store_dwordx4 v[88:89], v[72:75], off offset:64 sc1
	v_pk_mul_f32 v[240:241], v[124:125], v[74:75]
	v_cvt_pk_bf16_f32 v242, v242, v243
	s_nop 0
	v_cvt_pk_bf16_f32 v243, v240, v241
	global_store_dwordx2 v[86:87], v[242:243], off offset:32
	v_mul_f32_e32 v73, v73, v73
	v_mul_f32_e32 v75, v75, v75
	v_fmac_f32_e32 v73, v72, v72
	v_fmac_f32_e32 v75, v74, v74
	v_add_f32_e32 v72, v73, v75
	v_add_f32_e32 v72, v76, v72
	s_waitcnt vmcnt(5)
	v_pk_fma_f32 v[68:69], v[68:69], v[148:149], v[244:245]
	v_pk_fma_f32 v[70:71], v[70:71], v[152:153], v[246:247]
	v_pk_mul_f32 v[246:247], v[122:123], v[68:69]
	global_store_dwordx4 v[88:89], v[68:71], off offset:512 sc1
	v_pk_mul_f32 v[244:245], v[120:121], v[70:71]
	v_cvt_pk_bf16_f32 v246, v246, v247
	s_nop 0
	v_cvt_pk_bf16_f32 v247, v244, v245
	global_store_dwordx2 v[86:87], v[246:247], off offset:256
	v_mul_f32_e32 v69, v69, v69
	v_mul_f32_e32 v71, v71, v71
	v_fmac_f32_e32 v69, v68, v68
	v_fmac_f32_e32 v71, v70, v70
	v_add_f32_e32 v68, v69, v71
	v_add_f32_e32 v70, v72, v68
	s_waitcnt vmcnt(6)
	v_pk_fma_f32 v[68:69], v[66:67], v[118:119], v[84:85]
	v_pk_fma_f32 v[66:67], v[64:65], v[116:117], v[82:83]
	v_mul_f32_e32 v65, v69, v69
	v_mul_f32_e32 v64, v67, v67
	v_fmac_f32_e32 v64, v66, v66
	v_fmac_f32_e32 v65, v68, v68
	v_add_f32_e32 v64, v64, v65
	v_add_f32_e32 v64, v70, v64
	ds_bpermute_b32 v65, v174, v64
	global_store_dwordx4 v[88:89], v[66:69], off offset:576 sc1
	s_waitcnt lgkmcnt(0)
	v_add_f32_e32 v64, v64, v65
	ds_bpermute_b32 v65, v175, v64
	v_pk_mul_f32 v[66:67], v[112:113], v[66:67]
	v_pk_mul_f32 v[68:69], v[114:115], v[68:69]
	v_cvt_pk_bf16_f32 v66, v66, v67
	s_nop 0
	v_cvt_pk_bf16_f32 v67, v68, v69
	global_store_dwordx2 v[86:87], v[66:67], off offset:288
	s_and_saveexec_b64 s[36:37], s[0:1]
	s_cbranch_execz .LBB0_435
	v_readlane_b32 s40, v249, 31
	s_waitcnt lgkmcnt(0)
	v_add_f32_e32 v66, v64, v65
	v_lshlrev_b64 v[64:65], 6, v[80:81]
	v_readlane_b32 s41, v249, 32
	s_lshl_b32 s22, s38, 2
	s_nop 0
	v_lshl_add_u64 v[64:65], s[40:41], 0, v[64:65]
	v_lshl_add_u64 v[64:65], v[64:65], 0, s[22:23]
	s_lshl_b32 s22, s50, 2
	v_lshl_add_u64 v[64:65], v[64:65], 0, s[22:23]
	global_store_dword v[64:65], v66, off
; __device__ __forceinline__ unsigned cvt_pk_bf16(float lo, float hi) { unsigned r; asm volatile("v_cvt_pk_bf16_f32 %0, %1, %2" : "=v"(r) : "v"(lo), "v"(hi)); return r; }
;     __device__ __forceinline__ void operator()(const f32x4 (&acc)[2][2][4][2], const Unit& u, int wr, int wc, int fr, int fq) const {
;     ...
;         for (int ai = 0; ai < 2; ++ai)
; #pragma unroll
;             for (int m = 0; m < 4; ++m) { const int row = row0 + ai * HALF + m * 16; const size_t off = (size_t)row * D + col0;
;                 float ssq = 0.f;
; #pragma unroll
;                 for (int bj = 0; bj < 2; ++bj)
; #pragma unroll
;                     for (int n = 0; n < 2; ++n) { const f32x4 bs = *(const f32x4*)(base + off + bj * HALF + n * 16);
;                         const f32x4 o = bs + gv[bj][n] * acc[ai][bj][m][n];
;                         *(f32x4*)(out + off + bj * HALF + n * 16) = o;
;                         if (FOLD) { ssq += (o.x * o.x + o.y * o.y) + (o.z * o.z + o.w * o.w); const f32x4 q = o * sv[bj][n];
;                             u32x2 w; w.x = cvt_pk_bf16(q.x, q.y); w.y = cvt_pk_bf16(q.z, q.w); *(u32x2*)(U2 + off + bj * HALF + n * 16) = w; } }
;                 if (FOLD) { ssq += __shfl_xor(ssq, 16); ssq += __shfl_xor(ssq, 32);
;                     if (fq == 0) part[(size_t)row * 16 + (u.pn & 3) * 4 + wc] = ssq; } }
.LBB0_435:
	s_or_b64 exec, exec, s[36:37]
	v_add_u32_e32 v64, 0x80, v146
	s_waitcnt lgkmcnt(0)
	v_ashrrev_i32_e32 v65, 31, v64
	v_lshlrev_b64 v[66:67], 10, v[64:65]
	v_lshl_add_u64 v[70:71], v[66:67], 0, v[144:145]
	v_readlane_b32 s72, v248, 11
	v_lshlrev_b64 v[72:73], 2, v[70:71]
	v_readlane_b32 s73, v248, 12
	v_readlane_b32 s74, v248, 13
	v_readlane_b32 s75, v248, 14
	v_lshl_add_u64 v[74:75], s[72:73], 0, v[72:73]
	global_load_dwordx4 v[236:239], v[74:75], off
	global_load_dwordx4 v[240:243], v[74:75], off offset:64
	global_load_dwordx4 v[244:247], v[74:75], off offset:512
	global_load_dwordx4 v[66:69], v[74:75], off offset:576
	v_readlane_b32 s76, v248, 15
	v_readlane_b32 s77, v248, 16
	v_readlane_b32 s78, v248, 17
	v_readlane_b32 s79, v248, 18
	v_readlane_b32 s36, v249, 43
	v_readlane_b32 s72, v248, 0
	v_readlane_b32 s37, v249, 44
	v_readlane_b32 s78, v248, 6
	v_readlane_b32 s79, v248, 7
	v_lshl_add_u64 v[70:71], v[70:71], 1, s[36:37]
	v_readlane_b32 s80, v248, 19
	v_lshl_add_u64 v[72:73], s[78:79], 0, v[72:73]
	v_readlane_b32 s81, v248, 20
	v_readlane_b32 s82, v248, 21
	v_readlane_b32 s83, v248, 22
	v_readlane_b32 s84, v248, 23
	v_readlane_b32 s85, v248, 24
	v_readlane_b32 s86, v248, 25
	v_readlane_b32 s87, v248, 26
	v_readlane_b32 s73, v248, 1
	v_readlane_b32 s74, v248, 2
	v_readlane_b32 s75, v248, 3
	v_readlane_b32 s76, v248, 4
	v_readlane_b32 s77, v248, 5
	s_waitcnt vmcnt(3)
	v_pk_fma_f32 v[60:61], v[60:61], v[158:159], v[236:237]
	v_pk_fma_f32 v[62:63], v[62:63], v[156:157], v[238:239]
	v_pk_mul_f32 v[238:239], v[162:163], v[60:61]
	global_store_dwordx4 v[72:73], v[60:63], off sc1
	v_pk_mul_f32 v[236:237], v[160:161], v[62:63]
	v_cvt_pk_bf16_f32 v238, v238, v239
	s_nop 0
	v_cvt_pk_bf16_f32 v239, v236, v237
	global_store_dwordx2 v[70:71], v[238:239], off
	v_mul_f32_e32 v61, v61, v61
	v_mul_f32_e32 v63, v63, v63
	v_fmac_f32_e32 v61, v60, v60
	v_fmac_f32_e32 v63, v62, v62
	v_add_f32_e32 v60, v61, v63
	s_waitcnt vmcnt(4)
	v_pk_fma_f32 v[56:57], v[56:57], v[150:151], v[240:241]
	v_pk_fma_f32 v[58:59], v[58:59], v[154:155], v[242:243]
	v_pk_mul_f32 v[242:243], v[126:127], v[56:57]
	global_store_dwordx4 v[72:73], v[56:59], off offset:64 sc1
	v_pk_mul_f32 v[240:241], v[124:125], v[58:59]
	v_cvt_pk_bf16_f32 v242, v242, v243
	s_nop 0
	v_cvt_pk_bf16_f32 v243, v240, v241
	global_store_dwordx2 v[70:71], v[242:243], off offset:32
	v_mul_f32_e32 v57, v57, v57
	v_mul_f32_e32 v59, v59, v59
	v_fmac_f32_e32 v57, v56, v56
	v_fmac_f32_e32 v59, v58, v58
	v_add_f32_e32 v56, v57, v59
	v_add_f32_e32 v56, v60, v56
	s_waitcnt vmcnt(5)
	v_pk_fma_f32 v[52:53], v[52:53], v[148:149], v[244:245]
	v_pk_fma_f32 v[54:55], v[54:55], v[152:153], v[246:247]
	v_pk_mul_f32 v[246:247], v[122:123], v[52:53]
	global_store_dwordx4 v[72:73], v[52:55], off offset:512 sc1
	v_pk_mul_f32 v[244:245], v[120:121], v[54:55]
	v_cvt_pk_bf16_f32 v246, v246, v247
	s_nop 0
	v_cvt_pk_bf16_f32 v247, v244, v245
	global_store_dwordx2 v[70:71], v[246:247], off offset:256
	v_mul_f32_e32 v53, v53, v53
	v_mul_f32_e32 v55, v55, v55
	v_fmac_f32_e32 v53, v52, v52
	v_fmac_f32_e32 v55, v54, v54
	v_add_f32_e32 v52, v53, v55
	v_add_f32_e32 v54, v56, v52
	s_waitcnt vmcnt(6)
	v_pk_fma_f32 v[52:53], v[50:51], v[118:119], v[68:69]
	v_pk_fma_f32 v[50:51], v[48:49], v[116:117], v[66:67]
	v_mul_f32_e32 v49, v53, v53
	v_mul_f32_e32 v48, v51, v51
	v_fmac_f32_e32 v48, v50, v50
	v_fmac_f32_e32 v49, v52, v52
	v_add_f32_e32 v48, v48, v49
	v_add_f32_e32 v48, v54, v48
	ds_bpermute_b32 v49, v174, v48
	global_store_dwordx4 v[72:73], v[50:53], off offset:576 sc1
	s_waitcnt lgkmcnt(0)
	v_add_f32_e32 v48, v48, v49
	ds_bpermute_b32 v49, v175, v48
	v_pk_mul_f32 v[50:51], v[112:113], v[50:51]
	v_pk_mul_f32 v[52:53], v[114:115], v[52:53]
	v_cvt_pk_bf16_f32 v50, v50, v51
	s_nop 0
	v_cvt_pk_bf16_f32 v51, v52, v53
	global_store_dwordx2 v[70:71], v[50:51], off offset:288
	s_and_saveexec_b64 s[36:37], s[0:1]
	s_cbranch_execz .LBB0_437
	v_readlane_b32 s40, v249, 31
	s_waitcnt lgkmcnt(0)
	v_add_f32_e32 v50, v48, v49
	v_lshlrev_b64 v[48:49], 6, v[64:65]
	v_readlane_b32 s41, v249, 32
	s_lshl_b32 s22, s38, 2
	s_nop 0
	v_lshl_add_u64 v[48:49], s[40:41], 0, v[48:49]
	v_lshl_add_u64 v[48:49], v[48:49], 0, s[22:23]
	s_lshl_b32 s22, s50, 2
	v_lshl_add_u64 v[48:49], v[48:49], 0, s[22:23]
	global_store_dword v[48:49], v50, off
; __device__ __forceinline__ unsigned cvt_pk_bf16(float lo, float hi) { unsigned r; asm volatile("v_cvt_pk_bf16_f32 %0, %1, %2" : "=v"(r) : "v"(lo), "v"(hi)); return r; }
;     __device__ __forceinline__ void operator()(const f32x4 (&acc)[2][2][4][2], const Unit& u, int wr, int wc, int fr, int fq) const {
;     ...
;         for (int ai = 0; ai < 2; ++ai)
; #pragma unroll
;             for (int m = 0; m < 4; ++m) { const int row = row0 + ai * HALF + m * 16; const size_t off = (size_t)row * D + col0;
;                 float ssq = 0.f;
; #pragma unroll
;                 for (int bj = 0; bj < 2; ++bj)
; #pragma unroll
;                     for (int n = 0; n < 2; ++n) { const f32x4 bs = *(const f32x4*)(base + off + bj * HALF + n * 16);
;                         const f32x4 o = bs + gv[bj][n] * acc[ai][bj][m][n];
;                         *(f32x4*)(out + off + bj * HALF + n * 16) = o;
;                         if (FOLD) { ssq += (o.x * o.x + o.y * o.y) + (o.z * o.z + o.w * o.w); const f32x4 q = o * sv[bj][n];
;                             u32x2 w; w.x = cvt_pk_bf16(q.x, q.y); w.y = cvt_pk_bf16(q.z, q.w); *(u32x2*)(U2 + off + bj * HALF + n * 16) = w; } }
;                 if (FOLD) { ssq += __shfl_xor(ssq, 16); ssq += __shfl_xor(ssq, 32);
;                     if (fq == 0) part[(size_t)row * 16 + (u.pn & 3) * 4 + wc] = ssq; } }
.LBB0_437:
	s_or_b64 exec, exec, s[36:37]
	v_add_u32_e32 v48, 0x90, v146
	s_waitcnt lgkmcnt(0)
	v_ashrrev_i32_e32 v49, 31, v48
	v_lshlrev_b64 v[50:51], 10, v[48:49]
	v_lshl_add_u64 v[54:55], v[50:51], 0, v[144:145]
	v_readlane_b32 s72, v248, 11
	v_lshlrev_b64 v[56:57], 2, v[54:55]
	v_readlane_b32 s73, v248, 12
	v_readlane_b32 s74, v248, 13
	v_readlane_b32 s75, v248, 14
	v_lshl_add_u64 v[58:59], s[72:73], 0, v[56:57]
	global_load_dwordx4 v[236:239], v[58:59], off
	global_load_dwordx4 v[240:243], v[58:59], off offset:64
	global_load_dwordx4 v[244:247], v[58:59], off offset:512
	global_load_dwordx4 v[50:53], v[58:59], off offset:576
	v_readlane_b32 s76, v248, 15
	v_readlane_b32 s77, v248, 16
	v_readlane_b32 s78, v248, 17
	v_readlane_b32 s79, v248, 18
	v_readlane_b32 s36, v249, 43
	v_readlane_b32 s72, v248, 0
	v_readlane_b32 s37, v249, 44
	v_readlane_b32 s78, v248, 6
	v_readlane_b32 s79, v248, 7
	v_lshl_add_u64 v[54:55], v[54:55], 1, s[36:37]
	v_readlane_b32 s80, v248, 19
	v_lshl_add_u64 v[56:57], s[78:79], 0, v[56:57]
	v_readlane_b32 s81, v248, 20
	v_readlane_b32 s82, v248, 21
	v_readlane_b32 s83, v248, 22
	v_readlane_b32 s84, v248, 23
	v_readlane_b32 s85, v248, 24
	v_readlane_b32 s86, v248, 25
	v_readlane_b32 s87, v248, 26
	v_readlane_b32 s73, v248, 1
	v_readlane_b32 s74, v248, 2
	v_readlane_b32 s75, v248, 3
	v_readlane_b32 s76, v248, 4
	v_readlane_b32 s77, v248, 5
	s_waitcnt vmcnt(3)
	v_pk_fma_f32 v[44:45], v[44:45], v[158:159], v[236:237]
	v_pk_fma_f32 v[46:47], v[46:47], v[156:157], v[238:239]
	v_pk_mul_f32 v[238:239], v[162:163], v[44:45]
	global_store_dwordx4 v[56:57], v[44:47], off sc1
	v_pk_mul_f32 v[236:237], v[160:161], v[46:47]
	v_cvt_pk_bf16_f32 v238, v238, v239
	s_nop 0
	v_cvt_pk_bf16_f32 v239, v236, v237
	global_store_dwordx2 v[54:55], v[238:239], off
	v_mul_f32_e32 v45, v45, v45
	v_mul_f32_e32 v47, v47, v47
	v_fmac_f32_e32 v45, v44, v44
	v_fmac_f32_e32 v47, v46, v46
	v_add_f32_e32 v44, v45, v47
	s_waitcnt vmcnt(4)
	v_pk_fma_f32 v[40:41], v[40:41], v[150:151], v[240:241]
	v_pk_fma_f32 v[42:43], v[42:43], v[154:155], v[242:243]
	v_pk_mul_f32 v[242:243], v[126:127], v[40:41]
	global_store_dwordx4 v[56:57], v[40:43], off offset:64 sc1
	v_pk_mul_f32 v[240:241], v[124:125], v[42:43]
	v_cvt_pk_bf16_f32 v242, v242, v243
	s_nop 0
	v_cvt_pk_bf16_f32 v243, v240, v241
	global_store_dwordx2 v[54:55], v[242:243], off offset:32
	v_mul_f32_e32 v41, v41, v41
	v_mul_f32_e32 v43, v43, v43
	v_fmac_f32_e32 v41, v40, v40
	v_fmac_f32_e32 v43, v42, v42
	v_add_f32_e32 v40, v41, v43
	v_add_f32_e32 v40, v44, v40
	s_waitcnt vmcnt(5)
	v_pk_fma_f32 v[36:37], v[36:37], v[148:149], v[244:245]
	v_pk_fma_f32 v[38:39], v[38:39], v[152:153], v[246:247]
	v_pk_mul_f32 v[246:247], v[122:123], v[36:37]
	global_store_dwordx4 v[56:57], v[36:39], off offset:512 sc1
	v_pk_mul_f32 v[244:245], v[120:121], v[38:39]
	v_cvt_pk_bf16_f32 v246, v246, v247
	s_nop 0
	v_cvt_pk_bf16_f32 v247, v244, v245
	global_store_dwordx2 v[54:55], v[246:247], off offset:256
	v_mul_f32_e32 v37, v37, v37
	v_mul_f32_e32 v39, v39, v39
	v_fmac_f32_e32 v37, v36, v36
	v_fmac_f32_e32 v39, v38, v38
	v_add_f32_e32 v36, v37, v39
	v_add_f32_e32 v38, v40, v36
	s_waitcnt vmcnt(6)
	v_pk_fma_f32 v[36:37], v[34:35], v[118:119], v[52:53]
	v_pk_fma_f32 v[34:35], v[32:33], v[116:117], v[50:51]
	v_mul_f32_e32 v33, v37, v37
	v_mul_f32_e32 v32, v35, v35
	v_fmac_f32_e32 v32, v34, v34
	v_fmac_f32_e32 v33, v36, v36
	v_add_f32_e32 v32, v32, v33
	v_add_f32_e32 v32, v38, v32
	ds_bpermute_b32 v33, v174, v32
	global_store_dwordx4 v[56:57], v[34:37], off offset:576 sc1
	s_waitcnt lgkmcnt(0)
	v_add_f32_e32 v32, v32, v33
	ds_bpermute_b32 v33, v175, v32
	v_pk_mul_f32 v[34:35], v[112:113], v[34:35]
	v_pk_mul_f32 v[36:37], v[114:115], v[36:37]
	v_cvt_pk_bf16_f32 v34, v34, v35
	s_nop 0
	v_cvt_pk_bf16_f32 v35, v36, v37
	global_store_dwordx2 v[54:55], v[34:35], off offset:288
	s_and_saveexec_b64 s[36:37], s[0:1]
	s_cbranch_execz .LBB0_439
	v_readlane_b32 s40, v249, 31
	s_waitcnt lgkmcnt(0)
	v_add_f32_e32 v34, v32, v33
	v_lshlrev_b64 v[32:33], 6, v[48:49]
	v_readlane_b32 s41, v249, 32
	s_lshl_b32 s22, s38, 2
	s_nop 0
	v_lshl_add_u64 v[32:33], s[40:41], 0, v[32:33]
	v_lshl_add_u64 v[32:33], v[32:33], 0, s[22:23]
	s_lshl_b32 s22, s50, 2
	v_lshl_add_u64 v[32:33], v[32:33], 0, s[22:23]
	global_store_dword v[32:33], v34, off
; __device__ __forceinline__ unsigned cvt_pk_bf16(float lo, float hi) { unsigned r; asm volatile("v_cvt_pk_bf16_f32 %0, %1, %2" : "=v"(r) : "v"(lo), "v"(hi)); return r; }
;     __device__ __forceinline__ void operator()(const f32x4 (&acc)[2][2][4][2], const Unit& u, int wr, int wc, int fr, int fq) const {
;     ...
;         for (int ai = 0; ai < 2; ++ai)
; #pragma unroll
;             for (int m = 0; m < 4; ++m) { const int row = row0 + ai * HALF + m * 16; const size_t off = (size_t)row * D + col0;
;                 float ssq = 0.f;
; #pragma unroll
;                 for (int bj = 0; bj < 2; ++bj)
; #pragma unroll
;                     for (int n = 0; n < 2; ++n) { const f32x4 bs = *(const f32x4*)(base + off + bj * HALF + n * 16);
;                         const f32x4 o = bs + gv[bj][n] * acc[ai][bj][m][n];
;                         *(f32x4*)(out + off + bj * HALF + n * 16) = o;
;                         if (FOLD) { ssq += (o.x * o.x + o.y * o.y) + (o.z * o.z + o.w * o.w); const f32x4 q = o * sv[bj][n];
;                             u32x2 w; w.x = cvt_pk_bf16(q.x, q.y); w.y = cvt_pk_bf16(q.z, q.w); *(u32x2*)(U2 + off + bj * HALF + n * 16) = w; } }
;                 if (FOLD) { ssq += __shfl_xor(ssq, 16); ssq += __shfl_xor(ssq, 32);
;                     if (fq == 0) part[(size_t)row * 16 + (u.pn & 3) * 4 + wc] = ssq; } }
.LBB0_439:
	s_or_b64 exec, exec, s[36:37]
	v_add_u32_e32 v32, 0xa0, v146
	s_waitcnt lgkmcnt(0)
	v_ashrrev_i32_e32 v33, 31, v32
	v_lshlrev_b64 v[34:35], 10, v[32:33]
	v_lshl_add_u64 v[38:39], v[34:35], 0, v[144:145]
	v_readlane_b32 s72, v248, 11
	v_lshlrev_b64 v[40:41], 2, v[38:39]
	v_readlane_b32 s73, v248, 12
	v_readlane_b32 s74, v248, 13
	v_readlane_b32 s75, v248, 14
	v_lshl_add_u64 v[42:43], s[72:73], 0, v[40:41]
	global_load_dwordx4 v[236:239], v[42:43], off
	global_load_dwordx4 v[240:243], v[42:43], off offset:64
	global_load_dwordx4 v[244:247], v[42:43], off offset:512
	global_load_dwordx4 v[34:37], v[42:43], off offset:576
	v_readlane_b32 s76, v248, 15
	v_readlane_b32 s77, v248, 16
	v_readlane_b32 s78, v248, 17
	v_readlane_b32 s79, v248, 18
	v_readlane_b32 s36, v249, 43
	v_readlane_b32 s72, v248, 0
	v_readlane_b32 s37, v249, 44
	v_readlane_b32 s78, v248, 6
	v_readlane_b32 s79, v248, 7
	v_lshl_add_u64 v[38:39], v[38:39], 1, s[36:37]
	v_readlane_b32 s80, v248, 19
	v_lshl_add_u64 v[40:41], s[78:79], 0, v[40:41]
	v_readlane_b32 s81, v248, 20
	v_readlane_b32 s82, v248, 21
	v_readlane_b32 s83, v248, 22
	v_readlane_b32 s84, v248, 23
	v_readlane_b32 s85, v248, 24
	v_readlane_b32 s86, v248, 25
	v_readlane_b32 s87, v248, 26
	v_readlane_b32 s73, v248, 1
	v_readlane_b32 s74, v248, 2
	v_readlane_b32 s75, v248, 3
	v_readlane_b32 s76, v248, 4
	v_readlane_b32 s77, v248, 5
	s_waitcnt vmcnt(3)
	v_pk_fma_f32 v[28:29], v[28:29], v[158:159], v[236:237]
	v_pk_fma_f32 v[30:31], v[30:31], v[156:157], v[238:239]
	v_pk_mul_f32 v[238:239], v[162:163], v[28:29]
	global_store_dwordx4 v[40:41], v[28:31], off sc1
	v_pk_mul_f32 v[236:237], v[160:161], v[30:31]
	v_cvt_pk_bf16_f32 v238, v238, v239
	s_nop 0
	v_cvt_pk_bf16_f32 v239, v236, v237
	global_store_dwordx2 v[38:39], v[238:239], off
	v_mul_f32_e32 v29, v29, v29
	v_mul_f32_e32 v31, v31, v31
	v_fmac_f32_e32 v29, v28, v28
	v_fmac_f32_e32 v31, v30, v30
	v_add_f32_e32 v28, v29, v31
	s_waitcnt vmcnt(4)
	v_pk_fma_f32 v[24:25], v[24:25], v[150:151], v[240:241]
	v_pk_fma_f32 v[26:27], v[26:27], v[154:155], v[242:243]
	v_pk_mul_f32 v[242:243], v[126:127], v[24:25]
	global_store_dwordx4 v[40:41], v[24:27], off offset:64 sc1
	v_pk_mul_f32 v[240:241], v[124:125], v[26:27]
	v_cvt_pk_bf16_f32 v242, v242, v243
	s_nop 0
	v_cvt_pk_bf16_f32 v243, v240, v241
	global_store_dwordx2 v[38:39], v[242:243], off offset:32
	v_mul_f32_e32 v25, v25, v25
	v_mul_f32_e32 v27, v27, v27
	v_fmac_f32_e32 v25, v24, v24
	v_fmac_f32_e32 v27, v26, v26
	v_add_f32_e32 v24, v25, v27
	v_add_f32_e32 v24, v28, v24
	s_waitcnt vmcnt(5)
	v_pk_fma_f32 v[20:21], v[20:21], v[148:149], v[244:245]
	v_pk_fma_f32 v[22:23], v[22:23], v[152:153], v[246:247]
	v_pk_mul_f32 v[246:247], v[122:123], v[20:21]
	global_store_dwordx4 v[40:41], v[20:23], off offset:512 sc1
	v_pk_mul_f32 v[244:245], v[120:121], v[22:23]
	v_cvt_pk_bf16_f32 v246, v246, v247
	s_nop 0
	v_cvt_pk_bf16_f32 v247, v244, v245
	global_store_dwordx2 v[38:39], v[246:247], off offset:256
	v_mul_f32_e32 v21, v21, v21
	v_mul_f32_e32 v23, v23, v23
	v_fmac_f32_e32 v21, v20, v20
	v_fmac_f32_e32 v23, v22, v22
	v_add_f32_e32 v20, v21, v23
	v_add_f32_e32 v22, v24, v20
	s_waitcnt vmcnt(6)
	v_pk_fma_f32 v[20:21], v[18:19], v[118:119], v[36:37]
	v_pk_fma_f32 v[18:19], v[16:17], v[116:117], v[34:35]
	v_mul_f32_e32 v17, v21, v21
	v_mul_f32_e32 v16, v19, v19
	v_fmac_f32_e32 v16, v18, v18
	v_fmac_f32_e32 v17, v20, v20
	v_add_f32_e32 v16, v16, v17
	v_add_f32_e32 v16, v22, v16
	ds_bpermute_b32 v17, v174, v16
	global_store_dwordx4 v[40:41], v[18:21], off offset:576 sc1
	s_waitcnt lgkmcnt(0)
	v_add_f32_e32 v16, v16, v17
	ds_bpermute_b32 v17, v175, v16
	v_pk_mul_f32 v[18:19], v[112:113], v[18:19]
	v_pk_mul_f32 v[20:21], v[114:115], v[20:21]
	v_cvt_pk_bf16_f32 v18, v18, v19
	s_nop 0
	v_cvt_pk_bf16_f32 v19, v20, v21
	global_store_dwordx2 v[38:39], v[18:19], off offset:288
	s_and_saveexec_b64 s[36:37], s[0:1]
	s_cbranch_execz .LBB0_441
	v_readlane_b32 s40, v249, 31
	s_waitcnt lgkmcnt(0)
	v_add_f32_e32 v18, v16, v17
	v_lshlrev_b64 v[16:17], 6, v[32:33]
	v_readlane_b32 s41, v249, 32
	s_lshl_b32 s22, s38, 2
	s_nop 0
	v_lshl_add_u64 v[16:17], s[40:41], 0, v[16:17]
	v_lshl_add_u64 v[16:17], v[16:17], 0, s[22:23]
	s_lshl_b32 s22, s50, 2
	v_lshl_add_u64 v[16:17], v[16:17], 0, s[22:23]
	global_store_dword v[16:17], v18, off
; __device__ __forceinline__ unsigned cvt_pk_bf16(float lo, float hi) { unsigned r; asm volatile("v_cvt_pk_bf16_f32 %0, %1, %2" : "=v"(r) : "v"(lo), "v"(hi)); return r; }
;     __device__ __forceinline__ void operator()(const f32x4 (&acc)[2][2][4][2], const Unit& u, int wr, int wc, int fr, int fq) const {
;     ...
;         for (int ai = 0; ai < 2; ++ai)
; #pragma unroll
;             for (int m = 0; m < 4; ++m) { const int row = row0 + ai * HALF + m * 16; const size_t off = (size_t)row * D + col0;
;                 float ssq = 0.f;
; #pragma unroll
;                 for (int bj = 0; bj < 2; ++bj)
; #pragma unroll
;                     for (int n = 0; n < 2; ++n) { const f32x4 bs = *(const f32x4*)(base + off + bj * HALF + n * 16);
;                         const f32x4 o = bs + gv[bj][n] * acc[ai][bj][m][n];
;                         *(f32x4*)(out + off + bj * HALF + n * 16) = o;
;                         if (FOLD) { ssq += (o.x * o.x + o.y * o.y) + (o.z * o.z + o.w * o.w); const f32x4 q = o * sv[bj][n];
;                             u32x2 w; w.x = cvt_pk_bf16(q.x, q.y); w.y = cvt_pk_bf16(q.z, q.w); *(u32x2*)(U2 + off + bj * HALF + n * 16) = w; } }
;                 if (FOLD) { ssq += __shfl_xor(ssq, 16); ssq += __shfl_xor(ssq, 32);
;                     if (fq == 0) part[(size_t)row * 16 + (u.pn & 3) * 4 + wc] = ssq; } }
.LBB0_441:
	s_or_b64 exec, exec, s[36:37]
	v_add_u32_e32 v16, 0xb0, v146
	s_waitcnt lgkmcnt(0)
	v_ashrrev_i32_e32 v17, 31, v16
	v_lshlrev_b64 v[18:19], 10, v[16:17]
	v_lshl_add_u64 v[22:23], v[18:19], 0, v[144:145]
	v_readlane_b32 s72, v248, 11
	v_lshlrev_b64 v[24:25], 2, v[22:23]
	v_readlane_b32 s73, v248, 12
	v_readlane_b32 s74, v248, 13
	v_readlane_b32 s75, v248, 14
	v_lshl_add_u64 v[26:27], s[72:73], 0, v[24:25]
	global_load_dwordx4 v[236:239], v[26:27], off
	global_load_dwordx4 v[240:243], v[26:27], off offset:64
	global_load_dwordx4 v[244:247], v[26:27], off offset:512
	global_load_dwordx4 v[18:21], v[26:27], off offset:576
	v_readlane_b32 s76, v248, 15
	v_readlane_b32 s77, v248, 16
	v_readlane_b32 s78, v248, 17
	v_readlane_b32 s79, v248, 18
	v_readlane_b32 s36, v249, 43
	v_readlane_b32 s72, v248, 0
	v_readlane_b32 s37, v249, 44
	v_readlane_b32 s78, v248, 6
	v_readlane_b32 s79, v248, 7
	v_lshl_add_u64 v[22:23], v[22:23], 1, s[36:37]
	v_readlane_b32 s80, v248, 19
	v_lshl_add_u64 v[24:25], s[78:79], 0, v[24:25]
	v_readlane_b32 s81, v248, 20
	v_readlane_b32 s82, v248, 21
	v_readlane_b32 s83, v248, 22
	v_readlane_b32 s84, v248, 23
	v_readlane_b32 s85, v248, 24
	v_readlane_b32 s86, v248, 25
	v_readlane_b32 s87, v248, 26
	v_readlane_b32 s73, v248, 1
	v_readlane_b32 s74, v248, 2
	v_readlane_b32 s75, v248, 3
	v_readlane_b32 s76, v248, 4
	v_readlane_b32 s77, v248, 5
	s_waitcnt vmcnt(3)
	v_pk_fma_f32 v[12:13], v[12:13], v[158:159], v[236:237]
	v_pk_fma_f32 v[14:15], v[14:15], v[156:157], v[238:239]
	v_pk_mul_f32 v[238:239], v[162:163], v[12:13]
	global_store_dwordx4 v[24:25], v[12:15], off sc1
	v_pk_mul_f32 v[236:237], v[160:161], v[14:15]
	v_cvt_pk_bf16_f32 v238, v238, v239
	s_nop 0
	v_cvt_pk_bf16_f32 v239, v236, v237
	global_store_dwordx2 v[22:23], v[238:239], off
	v_mul_f32_e32 v13, v13, v13
	v_mul_f32_e32 v15, v15, v15
	v_fmac_f32_e32 v13, v12, v12
	v_fmac_f32_e32 v15, v14, v14
	v_add_f32_e32 v12, v13, v15
	s_waitcnt vmcnt(4)
	v_pk_fma_f32 v[8:9], v[8:9], v[150:151], v[240:241]
	v_pk_fma_f32 v[10:11], v[10:11], v[154:155], v[242:243]
	v_pk_mul_f32 v[242:243], v[126:127], v[8:9]
	global_store_dwordx4 v[24:25], v[8:11], off offset:64 sc1
	v_pk_mul_f32 v[240:241], v[124:125], v[10:11]
	v_cvt_pk_bf16_f32 v242, v242, v243
	s_nop 0
	v_cvt_pk_bf16_f32 v243, v240, v241
	global_store_dwordx2 v[22:23], v[242:243], off offset:32
	v_mul_f32_e32 v9, v9, v9
	v_mul_f32_e32 v11, v11, v11
	v_fmac_f32_e32 v9, v8, v8
	v_fmac_f32_e32 v11, v10, v10
	v_add_f32_e32 v8, v9, v11
	v_add_f32_e32 v8, v12, v8
	s_waitcnt vmcnt(5)
	v_pk_fma_f32 v[4:5], v[4:5], v[148:149], v[244:245]
	v_pk_fma_f32 v[6:7], v[6:7], v[152:153], v[246:247]
	v_pk_mul_f32 v[246:247], v[122:123], v[4:5]
	global_store_dwordx4 v[24:25], v[4:7], off offset:512 sc1
	v_pk_mul_f32 v[244:245], v[120:121], v[6:7]
	v_cvt_pk_bf16_f32 v246, v246, v247
	s_nop 0
	v_cvt_pk_bf16_f32 v247, v244, v245
	global_store_dwordx2 v[22:23], v[246:247], off offset:256
	v_mul_f32_e32 v5, v5, v5
	v_mul_f32_e32 v7, v7, v7
	v_fmac_f32_e32 v5, v4, v4
	v_fmac_f32_e32 v7, v6, v6
	v_add_f32_e32 v4, v5, v7
	v_add_f32_e32 v6, v8, v4
	s_waitcnt vmcnt(6)
	v_pk_fma_f32 v[4:5], v[2:3], v[118:119], v[20:21]
	v_pk_fma_f32 v[2:3], v[0:1], v[116:117], v[18:19]
	v_mul_f32_e32 v1, v5, v5
	v_mul_f32_e32 v0, v3, v3
	v_fmac_f32_e32 v0, v2, v2
	v_fmac_f32_e32 v1, v4, v4
	v_add_f32_e32 v0, v0, v1
	v_add_f32_e32 v0, v6, v0
	ds_bpermute_b32 v1, v174, v0
	global_store_dwordx4 v[24:25], v[2:5], off offset:576 sc1
	s_waitcnt lgkmcnt(0)
	v_add_f32_e32 v0, v0, v1
	ds_bpermute_b32 v1, v175, v0
	v_pk_mul_f32 v[2:3], v[112:113], v[2:3]
	v_pk_mul_f32 v[4:5], v[114:115], v[4:5]
	v_cvt_pk_bf16_f32 v2, v2, v3
	s_nop 0
	v_cvt_pk_bf16_f32 v3, v4, v5
	global_store_dwordx2 v[22:23], v[2:3], off offset:288
	s_and_saveexec_b64 s[36:37], s[0:1]
	s_cbranch_execz .LBB0_443
	v_readlane_b32 s40, v249, 31
	s_waitcnt lgkmcnt(0)
	v_add_f32_e32 v2, v0, v1
	v_lshlrev_b64 v[0:1], 6, v[16:17]
	v_readlane_b32 s41, v249, 32
	s_lshl_b32 s22, s38, 2
	s_nop 0
	v_lshl_add_u64 v[0:1], s[40:41], 0, v[0:1]
	v_lshl_add_u64 v[0:1], v[0:1], 0, s[22:23]
	s_lshl_b32 s22, s50, 2
	v_lshl_add_u64 v[0:1], v[0:1], 0, s[22:23]
	global_store_dword v[0:1], v2, off

;     __device__ __forceinline__ void operator()(const f32x4 (&acc)[2][2][4][2], const Unit& u, int wr, int wc, int fr, int fq) const {
;     ...
;         if (MODE == 3) {
; #pragma unroll
;             for (int i = 0; i < 8; ++i) { const f32x4 t = *(const f32x4*)(p0 + (size_t)(row0 + (i >> 2) * HALF + (i & 3) * 16) * 16 + 4 * fq); rs[i] = (t.x + t.y) + (t.z + t.w); }
; #pragma unroll
;             for (int i = 0; i < 8; ++i) { float t = rs[i]; t += __shfl_xor(t, 16); t += __shfl_xor(t, 32); rs[i] = __builtin_amdgcn_rsqf(t * (1.f / 1024.f) + 1e-6f); }
;         }
;     ...
;             if (MODE == 3) { b0 = *(const f32x4*)(p1 + (size_t)(u.pm >> 4) * ldc + c); b1 = *(const f32x4*)(p1 + (size_t)(u.pm >> 4) * ldc + c + 4); }
.LBB0_514:
	v_lshl_add_u32 v186, s34, 8, v155
	v_ashrrev_i32_e32 v187, 31, v186
	v_or_b32_e32 v184, 16, v186
	v_lshlrev_b64 v[128:129], 6, v[186:187]
	v_ashrrev_i32_e32 v185, 31, v184
	v_lshl_add_u64 v[128:129], v[144:145], 0, v[128:129]
	v_lshlrev_b64 v[130:131], 6, v[184:185]
	v_lshl_add_u64 v[130:131], v[144:145], 0, v[130:131]
	global_load_dwordx4 v[190:193], v[128:129], off
	global_load_dwordx4 v[194:197], v[130:131], off
	v_or_b32_e32 v180, 32, v186
	v_ashrrev_i32_e32 v181, 31, v180
	v_or_b32_e32 v176, 48, v186
	v_lshlrev_b64 v[128:129], 6, v[180:181]
	v_ashrrev_i32_e32 v177, 31, v176
	v_lshl_add_u64 v[128:129], v[144:145], 0, v[128:129]
	v_lshlrev_b64 v[130:131], 6, v[176:177]
	v_lshl_add_u64 v[130:131], v[144:145], 0, v[130:131]
	global_load_dwordx4 v[198:201], v[128:129], off
	global_load_dwordx4 v[202:205], v[130:131], off
	v_add_u32_e32 v170, 0x80, v186
	v_ashrrev_i32_e32 v171, 31, v170
	v_add_u32_e32 v168, 0x90, v186
	v_lshlrev_b64 v[128:129], 6, v[170:171]
	v_ashrrev_i32_e32 v169, 31, v168
	v_lshl_add_u64 v[128:129], v[144:145], 0, v[128:129]
	v_lshlrev_b64 v[130:131], 6, v[168:169]
	v_lshl_add_u64 v[130:131], v[144:145], 0, v[130:131]
	global_load_dwordx4 v[208:211], v[128:129], off
	global_load_dwordx4 v[212:215], v[130:131], off
	v_add_u32_e32 v164, 0xa0, v186
	v_ashrrev_i32_e32 v165, 31, v164
	v_lshlrev_b64 v[128:129], 6, v[164:165]
	v_add_u32_e32 v160, 0xb0, v186
	v_lshl_add_u64 v[128:129], v[144:145], 0, v[128:129]
	v_ashrrev_i32_e32 v161, 31, v160
	global_load_dwordx4 v[216:219], v[128:129], off
	v_lshlrev_b64 v[128:129], 6, v[160:161]
	v_lshl_add_u64 v[128:129], v[144:145], 0, v[128:129]
	global_load_dwordx4 v[220:223], v[128:129], off
	s_ashr_i32 s4, s34, 4
	s_mul_hi_i32 s5, s4, 0x2400
	s_mulk_i32 s4, 0x2400
	v_lshl_or_b32 v224, s54, 8, v159
	s_add_u32 s4, s8, s4
	v_ashrrev_i32_e32 v225, 31, v224
	s_addc_u32 s5, s9, s5
	v_lshl_add_u64 v[174:175], v[224:225], 2, s[4:5]
	global_load_dwordx4 v[128:131], v[174:175], off offset:16
	global_load_dwordx4 v[132:135], v[174:175], off
	v_and_b32_e32 v166, 64, v183
	v_xor_b32_e32 v154, 16, v183
	v_add_u32_e32 v166, 64, v166
	v_cmp_lt_i32_e32 vcc, v154, v166
	v_xor_b32_e32 v177, 32, v183
	v_readlane_b32 s4, v248, 61
	v_cndmask_b32_e32 v154, v183, v154, vcc
	v_lshlrev_b32_e32 v154, 2, v154
	v_cmp_lt_i32_e32 vcc, v177, v166
	v_readlane_b32 s5, v248, 62
	s_waitcnt vmcnt(0)
	v_mov_b32_e32 v226, v191
	v_mov_b32_e32 v227, v192
	v_mov_b32_e32 v191, v193
	v_pk_add_f32 v[190:191], v[226:227], v[190:191]
	v_mov_b32_e32 v192, v195
	v_add_f32_e32 v156, v190, v191
	ds_bpermute_b32 v172, v154, v156
	v_mov_b32_e32 v193, v196
	v_mov_b32_e32 v195, v197
	v_pk_add_f32 v[190:191], v[192:193], v[194:195]
	v_cndmask_b32_e32 v166, v183, v177, vcc
	v_add_f32_e32 v158, v190, v191
	v_lshlrev_b32_e32 v177, 2, v166
	s_waitcnt lgkmcnt(0)
	v_add_f32_e32 v156, v156, v172
	ds_bpermute_b32 v166, v177, v156
	ds_bpermute_b32 v172, v154, v158
	v_mov_b32_e32 v196, v199
	v_mov_b32_e32 v197, v200
	v_mov_b32_e32 v199, v201
	v_pk_add_f32 v[192:193], v[196:197], v[198:199]
	s_waitcnt lgkmcnt(1)
	v_add_f32_e32 v156, v156, v166
	v_add_f32_e32 v161, v192, v193
	ds_bpermute_b32 v166, v154, v161
	s_waitcnt lgkmcnt(1)
	v_add_f32_e32 v158, v158, v172
	ds_bpermute_b32 v172, v177, v158
	v_mov_b32_e32 v200, v203
	v_mov_b32_e32 v201, v204
	v_mov_b32_e32 v203, v205
	v_fmamk_f32 v156, v156, 0x3a800000, v188
	v_mov_b32_e32 v204, v209
	v_mov_b32_e32 v205, v210
	v_mov_b32_e32 v209, v211
	v_pk_add_f32 v[194:195], v[200:201], v[202:203]
	v_rsq_f32_e32 v182, v156
	s_waitcnt lgkmcnt(1)
	v_add_f32_e32 v156, v161, v166
	v_pk_add_f32 v[196:197], v[204:205], v[208:209]
	v_add_f32_e32 v162, v194, v195
	ds_bpermute_b32 v161, v177, v156
	s_waitcnt lgkmcnt(1)
	v_add_f32_e32 v158, v158, v172
	v_add_f32_e32 v165, v196, v197
	v_fmamk_f32 v158, v158, 0x3a800000, v188
	ds_bpermute_b32 v166, v154, v162
	v_rsq_f32_e32 v178, v158
	ds_bpermute_b32 v158, v154, v165
	v_mov_b32_e32 v210, v213
	v_mov_b32_e32 v211, v214
	v_mov_b32_e32 v213, v215
	s_waitcnt lgkmcnt(2)
	v_add_f32_e32 v156, v156, v161
	v_pk_add_f32 v[198:199], v[210:211], v[212:213]
	v_fmamk_f32 v156, v156, 0x3a800000, v188
	s_waitcnt lgkmcnt(1)
	v_add_f32_e32 v161, v162, v166
	v_add_f32_e32 v169, v198, v199
	ds_bpermute_b32 v162, v177, v161
	v_rsq_f32_e32 v172, v156
	s_waitcnt lgkmcnt(1)
	v_add_f32_e32 v156, v165, v158
	ds_bpermute_b32 v158, v177, v156
	ds_bpermute_b32 v165, v154, v169
	v_mov_b32_e32 v214, v217
	v_mov_b32_e32 v215, v218
	v_mov_b32_e32 v217, v219
	v_pk_add_f32 v[200:201], v[214:215], v[216:217]
	s_waitcnt lgkmcnt(2)
	v_add_f32_e32 v161, v161, v162
	v_mov_b32_e32 v218, v221
	v_mov_b32_e32 v219, v222
	v_add_f32_e32 v171, v200, v201
	v_mov_b32_e32 v221, v223
	v_fmamk_f32 v161, v161, 0x3a800000, v188
	s_waitcnt lgkmcnt(1)
	v_add_f32_e32 v156, v156, v158
	s_waitcnt lgkmcnt(0)
	v_add_f32_e32 v158, v169, v165
	v_pk_add_f32 v[190:191], v[218:219], v[220:221]
	v_rsq_f32_e32 v166, v161
	ds_bpermute_b32 v161, v177, v158
	ds_bpermute_b32 v165, v154, v171
	v_add_f32_e32 v181, v190, v191
	ds_bpermute_b32 v154, v154, v181
	v_mov_b64_e32 v[190:191], s[4:5]
	v_fmamk_f32 v156, v156, 0x3a800000, v188
	v_mad_i64_i32 v[186:187], s[4:5], v186, s52, v[190:191]
	v_lshlrev_b64 v[192:193], 1, v[224:225]
	v_rsq_f32_e32 v162, v156
	s_waitcnt lgkmcnt(2)
	v_add_f32_e32 v156, v158, v161
	s_waitcnt lgkmcnt(1)
; __device__ __forceinline__ unsigned cvt_pk_bf16(float lo, float hi) { unsigned r; asm volatile("v_cvt_pk_bf16_f32 %0, %1, %2" : "=v"(r) : "v"(lo), "v"(hi)); return r; }
; __device__ __forceinline__ float sigmoidf_(float x) { return __builtin_amdgcn_rcpf(1.f + __expf(-x)); }
;     __device__ __forceinline__ void operator()(const f32x4 (&acc)[2][2][4][2], const Unit& u, int wr, int wc, int fr, int fq) const {
;     ...
;             for (int ai = 0; ai < 2; ++ai)
; #pragma unroll
;                 for (int m = 0; m < 4; ++m) { bf16_t* rowp = O + (size_t)(row0 + ai * HALF + m * 16) * ldc + c;
;                     f32x4 v0, v1;
;                     if (MODE == 3) { const float rstd = rs[ai * 4 + m]; v0 = acc[ai][bj][m][0] * rstd + b0; v1 = acc[ai][bj][m][1] * rstd + b1; }
;                     else { v0 = acc[ai][bj][m][0] + b0; v1 = acc[ai][bj][m][1] + b1; }
;                     if (MODE == 1 || MODE == 2) {
; #pragma unroll
;                         for (int e = 0; e < 4; ++e) {
;                             if (kind == 1) { v0[e] = 2.f * sigmoidf_(2.f * v0[e]) - 1.f; v1[e] = 2.f * sigmoidf_(2.f * v1[e]) - 1.f; }
;                             else if (kind == 2) { v0[e] = sigmoidf_(v0[e]); v1[e] = sigmoidf_(v1[e]); }
;                             else if (kind == 3) { v0[e] = 0.60653066f * sigmoidf_(v0[e]); v1[e] = 0.60653066f * sigmoidf_(v1[e]); }
;                         }
;                     }
;                     u32x4 w; w.x = cvt_pk_bf16(v0[0], v0[1]); w.y = cvt_pk_bf16(v0[2], v0[3]); w.z = cvt_pk_bf16(v1[0], v1[1]); w.w = cvt_pk_bf16(v1[2], v1[3]);
;                     *(u32x4*)rowp = w; }
	v_add_f32_e32 v161, v171, v165
	v_lshl_add_u64 v[186:187], v[186:187], 0, v[192:193]
	v_pk_fma_f32 v[126:127], v[126:127], v[182:183], v[134:135] op_sel_hi:[1,0,1]
	v_pk_fma_f32 v[124:125], v[124:125], v[182:183], v[132:133] op_sel_hi:[1,0,1]
	v_pk_fma_f32 v[194:195], v[122:123], v[182:183], v[130:131] op_sel_hi:[1,0,1]
	v_pk_fma_f32 v[122:123], v[120:121], v[182:183], v[128:129] op_sel_hi:[1,0,1]
	v_cvt_pk_bf16_f32 v120, v124, v125
	v_cvt_pk_bf16_f32 v121, v126, v127
	ds_bpermute_b32 v165, v177, v161
	v_cvt_pk_bf16_f32 v122, v122, v123
	v_cvt_pk_bf16_f32 v123, v194, v195
	global_store_dwordx4 v[186:187], v[120:123], off sc1
	s_waitcnt lgkmcnt(1)
	v_add_f32_e32 v154, v181, v154
	v_pk_fma_f32 v[118:119], v[118:119], v[178:179], v[134:135] op_sel_hi:[1,0,1]
	v_mad_i64_i32 v[120:121], s[4:5], v184, s52, v[190:191]
	v_lshl_add_u64 v[120:121], v[120:121], 0, v[192:193]
	v_pk_fma_f32 v[116:117], v[116:117], v[178:179], v[132:133] op_sel_hi:[1,0,1]
	v_pk_fma_f32 v[122:123], v[114:115], v[178:179], v[130:131] op_sel_hi:[1,0,1]
	v_pk_fma_f32 v[114:115], v[112:113], v[178:179], v[128:129] op_sel_hi:[1,0,1]
	v_cvt_pk_bf16_f32 v112, v116, v117
	v_cvt_pk_bf16_f32 v113, v118, v119
	ds_bpermute_b32 v169, v177, v154
	v_cvt_pk_bf16_f32 v114, v114, v115
	v_cvt_pk_bf16_f32 v115, v122, v123
	global_store_dwordx4 v[120:121], v[112:115], off sc1
	v_pk_fma_f32 v[110:111], v[110:111], v[172:173], v[134:135] op_sel_hi:[1,0,1]
	v_pk_fma_f32 v[108:109], v[108:109], v[172:173], v[132:133] op_sel_hi:[1,0,1]
	v_mad_i64_i32 v[112:113], s[4:5], v180, s52, v[190:191]
	v_lshl_add_u64 v[112:113], v[112:113], 0, v[192:193]
	v_pk_fma_f32 v[114:115], v[106:107], v[172:173], v[130:131] op_sel_hi:[1,0,1]
	v_pk_fma_f32 v[106:107], v[104:105], v[172:173], v[128:129] op_sel_hi:[1,0,1]
	v_cvt_pk_bf16_f32 v104, v108, v109
	v_cvt_pk_bf16_f32 v105, v110, v111
	v_fmamk_f32 v156, v156, 0x3a800000, v188
	v_cvt_pk_bf16_f32 v106, v106, v107
	v_cvt_pk_bf16_f32 v107, v114, v115
	global_store_dwordx4 v[112:113], v[104:107], off sc1
	v_rsq_f32_e32 v158, v156
	s_waitcnt lgkmcnt(1)
	v_add_f32_e32 v156, v161, v165
	v_mad_i64_i32 v[104:105], s[4:5], v176, s52, v[190:191]
	v_lshl_add_u64 v[104:105], v[104:105], 0, v[192:193]
	v_pk_fma_f32 v[102:103], v[102:103], v[166:167], v[134:135] op_sel_hi:[1,0,1]
	v_pk_fma_f32 v[100:101], v[100:101], v[166:167], v[132:133] op_sel_hi:[1,0,1]
	v_pk_fma_f32 v[106:107], v[98:99], v[166:167], v[130:131] op_sel_hi:[1,0,1]
	v_pk_fma_f32 v[98:99], v[96:97], v[166:167], v[128:129] op_sel_hi:[1,0,1]
	v_cvt_pk_bf16_f32 v96, v100, v101
	v_cvt_pk_bf16_f32 v97, v102, v103
	v_fmamk_f32 v156, v156, 0x3a800000, v188
	v_cvt_pk_bf16_f32 v98, v98, v99
	v_cvt_pk_bf16_f32 v99, v106, v107
	global_store_dwordx4 v[104:105], v[96:99], off sc1
	v_rsq_f32_e32 v156, v156
	s_waitcnt lgkmcnt(0)
	v_add_f32_e32 v154, v154, v169
	v_mad_i64_i32 v[96:97], s[4:5], v170, s52, v[190:191]
	v_lshl_add_u64 v[96:97], v[96:97], 0, v[192:193]
	v_pk_fma_f32 v[94:95], v[94:95], v[162:163], v[134:135] op_sel_hi:[1,0,1]
	v_pk_fma_f32 v[92:93], v[92:93], v[162:163], v[132:133] op_sel_hi:[1,0,1]
	v_pk_fma_f32 v[98:99], v[90:91], v[162:163], v[130:131] op_sel_hi:[1,0,1]
	v_pk_fma_f32 v[90:91], v[88:89], v[162:163], v[128:129] op_sel_hi:[1,0,1]
	v_cvt_pk_bf16_f32 v88, v92, v93
	v_cvt_pk_bf16_f32 v89, v94, v95
	v_fmamk_f32 v154, v154, 0x3a800000, v188
	v_cvt_pk_bf16_f32 v90, v90, v91
	v_cvt_pk_bf16_f32 v91, v98, v99
	global_store_dwordx4 v[96:97], v[88:91], off sc1
	v_rsq_f32_e32 v154, v154
	v_pk_fma_f32 v[86:87], v[86:87], v[158:159], v[134:135] op_sel_hi:[1,0,1]
	v_mad_i64_i32 v[88:89], s[4:5], v168, s52, v[190:191]
	v_lshl_add_u64 v[88:89], v[88:89], 0, v[192:193]
	v_pk_fma_f32 v[84:85], v[84:85], v[158:159], v[132:133] op_sel_hi:[1,0,1]
	v_pk_fma_f32 v[90:91], v[82:83], v[158:159], v[130:131] op_sel_hi:[1,0,1]
	v_pk_fma_f32 v[82:83], v[80:81], v[158:159], v[128:129] op_sel_hi:[1,0,1]
	v_cvt_pk_bf16_f32 v80, v84, v85
	v_cvt_pk_bf16_f32 v81, v86, v87
	v_pk_fma_f32 v[78:79], v[78:79], v[156:157], v[134:135] op_sel_hi:[1,0,1]
	v_cvt_pk_bf16_f32 v82, v82, v83
	v_cvt_pk_bf16_f32 v83, v90, v91
	global_store_dwordx4 v[88:89], v[80:83], off sc1
	v_pk_fma_f32 v[76:77], v[76:77], v[156:157], v[132:133] op_sel_hi:[1,0,1]
	v_pk_fma_f32 v[70:71], v[70:71], v[154:155], v[134:135] op_sel_hi:[1,0,1]
	v_mad_i64_i32 v[80:81], s[4:5], v164, s52, v[190:191]
	v_lshl_add_u64 v[80:81], v[80:81], 0, v[192:193]
	v_pk_fma_f32 v[82:83], v[74:75], v[156:157], v[130:131] op_sel_hi:[1,0,1]
	v_pk_fma_f32 v[74:75], v[72:73], v[156:157], v[128:129] op_sel_hi:[1,0,1]
	v_cvt_pk_bf16_f32 v72, v76, v77
	v_cvt_pk_bf16_f32 v73, v78, v79
	v_pk_fma_f32 v[68:69], v[68:69], v[154:155], v[132:133] op_sel_hi:[1,0,1]
	v_cvt_pk_bf16_f32 v74, v74, v75
	v_cvt_pk_bf16_f32 v75, v82, v83
	global_store_dwordx4 v[80:81], v[72:75], off sc1
	s_and_b64 vcc, exec, s[2:3]
	s_mov_b64 s[2:3], -1
	v_mad_i64_i32 v[72:73], s[4:5], v160, s52, v[190:191]
	v_lshl_add_u64 v[72:73], v[72:73], 0, v[192:193]
	v_pk_fma_f32 v[74:75], v[66:67], v[154:155], v[130:131] op_sel_hi:[1,0,1]
	v_pk_fma_f32 v[66:67], v[64:65], v[154:155], v[128:129] op_sel_hi:[1,0,1]
	v_cvt_pk_bf16_f32 v64, v68, v69
	v_cvt_pk_bf16_f32 v65, v70, v71
	s_nop 0
	v_cvt_pk_bf16_f32 v66, v66, v67
	v_cvt_pk_bf16_f32 v67, v74, v75
	global_store_dwordx4 v[72:73], v[64:67], off sc1
	global_load_dwordx4 v[64:67], v[174:175], off offset:512
	s_nop 0
	global_load_dwordx4 v[68:71], v[174:175], off offset:528
	s_waitcnt vmcnt(1)
; __device__ __forceinline__ unsigned cvt_pk_bf16(float lo, float hi) { unsigned r; asm volatile("v_cvt_pk_bf16_f32 %0, %1, %2" : "=v"(r) : "v"(lo), "v"(hi)); return r; }
; #define PG8_BAR __builtin_amdgcn_s_barrier()
; template <class Epi, class Sched, bool ALIGN_EPI = false, bool SP2 = false>
; __device__ __forceinline__ void gemm_phase(PG8_LAS unsigned char* lds, const Gemm g, const Sched& S, const Epi& E) {
;     ...
;         if constexpr (ALIGN_EPI) { if (wr == 0) PG8_BAR; }
;         if constexpr (!Epi::AFTER_DRAIN) { E(acc, cur, wr, wc, fr, fq); S.done(cur); }
;         if (!has_next) break;
; #pragma unroll
;         for (int a = 0; a < 2; ++a)
; #pragma unroll
;             for (int b = 0; b < 2; ++b)
; #pragma unroll
;                 for (int m = 0; m < 4; ++m)
; #pragma unroll
;                     for (int n = 0; n < 2; ++n) acc[a][b][m][n] = (f32x4){0.f, 0.f, 0.f, 0.f};
;         cur = nxt; cA = nA; cB = nB; ++ui;
;         if constexpr (ALIGN_EPI) { if (wr == 1) PG8_BAR; }
;     __device__ __forceinline__ void operator()(const f32x4 (&acc)[2][2][4][2], const Unit& u, int wr, int wc, int fr, int fq) const {
;     ...
;             for (int ai = 0; ai < 2; ++ai)
; #pragma unroll
;                 for (int m = 0; m < 4; ++m) { bf16_t* rowp = O + (size_t)(row0 + ai * HALF + m * 16) * ldc + c;
;                     f32x4 v0, v1;
;                     if (MODE == 3) { const float rstd = rs[ai * 4 + m]; v0 = acc[ai][bj][m][0] * rstd + b0; v1 = acc[ai][bj][m][1] * rstd + b1; }
;                     else { v0 = acc[ai][bj][m][0] + b0; v1 = acc[ai][bj][m][1] + b1; }
;                     if (MODE == 1 || MODE == 2) {
; #pragma unroll
;                         for (int e = 0; e < 4; ++e) {
;                             if (kind == 1) { v0[e] = 2.f * sigmoidf_(2.f * v0[e]) - 1.f; v1[e] = 2.f * sigmoidf_(2.f * v1[e]) - 1.f; }
;                             else if (kind == 2) { v0[e] = sigmoidf_(v0[e]); v1[e] = sigmoidf_(v1[e]); }
;                             else if (kind == 3) { v0[e] = 0.60653066f * sigmoidf_(v0[e]); v1[e] = 0.60653066f * sigmoidf_(v1[e]); }
;                         }
;                     }
;                     u32x4 w; w.x = cvt_pk_bf16(v0[0], v0[1]); w.y = cvt_pk_bf16(v0[2], v0[3]); w.z = cvt_pk_bf16(v1[0], v1[1]); w.w = cvt_pk_bf16(v1[2], v1[3]);
;                     *(u32x4*)rowp = w; }
	v_pk_fma_f32 v[62:63], v[62:63], v[182:183], v[66:67] op_sel_hi:[1,0,1]
	v_pk_fma_f32 v[60:61], v[60:61], v[182:183], v[64:65] op_sel_hi:[1,0,1]
	s_waitcnt vmcnt(0)
	v_pk_fma_f32 v[74:75], v[58:59], v[182:183], v[70:71] op_sel_hi:[1,0,1]
	v_pk_fma_f32 v[58:59], v[56:57], v[182:183], v[68:69] op_sel_hi:[1,0,1]
	v_cvt_pk_bf16_f32 v56, v60, v61
	v_cvt_pk_bf16_f32 v57, v62, v63
	v_pk_fma_f32 v[54:55], v[54:55], v[178:179], v[66:67] op_sel_hi:[1,0,1]
	v_cvt_pk_bf16_f32 v58, v58, v59
	v_cvt_pk_bf16_f32 v59, v74, v75
	global_store_dwordx4 v[186:187], v[56:59], off offset:256 sc1
	v_pk_fma_f32 v[52:53], v[52:53], v[178:179], v[64:65] op_sel_hi:[1,0,1]
	v_pk_fma_f32 v[46:47], v[46:47], v[172:173], v[66:67] op_sel_hi:[1,0,1]
	v_pk_fma_f32 v[56:57], v[50:51], v[178:179], v[70:71] op_sel_hi:[1,0,1]
	v_pk_fma_f32 v[50:51], v[48:49], v[178:179], v[68:69] op_sel_hi:[1,0,1]
	v_cvt_pk_bf16_f32 v48, v52, v53
	v_cvt_pk_bf16_f32 v49, v54, v55
	v_pk_fma_f32 v[44:45], v[44:45], v[172:173], v[64:65] op_sel_hi:[1,0,1]
	v_cvt_pk_bf16_f32 v50, v50, v51
	v_cvt_pk_bf16_f32 v51, v56, v57
	global_store_dwordx4 v[120:121], v[48:51], off offset:256 sc1
	v_pk_fma_f32 v[38:39], v[38:39], v[166:167], v[66:67] op_sel_hi:[1,0,1]
	v_pk_fma_f32 v[36:37], v[36:37], v[166:167], v[64:65] op_sel_hi:[1,0,1]
	v_pk_fma_f32 v[48:49], v[42:43], v[172:173], v[70:71] op_sel_hi:[1,0,1]
	v_pk_fma_f32 v[42:43], v[40:41], v[172:173], v[68:69] op_sel_hi:[1,0,1]
	v_cvt_pk_bf16_f32 v40, v44, v45
	v_cvt_pk_bf16_f32 v41, v46, v47
	v_pk_fma_f32 v[30:31], v[30:31], v[162:163], v[66:67] op_sel_hi:[1,0,1]
	v_cvt_pk_bf16_f32 v42, v42, v43
	v_cvt_pk_bf16_f32 v43, v48, v49
	global_store_dwordx4 v[112:113], v[40:43], off offset:256 sc1
	v_pk_fma_f32 v[28:29], v[28:29], v[162:163], v[64:65] op_sel_hi:[1,0,1]
	v_pk_fma_f32 v[22:23], v[22:23], v[158:159], v[66:67] op_sel_hi:[1,0,1]
	v_pk_fma_f32 v[40:41], v[34:35], v[166:167], v[70:71] op_sel_hi:[1,0,1]
	v_pk_fma_f32 v[34:35], v[32:33], v[166:167], v[68:69] op_sel_hi:[1,0,1]
	v_cvt_pk_bf16_f32 v32, v36, v37
	v_cvt_pk_bf16_f32 v33, v38, v39
	v_pk_fma_f32 v[20:21], v[20:21], v[158:159], v[64:65] op_sel_hi:[1,0,1]
	v_cvt_pk_bf16_f32 v34, v34, v35
	v_cvt_pk_bf16_f32 v35, v40, v41
	global_store_dwordx4 v[104:105], v[32:35], off offset:256 sc1
	v_pk_fma_f32 v[14:15], v[14:15], v[156:157], v[66:67] op_sel_hi:[1,0,1]
	v_pk_fma_f32 v[12:13], v[12:13], v[156:157], v[64:65] op_sel_hi:[1,0,1]
	v_pk_fma_f32 v[32:33], v[26:27], v[162:163], v[70:71] op_sel_hi:[1,0,1]
	v_pk_fma_f32 v[26:27], v[24:25], v[162:163], v[68:69] op_sel_hi:[1,0,1]
	v_cvt_pk_bf16_f32 v24, v28, v29
	v_cvt_pk_bf16_f32 v25, v30, v31
	v_pk_fma_f32 v[6:7], v[6:7], v[154:155], v[66:67] op_sel_hi:[1,0,1]
	v_cvt_pk_bf16_f32 v26, v26, v27
	v_cvt_pk_bf16_f32 v27, v32, v33
	global_store_dwordx4 v[96:97], v[24:27], off offset:256 sc1
	v_pk_fma_f32 v[4:5], v[4:5], v[154:155], v[64:65] op_sel_hi:[1,0,1]
	s_nop 0
	v_pk_fma_f32 v[24:25], v[18:19], v[158:159], v[70:71] op_sel_hi:[1,0,1]
	v_pk_fma_f32 v[18:19], v[16:17], v[158:159], v[68:69] op_sel_hi:[1,0,1]
	v_cvt_pk_bf16_f32 v16, v20, v21
	v_cvt_pk_bf16_f32 v17, v22, v23
	s_nop 0
	v_cvt_pk_bf16_f32 v18, v18, v19
	v_cvt_pk_bf16_f32 v19, v24, v25
	global_store_dwordx4 v[88:89], v[16:19], off offset:256 sc1
	s_nop 1
	v_pk_fma_f32 v[16:17], v[10:11], v[156:157], v[70:71] op_sel_hi:[1,0,1]
	v_pk_fma_f32 v[10:11], v[8:9], v[156:157], v[68:69] op_sel_hi:[1,0,1]
	v_cvt_pk_bf16_f32 v8, v12, v13
	v_cvt_pk_bf16_f32 v9, v14, v15
	s_nop 0
	v_cvt_pk_bf16_f32 v10, v10, v11
	v_cvt_pk_bf16_f32 v11, v16, v17
	global_store_dwordx4 v[80:81], v[8:11], off offset:256 sc1
	s_nop 1
	v_pk_fma_f32 v[8:9], v[2:3], v[154:155], v[70:71] op_sel_hi:[1,0,1]
	v_pk_fma_f32 v[2:3], v[0:1], v[154:155], v[68:69] op_sel_hi:[1,0,1]
	v_cvt_pk_bf16_f32 v0, v4, v5
	v_cvt_pk_bf16_f32 v1, v6, v7
	s_nop 0
	v_cvt_pk_bf16_f32 v2, v2, v3
	v_cvt_pk_bf16_f32 v3, v8, v9
	global_store_dwordx4 v[72:73], v[0:3], off offset:256 sc1
	s_cbranch_vccnz .LBB0_504
	s_andn2_b64 vcc, exec, s[20:21]
	s_cbranch_vccnz .LBB0_503
	s_barrier
	s_branch .LBB0_503

; __device__ __forceinline__ void dsa_prep(const Args& a, unsigned char* lds, int tid) {
;     ...
;         {
;             const int col = tid >> 1, half = tid & 1;
;             bf16* dst = VT + ((size_t)(b * 4 + (col >> 6)) * 64 + (col & 63)) * SEQ + tt0 + half * 32;
; #pragma unroll
;             for (int i = 0; i < 4; ++i) *(u32x4*)(dst + 8 * i) = *(const u32x4*)(vt + col * 72 + half * 32 + 8 * i);
;         }
;         __syncthreads();
.LBB0_572:
	s_or_b64 exec, exec, s[12:13]
	s_ashr_i32 s12, s23, 4
	s_and_b32 s12, s12, -4
	v_add_u32_e32 v44, s12, v69
	v_ashrrev_i32_e32 v45, 31, v44
	s_and_b32 s6, s6, 0xfc0
	v_lshlrev_b64 v[44:45], 19, v[44:45]
	v_lshl_add_u64 v[44:45], v[20:21], 0, v[44:45]
	s_lshl_b32 s6, s6, 1
	v_lshl_add_u64 v[44:45], v[44:45], 0, s[6:7]
	v_mov_b32_e32 v43, v13
	s_waitcnt lgkmcnt(0)
	s_barrier
	v_lshl_add_u64 v[60:61], v[44:45], 0, v[42:43]
	ds_read_b128 v[44:47], v70
	ds_read_b128 v[48:51], v70 offset:16
	ds_read_b128 v[52:55], v70 offset:32
	ds_read_b128 v[56:59], v70 offset:48
	v_readlane_b32 s6, v248, 59
	s_add_i32 s23, s23, s6
	v_add_u32_e32 v28, s20, v28
	s_cmpk_gt_i32 s23, 0x1ff
	s_waitcnt lgkmcnt(3)
	global_store_dwordx4 v[60:61], v[44:47], off sc1
	s_waitcnt lgkmcnt(2)
	global_store_dwordx4 v[60:61], v[48:51], off offset:16 sc1
	s_waitcnt lgkmcnt(1)
	global_store_dwordx4 v[60:61], v[52:55], off offset:32 sc1
	s_waitcnt lgkmcnt(0)
	global_store_dwordx4 v[60:61], v[56:59], off offset:48 sc1
	s_barrier
	s_cbranch_scc1 .LBB0_594

; __device__ __forceinline__ unsigned cvt_pk_bf16(float lo, float hi) { unsigned r; asm volatile("v_cvt_pk_bf16_f32 %0, %1, %2" : "=v"(r) : "v"(lo), "v"(hi)); return r; }
;     __device__ __forceinline__ void operator()(const f32x4 (&acc)[2][2][4][2], const Unit& u, int wr, int wc, int fr, int fq) const {
;         const int row0 = u.pm * BM + wr * 64 + fr, col0 = u.pn * BM + wc * 32 + 4 * fq;
;         const float* gp = gate + (size_t)(u.pm >> 4) * NMOD;
;         f32x4 gv[2][2], sv[2][2];
; #pragma unroll
;         for (int bj = 0; bj < 2; ++bj)
; #pragma unroll
;             for (int n = 0; n < 2; ++n) { gv[bj][n] = *(const f32x4*)(gp + col0 + bj * HALF + n * 16) * (HALFSC ? 0.5f : 1.0f);
;                 if (FOLD) sv[bj][n] = *(const f32x4*)(scn + (size_t)(u.pm >> 4) * NMOD + col0 + bj * HALF + n * 16) + 1.0f; }
; #pragma unroll
;         for (int ai = 0; ai < 2; ++ai)
; #pragma unroll
;             for (int m = 0; m < 4; ++m) { const int row = row0 + ai * HALF + m * 16; const size_t off = (size_t)row * D + col0;
;                 float ssq = 0.f;
; #pragma unroll
;                 for (int bj = 0; bj < 2; ++bj)
; #pragma unroll
;                     for (int n = 0; n < 2; ++n) { const f32x4 bs = *(const f32x4*)(base + off + bj * HALF + n * 16);
;                         const f32x4 o = bs + gv[bj][n] * acc[ai][bj][m][n];
;                         *(f32x4*)(out + off + bj * HALF + n * 16) = o;
;                         if (FOLD) { ssq += (o.x * o.x + o.y * o.y) + (o.z * o.z + o.w * o.w); const f32x4 q = o * sv[bj][n];
;                             u32x2 w; w.x = cvt_pk_bf16(q.x, q.y); w.y = cvt_pk_bf16(q.z, q.w); *(u32x2*)(U2 + off + bj * HALF + n * 16) = w; } }
;                 if (FOLD) { ssq += __shfl_xor(ssq, 16); ssq += __shfl_xor(ssq, 32);
;                     if (fq == 0) part[(size_t)row * 16 + (u.pn & 3) * 4 + wc] = ssq; } }
.LBB0_1102:
	s_ashr_i32 s4, s12, 4
	v_lshl_or_b32 v160, s56, 8, v170
	s_mul_i32 s34, s4, 0x9000
	s_mul_hi_i32 s27, s4, 0x9000
	s_add_u32 s4, s42, s34
	v_ashrrev_i32_e32 v161, 31, v160
	v_lshl_add_u32 v162, s12, 8, v168
	s_addc_u32 s5, s43, s27
	v_lshlrev_b64 v[96:97], 2, v[160:161]
	v_ashrrev_i32_e32 v163, 31, v162
	v_lshl_add_u64 v[98:99], s[4:5], 0, v[96:97]
	s_add_u32 s4, s44, s34
	v_lshlrev_b64 v[104:105], 10, v[162:163]
	v_readlane_b32 s60, v248, 0
	v_lshl_add_u64 v[104:105], v[104:105], 0, v[160:161]
	v_readlane_b32 s66, v248, 6
	v_readlane_b32 s67, v248, 7
	s_addc_u32 s5, s45, s27
	v_lshl_add_u64 v[186:187], s[4:5], 0, v[96:97]
	v_lshl_add_u64 v[194:195], v[104:105], 2, s[66:67]
	global_load_dwordx4 v[100:103], v[98:99], off
	global_load_dwordx4 v[174:177], v[186:187], off
	global_load_dwordx4 v[164:167], v[194:195], off
	v_readlane_b32 s4, v249, 43
	v_readlane_b32 s5, v249, 44
	v_readlane_b32 s61, v248, 1
	v_readlane_b32 s62, v248, 2
	v_lshl_add_u64 v[196:197], v[104:105], 1, s[4:5]
	global_load_dwordx4 v[108:111], v[98:99], off offset:64
	global_load_dwordx4 v[104:107], v[98:99], off offset:512
	s_nop 0
	global_load_dwordx4 v[96:99], v[98:99], off offset:576
	s_nop 0
	global_load_dwordx4 v[178:181], v[186:187], off offset:64
	global_load_dwordx4 v[182:185], v[186:187], off offset:512
	s_nop 0
	global_load_dwordx4 v[186:189], v[186:187], off offset:576
	global_load_dwordx4 v[236:239], v[194:195], off offset:64
	global_load_dwordx4 v[240:243], v[194:195], off offset:512
	global_load_dwordx4 v[244:247], v[194:195], off offset:576
	s_lshl_b32 s4, s56, 2
	s_and_b32 s27, s4, 12
	v_readlane_b32 s63, v248, 3
	v_readlane_b32 s64, v248, 4
	v_readlane_b32 s65, v248, 5
	s_waitcnt vmcnt(3)
	v_pk_fma_f32 v[192:193], v[142:143], v[102:103], v[166:167]
	v_pk_fma_f32 v[190:191], v[140:141], v[100:101], v[164:165]
	v_pk_add_f32 v[166:167], v[174:175], 1.0 op_sel_hi:[1,0]
	v_pk_add_f32 v[164:165], v[176:177], 1.0 op_sel_hi:[1,0]
	v_pk_mul_f32 v[142:143], v[166:167], v[190:191]
	global_store_dwordx4 v[194:195], v[190:193], off sc1
	v_pk_mul_f32 v[140:141], v[164:165], v[192:193]
	v_cvt_pk_bf16_f32 v142, v142, v143
	s_nop 0
	v_cvt_pk_bf16_f32 v143, v140, v141
	global_store_dwordx2 v[196:197], v[142:143], off
	v_pk_add_f32 v[142:143], v[178:179], 1.0 op_sel_hi:[1,0]
	v_pk_add_f32 v[140:141], v[180:181], 1.0 op_sel_hi:[1,0]
	v_mul_f32_e32 v191, v191, v191
	v_mul_f32_e32 v193, v193, v193
	v_fmac_f32_e32 v191, v190, v190
	v_fmac_f32_e32 v193, v192, v192
	s_waitcnt vmcnt(4)
	v_pk_fma_f32 v[174:175], v[136:137], v[108:109], v[236:237]
	v_pk_fma_f32 v[176:177], v[138:139], v[110:111], v[238:239]
	v_pk_mul_f32 v[138:139], v[142:143], v[174:175]
	global_store_dwordx4 v[194:195], v[174:177], off offset:64 sc1
	v_pk_mul_f32 v[136:137], v[140:141], v[176:177]
	v_cvt_pk_bf16_f32 v138, v138, v139
	s_nop 0
	v_cvt_pk_bf16_f32 v139, v136, v137
	global_store_dwordx2 v[196:197], v[138:139], off offset:32
	v_pk_add_f32 v[138:139], v[182:183], 1.0 op_sel_hi:[1,0]
	v_pk_add_f32 v[136:137], v[184:185], 1.0 op_sel_hi:[1,0]
	v_mul_f32_e32 v175, v175, v175
	v_mul_f32_e32 v177, v177, v177
	v_fmac_f32_e32 v175, v174, v174
	v_fmac_f32_e32 v177, v176, v176
	v_add_f32_e32 v174, v175, v177
	s_waitcnt vmcnt(5)
	v_pk_fma_f32 v[178:179], v[132:133], v[104:105], v[240:241]
	v_pk_fma_f32 v[180:181], v[134:135], v[106:107], v[242:243]
	v_pk_mul_f32 v[134:135], v[138:139], v[178:179]
	global_store_dwordx4 v[194:195], v[178:181], off offset:512 sc1
	v_pk_mul_f32 v[132:133], v[136:137], v[180:181]
	v_cvt_pk_bf16_f32 v134, v134, v135
	v_mul_f32_e32 v175, v179, v179
	v_cvt_pk_bf16_f32 v135, v132, v133
	global_store_dwordx2 v[196:197], v[134:135], off offset:256
	v_mul_f32_e32 v176, v181, v181
	v_pk_add_f32 v[132:133], v[186:187], 1.0 op_sel_hi:[1,0]
	v_add_f32_e32 v186, v191, v193
	v_fmac_f32_e32 v175, v178, v178
	v_fmac_f32_e32 v176, v180, v180
	v_add_f32_e32 v174, v186, v174
	v_add_f32_e32 v175, v175, v176
	v_add_f32_e32 v178, v174, v175
	v_pk_add_f32 v[134:135], v[188:189], 1.0 op_sel_hi:[1,0]
	s_waitcnt vmcnt(6)
	v_pk_fma_f32 v[176:177], v[130:131], v[98:99], v[246:247]
	v_pk_fma_f32 v[174:175], v[128:129], v[96:97], v[244:245]
	v_mul_f32_e32 v129, v177, v177
	v_mul_f32_e32 v128, v175, v175
	v_fmac_f32_e32 v128, v174, v174
	v_fmac_f32_e32 v129, v176, v176
	v_add_f32_e32 v128, v128, v129
	v_add_f32_e32 v128, v178, v128
	ds_bpermute_b32 v129, v207, v128
	global_store_dwordx4 v[194:195], v[174:177], off offset:576 sc1
	v_pk_mul_f32 v[130:131], v[134:135], v[176:177]
	s_waitcnt lgkmcnt(0)
	v_add_f32_e32 v128, v128, v129
	ds_bpermute_b32 v129, v208, v128
	v_pk_mul_f32 v[174:175], v[132:133], v[174:175]
	s_nop 0
	v_cvt_pk_bf16_f32 v174, v174, v175
	v_cvt_pk_bf16_f32 v175, v130, v131
	global_store_dwordx2 v[196:197], v[174:175], off offset:288
	s_and_saveexec_b64 s[4:5], s[0:1]
	s_cbranch_execz .LBB0_1104
	v_readlane_b32 s34, v249, 31
	v_lshlrev_b64 v[130:131], 6, v[162:163]
	v_readlane_b32 s35, v249, 32
	s_lshl_b32 s12, s27, 2
	s_waitcnt lgkmcnt(0)
	v_add_f32_e32 v128, v128, v129
	v_lshl_add_u64 v[130:131], s[34:35], 0, v[130:131]
	v_lshl_add_u64 v[130:131], v[130:131], 0, s[12:13]
	s_lshl_b32 s12, s46, 2
	v_lshl_add_u64 v[130:131], v[130:131], 0, s[12:13]
	global_store_dword v[130:131], v128, off
; __device__ __forceinline__ unsigned cvt_pk_bf16(float lo, float hi) { unsigned r; asm volatile("v_cvt_pk_bf16_f32 %0, %1, %2" : "=v"(r) : "v"(lo), "v"(hi)); return r; }
;     __device__ __forceinline__ void operator()(const f32x4 (&acc)[2][2][4][2], const Unit& u, int wr, int wc, int fr, int fq) const {
;     ...
;         for (int ai = 0; ai < 2; ++ai)
; #pragma unroll
;             for (int m = 0; m < 4; ++m) { const int row = row0 + ai * HALF + m * 16; const size_t off = (size_t)row * D + col0;
;                 float ssq = 0.f;
; #pragma unroll
;                 for (int bj = 0; bj < 2; ++bj)
; #pragma unroll
;                     for (int n = 0; n < 2; ++n) { const f32x4 bs = *(const f32x4*)(base + off + bj * HALF + n * 16);
;                         const f32x4 o = bs + gv[bj][n] * acc[ai][bj][m][n];
;                         *(f32x4*)(out + off + bj * HALF + n * 16) = o;
;                         if (FOLD) { ssq += (o.x * o.x + o.y * o.y) + (o.z * o.z + o.w * o.w); const f32x4 q = o * sv[bj][n];
;                             u32x2 w; w.x = cvt_pk_bf16(q.x, q.y); w.y = cvt_pk_bf16(q.z, q.w); *(u32x2*)(U2 + off + bj * HALF + n * 16) = w; } }
;                 if (FOLD) { ssq += __shfl_xor(ssq, 16); ssq += __shfl_xor(ssq, 32);
;                     if (fq == 0) part[(size_t)row * 16 + (u.pn & 3) * 4 + wc] = ssq; } }
.LBB0_1104:
	s_or_b64 exec, exec, s[4:5]
	v_or_b32_e32 v128, 16, v162
	s_waitcnt lgkmcnt(0)
	v_ashrrev_i32_e32 v129, 31, v128
	v_lshlrev_b64 v[130:131], 10, v[128:129]
	v_readlane_b32 s56, v248, 0
	v_lshl_add_u64 v[130:131], v[130:131], 0, v[160:161]
	v_readlane_b32 s62, v248, 6
	v_readlane_b32 s63, v248, 7
	v_readlane_b32 s4, v249, 43
	v_readlane_b32 s5, v249, 44
	v_lshl_add_u64 v[178:179], v[130:131], 2, s[62:63]
	global_load_dwordx4 v[236:239], v[178:179], off
	global_load_dwordx4 v[240:243], v[178:179], off offset:64
	global_load_dwordx4 v[244:247], v[178:179], off offset:512
	global_load_dwordx4 v[174:177], v[178:179], off offset:576
	v_lshl_add_u64 v[130:131], v[130:131], 1, s[4:5]
	v_readlane_b32 s57, v248, 1
	v_readlane_b32 s58, v248, 2
	v_readlane_b32 s59, v248, 3
	v_readlane_b32 s60, v248, 4
	v_readlane_b32 s61, v248, 5
	s_waitcnt vmcnt(3)
	v_pk_fma_f32 v[124:125], v[124:125], v[100:101], v[236:237]
	v_pk_fma_f32 v[126:127], v[126:127], v[102:103], v[238:239]
	v_pk_mul_f32 v[238:239], v[166:167], v[124:125]
	global_store_dwordx4 v[178:179], v[124:127], off sc1
	v_pk_mul_f32 v[236:237], v[164:165], v[126:127]
	v_cvt_pk_bf16_f32 v238, v238, v239
	s_nop 0
	v_cvt_pk_bf16_f32 v239, v236, v237
	global_store_dwordx2 v[130:131], v[238:239], off
	v_mul_f32_e32 v125, v125, v125
	v_mul_f32_e32 v127, v127, v127
	v_fmac_f32_e32 v125, v124, v124
	v_fmac_f32_e32 v127, v126, v126
	v_add_f32_e32 v124, v125, v127
	s_waitcnt vmcnt(4)
	v_pk_fma_f32 v[120:121], v[120:121], v[108:109], v[240:241]
	v_pk_fma_f32 v[122:123], v[122:123], v[110:111], v[242:243]
	v_pk_mul_f32 v[242:243], v[142:143], v[120:121]
	global_store_dwordx4 v[178:179], v[120:123], off offset:64 sc1
	v_pk_mul_f32 v[240:241], v[140:141], v[122:123]
	v_cvt_pk_bf16_f32 v242, v242, v243
	s_nop 0
	v_cvt_pk_bf16_f32 v243, v240, v241
	global_store_dwordx2 v[130:131], v[242:243], off offset:32
	v_mul_f32_e32 v121, v121, v121
	v_mul_f32_e32 v123, v123, v123
	v_fmac_f32_e32 v121, v120, v120
	v_fmac_f32_e32 v123, v122, v122
	v_add_f32_e32 v120, v121, v123
	v_add_f32_e32 v120, v124, v120
	s_waitcnt vmcnt(5)
	v_pk_fma_f32 v[116:117], v[116:117], v[104:105], v[244:245]
	v_pk_fma_f32 v[118:119], v[118:119], v[106:107], v[246:247]
	v_pk_mul_f32 v[246:247], v[138:139], v[116:117]
	global_store_dwordx4 v[178:179], v[116:119], off offset:512 sc1
	v_pk_mul_f32 v[244:245], v[136:137], v[118:119]
	v_cvt_pk_bf16_f32 v246, v246, v247
	s_nop 0
	v_cvt_pk_bf16_f32 v247, v244, v245
	global_store_dwordx2 v[130:131], v[246:247], off offset:256
	v_mul_f32_e32 v117, v117, v117
	v_mul_f32_e32 v119, v119, v119
	v_fmac_f32_e32 v117, v116, v116
	v_fmac_f32_e32 v119, v118, v118
	v_add_f32_e32 v116, v117, v119
	v_add_f32_e32 v118, v120, v116
	s_waitcnt vmcnt(6)
	v_pk_fma_f32 v[116:117], v[114:115], v[98:99], v[176:177]
	v_pk_fma_f32 v[114:115], v[112:113], v[96:97], v[174:175]
	v_mul_f32_e32 v113, v117, v117
	v_mul_f32_e32 v112, v115, v115
	v_fmac_f32_e32 v112, v114, v114
	v_fmac_f32_e32 v113, v116, v116
	v_add_f32_e32 v112, v112, v113
	v_add_f32_e32 v112, v118, v112
	ds_bpermute_b32 v113, v207, v112
	global_store_dwordx4 v[178:179], v[114:117], off offset:576 sc1
	s_waitcnt lgkmcnt(0)
	v_add_f32_e32 v112, v112, v113
	ds_bpermute_b32 v113, v208, v112
	v_pk_mul_f32 v[114:115], v[132:133], v[114:115]
	v_pk_mul_f32 v[116:117], v[134:135], v[116:117]
	v_cvt_pk_bf16_f32 v114, v114, v115
	s_nop 0
	v_cvt_pk_bf16_f32 v115, v116, v117
	global_store_dwordx2 v[130:131], v[114:115], off offset:288
	s_and_saveexec_b64 s[4:5], s[0:1]
	s_cbranch_execz .LBB0_1106
	v_readlane_b32 s34, v249, 31
	v_lshlrev_b64 v[114:115], 6, v[128:129]
	v_readlane_b32 s35, v249, 32
	s_lshl_b32 s12, s27, 2
	s_waitcnt lgkmcnt(0)
	v_add_f32_e32 v112, v112, v113
	v_lshl_add_u64 v[114:115], s[34:35], 0, v[114:115]
	v_lshl_add_u64 v[114:115], v[114:115], 0, s[12:13]
	s_lshl_b32 s12, s46, 2
	v_lshl_add_u64 v[114:115], v[114:115], 0, s[12:13]
	global_store_dword v[114:115], v112, off
.LBB0_1106:
	s_or_b64 exec, exec, s[4:5]
	v_or_b32_e32 v112, 32, v162
	s_waitcnt lgkmcnt(0)
	v_ashrrev_i32_e32 v113, 31, v112
	v_lshlrev_b64 v[114:115], 10, v[112:113]
	v_readlane_b32 s56, v248, 0
	v_lshl_add_u64 v[118:119], v[114:115], 0, v[160:161]
	v_readlane_b32 s62, v248, 6
	v_readlane_b32 s63, v248, 7
	v_readlane_b32 s4, v249, 43
	v_readlane_b32 s5, v249, 44
	v_lshl_add_u64 v[120:121], v[118:119], 2, s[62:63]
	global_load_dwordx4 v[236:239], v[120:121], off
	global_load_dwordx4 v[240:243], v[120:121], off offset:64
	global_load_dwordx4 v[244:247], v[120:121], off offset:512
	global_load_dwordx4 v[114:117], v[120:121], off offset:576
	v_lshl_add_u64 v[118:119], v[118:119], 1, s[4:5]
	v_readlane_b32 s57, v248, 1
	v_readlane_b32 s58, v248, 2
	v_readlane_b32 s59, v248, 3
	v_readlane_b32 s60, v248, 4
	v_readlane_b32 s61, v248, 5
	s_waitcnt vmcnt(3)
	v_pk_fma_f32 v[92:93], v[92:93], v[100:101], v[236:237]
	v_pk_fma_f32 v[94:95], v[94:95], v[102:103], v[238:239]
	v_pk_mul_f32 v[238:239], v[166:167], v[92:93]
	global_store_dwordx4 v[120:121], v[92:95], off sc1
	v_pk_mul_f32 v[236:237], v[164:165], v[94:95]
	v_cvt_pk_bf16_f32 v238, v238, v239
	s_nop 0
	v_cvt_pk_bf16_f32 v239, v236, v237
	global_store_dwordx2 v[118:119], v[238:239], off
	v_mul_f32_e32 v93, v93, v93
	v_mul_f32_e32 v95, v95, v95
	v_fmac_f32_e32 v93, v92, v92
	v_fmac_f32_e32 v95, v94, v94
	v_add_f32_e32 v92, v93, v95
	s_waitcnt vmcnt(4)
; __device__ __forceinline__ unsigned cvt_pk_bf16(float lo, float hi) { unsigned r; asm volatile("v_cvt_pk_bf16_f32 %0, %1, %2" : "=v"(r) : "v"(lo), "v"(hi)); return r; }
;     __device__ __forceinline__ void operator()(const f32x4 (&acc)[2][2][4][2], const Unit& u, int wr, int wc, int fr, int fq) const {
;     ...
;         for (int ai = 0; ai < 2; ++ai)
; #pragma unroll
;             for (int m = 0; m < 4; ++m) { const int row = row0 + ai * HALF + m * 16; const size_t off = (size_t)row * D + col0;
;                 float ssq = 0.f;
; #pragma unroll
;                 for (int bj = 0; bj < 2; ++bj)
; #pragma unroll
;                     for (int n = 0; n < 2; ++n) { const f32x4 bs = *(const f32x4*)(base + off + bj * HALF + n * 16);
;                         const f32x4 o = bs + gv[bj][n] * acc[ai][bj][m][n];
;                         *(f32x4*)(out + off + bj * HALF + n * 16) = o;
;                         if (FOLD) { ssq += (o.x * o.x + o.y * o.y) + (o.z * o.z + o.w * o.w); const f32x4 q = o * sv[bj][n];
;                             u32x2 w; w.x = cvt_pk_bf16(q.x, q.y); w.y = cvt_pk_bf16(q.z, q.w); *(u32x2*)(U2 + off + bj * HALF + n * 16) = w; } }
;                 if (FOLD) { ssq += __shfl_xor(ssq, 16); ssq += __shfl_xor(ssq, 32);
;                     if (fq == 0) part[(size_t)row * 16 + (u.pn & 3) * 4 + wc] = ssq; } }
	v_pk_fma_f32 v[88:89], v[88:89], v[108:109], v[240:241]
	v_pk_fma_f32 v[90:91], v[90:91], v[110:111], v[242:243]
	v_pk_mul_f32 v[242:243], v[142:143], v[88:89]
	global_store_dwordx4 v[120:121], v[88:91], off offset:64 sc1
	v_pk_mul_f32 v[240:241], v[140:141], v[90:91]
	v_cvt_pk_bf16_f32 v242, v242, v243
	s_nop 0
	v_cvt_pk_bf16_f32 v243, v240, v241
	global_store_dwordx2 v[118:119], v[242:243], off offset:32
	v_mul_f32_e32 v89, v89, v89
	v_mul_f32_e32 v91, v91, v91
	v_fmac_f32_e32 v89, v88, v88
	v_fmac_f32_e32 v91, v90, v90
	v_add_f32_e32 v88, v89, v91
	v_add_f32_e32 v88, v92, v88
	s_waitcnt vmcnt(5)
	v_pk_fma_f32 v[84:85], v[84:85], v[104:105], v[244:245]
	v_pk_fma_f32 v[86:87], v[86:87], v[106:107], v[246:247]
	v_pk_mul_f32 v[246:247], v[138:139], v[84:85]
	global_store_dwordx4 v[120:121], v[84:87], off offset:512 sc1
	v_pk_mul_f32 v[244:245], v[136:137], v[86:87]
	v_cvt_pk_bf16_f32 v246, v246, v247
	s_nop 0
	v_cvt_pk_bf16_f32 v247, v244, v245
	global_store_dwordx2 v[118:119], v[246:247], off offset:256
	v_mul_f32_e32 v85, v85, v85
	v_mul_f32_e32 v87, v87, v87
	v_fmac_f32_e32 v85, v84, v84
	v_fmac_f32_e32 v87, v86, v86
	v_add_f32_e32 v84, v85, v87
	v_add_f32_e32 v86, v88, v84
	s_waitcnt vmcnt(6)
	v_pk_fma_f32 v[84:85], v[82:83], v[98:99], v[116:117]
	v_pk_fma_f32 v[82:83], v[80:81], v[96:97], v[114:115]
	v_mul_f32_e32 v81, v85, v85
	v_mul_f32_e32 v80, v83, v83
	v_fmac_f32_e32 v80, v82, v82
	v_fmac_f32_e32 v81, v84, v84
	v_add_f32_e32 v80, v80, v81
	v_add_f32_e32 v80, v86, v80
	ds_bpermute_b32 v81, v207, v80
	global_store_dwordx4 v[120:121], v[82:85], off offset:576 sc1
	s_waitcnt lgkmcnt(0)
	v_add_f32_e32 v80, v80, v81
	ds_bpermute_b32 v81, v208, v80
	v_pk_mul_f32 v[82:83], v[132:133], v[82:83]
	v_pk_mul_f32 v[84:85], v[134:135], v[84:85]
	v_cvt_pk_bf16_f32 v82, v82, v83
	s_nop 0
	v_cvt_pk_bf16_f32 v83, v84, v85
	global_store_dwordx2 v[118:119], v[82:83], off offset:288
	s_and_saveexec_b64 s[4:5], s[0:1]
	s_cbranch_execz .LBB0_1108
	v_readlane_b32 s34, v249, 31
	v_lshlrev_b64 v[82:83], 6, v[112:113]
	v_readlane_b32 s35, v249, 32
	s_lshl_b32 s12, s27, 2
	s_waitcnt lgkmcnt(0)
	v_add_f32_e32 v80, v80, v81
	v_lshl_add_u64 v[82:83], s[34:35], 0, v[82:83]
	v_lshl_add_u64 v[82:83], v[82:83], 0, s[12:13]
	s_lshl_b32 s12, s46, 2
	v_lshl_add_u64 v[82:83], v[82:83], 0, s[12:13]
	global_store_dword v[82:83], v80, off
.LBB0_1108:
	s_or_b64 exec, exec, s[4:5]
	v_or_b32_e32 v80, 48, v162
	s_waitcnt lgkmcnt(0)
	v_ashrrev_i32_e32 v81, 31, v80
	v_lshlrev_b64 v[82:83], 10, v[80:81]
	v_readlane_b32 s56, v248, 0
	v_lshl_add_u64 v[86:87], v[82:83], 0, v[160:161]
	v_readlane_b32 s62, v248, 6
	v_readlane_b32 s63, v248, 7
	v_readlane_b32 s4, v249, 43
	v_readlane_b32 s5, v249, 44
	v_lshl_add_u64 v[88:89], v[86:87], 2, s[62:63]
	global_load_dwordx4 v[236:239], v[88:89], off
	global_load_dwordx4 v[240:243], v[88:89], off offset:64
	global_load_dwordx4 v[244:247], v[88:89], off offset:512
	global_load_dwordx4 v[82:85], v[88:89], off offset:576
	v_lshl_add_u64 v[86:87], v[86:87], 1, s[4:5]
	v_readlane_b32 s57, v248, 1
	v_readlane_b32 s58, v248, 2
	v_readlane_b32 s59, v248, 3
	v_readlane_b32 s60, v248, 4
	v_readlane_b32 s61, v248, 5
	s_waitcnt vmcnt(3)
	v_pk_fma_f32 v[76:77], v[76:77], v[100:101], v[236:237]
	v_pk_fma_f32 v[78:79], v[78:79], v[102:103], v[238:239]
	v_pk_mul_f32 v[238:239], v[166:167], v[76:77]
	global_store_dwordx4 v[88:89], v[76:79], off sc1
	v_pk_mul_f32 v[236:237], v[164:165], v[78:79]
	v_cvt_pk_bf16_f32 v238, v238, v239
	s_nop 0
	v_cvt_pk_bf16_f32 v239, v236, v237
	global_store_dwordx2 v[86:87], v[238:239], off
	v_mul_f32_e32 v77, v77, v77
	v_mul_f32_e32 v79, v79, v79
	v_fmac_f32_e32 v77, v76, v76
	v_fmac_f32_e32 v79, v78, v78
	v_add_f32_e32 v76, v77, v79
	s_waitcnt vmcnt(4)
	v_pk_fma_f32 v[72:73], v[72:73], v[108:109], v[240:241]
	v_pk_fma_f32 v[74:75], v[74:75], v[110:111], v[242:243]
	v_pk_mul_f32 v[242:243], v[142:143], v[72:73]
	global_store_dwordx4 v[88:89], v[72:75], off offset:64 sc1
	v_pk_mul_f32 v[240:241], v[140:141], v[74:75]
	v_cvt_pk_bf16_f32 v242, v242, v243
	s_nop 0
	v_cvt_pk_bf16_f32 v243, v240, v241
	global_store_dwordx2 v[86:87], v[242:243], off offset:32
	v_mul_f32_e32 v73, v73, v73
	v_mul_f32_e32 v75, v75, v75
	v_fmac_f32_e32 v73, v72, v72
	v_fmac_f32_e32 v75, v74, v74
	v_add_f32_e32 v72, v73, v75
	v_add_f32_e32 v72, v76, v72
	s_waitcnt vmcnt(5)
	v_pk_fma_f32 v[68:69], v[68:69], v[104:105], v[244:245]
	v_pk_fma_f32 v[70:71], v[70:71], v[106:107], v[246:247]
	v_pk_mul_f32 v[246:247], v[138:139], v[68:69]
	global_store_dwordx4 v[88:89], v[68:71], off offset:512 sc1
	v_pk_mul_f32 v[244:245], v[136:137], v[70:71]
	v_cvt_pk_bf16_f32 v246, v246, v247
	s_nop 0
	v_cvt_pk_bf16_f32 v247, v244, v245
	global_store_dwordx2 v[86:87], v[246:247], off offset:256
	v_mul_f32_e32 v69, v69, v69
	v_mul_f32_e32 v71, v71, v71
	v_fmac_f32_e32 v69, v68, v68
	v_fmac_f32_e32 v71, v70, v70
	v_add_f32_e32 v68, v69, v71
	v_add_f32_e32 v70, v72, v68
	s_waitcnt vmcnt(6)
	v_pk_fma_f32 v[68:69], v[66:67], v[98:99], v[84:85]
	v_pk_fma_f32 v[66:67], v[64:65], v[96:97], v[82:83]
	v_mul_f32_e32 v65, v69, v69
	v_mul_f32_e32 v64, v67, v67
	v_fmac_f32_e32 v64, v66, v66
	v_fmac_f32_e32 v65, v68, v68
	v_add_f32_e32 v64, v64, v65
	v_add_f32_e32 v64, v70, v64
	ds_bpermute_b32 v65, v207, v64
	global_store_dwordx4 v[88:89], v[66:69], off offset:576 sc1
	s_waitcnt lgkmcnt(0)
	v_add_f32_e32 v64, v64, v65
	ds_bpermute_b32 v65, v208, v64
	v_pk_mul_f32 v[66:67], v[132:133], v[66:67]
	v_pk_mul_f32 v[68:69], v[134:135], v[68:69]
	v_cvt_pk_bf16_f32 v66, v66, v67
	s_nop 0
	v_cvt_pk_bf16_f32 v67, v68, v69
	global_store_dwordx2 v[86:87], v[66:67], off offset:288
	s_and_saveexec_b64 s[4:5], s[0:1]
	s_cbranch_execz .LBB0_1110
	v_readlane_b32 s34, v249, 31
	v_lshlrev_b64 v[66:67], 6, v[80:81]
	v_readlane_b32 s35, v249, 32
	s_lshl_b32 s12, s27, 2
	s_waitcnt lgkmcnt(0)
	v_add_f32_e32 v64, v64, v65
	v_lshl_add_u64 v[66:67], s[34:35], 0, v[66:67]
	v_lshl_add_u64 v[66:67], v[66:67], 0, s[12:13]
	s_lshl_b32 s12, s46, 2
	v_lshl_add_u64 v[66:67], v[66:67], 0, s[12:13]
	global_store_dword v[66:67], v64, off
; __device__ __forceinline__ unsigned cvt_pk_bf16(float lo, float hi) { unsigned r; asm volatile("v_cvt_pk_bf16_f32 %0, %1, %2" : "=v"(r) : "v"(lo), "v"(hi)); return r; }
;     __device__ __forceinline__ void operator()(const f32x4 (&acc)[2][2][4][2], const Unit& u, int wr, int wc, int fr, int fq) const {
;     ...
;         for (int ai = 0; ai < 2; ++ai)
; #pragma unroll
;             for (int m = 0; m < 4; ++m) { const int row = row0 + ai * HALF + m * 16; const size_t off = (size_t)row * D + col0;
;                 float ssq = 0.f;
; #pragma unroll
;                 for (int bj = 0; bj < 2; ++bj)
; #pragma unroll
;                     for (int n = 0; n < 2; ++n) { const f32x4 bs = *(const f32x4*)(base + off + bj * HALF + n * 16);
;                         const f32x4 o = bs + gv[bj][n] * acc[ai][bj][m][n];
;                         *(f32x4*)(out + off + bj * HALF + n * 16) = o;
;                         if (FOLD) { ssq += (o.x * o.x + o.y * o.y) + (o.z * o.z + o.w * o.w); const f32x4 q = o * sv[bj][n];
;                             u32x2 w; w.x = cvt_pk_bf16(q.x, q.y); w.y = cvt_pk_bf16(q.z, q.w); *(u32x2*)(U2 + off + bj * HALF + n * 16) = w; } }
;                 if (FOLD) { ssq += __shfl_xor(ssq, 16); ssq += __shfl_xor(ssq, 32);
;                     if (fq == 0) part[(size_t)row * 16 + (u.pn & 3) * 4 + wc] = ssq; } }
.LBB0_1110:
	s_or_b64 exec, exec, s[4:5]
	v_add_u32_e32 v64, 0x80, v162
	s_waitcnt lgkmcnt(0)
	v_ashrrev_i32_e32 v65, 31, v64
	v_lshlrev_b64 v[66:67], 10, v[64:65]
	v_readlane_b32 s56, v248, 0
	v_lshl_add_u64 v[70:71], v[66:67], 0, v[160:161]
	v_readlane_b32 s62, v248, 6
	v_readlane_b32 s63, v248, 7
	v_readlane_b32 s4, v249, 43
	v_readlane_b32 s5, v249, 44
	v_lshl_add_u64 v[72:73], v[70:71], 2, s[62:63]
	global_load_dwordx4 v[236:239], v[72:73], off
	global_load_dwordx4 v[240:243], v[72:73], off offset:64
	global_load_dwordx4 v[244:247], v[72:73], off offset:512
	global_load_dwordx4 v[66:69], v[72:73], off offset:576
	v_lshl_add_u64 v[70:71], v[70:71], 1, s[4:5]
	v_readlane_b32 s57, v248, 1
	v_readlane_b32 s58, v248, 2
	v_readlane_b32 s59, v248, 3
	v_readlane_b32 s60, v248, 4
	v_readlane_b32 s61, v248, 5
	s_waitcnt vmcnt(3)
	v_pk_fma_f32 v[60:61], v[60:61], v[100:101], v[236:237]
	v_pk_fma_f32 v[62:63], v[62:63], v[102:103], v[238:239]
	v_pk_mul_f32 v[238:239], v[166:167], v[60:61]
	global_store_dwordx4 v[72:73], v[60:63], off sc1
	v_pk_mul_f32 v[236:237], v[164:165], v[62:63]
	v_cvt_pk_bf16_f32 v238, v238, v239
	s_nop 0
	v_cvt_pk_bf16_f32 v239, v236, v237
	global_store_dwordx2 v[70:71], v[238:239], off
	v_mul_f32_e32 v61, v61, v61
	v_mul_f32_e32 v63, v63, v63
	v_fmac_f32_e32 v61, v60, v60
	v_fmac_f32_e32 v63, v62, v62
	v_add_f32_e32 v60, v61, v63
	s_waitcnt vmcnt(4)
	v_pk_fma_f32 v[56:57], v[56:57], v[108:109], v[240:241]
	v_pk_fma_f32 v[58:59], v[58:59], v[110:111], v[242:243]
	v_pk_mul_f32 v[242:243], v[142:143], v[56:57]
	global_store_dwordx4 v[72:73], v[56:59], off offset:64 sc1
	v_pk_mul_f32 v[240:241], v[140:141], v[58:59]
	v_cvt_pk_bf16_f32 v242, v242, v243
	s_nop 0
	v_cvt_pk_bf16_f32 v243, v240, v241
	global_store_dwordx2 v[70:71], v[242:243], off offset:32
	v_mul_f32_e32 v57, v57, v57
	v_mul_f32_e32 v59, v59, v59
	v_fmac_f32_e32 v57, v56, v56
	v_fmac_f32_e32 v59, v58, v58
	v_add_f32_e32 v56, v57, v59
	v_add_f32_e32 v56, v60, v56
	s_waitcnt vmcnt(5)
	v_pk_fma_f32 v[52:53], v[52:53], v[104:105], v[244:245]
	v_pk_fma_f32 v[54:55], v[54:55], v[106:107], v[246:247]
	v_pk_mul_f32 v[246:247], v[138:139], v[52:53]
	global_store_dwordx4 v[72:73], v[52:55], off offset:512 sc1
	v_pk_mul_f32 v[244:245], v[136:137], v[54:55]
	v_cvt_pk_bf16_f32 v246, v246, v247
	s_nop 0
	v_cvt_pk_bf16_f32 v247, v244, v245
	global_store_dwordx2 v[70:71], v[246:247], off offset:256
	v_mul_f32_e32 v53, v53, v53
	v_mul_f32_e32 v55, v55, v55
	v_fmac_f32_e32 v53, v52, v52
	v_fmac_f32_e32 v55, v54, v54
	v_add_f32_e32 v52, v53, v55
	v_add_f32_e32 v54, v56, v52
	s_waitcnt vmcnt(6)
	v_pk_fma_f32 v[52:53], v[50:51], v[98:99], v[68:69]
	v_pk_fma_f32 v[50:51], v[48:49], v[96:97], v[66:67]
	v_mul_f32_e32 v49, v53, v53
	v_mul_f32_e32 v48, v51, v51
	v_fmac_f32_e32 v48, v50, v50
	v_fmac_f32_e32 v49, v52, v52
	v_add_f32_e32 v48, v48, v49
	v_add_f32_e32 v48, v54, v48
	ds_bpermute_b32 v49, v207, v48
	global_store_dwordx4 v[72:73], v[50:53], off offset:576 sc1
	s_waitcnt lgkmcnt(0)
	v_add_f32_e32 v48, v48, v49
	ds_bpermute_b32 v49, v208, v48
	v_pk_mul_f32 v[50:51], v[132:133], v[50:51]
	v_pk_mul_f32 v[52:53], v[134:135], v[52:53]
	v_cvt_pk_bf16_f32 v50, v50, v51
	s_nop 0
	v_cvt_pk_bf16_f32 v51, v52, v53
	global_store_dwordx2 v[70:71], v[50:51], off offset:288
	s_and_saveexec_b64 s[4:5], s[0:1]
	s_cbranch_execz .LBB0_1112
	v_readlane_b32 s34, v249, 31
	v_lshlrev_b64 v[50:51], 6, v[64:65]
	v_readlane_b32 s35, v249, 32
	s_lshl_b32 s12, s27, 2
	s_waitcnt lgkmcnt(0)
	v_add_f32_e32 v48, v48, v49
	v_lshl_add_u64 v[50:51], s[34:35], 0, v[50:51]
	v_lshl_add_u64 v[50:51], v[50:51], 0, s[12:13]
	s_lshl_b32 s12, s46, 2
	v_lshl_add_u64 v[50:51], v[50:51], 0, s[12:13]
	global_store_dword v[50:51], v48, off
.LBB0_1112:
	s_or_b64 exec, exec, s[4:5]
	v_add_u32_e32 v48, 0x90, v162
	s_waitcnt lgkmcnt(0)
	v_ashrrev_i32_e32 v49, 31, v48
	v_lshlrev_b64 v[50:51], 10, v[48:49]
	v_readlane_b32 s56, v248, 0
	v_lshl_add_u64 v[54:55], v[50:51], 0, v[160:161]
	v_readlane_b32 s62, v248, 6
	v_readlane_b32 s63, v248, 7
	v_readlane_b32 s4, v249, 43
	v_readlane_b32 s5, v249, 44
	v_lshl_add_u64 v[56:57], v[54:55], 2, s[62:63]
	global_load_dwordx4 v[236:239], v[56:57], off
	global_load_dwordx4 v[240:243], v[56:57], off offset:64
	global_load_dwordx4 v[244:247], v[56:57], off offset:512
	global_load_dwordx4 v[50:53], v[56:57], off offset:576
	v_lshl_add_u64 v[54:55], v[54:55], 1, s[4:5]
	v_readlane_b32 s57, v248, 1
	v_readlane_b32 s58, v248, 2
	v_readlane_b32 s59, v248, 3
	v_readlane_b32 s60, v248, 4
	v_readlane_b32 s61, v248, 5
	s_waitcnt vmcnt(3)
	v_pk_fma_f32 v[44:45], v[44:45], v[100:101], v[236:237]
	v_pk_fma_f32 v[46:47], v[46:47], v[102:103], v[238:239]
	v_pk_mul_f32 v[238:239], v[166:167], v[44:45]
	global_store_dwordx4 v[56:57], v[44:47], off sc1
	v_pk_mul_f32 v[236:237], v[164:165], v[46:47]
	v_cvt_pk_bf16_f32 v238, v238, v239
	s_nop 0
	v_cvt_pk_bf16_f32 v239, v236, v237
	global_store_dwordx2 v[54:55], v[238:239], off
	v_mul_f32_e32 v45, v45, v45
	v_mul_f32_e32 v47, v47, v47
	v_fmac_f32_e32 v45, v44, v44
	v_fmac_f32_e32 v47, v46, v46
	v_add_f32_e32 v44, v45, v47
	s_waitcnt vmcnt(4)
	v_pk_fma_f32 v[40:41], v[40:41], v[108:109], v[240:241]
	v_pk_fma_f32 v[42:43], v[42:43], v[110:111], v[242:243]
	v_pk_mul_f32 v[242:243], v[142:143], v[40:41]
	global_store_dwordx4 v[56:57], v[40:43], off offset:64 sc1
	v_pk_mul_f32 v[240:241], v[140:141], v[42:43]
	v_cvt_pk_bf16_f32 v242, v242, v243
	s_nop 0
	v_cvt_pk_bf16_f32 v243, v240, v241
	global_store_dwordx2 v[54:55], v[242:243], off offset:32
	v_mul_f32_e32 v41, v41, v41
	v_mul_f32_e32 v43, v43, v43
	v_fmac_f32_e32 v41, v40, v40
	v_fmac_f32_e32 v43, v42, v42
	v_add_f32_e32 v40, v41, v43
	v_add_f32_e32 v40, v44, v40
	s_waitcnt vmcnt(5)
; __device__ __forceinline__ unsigned cvt_pk_bf16(float lo, float hi) { unsigned r; asm volatile("v_cvt_pk_bf16_f32 %0, %1, %2" : "=v"(r) : "v"(lo), "v"(hi)); return r; }
;     __device__ __forceinline__ void operator()(const f32x4 (&acc)[2][2][4][2], const Unit& u, int wr, int wc, int fr, int fq) const {
;     ...
;         for (int ai = 0; ai < 2; ++ai)
; #pragma unroll
;             for (int m = 0; m < 4; ++m) { const int row = row0 + ai * HALF + m * 16; const size_t off = (size_t)row * D + col0;
;                 float ssq = 0.f;
; #pragma unroll
;                 for (int bj = 0; bj < 2; ++bj)
; #pragma unroll
;                     for (int n = 0; n < 2; ++n) { const f32x4 bs = *(const f32x4*)(base + off + bj * HALF + n * 16);
;                         const f32x4 o = bs + gv[bj][n] * acc[ai][bj][m][n];
;                         *(f32x4*)(out + off + bj * HALF + n * 16) = o;
;                         if (FOLD) { ssq += (o.x * o.x + o.y * o.y) + (o.z * o.z + o.w * o.w); const f32x4 q = o * sv[bj][n];
;                             u32x2 w; w.x = cvt_pk_bf16(q.x, q.y); w.y = cvt_pk_bf16(q.z, q.w); *(u32x2*)(U2 + off + bj * HALF + n * 16) = w; } }
;                 if (FOLD) { ssq += __shfl_xor(ssq, 16); ssq += __shfl_xor(ssq, 32);
;                     if (fq == 0) part[(size_t)row * 16 + (u.pn & 3) * 4 + wc] = ssq; } }
	v_pk_fma_f32 v[36:37], v[36:37], v[104:105], v[244:245]
	v_pk_fma_f32 v[38:39], v[38:39], v[106:107], v[246:247]
	v_pk_mul_f32 v[246:247], v[138:139], v[36:37]
	global_store_dwordx4 v[56:57], v[36:39], off offset:512 sc1
	v_pk_mul_f32 v[244:245], v[136:137], v[38:39]
	v_cvt_pk_bf16_f32 v246, v246, v247
	s_nop 0
	v_cvt_pk_bf16_f32 v247, v244, v245
	global_store_dwordx2 v[54:55], v[246:247], off offset:256
	v_mul_f32_e32 v37, v37, v37
	v_mul_f32_e32 v39, v39, v39
	v_fmac_f32_e32 v37, v36, v36
	v_fmac_f32_e32 v39, v38, v38
	v_add_f32_e32 v36, v37, v39
	v_add_f32_e32 v38, v40, v36
	s_waitcnt vmcnt(6)
	v_pk_fma_f32 v[36:37], v[34:35], v[98:99], v[52:53]
	v_pk_fma_f32 v[34:35], v[32:33], v[96:97], v[50:51]
	v_mul_f32_e32 v33, v37, v37
	v_mul_f32_e32 v32, v35, v35
	v_fmac_f32_e32 v32, v34, v34
	v_fmac_f32_e32 v33, v36, v36
	v_add_f32_e32 v32, v32, v33
	v_add_f32_e32 v32, v38, v32
	ds_bpermute_b32 v33, v207, v32
	global_store_dwordx4 v[56:57], v[34:37], off offset:576 sc1
	s_waitcnt lgkmcnt(0)
	v_add_f32_e32 v32, v32, v33
	ds_bpermute_b32 v33, v208, v32
	v_pk_mul_f32 v[34:35], v[132:133], v[34:35]
	v_pk_mul_f32 v[36:37], v[134:135], v[36:37]
	v_cvt_pk_bf16_f32 v34, v34, v35
	s_nop 0
	v_cvt_pk_bf16_f32 v35, v36, v37
	global_store_dwordx2 v[54:55], v[34:35], off offset:288
	s_and_saveexec_b64 s[4:5], s[0:1]
	s_cbranch_execz .LBB0_1114
	v_readlane_b32 s34, v249, 31
	v_lshlrev_b64 v[34:35], 6, v[48:49]
	v_readlane_b32 s35, v249, 32
	s_lshl_b32 s12, s27, 2
	s_waitcnt lgkmcnt(0)
	v_add_f32_e32 v32, v32, v33
	v_lshl_add_u64 v[34:35], s[34:35], 0, v[34:35]
	v_lshl_add_u64 v[34:35], v[34:35], 0, s[12:13]
	s_lshl_b32 s12, s46, 2
	v_lshl_add_u64 v[34:35], v[34:35], 0, s[12:13]
	global_store_dword v[34:35], v32, off
.LBB0_1114:
	s_or_b64 exec, exec, s[4:5]
	v_add_u32_e32 v32, 0xa0, v162
	s_waitcnt lgkmcnt(0)
	v_ashrrev_i32_e32 v33, 31, v32
	v_lshlrev_b64 v[34:35], 10, v[32:33]
	v_readlane_b32 s56, v248, 0
	v_lshl_add_u64 v[38:39], v[34:35], 0, v[160:161]
	v_readlane_b32 s62, v248, 6
	v_readlane_b32 s63, v248, 7
	v_readlane_b32 s4, v249, 43
	v_readlane_b32 s5, v249, 44
	v_lshl_add_u64 v[40:41], v[38:39], 2, s[62:63]
	global_load_dwordx4 v[236:239], v[40:41], off
	global_load_dwordx4 v[240:243], v[40:41], off offset:64
	global_load_dwordx4 v[244:247], v[40:41], off offset:512
	global_load_dwordx4 v[34:37], v[40:41], off offset:576
	v_lshl_add_u64 v[38:39], v[38:39], 1, s[4:5]
	v_readlane_b32 s57, v248, 1
	v_readlane_b32 s58, v248, 2
	v_readlane_b32 s59, v248, 3
	v_readlane_b32 s60, v248, 4
	v_readlane_b32 s61, v248, 5
	s_waitcnt vmcnt(3)
	v_pk_fma_f32 v[28:29], v[28:29], v[100:101], v[236:237]
	v_pk_fma_f32 v[30:31], v[30:31], v[102:103], v[238:239]
	v_pk_mul_f32 v[238:239], v[166:167], v[28:29]
	global_store_dwordx4 v[40:41], v[28:31], off sc1
	v_pk_mul_f32 v[236:237], v[164:165], v[30:31]
	v_cvt_pk_bf16_f32 v238, v238, v239
	s_nop 0
	v_cvt_pk_bf16_f32 v239, v236, v237
	global_store_dwordx2 v[38:39], v[238:239], off
	v_mul_f32_e32 v29, v29, v29
	v_mul_f32_e32 v31, v31, v31
	v_fmac_f32_e32 v29, v28, v28
	v_fmac_f32_e32 v31, v30, v30
	v_add_f32_e32 v28, v29, v31
	s_waitcnt vmcnt(4)
	v_pk_fma_f32 v[24:25], v[24:25], v[108:109], v[240:241]
	v_pk_fma_f32 v[26:27], v[26:27], v[110:111], v[242:243]
	v_pk_mul_f32 v[242:243], v[142:143], v[24:25]
	global_store_dwordx4 v[40:41], v[24:27], off offset:64 sc1
	v_pk_mul_f32 v[240:241], v[140:141], v[26:27]
	v_cvt_pk_bf16_f32 v242, v242, v243
	s_nop 0
	v_cvt_pk_bf16_f32 v243, v240, v241
	global_store_dwordx2 v[38:39], v[242:243], off offset:32
	v_mul_f32_e32 v25, v25, v25
	v_mul_f32_e32 v27, v27, v27
	v_fmac_f32_e32 v25, v24, v24
	v_fmac_f32_e32 v27, v26, v26
	v_add_f32_e32 v24, v25, v27
	v_add_f32_e32 v24, v28, v24
	s_waitcnt vmcnt(5)
	v_pk_fma_f32 v[20:21], v[20:21], v[104:105], v[244:245]
	v_pk_fma_f32 v[22:23], v[22:23], v[106:107], v[246:247]
	v_pk_mul_f32 v[246:247], v[138:139], v[20:21]
	global_store_dwordx4 v[40:41], v[20:23], off offset:512 sc1
	v_pk_mul_f32 v[244:245], v[136:137], v[22:23]
	v_cvt_pk_bf16_f32 v246, v246, v247
	s_nop 0
	v_cvt_pk_bf16_f32 v247, v244, v245
	global_store_dwordx2 v[38:39], v[246:247], off offset:256
	v_mul_f32_e32 v21, v21, v21
	v_mul_f32_e32 v23, v23, v23
	v_fmac_f32_e32 v21, v20, v20
	v_fmac_f32_e32 v23, v22, v22
	v_add_f32_e32 v20, v21, v23
	v_add_f32_e32 v22, v24, v20
	s_waitcnt vmcnt(6)
	v_pk_fma_f32 v[20:21], v[18:19], v[98:99], v[36:37]
	v_pk_fma_f32 v[18:19], v[16:17], v[96:97], v[34:35]
	v_mul_f32_e32 v17, v21, v21
	v_mul_f32_e32 v16, v19, v19
	v_fmac_f32_e32 v16, v18, v18
	v_fmac_f32_e32 v17, v20, v20
	v_add_f32_e32 v16, v16, v17
	v_add_f32_e32 v16, v22, v16
	ds_bpermute_b32 v17, v207, v16
	global_store_dwordx4 v[40:41], v[18:21], off offset:576 sc1
	s_waitcnt lgkmcnt(0)
	v_add_f32_e32 v16, v16, v17
	ds_bpermute_b32 v17, v208, v16
	v_pk_mul_f32 v[18:19], v[132:133], v[18:19]
	v_pk_mul_f32 v[20:21], v[134:135], v[20:21]
	v_cvt_pk_bf16_f32 v18, v18, v19
	s_nop 0
	v_cvt_pk_bf16_f32 v19, v20, v21
	global_store_dwordx2 v[38:39], v[18:19], off offset:288
	s_and_saveexec_b64 s[4:5], s[0:1]
	s_cbranch_execz .LBB0_1116
	v_readlane_b32 s34, v249, 31
	v_lshlrev_b64 v[18:19], 6, v[32:33]
	v_readlane_b32 s35, v249, 32
	s_lshl_b32 s12, s27, 2
	s_waitcnt lgkmcnt(0)
	v_add_f32_e32 v16, v16, v17
	v_lshl_add_u64 v[18:19], s[34:35], 0, v[18:19]
	v_lshl_add_u64 v[18:19], v[18:19], 0, s[12:13]
	s_lshl_b32 s12, s46, 2
	v_lshl_add_u64 v[18:19], v[18:19], 0, s[12:13]
	global_store_dword v[18:19], v16, off
; __device__ __forceinline__ unsigned cvt_pk_bf16(float lo, float hi) { unsigned r; asm volatile("v_cvt_pk_bf16_f32 %0, %1, %2" : "=v"(r) : "v"(lo), "v"(hi)); return r; }
;     __device__ __forceinline__ void operator()(const f32x4 (&acc)[2][2][4][2], const Unit& u, int wr, int wc, int fr, int fq) const {
;     ...
;         for (int ai = 0; ai < 2; ++ai)
; #pragma unroll
;             for (int m = 0; m < 4; ++m) { const int row = row0 + ai * HALF + m * 16; const size_t off = (size_t)row * D + col0;
;                 float ssq = 0.f;
; #pragma unroll
;                 for (int bj = 0; bj < 2; ++bj)
; #pragma unroll
;                     for (int n = 0; n < 2; ++n) { const f32x4 bs = *(const f32x4*)(base + off + bj * HALF + n * 16);
;                         const f32x4 o = bs + gv[bj][n] * acc[ai][bj][m][n];
;                         *(f32x4*)(out + off + bj * HALF + n * 16) = o;
;                         if (FOLD) { ssq += (o.x * o.x + o.y * o.y) + (o.z * o.z + o.w * o.w); const f32x4 q = o * sv[bj][n];
;                             u32x2 w; w.x = cvt_pk_bf16(q.x, q.y); w.y = cvt_pk_bf16(q.z, q.w); *(u32x2*)(U2 + off + bj * HALF + n * 16) = w; } }
;                 if (FOLD) { ssq += __shfl_xor(ssq, 16); ssq += __shfl_xor(ssq, 32);
;                     if (fq == 0) part[(size_t)row * 16 + (u.pn & 3) * 4 + wc] = ssq; } }
.LBB0_1116:
	s_or_b64 exec, exec, s[4:5]
	v_add_u32_e32 v16, 0xb0, v162
	s_waitcnt lgkmcnt(0)
	v_ashrrev_i32_e32 v17, 31, v16
	v_lshlrev_b64 v[18:19], 10, v[16:17]
	v_readlane_b32 s56, v248, 0
	v_lshl_add_u64 v[22:23], v[18:19], 0, v[160:161]
	v_readlane_b32 s62, v248, 6
	v_readlane_b32 s63, v248, 7
	v_readlane_b32 s4, v249, 43
	v_readlane_b32 s5, v249, 44
	v_lshl_add_u64 v[24:25], v[22:23], 2, s[62:63]
	global_load_dwordx4 v[236:239], v[24:25], off
	global_load_dwordx4 v[240:243], v[24:25], off offset:64
	global_load_dwordx4 v[244:247], v[24:25], off offset:512
	global_load_dwordx4 v[18:21], v[24:25], off offset:576
	v_lshl_add_u64 v[22:23], v[22:23], 1, s[4:5]
	v_readlane_b32 s57, v248, 1
	v_readlane_b32 s58, v248, 2
	v_readlane_b32 s59, v248, 3
	v_readlane_b32 s60, v248, 4
	v_readlane_b32 s61, v248, 5
	s_waitcnt vmcnt(3)
	v_pk_fma_f32 v[12:13], v[12:13], v[100:101], v[236:237]
	v_pk_fma_f32 v[14:15], v[14:15], v[102:103], v[238:239]
	v_pk_mul_f32 v[238:239], v[166:167], v[12:13]
	global_store_dwordx4 v[24:25], v[12:15], off sc1
	v_pk_mul_f32 v[236:237], v[164:165], v[14:15]
	v_cvt_pk_bf16_f32 v238, v238, v239
	s_nop 0
	v_cvt_pk_bf16_f32 v239, v236, v237
	global_store_dwordx2 v[22:23], v[238:239], off
	v_mul_f32_e32 v13, v13, v13
	v_mul_f32_e32 v15, v15, v15
	v_fmac_f32_e32 v13, v12, v12
	v_fmac_f32_e32 v15, v14, v14
	v_add_f32_e32 v12, v13, v15
	s_waitcnt vmcnt(4)
	v_pk_fma_f32 v[8:9], v[8:9], v[108:109], v[240:241]
	v_pk_fma_f32 v[10:11], v[10:11], v[110:111], v[242:243]
	v_pk_mul_f32 v[242:243], v[142:143], v[8:9]
	global_store_dwordx4 v[24:25], v[8:11], off offset:64 sc1
	v_pk_mul_f32 v[240:241], v[140:141], v[10:11]
	v_cvt_pk_bf16_f32 v242, v242, v243
	s_nop 0
	v_cvt_pk_bf16_f32 v243, v240, v241
	global_store_dwordx2 v[22:23], v[242:243], off offset:32
	v_mul_f32_e32 v9, v9, v9
	v_mul_f32_e32 v11, v11, v11
	v_fmac_f32_e32 v9, v8, v8
	v_fmac_f32_e32 v11, v10, v10
	v_add_f32_e32 v8, v9, v11
	v_add_f32_e32 v8, v12, v8
	s_waitcnt vmcnt(5)
	v_pk_fma_f32 v[4:5], v[4:5], v[104:105], v[244:245]
	v_pk_fma_f32 v[6:7], v[6:7], v[106:107], v[246:247]
	v_pk_mul_f32 v[246:247], v[138:139], v[4:5]
	global_store_dwordx4 v[24:25], v[4:7], off offset:512 sc1
	v_pk_mul_f32 v[244:245], v[136:137], v[6:7]
	v_cvt_pk_bf16_f32 v246, v246, v247
	s_nop 0
	v_cvt_pk_bf16_f32 v247, v244, v245
	global_store_dwordx2 v[22:23], v[246:247], off offset:256
	v_mul_f32_e32 v5, v5, v5
	v_mul_f32_e32 v7, v7, v7
	v_fmac_f32_e32 v5, v4, v4
	v_fmac_f32_e32 v7, v6, v6
	v_add_f32_e32 v4, v5, v7
	v_add_f32_e32 v6, v8, v4
	s_waitcnt vmcnt(6)
	v_pk_fma_f32 v[4:5], v[2:3], v[98:99], v[20:21]
	v_pk_fma_f32 v[2:3], v[0:1], v[96:97], v[18:19]
	v_mul_f32_e32 v1, v5, v5
	v_mul_f32_e32 v0, v3, v3
	v_fmac_f32_e32 v0, v2, v2
	v_fmac_f32_e32 v1, v4, v4
	v_add_f32_e32 v0, v0, v1
	v_add_f32_e32 v0, v6, v0
	ds_bpermute_b32 v1, v207, v0
	global_store_dwordx4 v[24:25], v[2:5], off offset:576 sc1
	s_waitcnt lgkmcnt(0)
	v_add_f32_e32 v0, v0, v1
	ds_bpermute_b32 v1, v208, v0
	v_pk_mul_f32 v[2:3], v[132:133], v[2:3]
	v_pk_mul_f32 v[4:5], v[134:135], v[4:5]
	v_cvt_pk_bf16_f32 v2, v2, v3
	s_nop 0
	v_cvt_pk_bf16_f32 v3, v4, v5
	global_store_dwordx2 v[22:23], v[2:3], off offset:288
	s_and_saveexec_b64 s[4:5], s[0:1]
	s_cbranch_execz .LBB0_1118
	v_readlane_b32 s34, v249, 31
	v_lshlrev_b64 v[2:3], 6, v[16:17]
	v_readlane_b32 s35, v249, 32
	s_lshl_b32 s12, s27, 2
	s_waitcnt lgkmcnt(0)
	v_add_f32_e32 v0, v0, v1
	v_lshl_add_u64 v[2:3], s[34:35], 0, v[2:3]
	v_lshl_add_u64 v[2:3], v[2:3], 0, s[12:13]
	s_lshl_b32 s12, s46, 2
	v_lshl_add_u64 v[2:3], v[2:3], 0, s[12:13]
	global_store_dword v[2:3], v0, off

; __device__ __forceinline__ unsigned cvt_pk_bf16(float lo, float hi) { unsigned r; asm volatile("v_cvt_pk_bf16_f32 %0, %1, %2" : "=v"(r) : "v"(lo), "v"(hi)); return r; }
;     __device__ __forceinline__ void operator()(const f32x4 (&acc)[2][2][4][2], const Unit& u, int wr, int wc, int fr, int fq) const {
;         const int row0 = u.pm * BM + wr * 64 + fr, col0 = u.pn * BM + wc * 32 + 4 * fq;
;         const float* gp = gate + (size_t)(u.pm >> 4) * NMOD;
;         f32x4 gv[2][2], sv[2][2];
; #pragma unroll
;         for (int bj = 0; bj < 2; ++bj)
; #pragma unroll
;             for (int n = 0; n < 2; ++n) { gv[bj][n] = *(const f32x4*)(gp + col0 + bj * HALF + n * 16) * (HALFSC ? 0.5f : 1.0f);
;                 if (FOLD) sv[bj][n] = *(const f32x4*)(scn + (size_t)(u.pm >> 4) * NMOD + col0 + bj * HALF + n * 16) + 1.0f; }
; #pragma unroll
;         for (int ai = 0; ai < 2; ++ai)
; #pragma unroll
;             for (int m = 0; m < 4; ++m) { const int row = row0 + ai * HALF + m * 16; const size_t off = (size_t)row * D + col0;
;                 float ssq = 0.f;
; #pragma unroll
;                 for (int bj = 0; bj < 2; ++bj)
; #pragma unroll
;                     for (int n = 0; n < 2; ++n) { const f32x4 bs = *(const f32x4*)(base + off + bj * HALF + n * 16);
;                         const f32x4 o = bs + gv[bj][n] * acc[ai][bj][m][n];
;                         *(f32x4*)(out + off + bj * HALF + n * 16) = o;
;                         if (FOLD) { ssq += (o.x * o.x + o.y * o.y) + (o.z * o.z + o.w * o.w); const f32x4 q = o * sv[bj][n];
;                             u32x2 w; w.x = cvt_pk_bf16(q.x, q.y); w.y = cvt_pk_bf16(q.z, q.w); *(u32x2*)(U2 + off + bj * HALF + n * 16) = w; } }
;                 if (FOLD) { ssq += __shfl_xor(ssq, 16); ssq += __shfl_xor(ssq, 32);
;                     if (fq == 0) part[(size_t)row * 16 + (u.pn & 3) * 4 + wc] = ssq; } }
.LBB0_1272:
	s_ashr_i32 s34, s61, 4
	v_lshl_or_b32 v144, s20, 8, v170
	s_mul_i32 s37, s34, 0x9000
	s_mul_hi_i32 s36, s34, 0x9000
	s_add_u32 s34, s46, s37
	v_ashrrev_i32_e32 v145, 31, v144
	v_lshl_add_u32 v150, s61, 8, v168
	s_addc_u32 s35, s47, s36
	v_lshlrev_b64 v[156:157], 2, v[144:145]
	v_ashrrev_i32_e32 v151, 31, v150
	v_lshl_add_u64 v[160:161], s[34:35], 0, v[156:157]
	s_add_u32 s34, s48, s37
	v_lshlrev_b64 v[152:153], 10, v[150:151]
	v_readlane_b32 s72, v248, 0
	s_addc_u32 s35, s49, s36
	v_lshl_add_u64 v[162:163], v[152:153], 0, v[144:145]
	v_readlane_b32 s78, v248, 6
	v_readlane_b32 s79, v248, 7
	global_load_dwordx4 v[146:149], v[160:161], off
	v_lshl_add_u64 v[164:165], s[34:35], 0, v[156:157]
	v_lshl_add_u64 v[214:215], v[162:163], 2, s[78:79]
	global_load_dwordx4 v[152:155], v[214:215], off
	global_load_dwordx4 v[156:159], v[164:165], off
	v_readlane_b32 s34, v249, 43
	v_readlane_b32 s35, v249, 44
	global_load_dwordx4 v[174:177], v[160:161], off offset:64
	global_load_dwordx4 v[178:181], v[160:161], off offset:512
	global_load_dwordx4 v[182:185], v[160:161], off offset:576
	global_load_dwordx4 v[186:189], v[164:165], off offset:64
	global_load_dwordx4 v[190:193], v[164:165], off offset:512
	global_load_dwordx4 v[194:197], v[164:165], off offset:576
	global_load_dwordx4 v[236:239], v[214:215], off offset:64
	global_load_dwordx4 v[240:243], v[214:215], off offset:512
	global_load_dwordx4 v[244:247], v[214:215], off offset:576
	v_lshl_add_u64 v[216:217], v[162:163], 1, s[34:35]
	s_lshl_b32 s20, s20, 2
	s_and_b32 s36, s20, 12
	v_readlane_b32 s73, v248, 1
	v_readlane_b32 s74, v248, 2
	v_readlane_b32 s75, v248, 3
	v_readlane_b32 s76, v248, 4
	v_readlane_b32 s77, v248, 5
	s_waitcnt vmcnt(3)
	v_pk_mul_f32 v[162:163], v[146:147], 0.5 op_sel_hi:[1,0]
	v_pk_mul_f32 v[160:161], v[148:149], 0.5 op_sel_hi:[1,0]
	v_pk_fma_f32 v[198:199], v[124:125], v[162:163], v[152:153]
	v_pk_add_f32 v[166:167], v[156:157], 1.0 op_sel_hi:[1,0]
	v_pk_fma_f32 v[200:201], v[126:127], v[160:161], v[154:155]
	v_pk_add_f32 v[164:165], v[158:159], 1.0 op_sel_hi:[1,0]
	v_pk_mul_f32 v[126:127], v[166:167], v[198:199]
	global_store_dwordx4 v[214:215], v[198:201], off sc1
	v_pk_mul_f32 v[124:125], v[164:165], v[200:201]
	v_cvt_pk_bf16_f32 v126, v126, v127
	v_pk_mul_f32 v[154:155], v[174:175], 0.5 op_sel_hi:[1,0]
	v_cvt_pk_bf16_f32 v127, v124, v125
	global_store_dwordx2 v[216:217], v[126:127], off
	v_pk_mul_f32 v[158:159], v[176:177], 0.5 op_sel_hi:[1,0]
	v_pk_add_f32 v[148:149], v[186:187], 1.0 op_sel_hi:[1,0]
	v_pk_add_f32 v[126:127], v[188:189], 1.0 op_sel_hi:[1,0]
	v_pk_mul_f32 v[152:153], v[178:179], 0.5 op_sel_hi:[1,0]
	v_pk_mul_f32 v[156:157], v[180:181], 0.5 op_sel_hi:[1,0]
	v_pk_add_f32 v[146:147], v[190:191], 1.0 op_sel_hi:[1,0]
	v_pk_add_f32 v[124:125], v[192:193], 1.0 op_sel_hi:[1,0]
	s_waitcnt vmcnt(4)
	v_pk_fma_f32 v[174:175], v[120:121], v[154:155], v[236:237]
	v_pk_fma_f32 v[176:177], v[122:123], v[158:159], v[238:239]
	v_pk_mul_f32 v[122:123], v[148:149], v[174:175]
	global_store_dwordx4 v[214:215], v[174:177], off offset:64 sc1
	v_pk_mul_f32 v[120:121], v[126:127], v[176:177]
	v_cvt_pk_bf16_f32 v122, v122, v123
	s_nop 0
	v_cvt_pk_bf16_f32 v123, v120, v121
	global_store_dwordx2 v[216:217], v[122:123], off offset:32
	v_mul_f32_e32 v175, v175, v175
	v_mul_f32_e32 v177, v177, v177
	v_fmac_f32_e32 v175, v174, v174
	v_fmac_f32_e32 v177, v176, v176
	v_add_f32_e32 v174, v175, v177
	s_waitcnt vmcnt(5)
	v_pk_fma_f32 v[178:179], v[116:117], v[152:153], v[240:241]
	v_pk_fma_f32 v[180:181], v[118:119], v[156:157], v[242:243]
	v_pk_mul_f32 v[118:119], v[146:147], v[178:179]
	global_store_dwordx4 v[214:215], v[178:181], off offset:512 sc1
	v_pk_mul_f32 v[116:117], v[124:125], v[180:181]
	v_cvt_pk_bf16_f32 v118, v118, v119
	v_pk_mul_f32 v[120:121], v[182:183], 0.5 op_sel_hi:[1,0]
	v_cvt_pk_bf16_f32 v119, v116, v117
	global_store_dwordx2 v[216:217], v[118:119], off offset:256
	v_mul_f32_e32 v182, v199, v199
	v_mul_f32_e32 v183, v201, v201
	v_fmac_f32_e32 v182, v198, v198
	v_fmac_f32_e32 v183, v200, v200
	v_mul_f32_e32 v175, v179, v179
	v_mul_f32_e32 v176, v181, v181
	v_add_f32_e32 v182, v182, v183
	v_fmac_f32_e32 v175, v178, v178
	v_fmac_f32_e32 v176, v180, v180
	v_pk_mul_f32 v[122:123], v[184:185], 0.5 op_sel_hi:[1,0]
	v_add_f32_e32 v174, v182, v174
	v_add_f32_e32 v175, v175, v176
	v_add_f32_e32 v178, v174, v175
	v_pk_add_f32 v[116:117], v[194:195], 1.0 op_sel_hi:[1,0]
	v_pk_add_f32 v[118:119], v[196:197], 1.0 op_sel_hi:[1,0]
	s_waitcnt vmcnt(6)
	v_pk_fma_f32 v[176:177], v[114:115], v[122:123], v[246:247]
	v_pk_fma_f32 v[174:175], v[112:113], v[120:121], v[244:245]
	v_mul_f32_e32 v113, v177, v177
	v_mul_f32_e32 v112, v175, v175
	v_fmac_f32_e32 v112, v174, v174
	v_fmac_f32_e32 v113, v176, v176
	v_add_f32_e32 v112, v112, v113
	v_add_f32_e32 v112, v178, v112
	ds_bpermute_b32 v113, v207, v112
	global_store_dwordx4 v[214:215], v[174:177], off offset:576 sc1
	v_pk_mul_f32 v[114:115], v[118:119], v[176:177]
	s_waitcnt lgkmcnt(0)
	v_add_f32_e32 v112, v112, v113
	ds_bpermute_b32 v113, v208, v112
	v_pk_mul_f32 v[174:175], v[116:117], v[174:175]
	s_nop 0
	v_cvt_pk_bf16_f32 v174, v174, v175
	v_cvt_pk_bf16_f32 v175, v114, v115
	global_store_dwordx2 v[216:217], v[174:175], off offset:288
	s_and_saveexec_b64 s[34:35], s[0:1]
	s_cbranch_execz .LBB0_1274
	v_readlane_b32 s40, v249, 31
	s_waitcnt lgkmcnt(0)
	v_add_f32_e32 v114, v112, v113
	v_lshlrev_b64 v[112:113], 6, v[150:151]
	v_readlane_b32 s41, v249, 32
	s_lshl_b32 s20, s36, 2
	s_nop 0
	v_lshl_add_u64 v[112:113], s[40:41], 0, v[112:113]
	v_lshl_add_u64 v[112:113], v[112:113], 0, s[20:21]
	s_lshl_b32 s20, s50, 2
	v_lshl_add_u64 v[112:113], v[112:113], 0, s[20:21]
	global_store_dword v[112:113], v114, off
; __device__ __forceinline__ unsigned cvt_pk_bf16(float lo, float hi) { unsigned r; asm volatile("v_cvt_pk_bf16_f32 %0, %1, %2" : "=v"(r) : "v"(lo), "v"(hi)); return r; }
;     __device__ __forceinline__ void operator()(const f32x4 (&acc)[2][2][4][2], const Unit& u, int wr, int wc, int fr, int fq) const {
;     ...
;         for (int ai = 0; ai < 2; ++ai)
; #pragma unroll
;             for (int m = 0; m < 4; ++m) { const int row = row0 + ai * HALF + m * 16; const size_t off = (size_t)row * D + col0;
;                 float ssq = 0.f;
; #pragma unroll
;                 for (int bj = 0; bj < 2; ++bj)
; #pragma unroll
;                     for (int n = 0; n < 2; ++n) { const f32x4 bs = *(const f32x4*)(base + off + bj * HALF + n * 16);
;                         const f32x4 o = bs + gv[bj][n] * acc[ai][bj][m][n];
;                         *(f32x4*)(out + off + bj * HALF + n * 16) = o;
;                         if (FOLD) { ssq += (o.x * o.x + o.y * o.y) + (o.z * o.z + o.w * o.w); const f32x4 q = o * sv[bj][n];
;                             u32x2 w; w.x = cvt_pk_bf16(q.x, q.y); w.y = cvt_pk_bf16(q.z, q.w); *(u32x2*)(U2 + off + bj * HALF + n * 16) = w; } }
;                 if (FOLD) { ssq += __shfl_xor(ssq, 16); ssq += __shfl_xor(ssq, 32);
;                     if (fq == 0) part[(size_t)row * 16 + (u.pn & 3) * 4 + wc] = ssq; } }
.LBB0_1274:
	s_or_b64 exec, exec, s[34:35]
	v_or_b32_e32 v112, 16, v150
	s_waitcnt lgkmcnt(0)
	v_ashrrev_i32_e32 v113, 31, v112
	v_lshlrev_b64 v[114:115], 10, v[112:113]
	v_readlane_b32 s72, v248, 0
	v_lshl_add_u64 v[114:115], v[114:115], 0, v[144:145]
	v_readlane_b32 s78, v248, 6
	v_readlane_b32 s79, v248, 7
	v_readlane_b32 s34, v249, 43
	v_readlane_b32 s35, v249, 44
	v_lshl_add_u64 v[178:179], v[114:115], 2, s[78:79]
	global_load_dwordx4 v[236:239], v[178:179], off
	global_load_dwordx4 v[240:243], v[178:179], off offset:64
	global_load_dwordx4 v[244:247], v[178:179], off offset:512
	global_load_dwordx4 v[174:177], v[178:179], off offset:576
	v_lshl_add_u64 v[114:115], v[114:115], 1, s[34:35]
	v_readlane_b32 s73, v248, 1
	v_readlane_b32 s74, v248, 2
	v_readlane_b32 s75, v248, 3
	v_readlane_b32 s76, v248, 4
	v_readlane_b32 s77, v248, 5
	s_waitcnt vmcnt(3)
	v_pk_fma_f32 v[108:109], v[108:109], v[162:163], v[236:237]
	v_pk_fma_f32 v[110:111], v[110:111], v[160:161], v[238:239]
	v_pk_mul_f32 v[238:239], v[166:167], v[108:109]
	global_store_dwordx4 v[178:179], v[108:111], off sc1
	v_pk_mul_f32 v[236:237], v[164:165], v[110:111]
	v_cvt_pk_bf16_f32 v238, v238, v239
	s_nop 0
	v_cvt_pk_bf16_f32 v239, v236, v237
	global_store_dwordx2 v[114:115], v[238:239], off
	v_mul_f32_e32 v109, v109, v109
	v_mul_f32_e32 v111, v111, v111
	v_fmac_f32_e32 v109, v108, v108
	v_fmac_f32_e32 v111, v110, v110
	v_add_f32_e32 v108, v109, v111
	s_waitcnt vmcnt(4)
	v_pk_fma_f32 v[104:105], v[104:105], v[154:155], v[240:241]
	v_pk_fma_f32 v[106:107], v[106:107], v[158:159], v[242:243]
	v_pk_mul_f32 v[242:243], v[148:149], v[104:105]
	global_store_dwordx4 v[178:179], v[104:107], off offset:64 sc1
	v_pk_mul_f32 v[240:241], v[126:127], v[106:107]
	v_cvt_pk_bf16_f32 v242, v242, v243
	s_nop 0
	v_cvt_pk_bf16_f32 v243, v240, v241
	global_store_dwordx2 v[114:115], v[242:243], off offset:32
	v_mul_f32_e32 v105, v105, v105
	v_mul_f32_e32 v107, v107, v107
	v_fmac_f32_e32 v105, v104, v104
	v_fmac_f32_e32 v107, v106, v106
	v_add_f32_e32 v104, v105, v107
	v_add_f32_e32 v104, v108, v104
	s_waitcnt vmcnt(5)
	v_pk_fma_f32 v[100:101], v[100:101], v[152:153], v[244:245]
	v_pk_fma_f32 v[102:103], v[102:103], v[156:157], v[246:247]
	v_pk_mul_f32 v[246:247], v[146:147], v[100:101]
	global_store_dwordx4 v[178:179], v[100:103], off offset:512 sc1
	v_pk_mul_f32 v[244:245], v[124:125], v[102:103]
	v_cvt_pk_bf16_f32 v246, v246, v247
	s_nop 0
	v_cvt_pk_bf16_f32 v247, v244, v245
	global_store_dwordx2 v[114:115], v[246:247], off offset:256
	v_mul_f32_e32 v101, v101, v101
	v_mul_f32_e32 v103, v103, v103
	v_fmac_f32_e32 v101, v100, v100
	v_fmac_f32_e32 v103, v102, v102
	v_add_f32_e32 v100, v101, v103
	v_add_f32_e32 v102, v104, v100
	s_waitcnt vmcnt(6)
	v_pk_fma_f32 v[100:101], v[98:99], v[122:123], v[176:177]
	v_pk_fma_f32 v[98:99], v[96:97], v[120:121], v[174:175]
	v_mul_f32_e32 v97, v101, v101
	v_mul_f32_e32 v96, v99, v99
	v_fmac_f32_e32 v96, v98, v98
	v_fmac_f32_e32 v97, v100, v100
	v_add_f32_e32 v96, v96, v97
	v_add_f32_e32 v96, v102, v96
	ds_bpermute_b32 v97, v207, v96
	global_store_dwordx4 v[178:179], v[98:101], off offset:576 sc1
	s_waitcnt lgkmcnt(0)
	v_add_f32_e32 v96, v96, v97
	ds_bpermute_b32 v97, v208, v96
	v_pk_mul_f32 v[98:99], v[116:117], v[98:99]
	v_pk_mul_f32 v[100:101], v[118:119], v[100:101]
	v_cvt_pk_bf16_f32 v98, v98, v99
	s_nop 0
	v_cvt_pk_bf16_f32 v99, v100, v101
	global_store_dwordx2 v[114:115], v[98:99], off offset:288
	s_and_saveexec_b64 s[34:35], s[0:1]
	s_cbranch_execz .LBB0_1276
	v_readlane_b32 s40, v249, 31
	s_waitcnt lgkmcnt(0)
	v_add_f32_e32 v98, v96, v97
	v_lshlrev_b64 v[96:97], 6, v[112:113]
	v_readlane_b32 s41, v249, 32
	s_lshl_b32 s20, s36, 2
	s_nop 0
	v_lshl_add_u64 v[96:97], s[40:41], 0, v[96:97]
	v_lshl_add_u64 v[96:97], v[96:97], 0, s[20:21]
	s_lshl_b32 s20, s50, 2
	v_lshl_add_u64 v[96:97], v[96:97], 0, s[20:21]
	global_store_dword v[96:97], v98, off
.LBB0_1276:
	s_or_b64 exec, exec, s[34:35]
	v_or_b32_e32 v96, 32, v150
	s_waitcnt lgkmcnt(0)
	v_ashrrev_i32_e32 v97, 31, v96
	v_lshlrev_b64 v[98:99], 10, v[96:97]
	v_readlane_b32 s72, v248, 0
	v_lshl_add_u64 v[102:103], v[98:99], 0, v[144:145]
	v_readlane_b32 s78, v248, 6
	v_readlane_b32 s79, v248, 7
	v_readlane_b32 s34, v249, 43
	v_readlane_b32 s35, v249, 44
	v_lshl_add_u64 v[104:105], v[102:103], 2, s[78:79]
	global_load_dwordx4 v[236:239], v[104:105], off
	global_load_dwordx4 v[240:243], v[104:105], off offset:64
	global_load_dwordx4 v[244:247], v[104:105], off offset:512
	global_load_dwordx4 v[98:101], v[104:105], off offset:576
	v_lshl_add_u64 v[102:103], v[102:103], 1, s[34:35]
	v_readlane_b32 s73, v248, 1
	v_readlane_b32 s74, v248, 2
	v_readlane_b32 s75, v248, 3
	v_readlane_b32 s76, v248, 4
	v_readlane_b32 s77, v248, 5
	s_waitcnt vmcnt(3)
	v_pk_fma_f32 v[92:93], v[92:93], v[162:163], v[236:237]
	v_pk_fma_f32 v[94:95], v[94:95], v[160:161], v[238:239]
	v_pk_mul_f32 v[238:239], v[166:167], v[92:93]
	global_store_dwordx4 v[104:105], v[92:95], off sc1
	v_pk_mul_f32 v[236:237], v[164:165], v[94:95]
	v_cvt_pk_bf16_f32 v238, v238, v239
	s_nop 0
	v_cvt_pk_bf16_f32 v239, v236, v237
	global_store_dwordx2 v[102:103], v[238:239], off
	v_mul_f32_e32 v93, v93, v93
	v_mul_f32_e32 v95, v95, v95
	v_fmac_f32_e32 v93, v92, v92
	v_fmac_f32_e32 v95, v94, v94
	v_add_f32_e32 v92, v93, v95
	s_waitcnt vmcnt(4)
	v_pk_fma_f32 v[88:89], v[88:89], v[154:155], v[240:241]
	v_pk_fma_f32 v[90:91], v[90:91], v[158:159], v[242:243]
	v_pk_mul_f32 v[242:243], v[148:149], v[88:89]
	global_store_dwordx4 v[104:105], v[88:91], off offset:64 sc1
	v_pk_mul_f32 v[240:241], v[126:127], v[90:91]
	v_cvt_pk_bf16_f32 v242, v242, v243
	s_nop 0
	v_cvt_pk_bf16_f32 v243, v240, v241
	global_store_dwordx2 v[102:103], v[242:243], off offset:32
	v_mul_f32_e32 v89, v89, v89
	v_mul_f32_e32 v91, v91, v91
	v_fmac_f32_e32 v89, v88, v88
	v_fmac_f32_e32 v91, v90, v90
	v_add_f32_e32 v88, v89, v91
	v_add_f32_e32 v88, v92, v88
	s_waitcnt vmcnt(5)
; __device__ __forceinline__ unsigned cvt_pk_bf16(float lo, float hi) { unsigned r; asm volatile("v_cvt_pk_bf16_f32 %0, %1, %2" : "=v"(r) : "v"(lo), "v"(hi)); return r; }
;     __device__ __forceinline__ void operator()(const f32x4 (&acc)[2][2][4][2], const Unit& u, int wr, int wc, int fr, int fq) const {
;     ...
;         for (int ai = 0; ai < 2; ++ai)
; #pragma unroll
;             for (int m = 0; m < 4; ++m) { const int row = row0 + ai * HALF + m * 16; const size_t off = (size_t)row * D + col0;
;                 float ssq = 0.f;
; #pragma unroll
;                 for (int bj = 0; bj < 2; ++bj)
; #pragma unroll
;                     for (int n = 0; n < 2; ++n) { const f32x4 bs = *(const f32x4*)(base + off + bj * HALF + n * 16);
;                         const f32x4 o = bs + gv[bj][n] * acc[ai][bj][m][n];
;                         *(f32x4*)(out + off + bj * HALF + n * 16) = o;
;                         if (FOLD) { ssq += (o.x * o.x + o.y * o.y) + (o.z * o.z + o.w * o.w); const f32x4 q = o * sv[bj][n];
;                             u32x2 w; w.x = cvt_pk_bf16(q.x, q.y); w.y = cvt_pk_bf16(q.z, q.w); *(u32x2*)(U2 + off + bj * HALF + n * 16) = w; } }
;                 if (FOLD) { ssq += __shfl_xor(ssq, 16); ssq += __shfl_xor(ssq, 32);
;                     if (fq == 0) part[(size_t)row * 16 + (u.pn & 3) * 4 + wc] = ssq; } }
	v_pk_fma_f32 v[84:85], v[84:85], v[152:153], v[244:245]
	v_pk_fma_f32 v[86:87], v[86:87], v[156:157], v[246:247]
	v_pk_mul_f32 v[246:247], v[146:147], v[84:85]
	global_store_dwordx4 v[104:105], v[84:87], off offset:512 sc1
	v_pk_mul_f32 v[244:245], v[124:125], v[86:87]
	v_cvt_pk_bf16_f32 v246, v246, v247
	s_nop 0
	v_cvt_pk_bf16_f32 v247, v244, v245
	global_store_dwordx2 v[102:103], v[246:247], off offset:256
	v_mul_f32_e32 v85, v85, v85
	v_mul_f32_e32 v87, v87, v87
	v_fmac_f32_e32 v85, v84, v84
	v_fmac_f32_e32 v87, v86, v86
	v_add_f32_e32 v84, v85, v87
	v_add_f32_e32 v86, v88, v84
	s_waitcnt vmcnt(6)
	v_pk_fma_f32 v[84:85], v[82:83], v[122:123], v[100:101]
	v_pk_fma_f32 v[82:83], v[80:81], v[120:121], v[98:99]
	v_mul_f32_e32 v81, v85, v85
	v_mul_f32_e32 v80, v83, v83
	v_fmac_f32_e32 v80, v82, v82
	v_fmac_f32_e32 v81, v84, v84
	v_add_f32_e32 v80, v80, v81
	v_add_f32_e32 v80, v86, v80
	ds_bpermute_b32 v81, v207, v80
	global_store_dwordx4 v[104:105], v[82:85], off offset:576 sc1
	s_waitcnt lgkmcnt(0)
	v_add_f32_e32 v80, v80, v81
	ds_bpermute_b32 v81, v208, v80
	v_pk_mul_f32 v[82:83], v[116:117], v[82:83]
	v_pk_mul_f32 v[84:85], v[118:119], v[84:85]
	v_cvt_pk_bf16_f32 v82, v82, v83
	s_nop 0
	v_cvt_pk_bf16_f32 v83, v84, v85
	global_store_dwordx2 v[102:103], v[82:83], off offset:288
	s_and_saveexec_b64 s[34:35], s[0:1]
	s_cbranch_execz .LBB0_1278
	v_readlane_b32 s40, v249, 31
	s_waitcnt lgkmcnt(0)
	v_add_f32_e32 v82, v80, v81
	v_lshlrev_b64 v[80:81], 6, v[96:97]
	v_readlane_b32 s41, v249, 32
	s_lshl_b32 s20, s36, 2
	s_nop 0
	v_lshl_add_u64 v[80:81], s[40:41], 0, v[80:81]
	v_lshl_add_u64 v[80:81], v[80:81], 0, s[20:21]
	s_lshl_b32 s20, s50, 2
	v_lshl_add_u64 v[80:81], v[80:81], 0, s[20:21]
	global_store_dword v[80:81], v82, off
.LBB0_1278:
	s_or_b64 exec, exec, s[34:35]
	v_or_b32_e32 v80, 48, v150
	s_waitcnt lgkmcnt(0)
	v_ashrrev_i32_e32 v81, 31, v80
	v_lshlrev_b64 v[82:83], 10, v[80:81]
	v_readlane_b32 s72, v248, 0
	v_lshl_add_u64 v[86:87], v[82:83], 0, v[144:145]
	v_readlane_b32 s78, v248, 6
	v_readlane_b32 s79, v248, 7
	v_readlane_b32 s34, v249, 43
	v_readlane_b32 s35, v249, 44
	v_lshl_add_u64 v[88:89], v[86:87], 2, s[78:79]
	global_load_dwordx4 v[236:239], v[88:89], off
	global_load_dwordx4 v[240:243], v[88:89], off offset:64
	global_load_dwordx4 v[244:247], v[88:89], off offset:512
	global_load_dwordx4 v[82:85], v[88:89], off offset:576
	v_lshl_add_u64 v[86:87], v[86:87], 1, s[34:35]
	v_readlane_b32 s73, v248, 1
	v_readlane_b32 s74, v248, 2
	v_readlane_b32 s75, v248, 3
	v_readlane_b32 s76, v248, 4
	v_readlane_b32 s77, v248, 5
	s_waitcnt vmcnt(3)
	v_pk_fma_f32 v[76:77], v[76:77], v[162:163], v[236:237]
	v_pk_fma_f32 v[78:79], v[78:79], v[160:161], v[238:239]
	v_pk_mul_f32 v[238:239], v[166:167], v[76:77]
	global_store_dwordx4 v[88:89], v[76:79], off sc1
	v_pk_mul_f32 v[236:237], v[164:165], v[78:79]
	v_cvt_pk_bf16_f32 v238, v238, v239
	s_nop 0
	v_cvt_pk_bf16_f32 v239, v236, v237
	global_store_dwordx2 v[86:87], v[238:239], off
	v_mul_f32_e32 v77, v77, v77
	v_mul_f32_e32 v79, v79, v79
	v_fmac_f32_e32 v77, v76, v76
	v_fmac_f32_e32 v79, v78, v78
	v_add_f32_e32 v76, v77, v79
	s_waitcnt vmcnt(4)
	v_pk_fma_f32 v[72:73], v[72:73], v[154:155], v[240:241]
	v_pk_fma_f32 v[74:75], v[74:75], v[158:159], v[242:243]
	v_pk_mul_f32 v[242:243], v[148:149], v[72:73]
	global_store_dwordx4 v[88:89], v[72:75], off offset:64 sc1
	v_pk_mul_f32 v[240:241], v[126:127], v[74:75]
	v_cvt_pk_bf16_f32 v242, v242, v243
	s_nop 0
	v_cvt_pk_bf16_f32 v243, v240, v241
	global_store_dwordx2 v[86:87], v[242:243], off offset:32
	v_mul_f32_e32 v73, v73, v73
	v_mul_f32_e32 v75, v75, v75
	v_fmac_f32_e32 v73, v72, v72
	v_fmac_f32_e32 v75, v74, v74
	v_add_f32_e32 v72, v73, v75
	v_add_f32_e32 v72, v76, v72
	s_waitcnt vmcnt(5)
	v_pk_fma_f32 v[68:69], v[68:69], v[152:153], v[244:245]
	v_pk_fma_f32 v[70:71], v[70:71], v[156:157], v[246:247]
	v_pk_mul_f32 v[246:247], v[146:147], v[68:69]
	global_store_dwordx4 v[88:89], v[68:71], off offset:512 sc1
	v_pk_mul_f32 v[244:245], v[124:125], v[70:71]
	v_cvt_pk_bf16_f32 v246, v246, v247
	s_nop 0
	v_cvt_pk_bf16_f32 v247, v244, v245
	global_store_dwordx2 v[86:87], v[246:247], off offset:256
	v_mul_f32_e32 v69, v69, v69
	v_mul_f32_e32 v71, v71, v71
	v_fmac_f32_e32 v69, v68, v68
	v_fmac_f32_e32 v71, v70, v70
	v_add_f32_e32 v68, v69, v71
	v_add_f32_e32 v70, v72, v68
	s_waitcnt vmcnt(6)
	v_pk_fma_f32 v[68:69], v[66:67], v[122:123], v[84:85]
	v_pk_fma_f32 v[66:67], v[64:65], v[120:121], v[82:83]
	v_mul_f32_e32 v65, v69, v69
	v_mul_f32_e32 v64, v67, v67
	v_fmac_f32_e32 v64, v66, v66
	v_fmac_f32_e32 v65, v68, v68
	v_add_f32_e32 v64, v64, v65
	v_add_f32_e32 v64, v70, v64
	ds_bpermute_b32 v65, v207, v64
	global_store_dwordx4 v[88:89], v[66:69], off offset:576 sc1
	s_waitcnt lgkmcnt(0)
	v_add_f32_e32 v64, v64, v65
	ds_bpermute_b32 v65, v208, v64
	v_pk_mul_f32 v[66:67], v[116:117], v[66:67]
	v_pk_mul_f32 v[68:69], v[118:119], v[68:69]
	v_cvt_pk_bf16_f32 v66, v66, v67
	s_nop 0
	v_cvt_pk_bf16_f32 v67, v68, v69
	global_store_dwordx2 v[86:87], v[66:67], off offset:288
	s_and_saveexec_b64 s[34:35], s[0:1]
	s_cbranch_execz .LBB0_1280
	v_readlane_b32 s40, v249, 31
	s_waitcnt lgkmcnt(0)
	v_add_f32_e32 v66, v64, v65
	v_lshlrev_b64 v[64:65], 6, v[80:81]
	v_readlane_b32 s41, v249, 32
	s_lshl_b32 s20, s36, 2
	s_nop 0
	v_lshl_add_u64 v[64:65], s[40:41], 0, v[64:65]
	v_lshl_add_u64 v[64:65], v[64:65], 0, s[20:21]
	s_lshl_b32 s20, s50, 2
	v_lshl_add_u64 v[64:65], v[64:65], 0, s[20:21]
	global_store_dword v[64:65], v66, off
; __device__ __forceinline__ unsigned cvt_pk_bf16(float lo, float hi) { unsigned r; asm volatile("v_cvt_pk_bf16_f32 %0, %1, %2" : "=v"(r) : "v"(lo), "v"(hi)); return r; }
;     __device__ __forceinline__ void operator()(const f32x4 (&acc)[2][2][4][2], const Unit& u, int wr, int wc, int fr, int fq) const {
;     ...
;         for (int ai = 0; ai < 2; ++ai)
; #pragma unroll
;             for (int m = 0; m < 4; ++m) { const int row = row0 + ai * HALF + m * 16; const size_t off = (size_t)row * D + col0;
;                 float ssq = 0.f;
; #pragma unroll
;                 for (int bj = 0; bj < 2; ++bj)
; #pragma unroll
;                     for (int n = 0; n < 2; ++n) { const f32x4 bs = *(const f32x4*)(base + off + bj * HALF + n * 16);
;                         const f32x4 o = bs + gv[bj][n] * acc[ai][bj][m][n];
;                         *(f32x4*)(out + off + bj * HALF + n * 16) = o;
;                         if (FOLD) { ssq += (o.x * o.x + o.y * o.y) + (o.z * o.z + o.w * o.w); const f32x4 q = o * sv[bj][n];
;                             u32x2 w; w.x = cvt_pk_bf16(q.x, q.y); w.y = cvt_pk_bf16(q.z, q.w); *(u32x2*)(U2 + off + bj * HALF + n * 16) = w; } }
;                 if (FOLD) { ssq += __shfl_xor(ssq, 16); ssq += __shfl_xor(ssq, 32);
;                     if (fq == 0) part[(size_t)row * 16 + (u.pn & 3) * 4 + wc] = ssq; } }
.LBB0_1280:
	s_or_b64 exec, exec, s[34:35]
	v_add_u32_e32 v64, 0x80, v150
	s_waitcnt lgkmcnt(0)
	v_ashrrev_i32_e32 v65, 31, v64
	v_lshlrev_b64 v[66:67], 10, v[64:65]
	v_readlane_b32 s72, v248, 0
	v_lshl_add_u64 v[70:71], v[66:67], 0, v[144:145]
	v_readlane_b32 s78, v248, 6
	v_readlane_b32 s79, v248, 7
	v_readlane_b32 s34, v249, 43
	v_readlane_b32 s35, v249, 44
	v_lshl_add_u64 v[72:73], v[70:71], 2, s[78:79]
	global_load_dwordx4 v[236:239], v[72:73], off
	global_load_dwordx4 v[240:243], v[72:73], off offset:64
	global_load_dwordx4 v[244:247], v[72:73], off offset:512
	global_load_dwordx4 v[66:69], v[72:73], off offset:576
	v_lshl_add_u64 v[70:71], v[70:71], 1, s[34:35]
	v_readlane_b32 s73, v248, 1
	v_readlane_b32 s74, v248, 2
	v_readlane_b32 s75, v248, 3
	v_readlane_b32 s76, v248, 4
	v_readlane_b32 s77, v248, 5
	s_waitcnt vmcnt(3)
	v_pk_fma_f32 v[60:61], v[60:61], v[162:163], v[236:237]
	v_pk_fma_f32 v[62:63], v[62:63], v[160:161], v[238:239]
	v_pk_mul_f32 v[238:239], v[166:167], v[60:61]
	global_store_dwordx4 v[72:73], v[60:63], off sc1
	v_pk_mul_f32 v[236:237], v[164:165], v[62:63]
	v_cvt_pk_bf16_f32 v238, v238, v239
	s_nop 0
	v_cvt_pk_bf16_f32 v239, v236, v237
	global_store_dwordx2 v[70:71], v[238:239], off
	v_mul_f32_e32 v61, v61, v61
	v_mul_f32_e32 v63, v63, v63
	v_fmac_f32_e32 v61, v60, v60
	v_fmac_f32_e32 v63, v62, v62
	v_add_f32_e32 v60, v61, v63
	s_waitcnt vmcnt(4)
	v_pk_fma_f32 v[56:57], v[56:57], v[154:155], v[240:241]
	v_pk_fma_f32 v[58:59], v[58:59], v[158:159], v[242:243]
	v_pk_mul_f32 v[242:243], v[148:149], v[56:57]
	global_store_dwordx4 v[72:73], v[56:59], off offset:64 sc1
	v_pk_mul_f32 v[240:241], v[126:127], v[58:59]
	v_cvt_pk_bf16_f32 v242, v242, v243
	s_nop 0
	v_cvt_pk_bf16_f32 v243, v240, v241
	global_store_dwordx2 v[70:71], v[242:243], off offset:32
	v_mul_f32_e32 v57, v57, v57
	v_mul_f32_e32 v59, v59, v59
	v_fmac_f32_e32 v57, v56, v56
	v_fmac_f32_e32 v59, v58, v58
	v_add_f32_e32 v56, v57, v59
	v_add_f32_e32 v56, v60, v56
	s_waitcnt vmcnt(5)
	v_pk_fma_f32 v[52:53], v[52:53], v[152:153], v[244:245]
	v_pk_fma_f32 v[54:55], v[54:55], v[156:157], v[246:247]
	v_pk_mul_f32 v[246:247], v[146:147], v[52:53]
	global_store_dwordx4 v[72:73], v[52:55], off offset:512 sc1
	v_pk_mul_f32 v[244:245], v[124:125], v[54:55]
	v_cvt_pk_bf16_f32 v246, v246, v247
	s_nop 0
	v_cvt_pk_bf16_f32 v247, v244, v245
	global_store_dwordx2 v[70:71], v[246:247], off offset:256
	v_mul_f32_e32 v53, v53, v53
	v_mul_f32_e32 v55, v55, v55
	v_fmac_f32_e32 v53, v52, v52
	v_fmac_f32_e32 v55, v54, v54
	v_add_f32_e32 v52, v53, v55
	v_add_f32_e32 v54, v56, v52
	s_waitcnt vmcnt(6)
	v_pk_fma_f32 v[52:53], v[50:51], v[122:123], v[68:69]
	v_pk_fma_f32 v[50:51], v[48:49], v[120:121], v[66:67]
	v_mul_f32_e32 v49, v53, v53
	v_mul_f32_e32 v48, v51, v51
	v_fmac_f32_e32 v48, v50, v50
	v_fmac_f32_e32 v49, v52, v52
	v_add_f32_e32 v48, v48, v49
	v_add_f32_e32 v48, v54, v48
	ds_bpermute_b32 v49, v207, v48
	global_store_dwordx4 v[72:73], v[50:53], off offset:576 sc1
	s_waitcnt lgkmcnt(0)
	v_add_f32_e32 v48, v48, v49
	ds_bpermute_b32 v49, v208, v48
	v_pk_mul_f32 v[50:51], v[116:117], v[50:51]
	v_pk_mul_f32 v[52:53], v[118:119], v[52:53]
	v_cvt_pk_bf16_f32 v50, v50, v51
	s_nop 0
	v_cvt_pk_bf16_f32 v51, v52, v53
	global_store_dwordx2 v[70:71], v[50:51], off offset:288
	s_and_saveexec_b64 s[34:35], s[0:1]
	s_cbranch_execz .LBB0_1282
	v_readlane_b32 s40, v249, 31
	s_waitcnt lgkmcnt(0)
	v_add_f32_e32 v50, v48, v49
	v_lshlrev_b64 v[48:49], 6, v[64:65]
	v_readlane_b32 s41, v249, 32
	s_lshl_b32 s20, s36, 2
	s_nop 0
	v_lshl_add_u64 v[48:49], s[40:41], 0, v[48:49]
	v_lshl_add_u64 v[48:49], v[48:49], 0, s[20:21]
	s_lshl_b32 s20, s50, 2
	v_lshl_add_u64 v[48:49], v[48:49], 0, s[20:21]
	global_store_dword v[48:49], v50, off
.LBB0_1282:
	s_or_b64 exec, exec, s[34:35]
	v_add_u32_e32 v48, 0x90, v150
	s_waitcnt lgkmcnt(0)
	v_ashrrev_i32_e32 v49, 31, v48
	v_lshlrev_b64 v[50:51], 10, v[48:49]
	v_readlane_b32 s72, v248, 0
	v_lshl_add_u64 v[54:55], v[50:51], 0, v[144:145]
	v_readlane_b32 s78, v248, 6
	v_readlane_b32 s79, v248, 7
	v_readlane_b32 s34, v249, 43
	v_readlane_b32 s35, v249, 44
	v_lshl_add_u64 v[56:57], v[54:55], 2, s[78:79]
	global_load_dwordx4 v[236:239], v[56:57], off
	global_load_dwordx4 v[240:243], v[56:57], off offset:64
	global_load_dwordx4 v[244:247], v[56:57], off offset:512
	global_load_dwordx4 v[50:53], v[56:57], off offset:576
	v_lshl_add_u64 v[54:55], v[54:55], 1, s[34:35]
	v_readlane_b32 s73, v248, 1
	v_readlane_b32 s74, v248, 2
	v_readlane_b32 s75, v248, 3
	v_readlane_b32 s76, v248, 4
	v_readlane_b32 s77, v248, 5
	s_waitcnt vmcnt(3)
	v_pk_fma_f32 v[44:45], v[44:45], v[162:163], v[236:237]
	v_pk_fma_f32 v[46:47], v[46:47], v[160:161], v[238:239]
	v_pk_mul_f32 v[238:239], v[166:167], v[44:45]
	global_store_dwordx4 v[56:57], v[44:47], off sc1
	v_pk_mul_f32 v[236:237], v[164:165], v[46:47]
	v_cvt_pk_bf16_f32 v238, v238, v239
	s_nop 0
	v_cvt_pk_bf16_f32 v239, v236, v237
	global_store_dwordx2 v[54:55], v[238:239], off
	v_mul_f32_e32 v45, v45, v45
	v_mul_f32_e32 v47, v47, v47
	v_fmac_f32_e32 v45, v44, v44
	v_fmac_f32_e32 v47, v46, v46
	v_add_f32_e32 v44, v45, v47
	s_waitcnt vmcnt(4)
	v_pk_fma_f32 v[40:41], v[40:41], v[154:155], v[240:241]
	v_pk_fma_f32 v[42:43], v[42:43], v[158:159], v[242:243]
	v_pk_mul_f32 v[242:243], v[148:149], v[40:41]
	global_store_dwordx4 v[56:57], v[40:43], off offset:64 sc1
	v_pk_mul_f32 v[240:241], v[126:127], v[42:43]
	v_cvt_pk_bf16_f32 v242, v242, v243
	s_nop 0
	v_cvt_pk_bf16_f32 v243, v240, v241
	global_store_dwordx2 v[54:55], v[242:243], off offset:32
	v_mul_f32_e32 v41, v41, v41
	v_mul_f32_e32 v43, v43, v43
	v_fmac_f32_e32 v41, v40, v40
	v_fmac_f32_e32 v43, v42, v42
	v_add_f32_e32 v40, v41, v43
	v_add_f32_e32 v40, v44, v40
	s_waitcnt vmcnt(5)
; __device__ __forceinline__ unsigned cvt_pk_bf16(float lo, float hi) { unsigned r; asm volatile("v_cvt_pk_bf16_f32 %0, %1, %2" : "=v"(r) : "v"(lo), "v"(hi)); return r; }
;     __device__ __forceinline__ void operator()(const f32x4 (&acc)[2][2][4][2], const Unit& u, int wr, int wc, int fr, int fq) const {
;     ...
;         for (int ai = 0; ai < 2; ++ai)
; #pragma unroll
;             for (int m = 0; m < 4; ++m) { const int row = row0 + ai * HALF + m * 16; const size_t off = (size_t)row * D + col0;
;                 float ssq = 0.f;
; #pragma unroll
;                 for (int bj = 0; bj < 2; ++bj)
; #pragma unroll
;                     for (int n = 0; n < 2; ++n) { const f32x4 bs = *(const f32x4*)(base + off + bj * HALF + n * 16);
;                         const f32x4 o = bs + gv[bj][n] * acc[ai][bj][m][n];
;                         *(f32x4*)(out + off + bj * HALF + n * 16) = o;
;                         if (FOLD) { ssq += (o.x * o.x + o.y * o.y) + (o.z * o.z + o.w * o.w); const f32x4 q = o * sv[bj][n];
;                             u32x2 w; w.x = cvt_pk_bf16(q.x, q.y); w.y = cvt_pk_bf16(q.z, q.w); *(u32x2*)(U2 + off + bj * HALF + n * 16) = w; } }
;                 if (FOLD) { ssq += __shfl_xor(ssq, 16); ssq += __shfl_xor(ssq, 32);
;                     if (fq == 0) part[(size_t)row * 16 + (u.pn & 3) * 4 + wc] = ssq; } }
	v_pk_fma_f32 v[36:37], v[36:37], v[152:153], v[244:245]
	v_pk_fma_f32 v[38:39], v[38:39], v[156:157], v[246:247]
	v_pk_mul_f32 v[246:247], v[146:147], v[36:37]
	global_store_dwordx4 v[56:57], v[36:39], off offset:512 sc1
	v_pk_mul_f32 v[244:245], v[124:125], v[38:39]
	v_cvt_pk_bf16_f32 v246, v246, v247
	s_nop 0
	v_cvt_pk_bf16_f32 v247, v244, v245
	global_store_dwordx2 v[54:55], v[246:247], off offset:256
	v_mul_f32_e32 v37, v37, v37
	v_mul_f32_e32 v39, v39, v39
	v_fmac_f32_e32 v37, v36, v36
	v_fmac_f32_e32 v39, v38, v38
	v_add_f32_e32 v36, v37, v39
	v_add_f32_e32 v38, v40, v36
	s_waitcnt vmcnt(6)
	v_pk_fma_f32 v[36:37], v[34:35], v[122:123], v[52:53]
	v_pk_fma_f32 v[34:35], v[32:33], v[120:121], v[50:51]
	v_mul_f32_e32 v33, v37, v37
	v_mul_f32_e32 v32, v35, v35
	v_fmac_f32_e32 v32, v34, v34
	v_fmac_f32_e32 v33, v36, v36
	v_add_f32_e32 v32, v32, v33
	v_add_f32_e32 v32, v38, v32
	ds_bpermute_b32 v33, v207, v32
	global_store_dwordx4 v[56:57], v[34:37], off offset:576 sc1
	s_waitcnt lgkmcnt(0)
	v_add_f32_e32 v32, v32, v33
	ds_bpermute_b32 v33, v208, v32
	v_pk_mul_f32 v[34:35], v[116:117], v[34:35]
	v_pk_mul_f32 v[36:37], v[118:119], v[36:37]
	v_cvt_pk_bf16_f32 v34, v34, v35
	s_nop 0
	v_cvt_pk_bf16_f32 v35, v36, v37
	global_store_dwordx2 v[54:55], v[34:35], off offset:288
	s_and_saveexec_b64 s[34:35], s[0:1]
	s_cbranch_execz .LBB0_1284
	v_readlane_b32 s40, v249, 31
	s_waitcnt lgkmcnt(0)
	v_add_f32_e32 v34, v32, v33
	v_lshlrev_b64 v[32:33], 6, v[48:49]
	v_readlane_b32 s41, v249, 32
	s_lshl_b32 s20, s36, 2
	s_nop 0
	v_lshl_add_u64 v[32:33], s[40:41], 0, v[32:33]
	v_lshl_add_u64 v[32:33], v[32:33], 0, s[20:21]
	s_lshl_b32 s20, s50, 2
	v_lshl_add_u64 v[32:33], v[32:33], 0, s[20:21]
	global_store_dword v[32:33], v34, off
.LBB0_1284:
	s_or_b64 exec, exec, s[34:35]
	v_add_u32_e32 v32, 0xa0, v150
	s_waitcnt lgkmcnt(0)
	v_ashrrev_i32_e32 v33, 31, v32
	v_lshlrev_b64 v[34:35], 10, v[32:33]
	v_readlane_b32 s72, v248, 0
	v_lshl_add_u64 v[38:39], v[34:35], 0, v[144:145]
	v_readlane_b32 s78, v248, 6
	v_readlane_b32 s79, v248, 7
	v_readlane_b32 s34, v249, 43
	v_readlane_b32 s35, v249, 44
	v_lshl_add_u64 v[40:41], v[38:39], 2, s[78:79]
	global_load_dwordx4 v[236:239], v[40:41], off
	global_load_dwordx4 v[240:243], v[40:41], off offset:64
	global_load_dwordx4 v[244:247], v[40:41], off offset:512
	global_load_dwordx4 v[34:37], v[40:41], off offset:576
	v_lshl_add_u64 v[38:39], v[38:39], 1, s[34:35]
	v_readlane_b32 s73, v248, 1
	v_readlane_b32 s74, v248, 2
	v_readlane_b32 s75, v248, 3
	v_readlane_b32 s76, v248, 4
	v_readlane_b32 s77, v248, 5
	s_waitcnt vmcnt(3)
	v_pk_fma_f32 v[28:29], v[28:29], v[162:163], v[236:237]
	v_pk_fma_f32 v[30:31], v[30:31], v[160:161], v[238:239]
	v_pk_mul_f32 v[238:239], v[166:167], v[28:29]
	global_store_dwordx4 v[40:41], v[28:31], off sc1
	v_pk_mul_f32 v[236:237], v[164:165], v[30:31]
	v_cvt_pk_bf16_f32 v238, v238, v239
	s_nop 0
	v_cvt_pk_bf16_f32 v239, v236, v237
	global_store_dwordx2 v[38:39], v[238:239], off
	v_mul_f32_e32 v29, v29, v29
	v_mul_f32_e32 v31, v31, v31
	v_fmac_f32_e32 v29, v28, v28
	v_fmac_f32_e32 v31, v30, v30
	v_add_f32_e32 v28, v29, v31
	s_waitcnt vmcnt(4)
	v_pk_fma_f32 v[24:25], v[24:25], v[154:155], v[240:241]
	v_pk_fma_f32 v[26:27], v[26:27], v[158:159], v[242:243]
	v_pk_mul_f32 v[242:243], v[148:149], v[24:25]
	global_store_dwordx4 v[40:41], v[24:27], off offset:64 sc1
	v_pk_mul_f32 v[240:241], v[126:127], v[26:27]
	v_cvt_pk_bf16_f32 v242, v242, v243
	s_nop 0
	v_cvt_pk_bf16_f32 v243, v240, v241
	global_store_dwordx2 v[38:39], v[242:243], off offset:32
	v_mul_f32_e32 v25, v25, v25
	v_mul_f32_e32 v27, v27, v27
	v_fmac_f32_e32 v25, v24, v24
	v_fmac_f32_e32 v27, v26, v26
	v_add_f32_e32 v24, v25, v27
	v_add_f32_e32 v24, v28, v24
	s_waitcnt vmcnt(5)
	v_pk_fma_f32 v[20:21], v[20:21], v[152:153], v[244:245]
	v_pk_fma_f32 v[22:23], v[22:23], v[156:157], v[246:247]
	v_pk_mul_f32 v[246:247], v[146:147], v[20:21]
	global_store_dwordx4 v[40:41], v[20:23], off offset:512 sc1
	v_pk_mul_f32 v[244:245], v[124:125], v[22:23]
	v_cvt_pk_bf16_f32 v246, v246, v247
	s_nop 0
	v_cvt_pk_bf16_f32 v247, v244, v245
	global_store_dwordx2 v[38:39], v[246:247], off offset:256
	v_mul_f32_e32 v21, v21, v21
	v_mul_f32_e32 v23, v23, v23
	v_fmac_f32_e32 v21, v20, v20
	v_fmac_f32_e32 v23, v22, v22
	v_add_f32_e32 v20, v21, v23
	v_add_f32_e32 v22, v24, v20
	s_waitcnt vmcnt(6)
	v_pk_fma_f32 v[20:21], v[18:19], v[122:123], v[36:37]
	v_pk_fma_f32 v[18:19], v[16:17], v[120:121], v[34:35]
	v_mul_f32_e32 v17, v21, v21
	v_mul_f32_e32 v16, v19, v19
	v_fmac_f32_e32 v16, v18, v18
	v_fmac_f32_e32 v17, v20, v20
	v_add_f32_e32 v16, v16, v17
	v_add_f32_e32 v16, v22, v16
	ds_bpermute_b32 v17, v207, v16
	global_store_dwordx4 v[40:41], v[18:21], off offset:576 sc1
	s_waitcnt lgkmcnt(0)
	v_add_f32_e32 v16, v16, v17
	ds_bpermute_b32 v17, v208, v16
	v_pk_mul_f32 v[18:19], v[116:117], v[18:19]
	v_pk_mul_f32 v[20:21], v[118:119], v[20:21]
	v_cvt_pk_bf16_f32 v18, v18, v19
	s_nop 0
	v_cvt_pk_bf16_f32 v19, v20, v21
	global_store_dwordx2 v[38:39], v[18:19], off offset:288
	s_and_saveexec_b64 s[34:35], s[0:1]
	s_cbranch_execz .LBB0_1286
	v_readlane_b32 s40, v249, 31
	s_waitcnt lgkmcnt(0)
	v_add_f32_e32 v18, v16, v17
	v_lshlrev_b64 v[16:17], 6, v[32:33]
	v_readlane_b32 s41, v249, 32
	s_lshl_b32 s20, s36, 2
	s_nop 0
	v_lshl_add_u64 v[16:17], s[40:41], 0, v[16:17]
	v_lshl_add_u64 v[16:17], v[16:17], 0, s[20:21]
	s_lshl_b32 s20, s50, 2
	v_lshl_add_u64 v[16:17], v[16:17], 0, s[20:21]
	global_store_dword v[16:17], v18, off
; __device__ __forceinline__ unsigned cvt_pk_bf16(float lo, float hi) { unsigned r; asm volatile("v_cvt_pk_bf16_f32 %0, %1, %2" : "=v"(r) : "v"(lo), "v"(hi)); return r; }
;     __device__ __forceinline__ void operator()(const f32x4 (&acc)[2][2][4][2], const Unit& u, int wr, int wc, int fr, int fq) const {
;     ...
;         for (int ai = 0; ai < 2; ++ai)
; #pragma unroll
;             for (int m = 0; m < 4; ++m) { const int row = row0 + ai * HALF + m * 16; const size_t off = (size_t)row * D + col0;
;                 float ssq = 0.f;
; #pragma unroll
;                 for (int bj = 0; bj < 2; ++bj)
; #pragma unroll
;                     for (int n = 0; n < 2; ++n) { const f32x4 bs = *(const f32x4*)(base + off + bj * HALF + n * 16);
;                         const f32x4 o = bs + gv[bj][n] * acc[ai][bj][m][n];
;                         *(f32x4*)(out + off + bj * HALF + n * 16) = o;
;                         if (FOLD) { ssq += (o.x * o.x + o.y * o.y) + (o.z * o.z + o.w * o.w); const f32x4 q = o * sv[bj][n];
;                             u32x2 w; w.x = cvt_pk_bf16(q.x, q.y); w.y = cvt_pk_bf16(q.z, q.w); *(u32x2*)(U2 + off + bj * HALF + n * 16) = w; } }
;                 if (FOLD) { ssq += __shfl_xor(ssq, 16); ssq += __shfl_xor(ssq, 32);
;                     if (fq == 0) part[(size_t)row * 16 + (u.pn & 3) * 4 + wc] = ssq; } }
.LBB0_1286:
	s_or_b64 exec, exec, s[34:35]
	v_add_u32_e32 v16, 0xb0, v150
	s_waitcnt lgkmcnt(0)
	v_ashrrev_i32_e32 v17, 31, v16
	v_lshlrev_b64 v[18:19], 10, v[16:17]
	v_readlane_b32 s72, v248, 0
	v_lshl_add_u64 v[22:23], v[18:19], 0, v[144:145]
	v_readlane_b32 s78, v248, 6
	v_readlane_b32 s79, v248, 7
	v_readlane_b32 s34, v249, 43
	v_readlane_b32 s35, v249, 44
	v_lshl_add_u64 v[24:25], v[22:23], 2, s[78:79]
	global_load_dwordx4 v[236:239], v[24:25], off
	global_load_dwordx4 v[240:243], v[24:25], off offset:64
	global_load_dwordx4 v[244:247], v[24:25], off offset:512
	global_load_dwordx4 v[18:21], v[24:25], off offset:576
	v_lshl_add_u64 v[22:23], v[22:23], 1, s[34:35]
	v_readlane_b32 s73, v248, 1
	v_readlane_b32 s74, v248, 2
	v_readlane_b32 s75, v248, 3
	v_readlane_b32 s76, v248, 4
	v_readlane_b32 s77, v248, 5
	s_waitcnt vmcnt(3)
	v_pk_fma_f32 v[12:13], v[12:13], v[162:163], v[236:237]
	v_pk_fma_f32 v[14:15], v[14:15], v[160:161], v[238:239]
	v_pk_mul_f32 v[238:239], v[166:167], v[12:13]
	global_store_dwordx4 v[24:25], v[12:15], off sc1
	v_pk_mul_f32 v[236:237], v[164:165], v[14:15]
	v_cvt_pk_bf16_f32 v238, v238, v239
	s_nop 0
	v_cvt_pk_bf16_f32 v239, v236, v237
	global_store_dwordx2 v[22:23], v[238:239], off
	v_mul_f32_e32 v13, v13, v13
	v_mul_f32_e32 v15, v15, v15
	v_fmac_f32_e32 v13, v12, v12
	v_fmac_f32_e32 v15, v14, v14
	v_add_f32_e32 v12, v13, v15
	s_waitcnt vmcnt(4)
	v_pk_fma_f32 v[8:9], v[8:9], v[154:155], v[240:241]
	v_pk_fma_f32 v[10:11], v[10:11], v[158:159], v[242:243]
	v_pk_mul_f32 v[242:243], v[148:149], v[8:9]
	global_store_dwordx4 v[24:25], v[8:11], off offset:64 sc1
	v_pk_mul_f32 v[240:241], v[126:127], v[10:11]
	v_cvt_pk_bf16_f32 v242, v242, v243
	s_nop 0
	v_cvt_pk_bf16_f32 v243, v240, v241
	global_store_dwordx2 v[22:23], v[242:243], off offset:32
	v_mul_f32_e32 v9, v9, v9
	v_mul_f32_e32 v11, v11, v11
	v_fmac_f32_e32 v9, v8, v8
	v_fmac_f32_e32 v11, v10, v10
	v_add_f32_e32 v8, v9, v11
	v_add_f32_e32 v8, v12, v8
	s_waitcnt vmcnt(5)
	v_pk_fma_f32 v[4:5], v[4:5], v[152:153], v[244:245]
	v_pk_fma_f32 v[6:7], v[6:7], v[156:157], v[246:247]
	v_pk_mul_f32 v[246:247], v[146:147], v[4:5]
	global_store_dwordx4 v[24:25], v[4:7], off offset:512 sc1
	v_pk_mul_f32 v[244:245], v[124:125], v[6:7]
	v_cvt_pk_bf16_f32 v246, v246, v247
	s_nop 0
	v_cvt_pk_bf16_f32 v247, v244, v245
	global_store_dwordx2 v[22:23], v[246:247], off offset:256
	v_mul_f32_e32 v5, v5, v5
	v_mul_f32_e32 v7, v7, v7
	v_fmac_f32_e32 v5, v4, v4
	v_fmac_f32_e32 v7, v6, v6
	v_add_f32_e32 v4, v5, v7
	v_add_f32_e32 v6, v8, v4
	s_waitcnt vmcnt(6)
	v_pk_fma_f32 v[4:5], v[2:3], v[122:123], v[20:21]
	v_pk_fma_f32 v[2:3], v[0:1], v[120:121], v[18:19]
	v_mul_f32_e32 v1, v5, v5
	v_mul_f32_e32 v0, v3, v3
	v_fmac_f32_e32 v0, v2, v2
	v_fmac_f32_e32 v1, v4, v4
	v_add_f32_e32 v0, v0, v1
	v_add_f32_e32 v0, v6, v0
	ds_bpermute_b32 v1, v207, v0
	global_store_dwordx4 v[24:25], v[2:5], off offset:576 sc1
	s_waitcnt lgkmcnt(0)
	v_add_f32_e32 v0, v0, v1
	ds_bpermute_b32 v1, v208, v0
	v_pk_mul_f32 v[2:3], v[116:117], v[2:3]
	v_pk_mul_f32 v[4:5], v[118:119], v[4:5]
	v_cvt_pk_bf16_f32 v2, v2, v3
	s_nop 0
	v_cvt_pk_bf16_f32 v3, v4, v5
	global_store_dwordx2 v[22:23], v[2:3], off offset:288
	s_and_saveexec_b64 s[34:35], s[0:1]
	s_cbranch_execz .LBB0_1288
	v_readlane_b32 s40, v249, 31
	s_waitcnt lgkmcnt(0)
	v_add_f32_e32 v2, v0, v1
	v_lshlrev_b64 v[0:1], 6, v[16:17]
	v_readlane_b32 s41, v249, 32
	s_lshl_b32 s20, s36, 2
	s_nop 0
	v_lshl_add_u64 v[0:1], s[40:41], 0, v[0:1]
	v_lshl_add_u64 v[0:1], v[0:1], 0, s[20:21]
	s_lshl_b32 s20, s50, 2
	v_lshl_add_u64 v[0:1], v[0:1], 0, s[20:21]
	global_store_dword v[0:1], v2, off

;     __device__ __forceinline__ void operator()(const f32x4 (&acc)[2][2][4][2], const Unit& u, int wr, int wc, int fr, int fq) const {
;     ...
;         const float* gp = gate + (size_t)(u.pm >> 4) * NMOD;
;         f32x4 gv[2][2], sv[2][2];
; #pragma unroll
;         for (int bj = 0; bj < 2; ++bj)
; #pragma unroll
;             for (int n = 0; n < 2; ++n) { gv[bj][n] = *(const f32x4*)(gp + col0 + bj * HALF + n * 16) * (HALFSC ? 0.5f : 1.0f);
;                 if (FOLD) sv[bj][n] = *(const f32x4*)(scn + (size_t)(u.pm >> 4) * NMOD + col0 + bj * HALF + n * 16) + 1.0f; }
; #pragma unroll
;         for (int ai = 0; ai < 2; ++ai)
; #pragma unroll
;             for (int m = 0; m < 4; ++m) { const int row = row0 + ai * HALF + m * 16; const size_t off = (size_t)row * D + col0;
;                 float ssq = 0.f;
; #pragma unroll
;                 for (int bj = 0; bj < 2; ++bj)
; #pragma unroll
;                     for (int n = 0; n < 2; ++n) { const f32x4 bs = *(const f32x4*)(base + off + bj * HALF + n * 16);
;                         const f32x4 o = bs + gv[bj][n] * acc[ai][bj][m][n];
;                         *(f32x4*)(out + off + bj * HALF + n * 16) = o;
.LBB0_1440:
	s_ashr_i32 s28, s55, 4
	v_lshl_or_b32 v144, s56, 8, v166
	s_mul_hi_i32 s29, s28, 0x9000
	s_mul_i32 s28, s28, 0x9000
	s_add_u32 s28, s43, s28
	v_ashrrev_i32_e32 v145, 31, v144
	s_addc_u32 s29, s44, s29
	v_lshlrev_b64 v[162:163], 2, v[144:145]
	v_lshl_add_u64 v[160:161], s[28:29], 0, v[162:163]
	global_load_dwordx4 v[176:179], v[160:161], off
	global_load_dwordx4 v[180:183], v[160:161], off offset:64
	global_load_dwordx4 v[184:187], v[160:161], off offset:512
	global_load_dwordx4 v[144:147], v[160:161], off offset:576
	v_lshl_add_u32 v174, s55, 8, v164
	v_ashrrev_i32_e32 v175, 31, v174
	v_readlane_b32 s56, v248, 0
	v_readlane_b32 s62, v248, 6
	v_readlane_b32 s63, v248, 7
	s_mov_b64 s[28:29], 0x80000
	v_readlane_b32 s57, v248, 1
	v_readlane_b32 s58, v248, 2
	v_readlane_b32 s59, v248, 3
	v_readlane_b32 s60, v248, 4
	v_readlane_b32 s61, v248, 5
	s_waitcnt vmcnt(3)
	v_pk_mul_f32 v[156:157], v[178:179], 0.5 op_sel_hi:[1,0]
	v_pk_mul_f32 v[158:159], v[176:177], 0.5 op_sel_hi:[1,0]
	s_waitcnt vmcnt(2)
	v_pk_mul_f32 v[152:153], v[182:183], 0.5 op_sel_hi:[1,0]
	v_pk_mul_f32 v[154:155], v[180:181], 0.5 op_sel_hi:[1,0]
	s_waitcnt vmcnt(1)
	v_pk_mul_f32 v[148:149], v[186:187], 0.5 op_sel_hi:[1,0]
	v_pk_mul_f32 v[150:151], v[184:185], 0.5 op_sel_hi:[1,0]
	v_lshlrev_b64 v[160:161], 12, v[174:175]
	v_lshl_add_u64 v[160:161], s[62:63], 0, v[160:161]
	v_lshl_add_u64 v[160:161], v[160:161], 0, v[162:163]
	global_load_dwordx4 v[216:219], v[160:161], off
	global_load_dwordx4 v[220:223], v[160:161], off offset:64
	global_load_dwordx4 v[236:239], v[160:161], off offset:512
	global_load_dwordx4 v[240:243], v[160:161], off offset:576
	s_waitcnt vmcnt(3)
	v_pk_mul_f32 v[146:147], v[146:147], 0.5 op_sel_hi:[1,0]
	v_pk_mul_f32 v[144:145], v[144:145], 0.5 op_sel_hi:[1,0]
	v_pk_fma_f32 v[126:127], v[126:127], v[156:157], v[218:219]
	v_pk_fma_f32 v[124:125], v[124:125], v[158:159], v[216:217]
	global_store_dwordx4 v[160:161], v[124:127], off sc1
	s_waitcnt vmcnt(3)
	v_pk_fma_f32 v[122:123], v[122:123], v[152:153], v[222:223]
	v_pk_fma_f32 v[120:121], v[120:121], v[154:155], v[220:221]
	global_store_dwordx4 v[160:161], v[120:123], off offset:64 sc1
	s_waitcnt vmcnt(3)
	v_pk_fma_f32 v[118:119], v[118:119], v[148:149], v[238:239]
	v_pk_fma_f32 v[116:117], v[116:117], v[150:151], v[236:237]
	global_store_dwordx4 v[160:161], v[116:119], off offset:512 sc1
	s_waitcnt vmcnt(3)
	v_pk_fma_f32 v[114:115], v[114:115], v[146:147], v[242:243]
	v_pk_fma_f32 v[112:113], v[112:113], v[144:145], v[240:241]
	global_store_dwordx4 v[160:161], v[112:115], off offset:576 sc1
	s_nop 1
	v_or_b32_e32 v112, 16, v174
	v_ashrrev_i32_e32 v113, 31, v112
	v_lshlrev_b64 v[112:113], 12, v[112:113]
	v_lshl_add_u64 v[112:113], s[62:63], 0, v[112:113]
	v_lshl_add_u64 v[116:117], v[112:113], 0, v[162:163]
	global_load_dwordx4 v[216:219], v[116:117], off
	global_load_dwordx4 v[220:223], v[116:117], off offset:64
	global_load_dwordx4 v[236:239], v[116:117], off offset:512
	global_load_dwordx4 v[240:243], v[116:117], off offset:576
	s_waitcnt vmcnt(3)
	v_pk_fma_f32 v[110:111], v[110:111], v[156:157], v[218:219]
	v_pk_fma_f32 v[108:109], v[108:109], v[158:159], v[216:217]
	global_store_dwordx4 v[116:117], v[108:111], off sc1
	s_waitcnt vmcnt(3)
	v_pk_fma_f32 v[106:107], v[106:107], v[152:153], v[222:223]
	v_pk_fma_f32 v[104:105], v[104:105], v[154:155], v[220:221]
	global_store_dwordx4 v[116:117], v[104:107], off offset:64 sc1
	s_waitcnt vmcnt(3)
	v_pk_fma_f32 v[102:103], v[102:103], v[148:149], v[238:239]
	v_pk_fma_f32 v[100:101], v[100:101], v[150:151], v[236:237]
	global_store_dwordx4 v[116:117], v[100:103], off offset:512 sc1
	s_waitcnt vmcnt(3)
	v_pk_fma_f32 v[98:99], v[98:99], v[146:147], v[242:243]
	v_pk_fma_f32 v[96:97], v[96:97], v[144:145], v[240:241]
	global_store_dwordx4 v[116:117], v[96:99], off offset:576 sc1
	s_nop 1
	v_or_b32_e32 v96, 32, v174
	v_ashrrev_i32_e32 v97, 31, v96
	v_lshlrev_b64 v[96:97], 12, v[96:97]
	v_lshl_add_u64 v[96:97], s[62:63], 0, v[96:97]
	v_lshl_add_u64 v[100:101], v[96:97], 0, v[162:163]
	global_load_dwordx4 v[216:219], v[100:101], off
	global_load_dwordx4 v[220:223], v[100:101], off offset:64
	global_load_dwordx4 v[236:239], v[100:101], off offset:512
	global_load_dwordx4 v[240:243], v[100:101], off offset:576
	s_waitcnt vmcnt(3)
	v_pk_fma_f32 v[94:95], v[94:95], v[156:157], v[218:219]
	v_pk_fma_f32 v[92:93], v[92:93], v[158:159], v[216:217]
	global_store_dwordx4 v[100:101], v[92:95], off sc1
	s_waitcnt vmcnt(3)
	v_pk_fma_f32 v[90:91], v[90:91], v[152:153], v[222:223]
	v_pk_fma_f32 v[88:89], v[88:89], v[154:155], v[220:221]
	global_store_dwordx4 v[100:101], v[88:91], off offset:64 sc1
	s_waitcnt vmcnt(3)
	v_pk_fma_f32 v[86:87], v[86:87], v[148:149], v[238:239]
	v_pk_fma_f32 v[84:85], v[84:85], v[150:151], v[236:237]
	global_store_dwordx4 v[100:101], v[84:87], off offset:512 sc1
	s_waitcnt vmcnt(3)
	v_pk_fma_f32 v[82:83], v[82:83], v[146:147], v[242:243]
	v_pk_fma_f32 v[80:81], v[80:81], v[144:145], v[240:241]
	global_store_dwordx4 v[100:101], v[80:83], off offset:576 sc1
	s_nop 1
	v_or_b32_e32 v80, 48, v174
	v_ashrrev_i32_e32 v81, 31, v80
	v_lshlrev_b64 v[80:81], 12, v[80:81]
	v_lshl_add_u64 v[80:81], s[62:63], 0, v[80:81]
	v_lshl_add_u64 v[84:85], v[80:81], 0, v[162:163]
	global_load_dwordx4 v[216:219], v[84:85], off
	global_load_dwordx4 v[220:223], v[84:85], off offset:64
	global_load_dwordx4 v[236:239], v[84:85], off offset:512
	global_load_dwordx4 v[240:243], v[84:85], off offset:576
	s_waitcnt vmcnt(3)
; #define PG8_BAR __builtin_amdgcn_s_barrier()
; template <class Epi, class Sched, bool ALIGN_EPI = false, bool SP2 = false>
; __device__ __forceinline__ void gemm_phase(PG8_LAS unsigned char* lds, const Gemm g, const Sched& S, const Epi& E) {
;     ...
;         if constexpr (ALIGN_EPI) { if (wr == 0) PG8_BAR; }
;         if constexpr (!Epi::AFTER_DRAIN) { E(acc, cur, wr, wc, fr, fq); S.done(cur); }
;         if (!has_next) break;
; #pragma unroll
;         for (int a = 0; a < 2; ++a)
; #pragma unroll
;             for (int b = 0; b < 2; ++b)
; #pragma unroll
;                 for (int m = 0; m < 4; ++m)
; #pragma unroll
;                     for (int n = 0; n < 2; ++n) acc[a][b][m][n] = (f32x4){0.f, 0.f, 0.f, 0.f};
;         cur = nxt; cA = nA; cB = nB; ++ui;
;         if constexpr (ALIGN_EPI) { if (wr == 1) PG8_BAR; }
;     __device__ __forceinline__ void operator()(const f32x4 (&acc)[2][2][4][2], const Unit& u, int wr, int wc, int fr, int fq) const {
;     ...
;         for (int ai = 0; ai < 2; ++ai)
; #pragma unroll
;             for (int m = 0; m < 4; ++m) { const int row = row0 + ai * HALF + m * 16; const size_t off = (size_t)row * D + col0;
;                 float ssq = 0.f;
; #pragma unroll
;                 for (int bj = 0; bj < 2; ++bj)
; #pragma unroll
;                     for (int n = 0; n < 2; ++n) { const f32x4 bs = *(const f32x4*)(base + off + bj * HALF + n * 16);
;                         const f32x4 o = bs + gv[bj][n] * acc[ai][bj][m][n];
;                         *(f32x4*)(out + off + bj * HALF + n * 16) = o;
	v_pk_fma_f32 v[78:79], v[78:79], v[156:157], v[218:219]
	v_pk_fma_f32 v[76:77], v[76:77], v[158:159], v[216:217]
	global_store_dwordx4 v[84:85], v[76:79], off sc1
	s_waitcnt vmcnt(3)
	v_pk_fma_f32 v[74:75], v[74:75], v[152:153], v[222:223]
	v_pk_fma_f32 v[72:73], v[72:73], v[154:155], v[220:221]
	global_store_dwordx4 v[84:85], v[72:75], off offset:64 sc1
	s_waitcnt vmcnt(3)
	v_pk_fma_f32 v[70:71], v[70:71], v[148:149], v[238:239]
	v_pk_fma_f32 v[68:69], v[68:69], v[150:151], v[236:237]
	global_store_dwordx4 v[84:85], v[68:71], off offset:512 sc1
	s_waitcnt vmcnt(3)
	v_pk_fma_f32 v[64:65], v[64:65], v[144:145], v[240:241]
	v_lshl_add_u64 v[68:69], v[160:161], 0, s[28:29]
	s_mov_b32 s28, 0x80000
	v_pk_fma_f32 v[66:67], v[66:67], v[146:147], v[242:243]
	v_add_co_u32_e32 v70, vcc, s28, v160
	global_store_dwordx4 v[84:85], v[64:67], off offset:576 sc1
	s_nop 0
	v_addc_co_u32_e32 v71, vcc, 0, v161, vcc
	global_load_dwordx4 v[216:219], v[70:71], off
	global_load_dwordx4 v[220:223], v[68:69], off offset:64
	global_load_dwordx4 v[236:239], v[68:69], off offset:512
	global_load_dwordx4 v[240:243], v[68:69], off offset:576
	s_mov_b64 s[28:29], 0x90000
	s_waitcnt vmcnt(3)
	v_pk_fma_f32 v[62:63], v[62:63], v[156:157], v[218:219]
	v_pk_fma_f32 v[60:61], v[60:61], v[158:159], v[216:217]
	global_store_dwordx4 v[70:71], v[60:63], off sc1
	s_waitcnt vmcnt(3)
	v_pk_fma_f32 v[58:59], v[58:59], v[152:153], v[222:223]
	v_pk_fma_f32 v[56:57], v[56:57], v[154:155], v[220:221]
	global_store_dwordx4 v[68:69], v[56:59], off offset:64 sc1
	s_waitcnt vmcnt(3)
	v_pk_fma_f32 v[54:55], v[54:55], v[148:149], v[238:239]
	v_pk_fma_f32 v[52:53], v[52:53], v[150:151], v[236:237]
	global_store_dwordx4 v[68:69], v[52:55], off offset:512 sc1
	s_waitcnt vmcnt(3)
	v_pk_fma_f32 v[50:51], v[50:51], v[146:147], v[242:243]
	v_pk_fma_f32 v[48:49], v[48:49], v[144:145], v[240:241]
	global_store_dwordx4 v[68:69], v[48:51], off offset:576 sc1
	s_nop 1
	v_lshl_add_u64 v[48:49], v[160:161], 0, s[28:29]
	s_mov_b32 s28, 0x90000
	v_add_co_u32_e32 v54, vcc, s28, v160
	s_mov_b64 s[28:29], 0xa0000
	s_nop 0
	v_addc_co_u32_e32 v55, vcc, 0, v161, vcc
	global_load_dwordx4 v[216:219], v[54:55], off
	global_load_dwordx4 v[220:223], v[48:49], off offset:64
	global_load_dwordx4 v[236:239], v[48:49], off offset:512
	global_load_dwordx4 v[240:243], v[48:49], off offset:576
	s_waitcnt vmcnt(3)
	v_pk_fma_f32 v[46:47], v[46:47], v[156:157], v[218:219]
	v_pk_fma_f32 v[44:45], v[44:45], v[158:159], v[216:217]
	global_store_dwordx4 v[54:55], v[44:47], off sc1
	s_waitcnt vmcnt(3)
	v_pk_fma_f32 v[42:43], v[42:43], v[152:153], v[222:223]
	v_pk_fma_f32 v[40:41], v[40:41], v[154:155], v[220:221]
	global_store_dwordx4 v[48:49], v[40:43], off offset:64 sc1
	s_waitcnt vmcnt(3)
	v_pk_fma_f32 v[38:39], v[38:39], v[148:149], v[238:239]
	v_pk_fma_f32 v[36:37], v[36:37], v[150:151], v[236:237]
	global_store_dwordx4 v[48:49], v[36:39], off offset:512 sc1
	s_waitcnt vmcnt(3)
	v_pk_fma_f32 v[32:33], v[32:33], v[144:145], v[240:241]
	v_lshl_add_u64 v[36:37], v[160:161], 0, s[28:29]
	s_mov_b32 s28, 0xa0000
	v_pk_fma_f32 v[34:35], v[34:35], v[146:147], v[242:243]
	v_add_co_u32_e32 v38, vcc, s28, v160
	global_store_dwordx4 v[48:49], v[32:35], off offset:576 sc1
	s_nop 0
	v_addc_co_u32_e32 v39, vcc, 0, v161, vcc
	global_load_dwordx4 v[216:219], v[38:39], off
	global_load_dwordx4 v[220:223], v[36:37], off offset:64
	global_load_dwordx4 v[236:239], v[36:37], off offset:512
	global_load_dwordx4 v[240:243], v[36:37], off offset:576
	s_mov_b64 s[28:29], 0xb0000
	s_waitcnt vmcnt(3)
	v_pk_fma_f32 v[30:31], v[30:31], v[156:157], v[218:219]
	v_pk_fma_f32 v[28:29], v[28:29], v[158:159], v[216:217]
	global_store_dwordx4 v[38:39], v[28:31], off sc1
	s_waitcnt vmcnt(3)
	v_pk_fma_f32 v[26:27], v[26:27], v[152:153], v[222:223]
	v_pk_fma_f32 v[24:25], v[24:25], v[154:155], v[220:221]
	global_store_dwordx4 v[36:37], v[24:27], off offset:64 sc1
	s_waitcnt vmcnt(3)
	v_pk_fma_f32 v[22:23], v[22:23], v[148:149], v[238:239]
	v_pk_fma_f32 v[20:21], v[20:21], v[150:151], v[236:237]
	global_store_dwordx4 v[36:37], v[20:23], off offset:512 sc1
	s_waitcnt vmcnt(3)
	v_pk_fma_f32 v[18:19], v[18:19], v[146:147], v[242:243]
	v_pk_fma_f32 v[16:17], v[16:17], v[144:145], v[240:241]
	global_store_dwordx4 v[36:37], v[16:19], off offset:576 sc1
	s_nop 1
	v_lshl_add_u64 v[16:17], v[160:161], 0, s[28:29]
	s_mov_b32 s28, 0xb0000
	v_add_co_u32_e32 v22, vcc, s28, v160
	s_mov_b64 s[28:29], -1
	s_nop 0
	v_addc_co_u32_e32 v23, vcc, 0, v161, vcc
	global_load_dwordx4 v[216:219], v[22:23], off
	global_load_dwordx4 v[220:223], v[16:17], off offset:64
	global_load_dwordx4 v[236:239], v[16:17], off offset:512
	global_load_dwordx4 v[240:243], v[16:17], off offset:576
	s_and_b64 vcc, exec, s[0:1]
	s_waitcnt vmcnt(3)
	v_pk_fma_f32 v[14:15], v[14:15], v[156:157], v[218:219]
	v_pk_fma_f32 v[12:13], v[12:13], v[158:159], v[216:217]
	global_store_dwordx4 v[22:23], v[12:15], off sc1
	s_waitcnt vmcnt(3)
	v_pk_fma_f32 v[10:11], v[10:11], v[152:153], v[222:223]
	v_pk_fma_f32 v[8:9], v[8:9], v[154:155], v[220:221]
	global_store_dwordx4 v[16:17], v[8:11], off offset:64 sc1
	s_waitcnt vmcnt(3)
	v_pk_fma_f32 v[6:7], v[6:7], v[148:149], v[238:239]
	v_pk_fma_f32 v[4:5], v[4:5], v[150:151], v[236:237]
	global_store_dwordx4 v[16:17], v[4:7], off offset:512 sc1
	s_waitcnt vmcnt(3)
	v_pk_fma_f32 v[2:3], v[2:3], v[146:147], v[242:243]
	v_pk_fma_f32 v[0:1], v[0:1], v[144:145], v[240:241]
	global_store_dwordx4 v[16:17], v[0:3], off offset:576 sc1
	s_cbranch_vccnz .LBB0_1424
	s_andn2_b64 vcc, exec, s[14:15]
	s_cbranch_vccnz .LBB0_1423
	s_barrier
	s_branch .LBB0_1423

; __device__ __forceinline__ unsigned cvt_pk_bf16(float lo, float hi) { unsigned r; asm volatile("v_cvt_pk_bf16_f32 %0, %1, %2" : "=v"(r) : "v"(lo), "v"(hi)); return r; }
; __device__ __forceinline__ float sigmoidf_(float x) { return __builtin_amdgcn_rcpf(1.f + __expf(-x)); }
;     __device__ __forceinline__ void operator()(const f32x4 (&acc)[2][2][4][2], const Unit& u, int wr, int wc, int fr, int fq) const {
;     ...
;             for (int ai = 0; ai < 2; ++ai)
; #pragma unroll
;                 for (int m = 0; m < 4; ++m) { bf16_t* rowp = O + (size_t)(row0 + ai * HALF + m * 16) * ldc + c;
;                     f32x4 v0, v1;
;                     if (MODE == 3) { const float rstd = rs[ai * 4 + m]; v0 = acc[ai][bj][m][0] * rstd + b0; v1 = acc[ai][bj][m][1] * rstd + b1; }
;                     else { v0 = acc[ai][bj][m][0] + b0; v1 = acc[ai][bj][m][1] + b1; }
;                     if (MODE == 1 || MODE == 2) {
; #pragma unroll
;                         for (int e = 0; e < 4; ++e) {
;                             if (kind == 1) { v0[e] = 2.f * sigmoidf_(2.f * v0[e]) - 1.f; v1[e] = 2.f * sigmoidf_(2.f * v1[e]) - 1.f; }
;                             else if (kind == 2) { v0[e] = sigmoidf_(v0[e]); v1[e] = sigmoidf_(v1[e]); }
;                             else if (kind == 3) { v0[e] = 0.60653066f * sigmoidf_(v0[e]); v1[e] = 0.60653066f * sigmoidf_(v1[e]); }
;                         }
;                     }
;                     u32x4 w; w.x = cvt_pk_bf16(v0[0], v0[1]); w.y = cvt_pk_bf16(v0[2], v0[3]); w.z = cvt_pk_bf16(v1[0], v1[1]); w.w = cvt_pk_bf16(v1[2], v1[3]);
;                     *(u32x4*)rowp = w; }
.LBB0_1593:
	s_or_b64 exec, exec, s[4:5]
	v_lshl_add_u32 v128, s34, 8, v164
	v_mov_b64_e32 v[124:125], s[10:11]
	v_ashrrev_i32_e32 v3, 31, v2
	v_mad_i64_i32 v[124:125], s[4:5], v128, s57, v[124:125]
	v_lshl_add_u64 v[124:125], v[2:3], 1, v[124:125]
	v_cmp_lt_i32_e32 vcc, 1, v1
	v_cvt_pk_bf16_f32 v130, v140, v141
	v_cvt_pk_bf16_f32 v131, v142, v143
	v_cvt_pk_bf16_f32 v132, v144, v145
	v_cvt_pk_bf16_f32 v133, v146, v147
	global_store_dwordx4 v[124:125], v[130:133], off sc1
	s_and_saveexec_b64 s[4:5], vcc
	s_xor_b64 s[4:5], exec, s[4:5]
	s_cbranch_execz .LBB0_1595
	v_mul_f32_e32 v116, 0xbfb8aa3b, v116
	v_mul_f32_e32 v120, 0xbfb8aa3b, v120
	v_exp_f32_e32 v116, v116
	v_exp_f32_e32 v120, v120
	v_add_f32_e32 v116, 1.0, v116
	v_add_f32_e32 v120, 1.0, v120
	v_rcp_f32_e32 v116, v116
	v_rcp_f32_e32 v120, v120

; __device__ __forceinline__ unsigned cvt_pk_bf16(float lo, float hi) { unsigned r; asm volatile("v_cvt_pk_bf16_f32 %0, %1, %2" : "=v"(r) : "v"(lo), "v"(hi)); return r; }
; __device__ __forceinline__ float sigmoidf_(float x) { return __builtin_amdgcn_rcpf(1.f + __expf(-x)); }
;     __device__ __forceinline__ void operator()(const f32x4 (&acc)[2][2][4][2], const Unit& u, int wr, int wc, int fr, int fq) const {
;     ...
;             for (int ai = 0; ai < 2; ++ai)
; #pragma unroll
;                 for (int m = 0; m < 4; ++m) { bf16_t* rowp = O + (size_t)(row0 + ai * HALF + m * 16) * ldc + c;
;                     f32x4 v0, v1;
;                     if (MODE == 3) { const float rstd = rs[ai * 4 + m]; v0 = acc[ai][bj][m][0] * rstd + b0; v1 = acc[ai][bj][m][1] * rstd + b1; }
;                     else { v0 = acc[ai][bj][m][0] + b0; v1 = acc[ai][bj][m][1] + b1; }
;                     if (MODE == 1 || MODE == 2) {
; #pragma unroll
;                         for (int e = 0; e < 4; ++e) {
;                             if (kind == 1) { v0[e] = 2.f * sigmoidf_(2.f * v0[e]) - 1.f; v1[e] = 2.f * sigmoidf_(2.f * v1[e]) - 1.f; }
;                             else if (kind == 2) { v0[e] = sigmoidf_(v0[e]); v1[e] = sigmoidf_(v1[e]); }
;                             else if (kind == 3) { v0[e] = 0.60653066f * sigmoidf_(v0[e]); v1[e] = 0.60653066f * sigmoidf_(v1[e]); }
;                         }
;                     }
;                     u32x4 w; w.x = cvt_pk_bf16(v0[0], v0[1]); w.y = cvt_pk_bf16(v0[2], v0[3]); w.z = cvt_pk_bf16(v1[0], v1[1]); w.w = cvt_pk_bf16(v1[2], v1[3]);
;                     *(u32x4*)rowp = w; }
.LBB0_1617:
	s_or_b64 exec, exec, s[4:5]
	v_or_b32_e32 v129, 16, v128
	v_mov_b64_e32 v[126:127], s[10:11]
	v_mad_i64_i32 v[126:127], s[4:5], v129, s57, v[126:127]
	v_lshl_add_u64 v[126:127], v[2:3], 1, v[126:127]
	v_cmp_lt_i32_e32 vcc, 1, v1
	v_cvt_pk_bf16_f32 v116, v116, v117
	v_cvt_pk_bf16_f32 v117, v118, v119
	v_cvt_pk_bf16_f32 v118, v120, v121
	v_cvt_pk_bf16_f32 v119, v122, v123
	global_store_dwordx4 v[126:127], v[116:119], off sc1
	s_and_saveexec_b64 s[4:5], vcc
	s_xor_b64 s[4:5], exec, s[4:5]
	s_cbranch_execz .LBB0_1619
	v_mul_f32_e32 v108, 0xbfb8aa3b, v108
	v_mul_f32_e32 v112, 0xbfb8aa3b, v112
	v_exp_f32_e32 v108, v108
	v_exp_f32_e32 v112, v112
	v_add_f32_e32 v108, 1.0, v108
	v_add_f32_e32 v112, 1.0, v112
	v_rcp_f32_e32 v108, v108
	v_rcp_f32_e32 v112, v112

; __device__ __forceinline__ unsigned cvt_pk_bf16(float lo, float hi) { unsigned r; asm volatile("v_cvt_pk_bf16_f32 %0, %1, %2" : "=v"(r) : "v"(lo), "v"(hi)); return r; }
; __device__ __forceinline__ float sigmoidf_(float x) { return __builtin_amdgcn_rcpf(1.f + __expf(-x)); }
;     __device__ __forceinline__ void operator()(const f32x4 (&acc)[2][2][4][2], const Unit& u, int wr, int wc, int fr, int fq) const {
;     ...
;             for (int ai = 0; ai < 2; ++ai)
; #pragma unroll
;                 for (int m = 0; m < 4; ++m) { bf16_t* rowp = O + (size_t)(row0 + ai * HALF + m * 16) * ldc + c;
;                     f32x4 v0, v1;
;                     if (MODE == 3) { const float rstd = rs[ai * 4 + m]; v0 = acc[ai][bj][m][0] * rstd + b0; v1 = acc[ai][bj][m][1] * rstd + b1; }
;                     else { v0 = acc[ai][bj][m][0] + b0; v1 = acc[ai][bj][m][1] + b1; }
;                     if (MODE == 1 || MODE == 2) {
; #pragma unroll
;                         for (int e = 0; e < 4; ++e) {
;                             if (kind == 1) { v0[e] = 2.f * sigmoidf_(2.f * v0[e]) - 1.f; v1[e] = 2.f * sigmoidf_(2.f * v1[e]) - 1.f; }
;                             else if (kind == 2) { v0[e] = sigmoidf_(v0[e]); v1[e] = sigmoidf_(v1[e]); }
;                             else if (kind == 3) { v0[e] = 0.60653066f * sigmoidf_(v0[e]); v1[e] = 0.60653066f * sigmoidf_(v1[e]); }
;                         }
;                     }
;                     u32x4 w; w.x = cvt_pk_bf16(v0[0], v0[1]); w.y = cvt_pk_bf16(v0[2], v0[3]); w.z = cvt_pk_bf16(v1[0], v1[1]); w.w = cvt_pk_bf16(v1[2], v1[3]);
;                     *(u32x4*)rowp = w; }
.LBB0_1641:
	s_or_b64 exec, exec, s[4:5]
	v_or_b32_e32 v118, 32, v128
	v_mov_b64_e32 v[116:117], s[10:11]
	v_mad_i64_i32 v[116:117], s[4:5], v118, s57, v[116:117]
	v_lshl_add_u64 v[116:117], v[2:3], 1, v[116:117]
	v_cmp_lt_i32_e32 vcc, 1, v1
	v_cvt_pk_bf16_f32 v108, v108, v109
	v_cvt_pk_bf16_f32 v109, v110, v111
	v_cvt_pk_bf16_f32 v110, v112, v113
	v_cvt_pk_bf16_f32 v111, v114, v115
	global_store_dwordx4 v[116:117], v[108:111], off sc1
	s_and_saveexec_b64 s[4:5], vcc
	s_xor_b64 s[4:5], exec, s[4:5]
	s_cbranch_execz .LBB0_1643
	v_mul_f32_e32 v100, 0xbfb8aa3b, v100
	v_mul_f32_e32 v104, 0xbfb8aa3b, v104
	v_exp_f32_e32 v100, v100
	v_exp_f32_e32 v104, v104
	v_add_f32_e32 v100, 1.0, v100
	v_add_f32_e32 v104, 1.0, v104
	v_rcp_f32_e32 v100, v100
	v_rcp_f32_e32 v104, v104

; __device__ __forceinline__ unsigned cvt_pk_bf16(float lo, float hi) { unsigned r; asm volatile("v_cvt_pk_bf16_f32 %0, %1, %2" : "=v"(r) : "v"(lo), "v"(hi)); return r; }
; __device__ __forceinline__ float sigmoidf_(float x) { return __builtin_amdgcn_rcpf(1.f + __expf(-x)); }
;     __device__ __forceinline__ void operator()(const f32x4 (&acc)[2][2][4][2], const Unit& u, int wr, int wc, int fr, int fq) const {
;     ...
;             for (int ai = 0; ai < 2; ++ai)
; #pragma unroll
;                 for (int m = 0; m < 4; ++m) { bf16_t* rowp = O + (size_t)(row0 + ai * HALF + m * 16) * ldc + c;
;                     f32x4 v0, v1;
;                     if (MODE == 3) { const float rstd = rs[ai * 4 + m]; v0 = acc[ai][bj][m][0] * rstd + b0; v1 = acc[ai][bj][m][1] * rstd + b1; }
;                     else { v0 = acc[ai][bj][m][0] + b0; v1 = acc[ai][bj][m][1] + b1; }
;                     if (MODE == 1 || MODE == 2) {
; #pragma unroll
;                         for (int e = 0; e < 4; ++e) {
;                             if (kind == 1) { v0[e] = 2.f * sigmoidf_(2.f * v0[e]) - 1.f; v1[e] = 2.f * sigmoidf_(2.f * v1[e]) - 1.f; }
;                             else if (kind == 2) { v0[e] = sigmoidf_(v0[e]); v1[e] = sigmoidf_(v1[e]); }
;                             else if (kind == 3) { v0[e] = 0.60653066f * sigmoidf_(v0[e]); v1[e] = 0.60653066f * sigmoidf_(v1[e]); }
;                         }
;                     }
;                     u32x4 w; w.x = cvt_pk_bf16(v0[0], v0[1]); w.y = cvt_pk_bf16(v0[2], v0[3]); w.z = cvt_pk_bf16(v1[0], v1[1]); w.w = cvt_pk_bf16(v1[2], v1[3]);
;                     *(u32x4*)rowp = w; }
.LBB0_1665:
	s_or_b64 exec, exec, s[4:5]
	v_or_b32_e32 v110, 48, v128
	v_mov_b64_e32 v[108:109], s[10:11]
	v_mad_i64_i32 v[108:109], s[4:5], v110, s57, v[108:109]
	v_lshl_add_u64 v[108:109], v[2:3], 1, v[108:109]
	v_cmp_lt_i32_e32 vcc, 1, v1
	v_cvt_pk_bf16_f32 v100, v100, v101
	v_cvt_pk_bf16_f32 v101, v102, v103
	v_cvt_pk_bf16_f32 v102, v104, v105
	v_cvt_pk_bf16_f32 v103, v106, v107
	global_store_dwordx4 v[108:109], v[100:103], off sc1
	s_and_saveexec_b64 s[4:5], vcc
	s_xor_b64 s[4:5], exec, s[4:5]
	s_cbranch_execz .LBB0_1667
	v_mul_f32_e32 v92, 0xbfb8aa3b, v92
	v_mul_f32_e32 v96, 0xbfb8aa3b, v96
	v_exp_f32_e32 v92, v92
	v_exp_f32_e32 v96, v96
	v_add_f32_e32 v92, 1.0, v92
	v_add_f32_e32 v96, 1.0, v96
	v_rcp_f32_e32 v92, v92
	v_rcp_f32_e32 v96, v96

; __device__ __forceinline__ unsigned cvt_pk_bf16(float lo, float hi) { unsigned r; asm volatile("v_cvt_pk_bf16_f32 %0, %1, %2" : "=v"(r) : "v"(lo), "v"(hi)); return r; }
; __device__ __forceinline__ float sigmoidf_(float x) { return __builtin_amdgcn_rcpf(1.f + __expf(-x)); }
;     __device__ __forceinline__ void operator()(const f32x4 (&acc)[2][2][4][2], const Unit& u, int wr, int wc, int fr, int fq) const {
;     ...
;             for (int ai = 0; ai < 2; ++ai)
; #pragma unroll
;                 for (int m = 0; m < 4; ++m) { bf16_t* rowp = O + (size_t)(row0 + ai * HALF + m * 16) * ldc + c;
;                     f32x4 v0, v1;
;                     if (MODE == 3) { const float rstd = rs[ai * 4 + m]; v0 = acc[ai][bj][m][0] * rstd + b0; v1 = acc[ai][bj][m][1] * rstd + b1; }
;                     else { v0 = acc[ai][bj][m][0] + b0; v1 = acc[ai][bj][m][1] + b1; }
;                     if (MODE == 1 || MODE == 2) {
; #pragma unroll
;                         for (int e = 0; e < 4; ++e) {
;                             if (kind == 1) { v0[e] = 2.f * sigmoidf_(2.f * v0[e]) - 1.f; v1[e] = 2.f * sigmoidf_(2.f * v1[e]) - 1.f; }
;                             else if (kind == 2) { v0[e] = sigmoidf_(v0[e]); v1[e] = sigmoidf_(v1[e]); }
;                             else if (kind == 3) { v0[e] = 0.60653066f * sigmoidf_(v0[e]); v1[e] = 0.60653066f * sigmoidf_(v1[e]); }
;                         }
;                     }
;                     u32x4 w; w.x = cvt_pk_bf16(v0[0], v0[1]); w.y = cvt_pk_bf16(v0[2], v0[3]); w.z = cvt_pk_bf16(v1[0], v1[1]); w.w = cvt_pk_bf16(v1[2], v1[3]);
;                     *(u32x4*)rowp = w; }
.LBB0_1689:
	s_or_b64 exec, exec, s[4:5]
	v_add_u32_e32 v102, 0x80, v128
	v_mov_b64_e32 v[100:101], s[10:11]
	v_mad_i64_i32 v[100:101], s[4:5], v102, s57, v[100:101]
	v_lshl_add_u64 v[100:101], v[2:3], 1, v[100:101]
	v_cmp_lt_i32_e32 vcc, 1, v1
	v_cvt_pk_bf16_f32 v92, v92, v93
	v_cvt_pk_bf16_f32 v93, v94, v95
	v_cvt_pk_bf16_f32 v94, v96, v97
	v_cvt_pk_bf16_f32 v95, v98, v99
	global_store_dwordx4 v[100:101], v[92:95], off sc1
	s_and_saveexec_b64 s[4:5], vcc
	s_xor_b64 s[4:5], exec, s[4:5]
	s_cbranch_execz .LBB0_1691
	v_mul_f32_e32 v84, 0xbfb8aa3b, v84
	v_mul_f32_e32 v88, 0xbfb8aa3b, v88
	v_exp_f32_e32 v84, v84
	v_exp_f32_e32 v88, v88
	v_add_f32_e32 v84, 1.0, v84
	v_add_f32_e32 v88, 1.0, v88
	v_rcp_f32_e32 v84, v84
	v_rcp_f32_e32 v88, v88

; __device__ __forceinline__ unsigned cvt_pk_bf16(float lo, float hi) { unsigned r; asm volatile("v_cvt_pk_bf16_f32 %0, %1, %2" : "=v"(r) : "v"(lo), "v"(hi)); return r; }
; __device__ __forceinline__ float sigmoidf_(float x) { return __builtin_amdgcn_rcpf(1.f + __expf(-x)); }
;     __device__ __forceinline__ void operator()(const f32x4 (&acc)[2][2][4][2], const Unit& u, int wr, int wc, int fr, int fq) const {
;     ...
;             if (MODE == 1) { kind = (c >= 3072 && c < 3136) ? 1 : ((c >= 3200) ? 2 : 0); }
;             if (MODE == 3) { b0 = *(const f32x4*)(p1 + (size_t)(u.pm >> 4) * ldc + c); b1 = *(const f32x4*)(p1 + (size_t)(u.pm >> 4) * ldc + c + 4); }
;             if (MODE == 2) { if (c < 1024) { kind = 3; b0 = *(const f32x4*)(p0 + c); b1 = *(const f32x4*)(p0 + c + 4); } else { kind = 2; b0 = *(const f32x4*)(p1 + c - 1024); b1 = *(const f32x4*)(p1 + c - 1024 + 4); } }
; #pragma unroll
;             for (int ai = 0; ai < 2; ++ai)
; #pragma unroll
;                 for (int m = 0; m < 4; ++m) { bf16_t* rowp = O + (size_t)(row0 + ai * HALF + m * 16) * ldc + c;
;                     f32x4 v0, v1;
;                     if (MODE == 3) { const float rstd = rs[ai * 4 + m]; v0 = acc[ai][bj][m][0] * rstd + b0; v1 = acc[ai][bj][m][1] * rstd + b1; }
;                     else { v0 = acc[ai][bj][m][0] + b0; v1 = acc[ai][bj][m][1] + b1; }
;                     if (MODE == 1 || MODE == 2) {
; #pragma unroll
;                         for (int e = 0; e < 4; ++e) {
;                             if (kind == 1) { v0[e] = 2.f * sigmoidf_(2.f * v0[e]) - 1.f; v1[e] = 2.f * sigmoidf_(2.f * v1[e]) - 1.f; }
;                             else if (kind == 2) { v0[e] = sigmoidf_(v0[e]); v1[e] = sigmoidf_(v1[e]); }
;                             else if (kind == 3) { v0[e] = 0.60653066f * sigmoidf_(v0[e]); v1[e] = 0.60653066f * sigmoidf_(v1[e]); }
;                         }
;                     }
;                     u32x4 w; w.x = cvt_pk_bf16(v0[0], v0[1]); w.y = cvt_pk_bf16(v0[2], v0[3]); w.z = cvt_pk_bf16(v1[0], v1[1]); w.w = cvt_pk_bf16(v1[2], v1[3]);
;                     *(u32x4*)rowp = w; }
.LBB0_1713:
	s_or_b64 exec, exec, s[4:5]
	v_add_u32_e32 v94, 0x90, v128
	v_mov_b64_e32 v[92:93], s[10:11]
	v_mad_i64_i32 v[92:93], s[4:5], v94, s57, v[92:93]
	v_lshl_add_u64 v[92:93], v[2:3], 1, v[92:93]
	v_cmp_lt_i32_e32 vcc, 1, v1
	v_cvt_pk_bf16_f32 v84, v84, v85
	v_cvt_pk_bf16_f32 v85, v86, v87
	v_cvt_pk_bf16_f32 v86, v88, v89
	v_cvt_pk_bf16_f32 v87, v90, v91
	global_store_dwordx4 v[92:93], v[84:87], off sc1
	s_and_saveexec_b64 s[4:5], vcc
	s_xor_b64 s[4:5], exec, s[4:5]
	s_cbranch_execz .LBB0_1715
	v_mul_f32_e32 v76, 0xbfb8aa3b, v76
	v_mul_f32_e32 v80, 0xbfb8aa3b, v80
	v_exp_f32_e32 v76, v76
	v_exp_f32_e32 v80, v80
	v_add_f32_e32 v76, 1.0, v76
	v_add_f32_e32 v80, 1.0, v80
	v_rcp_f32_e32 v76, v76
	v_rcp_f32_e32 v80, v80

; __device__ __forceinline__ unsigned cvt_pk_bf16(float lo, float hi) { unsigned r; asm volatile("v_cvt_pk_bf16_f32 %0, %1, %2" : "=v"(r) : "v"(lo), "v"(hi)); return r; }
; __device__ __forceinline__ float sigmoidf_(float x) { return __builtin_amdgcn_rcpf(1.f + __expf(-x)); }
;     __device__ __forceinline__ void operator()(const f32x4 (&acc)[2][2][4][2], const Unit& u, int wr, int wc, int fr, int fq) const {
;     ...
;             if (MODE == 1) { kind = (c >= 3072 && c < 3136) ? 1 : ((c >= 3200) ? 2 : 0); }
;             if (MODE == 3) { b0 = *(const f32x4*)(p1 + (size_t)(u.pm >> 4) * ldc + c); b1 = *(const f32x4*)(p1 + (size_t)(u.pm >> 4) * ldc + c + 4); }
;             if (MODE == 2) { if (c < 1024) { kind = 3; b0 = *(const f32x4*)(p0 + c); b1 = *(const f32x4*)(p0 + c + 4); } else { kind = 2; b0 = *(const f32x4*)(p1 + c - 1024); b1 = *(const f32x4*)(p1 + c - 1024 + 4); } }
; #pragma unroll
;             for (int ai = 0; ai < 2; ++ai)
; #pragma unroll
;                 for (int m = 0; m < 4; ++m) { bf16_t* rowp = O + (size_t)(row0 + ai * HALF + m * 16) * ldc + c;
;                     f32x4 v0, v1;
;                     if (MODE == 3) { const float rstd = rs[ai * 4 + m]; v0 = acc[ai][bj][m][0] * rstd + b0; v1 = acc[ai][bj][m][1] * rstd + b1; }
;                     else { v0 = acc[ai][bj][m][0] + b0; v1 = acc[ai][bj][m][1] + b1; }
;                     if (MODE == 1 || MODE == 2) {
; #pragma unroll
;                         for (int e = 0; e < 4; ++e) {
;                             if (kind == 1) { v0[e] = 2.f * sigmoidf_(2.f * v0[e]) - 1.f; v1[e] = 2.f * sigmoidf_(2.f * v1[e]) - 1.f; }
;                             else if (kind == 2) { v0[e] = sigmoidf_(v0[e]); v1[e] = sigmoidf_(v1[e]); }
;                             else if (kind == 3) { v0[e] = 0.60653066f * sigmoidf_(v0[e]); v1[e] = 0.60653066f * sigmoidf_(v1[e]); }
;                         }
;                     }
;                     u32x4 w; w.x = cvt_pk_bf16(v0[0], v0[1]); w.y = cvt_pk_bf16(v0[2], v0[3]); w.z = cvt_pk_bf16(v1[0], v1[1]); w.w = cvt_pk_bf16(v1[2], v1[3]);
;                     *(u32x4*)rowp = w; }
.LBB0_1737:
	s_or_b64 exec, exec, s[4:5]
	v_add_u32_e32 v86, 0xa0, v128
	v_mov_b64_e32 v[84:85], s[10:11]
	v_mad_i64_i32 v[84:85], s[4:5], v86, s57, v[84:85]
	v_lshl_add_u64 v[84:85], v[2:3], 1, v[84:85]
	v_cmp_lt_i32_e32 vcc, 1, v1
	v_cvt_pk_bf16_f32 v76, v76, v77
	v_cvt_pk_bf16_f32 v77, v78, v79
	v_cvt_pk_bf16_f32 v78, v80, v81
	v_cvt_pk_bf16_f32 v79, v82, v83
	global_store_dwordx4 v[84:85], v[76:79], off sc1
	s_and_saveexec_b64 s[4:5], vcc
	s_xor_b64 s[4:5], exec, s[4:5]
	s_cbranch_execz .LBB0_1739
	v_mul_f32_e32 v68, 0xbfb8aa3b, v68
	v_mul_f32_e32 v72, 0xbfb8aa3b, v72
	v_exp_f32_e32 v68, v68
	v_exp_f32_e32 v72, v72
	v_add_f32_e32 v68, 1.0, v68
	v_add_f32_e32 v72, 1.0, v72
	v_rcp_f32_e32 v68, v68
	v_rcp_f32_e32 v72, v72

; __device__ __forceinline__ unsigned cvt_pk_bf16(float lo, float hi) { unsigned r; asm volatile("v_cvt_pk_bf16_f32 %0, %1, %2" : "=v"(r) : "v"(lo), "v"(hi)); return r; }
; __device__ __forceinline__ float sigmoidf_(float x) { return __builtin_amdgcn_rcpf(1.f + __expf(-x)); }
;     __device__ __forceinline__ void operator()(const f32x4 (&acc)[2][2][4][2], const Unit& u, int wr, int wc, int fr, int fq) const {
;     ...
;             if (MODE == 1) { kind = (c >= 3072 && c < 3136) ? 1 : ((c >= 3200) ? 2 : 0); }
;             if (MODE == 3) { b0 = *(const f32x4*)(p1 + (size_t)(u.pm >> 4) * ldc + c); b1 = *(const f32x4*)(p1 + (size_t)(u.pm >> 4) * ldc + c + 4); }
;             if (MODE == 2) { if (c < 1024) { kind = 3; b0 = *(const f32x4*)(p0 + c); b1 = *(const f32x4*)(p0 + c + 4); } else { kind = 2; b0 = *(const f32x4*)(p1 + c - 1024); b1 = *(const f32x4*)(p1 + c - 1024 + 4); } }
; #pragma unroll
;             for (int ai = 0; ai < 2; ++ai)
; #pragma unroll
;                 for (int m = 0; m < 4; ++m) { bf16_t* rowp = O + (size_t)(row0 + ai * HALF + m * 16) * ldc + c;
;                     f32x4 v0, v1;
;                     if (MODE == 3) { const float rstd = rs[ai * 4 + m]; v0 = acc[ai][bj][m][0] * rstd + b0; v1 = acc[ai][bj][m][1] * rstd + b1; }
;                     else { v0 = acc[ai][bj][m][0] + b0; v1 = acc[ai][bj][m][1] + b1; }
;                     if (MODE == 1 || MODE == 2) {
; #pragma unroll
;                         for (int e = 0; e < 4; ++e) {
;                             if (kind == 1) { v0[e] = 2.f * sigmoidf_(2.f * v0[e]) - 1.f; v1[e] = 2.f * sigmoidf_(2.f * v1[e]) - 1.f; }
;                             else if (kind == 2) { v0[e] = sigmoidf_(v0[e]); v1[e] = sigmoidf_(v1[e]); }
;                             else if (kind == 3) { v0[e] = 0.60653066f * sigmoidf_(v0[e]); v1[e] = 0.60653066f * sigmoidf_(v1[e]); }
;                         }
;                     }
;                     u32x4 w; w.x = cvt_pk_bf16(v0[0], v0[1]); w.y = cvt_pk_bf16(v0[2], v0[3]); w.z = cvt_pk_bf16(v1[0], v1[1]); w.w = cvt_pk_bf16(v1[2], v1[3]);
;                     *(u32x4*)rowp = w; }
.LBB0_1761:
	s_or_b64 exec, exec, s[4:5]
	v_add_u32_e32 v1, 0xb0, v128
	v_mov_b64_e32 v[76:77], s[10:11]
	v_mad_i64_i32 v[76:77], s[4:5], v1, s57, v[76:77]
	v_or_b32_e32 v1, 0x80, v2
	v_lshl_add_u64 v[76:77], v[2:3], 1, v[76:77]
	v_cmp_lt_i32_e32 vcc, s56, v1
	v_cvt_pk_bf16_f32 v68, v68, v69
	v_cvt_pk_bf16_f32 v69, v70, v71
	v_cvt_pk_bf16_f32 v70, v72, v73
	v_cvt_pk_bf16_f32 v71, v74, v75
	global_store_dwordx4 v[76:77], v[68:71], off sc1
	s_and_saveexec_b64 s[4:5], vcc
	s_cbranch_execz .LBB0_1765
	v_mul_f32_e32 v1, 0xbfb8aa3b, v60
	v_mul_f32_e32 v2, 0xbfb8aa3b, v64
	v_exp_f32_e32 v1, v1
	v_exp_f32_e32 v2, v2
	v_add_f32_e32 v1, 1.0, v1
	v_add_f32_e32 v2, 1.0, v2
	v_rcp_f32_e32 v60, v1
	v_rcp_f32_e32 v64, v2
	s_or_b64 exec, exec, s[4:5]
	s_and_saveexec_b64 s[4:5], vcc
	s_cbranch_execnz .LBB0_1766

; __device__ __forceinline__ unsigned cvt_pk_bf16(float lo, float hi) { unsigned r; asm volatile("v_cvt_pk_bf16_f32 %0, %1, %2" : "=v"(r) : "v"(lo), "v"(hi)); return r; }
; __device__ __forceinline__ float sigmoidf_(float x) { return __builtin_amdgcn_rcpf(1.f + __expf(-x)); }
;     __device__ __forceinline__ void operator()(const f32x4 (&acc)[2][2][4][2], const Unit& u, int wr, int wc, int fr, int fq) const {
;     ...
;             for (int ai = 0; ai < 2; ++ai)
; #pragma unroll
;                 for (int m = 0; m < 4; ++m) { bf16_t* rowp = O + (size_t)(row0 + ai * HALF + m * 16) * ldc + c;
;                     f32x4 v0, v1;
;                     if (MODE == 3) { const float rstd = rs[ai * 4 + m]; v0 = acc[ai][bj][m][0] * rstd + b0; v1 = acc[ai][bj][m][1] * rstd + b1; }
;                     else { v0 = acc[ai][bj][m][0] + b0; v1 = acc[ai][bj][m][1] + b1; }
;                     if (MODE == 1 || MODE == 2) {
; #pragma unroll
;                         for (int e = 0; e < 4; ++e) {
;                             if (kind == 1) { v0[e] = 2.f * sigmoidf_(2.f * v0[e]) - 1.f; v1[e] = 2.f * sigmoidf_(2.f * v1[e]) - 1.f; }
;                             else if (kind == 2) { v0[e] = sigmoidf_(v0[e]); v1[e] = sigmoidf_(v1[e]); }
;                             else if (kind == 3) { v0[e] = 0.60653066f * sigmoidf_(v0[e]); v1[e] = 0.60653066f * sigmoidf_(v1[e]); }
;                         }
;                     }
;                     u32x4 w; w.x = cvt_pk_bf16(v0[0], v0[1]); w.y = cvt_pk_bf16(v0[2], v0[3]); w.z = cvt_pk_bf16(v1[0], v1[1]); w.w = cvt_pk_bf16(v1[2], v1[3]);
;                     *(u32x4*)rowp = w; }
.LBB0_1769:
	s_or_b64 exec, exec, s[4:5]
	v_cvt_pk_bf16_f32 v60, v60, v61
	v_cvt_pk_bf16_f32 v61, v62, v63
	v_cvt_pk_bf16_f32 v62, v64, v65
	v_cvt_pk_bf16_f32 v63, v66, v67
	global_store_dwordx4 v[124:125], v[60:63], off offset:256 sc1
	s_and_saveexec_b64 s[4:5], vcc
	s_cbranch_execz .LBB0_1773
	v_mul_f32_e32 v1, 0xbfb8aa3b, v52
	v_mul_f32_e32 v2, 0xbfb8aa3b, v56
	v_exp_f32_e32 v1, v1
	v_exp_f32_e32 v2, v2
	v_add_f32_e32 v1, 1.0, v1
	v_add_f32_e32 v2, 1.0, v2
	v_rcp_f32_e32 v52, v1
	v_rcp_f32_e32 v56, v2
	s_or_b64 exec, exec, s[4:5]
	s_and_saveexec_b64 s[4:5], vcc
	s_cbranch_execnz .LBB0_1774

; __device__ __forceinline__ unsigned cvt_pk_bf16(float lo, float hi) { unsigned r; asm volatile("v_cvt_pk_bf16_f32 %0, %1, %2" : "=v"(r) : "v"(lo), "v"(hi)); return r; }
; __device__ __forceinline__ float sigmoidf_(float x) { return __builtin_amdgcn_rcpf(1.f + __expf(-x)); }
;     __device__ __forceinline__ void operator()(const f32x4 (&acc)[2][2][4][2], const Unit& u, int wr, int wc, int fr, int fq) const {
;     ...
;             for (int ai = 0; ai < 2; ++ai)
; #pragma unroll
;                 for (int m = 0; m < 4; ++m) { bf16_t* rowp = O + (size_t)(row0 + ai * HALF + m * 16) * ldc + c;
;                     f32x4 v0, v1;
;                     if (MODE == 3) { const float rstd = rs[ai * 4 + m]; v0 = acc[ai][bj][m][0] * rstd + b0; v1 = acc[ai][bj][m][1] * rstd + b1; }
;                     else { v0 = acc[ai][bj][m][0] + b0; v1 = acc[ai][bj][m][1] + b1; }
;                     if (MODE == 1 || MODE == 2) {
; #pragma unroll
;                         for (int e = 0; e < 4; ++e) {
;                             if (kind == 1) { v0[e] = 2.f * sigmoidf_(2.f * v0[e]) - 1.f; v1[e] = 2.f * sigmoidf_(2.f * v1[e]) - 1.f; }
;                             else if (kind == 2) { v0[e] = sigmoidf_(v0[e]); v1[e] = sigmoidf_(v1[e]); }
;                             else if (kind == 3) { v0[e] = 0.60653066f * sigmoidf_(v0[e]); v1[e] = 0.60653066f * sigmoidf_(v1[e]); }
;                         }
;                     }
;                     u32x4 w; w.x = cvt_pk_bf16(v0[0], v0[1]); w.y = cvt_pk_bf16(v0[2], v0[3]); w.z = cvt_pk_bf16(v1[0], v1[1]); w.w = cvt_pk_bf16(v1[2], v1[3]);
;                     *(u32x4*)rowp = w; }
.LBB0_1777:
	s_or_b64 exec, exec, s[4:5]
	v_cvt_pk_bf16_f32 v52, v52, v53
	v_cvt_pk_bf16_f32 v53, v54, v55
	v_cvt_pk_bf16_f32 v54, v56, v57
	v_cvt_pk_bf16_f32 v55, v58, v59
	global_store_dwordx4 v[126:127], v[52:55], off offset:256 sc1
	s_and_saveexec_b64 s[4:5], vcc
	s_cbranch_execz .LBB0_1781
	v_mul_f32_e32 v1, 0xbfb8aa3b, v44
	v_mul_f32_e32 v2, 0xbfb8aa3b, v48
	v_exp_f32_e32 v1, v1
	v_exp_f32_e32 v2, v2
	v_add_f32_e32 v1, 1.0, v1
	v_add_f32_e32 v2, 1.0, v2
	v_rcp_f32_e32 v44, v1
	v_rcp_f32_e32 v48, v2
	s_or_b64 exec, exec, s[4:5]
	s_and_saveexec_b64 s[4:5], vcc
	s_cbranch_execnz .LBB0_1782

; __device__ __forceinline__ unsigned cvt_pk_bf16(float lo, float hi) { unsigned r; asm volatile("v_cvt_pk_bf16_f32 %0, %1, %2" : "=v"(r) : "v"(lo), "v"(hi)); return r; }
; __device__ __forceinline__ float sigmoidf_(float x) { return __builtin_amdgcn_rcpf(1.f + __expf(-x)); }
;     __device__ __forceinline__ void operator()(const f32x4 (&acc)[2][2][4][2], const Unit& u, int wr, int wc, int fr, int fq) const {
;     ...
;             for (int ai = 0; ai < 2; ++ai)
; #pragma unroll
;                 for (int m = 0; m < 4; ++m) { bf16_t* rowp = O + (size_t)(row0 + ai * HALF + m * 16) * ldc + c;
;                     f32x4 v0, v1;
;                     if (MODE == 3) { const float rstd = rs[ai * 4 + m]; v0 = acc[ai][bj][m][0] * rstd + b0; v1 = acc[ai][bj][m][1] * rstd + b1; }
;                     else { v0 = acc[ai][bj][m][0] + b0; v1 = acc[ai][bj][m][1] + b1; }
;                     if (MODE == 1 || MODE == 2) {
; #pragma unroll
;                         for (int e = 0; e < 4; ++e) {
;                             if (kind == 1) { v0[e] = 2.f * sigmoidf_(2.f * v0[e]) - 1.f; v1[e] = 2.f * sigmoidf_(2.f * v1[e]) - 1.f; }
;                             else if (kind == 2) { v0[e] = sigmoidf_(v0[e]); v1[e] = sigmoidf_(v1[e]); }
;                             else if (kind == 3) { v0[e] = 0.60653066f * sigmoidf_(v0[e]); v1[e] = 0.60653066f * sigmoidf_(v1[e]); }
;                         }
;                     }
;                     u32x4 w; w.x = cvt_pk_bf16(v0[0], v0[1]); w.y = cvt_pk_bf16(v0[2], v0[3]); w.z = cvt_pk_bf16(v1[0], v1[1]); w.w = cvt_pk_bf16(v1[2], v1[3]);
;                     *(u32x4*)rowp = w; }
.LBB0_1785:
	s_or_b64 exec, exec, s[4:5]
	v_cvt_pk_bf16_f32 v44, v44, v45
	v_cvt_pk_bf16_f32 v45, v46, v47
	v_cvt_pk_bf16_f32 v46, v48, v49
	v_cvt_pk_bf16_f32 v47, v50, v51
	global_store_dwordx4 v[116:117], v[44:47], off offset:256 sc1
	s_and_saveexec_b64 s[4:5], vcc
	s_cbranch_execz .LBB0_1789
	v_mul_f32_e32 v1, 0xbfb8aa3b, v36
	v_mul_f32_e32 v2, 0xbfb8aa3b, v40
	v_exp_f32_e32 v1, v1
	v_exp_f32_e32 v2, v2
	v_add_f32_e32 v1, 1.0, v1
	v_add_f32_e32 v2, 1.0, v2
	v_rcp_f32_e32 v36, v1
	v_rcp_f32_e32 v40, v2
	s_or_b64 exec, exec, s[4:5]
	s_and_saveexec_b64 s[4:5], vcc
	s_cbranch_execnz .LBB0_1790

; __device__ __forceinline__ unsigned cvt_pk_bf16(float lo, float hi) { unsigned r; asm volatile("v_cvt_pk_bf16_f32 %0, %1, %2" : "=v"(r) : "v"(lo), "v"(hi)); return r; }
; __device__ __forceinline__ float sigmoidf_(float x) { return __builtin_amdgcn_rcpf(1.f + __expf(-x)); }
;     __device__ __forceinline__ void operator()(const f32x4 (&acc)[2][2][4][2], const Unit& u, int wr, int wc, int fr, int fq) const {
;     ...
;             for (int ai = 0; ai < 2; ++ai)
; #pragma unroll
;                 for (int m = 0; m < 4; ++m) { bf16_t* rowp = O + (size_t)(row0 + ai * HALF + m * 16) * ldc + c;
;                     f32x4 v0, v1;
;                     if (MODE == 3) { const float rstd = rs[ai * 4 + m]; v0 = acc[ai][bj][m][0] * rstd + b0; v1 = acc[ai][bj][m][1] * rstd + b1; }
;                     else { v0 = acc[ai][bj][m][0] + b0; v1 = acc[ai][bj][m][1] + b1; }
;                     if (MODE == 1 || MODE == 2) {
; #pragma unroll
;                         for (int e = 0; e < 4; ++e) {
;                             if (kind == 1) { v0[e] = 2.f * sigmoidf_(2.f * v0[e]) - 1.f; v1[e] = 2.f * sigmoidf_(2.f * v1[e]) - 1.f; }
;                             else if (kind == 2) { v0[e] = sigmoidf_(v0[e]); v1[e] = sigmoidf_(v1[e]); }
;                             else if (kind == 3) { v0[e] = 0.60653066f * sigmoidf_(v0[e]); v1[e] = 0.60653066f * sigmoidf_(v1[e]); }
;                         }
;                     }
;                     u32x4 w; w.x = cvt_pk_bf16(v0[0], v0[1]); w.y = cvt_pk_bf16(v0[2], v0[3]); w.z = cvt_pk_bf16(v1[0], v1[1]); w.w = cvt_pk_bf16(v1[2], v1[3]);
;                     *(u32x4*)rowp = w; }
.LBB0_1793:
	s_or_b64 exec, exec, s[4:5]
	v_cvt_pk_bf16_f32 v36, v36, v37
	v_cvt_pk_bf16_f32 v37, v38, v39
	v_cvt_pk_bf16_f32 v38, v40, v41
	v_cvt_pk_bf16_f32 v39, v42, v43
	global_store_dwordx4 v[108:109], v[36:39], off offset:256 sc1
	s_and_saveexec_b64 s[4:5], vcc
	s_cbranch_execz .LBB0_1797
	v_mul_f32_e32 v1, 0xbfb8aa3b, v28
	v_mul_f32_e32 v2, 0xbfb8aa3b, v32
	v_exp_f32_e32 v1, v1
	v_exp_f32_e32 v2, v2
	v_add_f32_e32 v1, 1.0, v1
	v_add_f32_e32 v2, 1.0, v2
	v_rcp_f32_e32 v28, v1
	v_rcp_f32_e32 v32, v2
	s_or_b64 exec, exec, s[4:5]
	s_and_saveexec_b64 s[4:5], vcc
	s_cbranch_execnz .LBB0_1798

; __device__ __forceinline__ unsigned cvt_pk_bf16(float lo, float hi) { unsigned r; asm volatile("v_cvt_pk_bf16_f32 %0, %1, %2" : "=v"(r) : "v"(lo), "v"(hi)); return r; }
; __device__ __forceinline__ float sigmoidf_(float x) { return __builtin_amdgcn_rcpf(1.f + __expf(-x)); }
;     __device__ __forceinline__ void operator()(const f32x4 (&acc)[2][2][4][2], const Unit& u, int wr, int wc, int fr, int fq) const {
;     ...
;             for (int ai = 0; ai < 2; ++ai)
; #pragma unroll
;                 for (int m = 0; m < 4; ++m) { bf16_t* rowp = O + (size_t)(row0 + ai * HALF + m * 16) * ldc + c;
;                     f32x4 v0, v1;
;                     if (MODE == 3) { const float rstd = rs[ai * 4 + m]; v0 = acc[ai][bj][m][0] * rstd + b0; v1 = acc[ai][bj][m][1] * rstd + b1; }
;                     else { v0 = acc[ai][bj][m][0] + b0; v1 = acc[ai][bj][m][1] + b1; }
;                     if (MODE == 1 || MODE == 2) {
; #pragma unroll
;                         for (int e = 0; e < 4; ++e) {
;                             if (kind == 1) { v0[e] = 2.f * sigmoidf_(2.f * v0[e]) - 1.f; v1[e] = 2.f * sigmoidf_(2.f * v1[e]) - 1.f; }
;                             else if (kind == 2) { v0[e] = sigmoidf_(v0[e]); v1[e] = sigmoidf_(v1[e]); }
;                             else if (kind == 3) { v0[e] = 0.60653066f * sigmoidf_(v0[e]); v1[e] = 0.60653066f * sigmoidf_(v1[e]); }
;                         }
;                     }
;                     u32x4 w; w.x = cvt_pk_bf16(v0[0], v0[1]); w.y = cvt_pk_bf16(v0[2], v0[3]); w.z = cvt_pk_bf16(v1[0], v1[1]); w.w = cvt_pk_bf16(v1[2], v1[3]);
;                     *(u32x4*)rowp = w; }
.LBB0_1801:
	s_or_b64 exec, exec, s[4:5]
	v_cvt_pk_bf16_f32 v28, v28, v29
	v_cvt_pk_bf16_f32 v29, v30, v31
	v_cvt_pk_bf16_f32 v30, v32, v33
	v_cvt_pk_bf16_f32 v31, v34, v35
	global_store_dwordx4 v[100:101], v[28:31], off offset:256 sc1
	s_and_saveexec_b64 s[4:5], vcc
	s_cbranch_execz .LBB0_1805
	v_mul_f32_e32 v1, 0xbfb8aa3b, v20
	v_mul_f32_e32 v2, 0xbfb8aa3b, v24
	v_exp_f32_e32 v1, v1
	v_exp_f32_e32 v2, v2
	v_add_f32_e32 v1, 1.0, v1
	v_add_f32_e32 v2, 1.0, v2
	v_rcp_f32_e32 v20, v1
	v_rcp_f32_e32 v24, v2
	s_or_b64 exec, exec, s[4:5]
	s_and_saveexec_b64 s[4:5], vcc
	s_cbranch_execnz .LBB0_1806

; __device__ __forceinline__ unsigned cvt_pk_bf16(float lo, float hi) { unsigned r; asm volatile("v_cvt_pk_bf16_f32 %0, %1, %2" : "=v"(r) : "v"(lo), "v"(hi)); return r; }
; __device__ __forceinline__ float sigmoidf_(float x) { return __builtin_amdgcn_rcpf(1.f + __expf(-x)); }
;     __device__ __forceinline__ void operator()(const f32x4 (&acc)[2][2][4][2], const Unit& u, int wr, int wc, int fr, int fq) const {
;     ...
;             for (int ai = 0; ai < 2; ++ai)
; #pragma unroll
;                 for (int m = 0; m < 4; ++m) { bf16_t* rowp = O + (size_t)(row0 + ai * HALF + m * 16) * ldc + c;
;                     f32x4 v0, v1;
;                     if (MODE == 3) { const float rstd = rs[ai * 4 + m]; v0 = acc[ai][bj][m][0] * rstd + b0; v1 = acc[ai][bj][m][1] * rstd + b1; }
;                     else { v0 = acc[ai][bj][m][0] + b0; v1 = acc[ai][bj][m][1] + b1; }
;                     if (MODE == 1 || MODE == 2) {
; #pragma unroll
;                         for (int e = 0; e < 4; ++e) {
;                             if (kind == 1) { v0[e] = 2.f * sigmoidf_(2.f * v0[e]) - 1.f; v1[e] = 2.f * sigmoidf_(2.f * v1[e]) - 1.f; }
;                             else if (kind == 2) { v0[e] = sigmoidf_(v0[e]); v1[e] = sigmoidf_(v1[e]); }
;                             else if (kind == 3) { v0[e] = 0.60653066f * sigmoidf_(v0[e]); v1[e] = 0.60653066f * sigmoidf_(v1[e]); }
;                         }
;                     }
;                     u32x4 w; w.x = cvt_pk_bf16(v0[0], v0[1]); w.y = cvt_pk_bf16(v0[2], v0[3]); w.z = cvt_pk_bf16(v1[0], v1[1]); w.w = cvt_pk_bf16(v1[2], v1[3]);
;                     *(u32x4*)rowp = w; }
.LBB0_1809:
	s_or_b64 exec, exec, s[4:5]
	v_cvt_pk_bf16_f32 v20, v20, v21
	v_cvt_pk_bf16_f32 v21, v22, v23
	v_cvt_pk_bf16_f32 v22, v24, v25
	v_cvt_pk_bf16_f32 v23, v26, v27
	global_store_dwordx4 v[92:93], v[20:23], off offset:256 sc1
	s_and_saveexec_b64 s[4:5], vcc
	s_cbranch_execz .LBB0_1813
	v_mul_f32_e32 v1, 0xbfb8aa3b, v12
	v_mul_f32_e32 v2, 0xbfb8aa3b, v16
	v_exp_f32_e32 v1, v1
	v_exp_f32_e32 v2, v2
	v_add_f32_e32 v1, 1.0, v1
	v_add_f32_e32 v2, 1.0, v2
	v_rcp_f32_e32 v12, v1
	v_rcp_f32_e32 v16, v2
	s_or_b64 exec, exec, s[4:5]
	s_and_saveexec_b64 s[4:5], vcc
	s_cbranch_execnz .LBB0_1814

; __device__ __forceinline__ unsigned cvt_pk_bf16(float lo, float hi) { unsigned r; asm volatile("v_cvt_pk_bf16_f32 %0, %1, %2" : "=v"(r) : "v"(lo), "v"(hi)); return r; }
; __device__ __forceinline__ float sigmoidf_(float x) { return __builtin_amdgcn_rcpf(1.f + __expf(-x)); }
;     __device__ __forceinline__ void operator()(const f32x4 (&acc)[2][2][4][2], const Unit& u, int wr, int wc, int fr, int fq) const {
;     ...
;             for (int ai = 0; ai < 2; ++ai)
; #pragma unroll
;                 for (int m = 0; m < 4; ++m) { bf16_t* rowp = O + (size_t)(row0 + ai * HALF + m * 16) * ldc + c;
;                     f32x4 v0, v1;
;                     if (MODE == 3) { const float rstd = rs[ai * 4 + m]; v0 = acc[ai][bj][m][0] * rstd + b0; v1 = acc[ai][bj][m][1] * rstd + b1; }
;                     else { v0 = acc[ai][bj][m][0] + b0; v1 = acc[ai][bj][m][1] + b1; }
;                     if (MODE == 1 || MODE == 2) {
; #pragma unroll
;                         for (int e = 0; e < 4; ++e) {
;                             if (kind == 1) { v0[e] = 2.f * sigmoidf_(2.f * v0[e]) - 1.f; v1[e] = 2.f * sigmoidf_(2.f * v1[e]) - 1.f; }
;                             else if (kind == 2) { v0[e] = sigmoidf_(v0[e]); v1[e] = sigmoidf_(v1[e]); }
;                             else if (kind == 3) { v0[e] = 0.60653066f * sigmoidf_(v0[e]); v1[e] = 0.60653066f * sigmoidf_(v1[e]); }
;                         }
;                     }
;                     u32x4 w; w.x = cvt_pk_bf16(v0[0], v0[1]); w.y = cvt_pk_bf16(v0[2], v0[3]); w.z = cvt_pk_bf16(v1[0], v1[1]); w.w = cvt_pk_bf16(v1[2], v1[3]);
;                     *(u32x4*)rowp = w; }
.LBB0_1817:
	s_or_b64 exec, exec, s[4:5]
	v_cvt_pk_bf16_f32 v12, v12, v13
	v_cvt_pk_bf16_f32 v13, v14, v15
	v_cvt_pk_bf16_f32 v14, v16, v17
	v_cvt_pk_bf16_f32 v15, v18, v19
	global_store_dwordx4 v[84:85], v[12:15], off offset:256 sc1
	s_and_saveexec_b64 s[4:5], vcc
	s_cbranch_execz .LBB0_1821
	v_mul_f32_e32 v1, 0xbfb8aa3b, v4
	v_mul_f32_e32 v2, 0xbfb8aa3b, v8
	v_exp_f32_e32 v1, v1
	v_exp_f32_e32 v2, v2
	v_add_f32_e32 v1, 1.0, v1
	v_add_f32_e32 v2, 1.0, v2
	v_rcp_f32_e32 v4, v1
	v_rcp_f32_e32 v8, v2
	s_or_b64 exec, exec, s[4:5]
	s_and_saveexec_b64 s[4:5], vcc
	s_cbranch_execnz .LBB0_1822

; __device__ __forceinline__ unsigned cvt_pk_bf16(float lo, float hi) { unsigned r; asm volatile("v_cvt_pk_bf16_f32 %0, %1, %2" : "=v"(r) : "v"(lo), "v"(hi)); return r; }
; #define PG8_BAR __builtin_amdgcn_s_barrier()
; template <class Epi, class Sched, bool ALIGN_EPI = false, bool SP2 = false>
; __device__ __forceinline__ void gemm_phase(PG8_LAS unsigned char* lds, const Gemm g, const Sched& S, const Epi& E) {
;     ...
;         if constexpr (ALIGN_EPI) { if (wr == 0) PG8_BAR; }
;         if constexpr (!Epi::AFTER_DRAIN) { E(acc, cur, wr, wc, fr, fq); S.done(cur); }
;         if (!has_next) break;
; #pragma unroll
;         for (int a = 0; a < 2; ++a)
; #pragma unroll
;             for (int b = 0; b < 2; ++b)
; #pragma unroll
;                 for (int m = 0; m < 4; ++m)
; #pragma unroll
;                     for (int n = 0; n < 2; ++n) acc[a][b][m][n] = (f32x4){0.f, 0.f, 0.f, 0.f};
;         cur = nxt; cA = nA; cB = nB; ++ui;
;         if constexpr (ALIGN_EPI) { if (wr == 1) PG8_BAR; }
;     __device__ __forceinline__ void operator()(const f32x4 (&acc)[2][2][4][2], const Unit& u, int wr, int wc, int fr, int fq) const {
;     ...
;             for (int ai = 0; ai < 2; ++ai)
; #pragma unroll
;                 for (int m = 0; m < 4; ++m) { bf16_t* rowp = O + (size_t)(row0 + ai * HALF + m * 16) * ldc + c;
;                     f32x4 v0, v1;
;                     if (MODE == 3) { const float rstd = rs[ai * 4 + m]; v0 = acc[ai][bj][m][0] * rstd + b0; v1 = acc[ai][bj][m][1] * rstd + b1; }
;                     else { v0 = acc[ai][bj][m][0] + b0; v1 = acc[ai][bj][m][1] + b1; }
;                     if (MODE == 1 || MODE == 2) {
; #pragma unroll
;                         for (int e = 0; e < 4; ++e) {
;                             if (kind == 1) { v0[e] = 2.f * sigmoidf_(2.f * v0[e]) - 1.f; v1[e] = 2.f * sigmoidf_(2.f * v1[e]) - 1.f; }
;                             else if (kind == 2) { v0[e] = sigmoidf_(v0[e]); v1[e] = sigmoidf_(v1[e]); }
;                             else if (kind == 3) { v0[e] = 0.60653066f * sigmoidf_(v0[e]); v1[e] = 0.60653066f * sigmoidf_(v1[e]); }
;                         }
;                     }
;                     u32x4 w; w.x = cvt_pk_bf16(v0[0], v0[1]); w.y = cvt_pk_bf16(v0[2], v0[3]); w.z = cvt_pk_bf16(v1[0], v1[1]); w.w = cvt_pk_bf16(v1[2], v1[3]);
;                     *(u32x4*)rowp = w; }
.LBB0_1825:
	s_or_b64 exec, exec, s[4:5]
	s_and_b64 vcc, exec, s[2:3]
	s_mov_b64 s[2:3], -1
	v_cvt_pk_bf16_f32 v2, v4, v5
	v_cvt_pk_bf16_f32 v3, v6, v7
	v_cvt_pk_bf16_f32 v4, v8, v9
	v_cvt_pk_bf16_f32 v5, v10, v11
	global_store_dwordx4 v[76:77], v[2:5], off offset:256 sc1
	s_cbranch_vccnz .LBB0_1558
	s_andn2_b64 vcc, exec, s[20:21]
	s_cbranch_vccnz .LBB0_1557
	s_barrier
	s_branch .LBB0_1557

; __device__ __forceinline__ unsigned cvt_pk_bf16(float lo, float hi) { unsigned r; asm volatile("v_cvt_pk_bf16_f32 %0, %1, %2" : "=v"(r) : "v"(lo), "v"(hi)); return r; }
; __device__ __forceinline__ float sigmoidf_(float x) { return __builtin_amdgcn_rcpf(1.f + __expf(-x)); }
;     __device__ __forceinline__ void operator()(const f32x4 (&acc)[2][2][4][2], const Unit& u, int wr, int wc, int fr, int fq) const {
;     ...
;             if (MODE == 2) { if (c < 1024) { kind = 3; b0 = *(const f32x4*)(p0 + c); b1 = *(const f32x4*)(p0 + c + 4); } else { kind = 2; b0 = *(const f32x4*)(p1 + c - 1024); b1 = *(const f32x4*)(p1 + c - 1024 + 4); } }
; #pragma unroll
;             for (int ai = 0; ai < 2; ++ai)
; #pragma unroll
;                 for (int m = 0; m < 4; ++m) { bf16_t* rowp = O + (size_t)(row0 + ai * HALF + m * 16) * ldc + c;
;                     f32x4 v0, v1;
;                     if (MODE == 3) { const float rstd = rs[ai * 4 + m]; v0 = acc[ai][bj][m][0] * rstd + b0; v1 = acc[ai][bj][m][1] * rstd + b1; }
;                     else { v0 = acc[ai][bj][m][0] + b0; v1 = acc[ai][bj][m][1] + b1; }
;                     if (MODE == 1 || MODE == 2) {
; #pragma unroll
;                         for (int e = 0; e < 4; ++e) {
;                             if (kind == 1) { v0[e] = 2.f * sigmoidf_(2.f * v0[e]) - 1.f; v1[e] = 2.f * sigmoidf_(2.f * v1[e]) - 1.f; }
;                             else if (kind == 2) { v0[e] = sigmoidf_(v0[e]); v1[e] = sigmoidf_(v1[e]); }
;                             else if (kind == 3) { v0[e] = 0.60653066f * sigmoidf_(v0[e]); v1[e] = 0.60653066f * sigmoidf_(v1[e]); }
;                         }
;                     }
;                     u32x4 w; w.x = cvt_pk_bf16(v0[0], v0[1]); w.y = cvt_pk_bf16(v0[2], v0[3]); w.z = cvt_pk_bf16(v1[0], v1[1]); w.w = cvt_pk_bf16(v1[2], v1[3]);
;                     *(u32x4*)rowp = w; }
.LBB0_1922:
	s_andn2_saveexec_b64 s[34:35], s[34:35]
	v_exp_f32_e32 v134, v134
	s_nop 0
	v_add_f32_e32 v134, 1.0, v134
	v_rcp_f32_e32 v169, v134
	s_or_b64 exec, exec, s[34:35]
	v_pk_add_f32 v[124:125], v[124:125], v[108:109]
	v_lshl_add_u32 v160, s56, 8, v162
	v_mul_f32_e32 v124, 0xbfb8aa3b, v124
	v_exp_f32_e32 v124, v124
	v_cndmask_b32_e64 v159, v159, 0, s[2:3]
	v_cndmask_b32_e64 v158, v158, v144, s[2:3]
	v_ashrrev_i32_e32 v161, 31, v160
	v_add_f32_e32 v124, 1.0, v124
	v_readlane_b32 s2, v251, 42
	v_rcp_f32_e32 v124, v124
	v_lshlrev_b64 v[134:135], 12, v[160:161]
	v_readlane_b32 s3, v251, 43
	v_cvt_pk_bf16_f32 v170, v132, v129
	v_cvt_pk_bf16_f32 v171, v128, v131
	v_pk_add_f32 v[128:129], v[126:127], v[110:111]
	v_pk_add_f32 v[126:127], v[122:123], v[106:107]
	v_lshl_add_u64 v[134:135], s[2:3], 0, v[134:135]
	v_pk_add_f32 v[122:123], v[120:121], v[104:105]
	v_lshl_add_u64 v[174:175], v[158:159], 1, v[134:135]
	v_mul_f32_e32 v120, 0xbfb8aa3b, v122
	v_cvt_pk_bf16_f32 v172, v130, v133
	v_cvt_pk_bf16_f32 v173, v168, v169
	global_store_dwordx4 v[174:175], v[170:173], off sc1
	s_and_saveexec_b64 s[2:3], vcc
	s_xor_b64 s[2:3], exec, s[2:3]
	s_cbranch_execz .LBB0_1926
	v_exp_f32_e32 v120, v120
	v_mul_f32_e32 v124, 0x3f1b4598, v124
	v_add_f32_e32 v120, 1.0, v120
	v_rcp_f32_e32 v120, v120
	s_nop 0
	v_mul_f32_e32 v122, 0x3f1b4598, v120

; __device__ __forceinline__ unsigned cvt_pk_bf16(float lo, float hi) { unsigned r; asm volatile("v_cvt_pk_bf16_f32 %0, %1, %2" : "=v"(r) : "v"(lo), "v"(hi)); return r; }
; __device__ __forceinline__ float sigmoidf_(float x) { return __builtin_amdgcn_rcpf(1.f + __expf(-x)); }
;     __device__ __forceinline__ void operator()(const f32x4 (&acc)[2][2][4][2], const Unit& u, int wr, int wc, int fr, int fq) const {
;     ...
;             if (MODE == 2) { if (c < 1024) { kind = 3; b0 = *(const f32x4*)(p0 + c); b1 = *(const f32x4*)(p0 + c + 4); } else { kind = 2; b0 = *(const f32x4*)(p1 + c - 1024); b1 = *(const f32x4*)(p1 + c - 1024 + 4); } }
; #pragma unroll
;             for (int ai = 0; ai < 2; ++ai)
; #pragma unroll
;                 for (int m = 0; m < 4; ++m) { bf16_t* rowp = O + (size_t)(row0 + ai * HALF + m * 16) * ldc + c;
;                     f32x4 v0, v1;
;                     if (MODE == 3) { const float rstd = rs[ai * 4 + m]; v0 = acc[ai][bj][m][0] * rstd + b0; v1 = acc[ai][bj][m][1] * rstd + b1; }
;                     else { v0 = acc[ai][bj][m][0] + b0; v1 = acc[ai][bj][m][1] + b1; }
;                     if (MODE == 1 || MODE == 2) {
; #pragma unroll
;                         for (int e = 0; e < 4; ++e) {
;                             if (kind == 1) { v0[e] = 2.f * sigmoidf_(2.f * v0[e]) - 1.f; v1[e] = 2.f * sigmoidf_(2.f * v1[e]) - 1.f; }
;                             else if (kind == 2) { v0[e] = sigmoidf_(v0[e]); v1[e] = sigmoidf_(v1[e]); }
;                             else if (kind == 3) { v0[e] = 0.60653066f * sigmoidf_(v0[e]); v1[e] = 0.60653066f * sigmoidf_(v1[e]); }
;                         }
;                     }
;                     u32x4 w; w.x = cvt_pk_bf16(v0[0], v0[1]); w.y = cvt_pk_bf16(v0[2], v0[3]); w.z = cvt_pk_bf16(v1[0], v1[1]); w.w = cvt_pk_bf16(v1[2], v1[3]);
;                     *(u32x4*)rowp = w; }
.LBB0_1938:
	s_andn2_saveexec_b64 s[2:3], s[2:3]
	v_exp_f32_e32 v126, v126
	s_nop 0
	v_add_f32_e32 v126, 1.0, v126
	v_rcp_f32_e32 v129, v126
	s_or_b64 exec, exec, s[2:3]
	v_pk_add_f32 v[116:117], v[116:117], v[108:109]
	v_or_b32_e32 v126, 16, v160
	v_mul_f32_e32 v116, 0xbfb8aa3b, v116
	v_exp_f32_e32 v116, v116
	v_ashrrev_i32_e32 v127, 31, v126
	v_readlane_b32 s2, v251, 42
	v_lshlrev_b64 v[126:127], 12, v[126:127]
	v_add_f32_e32 v116, 1.0, v116
	v_rcp_f32_e32 v116, v116
	v_readlane_b32 s3, v251, 43
	v_cvt_pk_bf16_f32 v130, v124, v121
	v_cvt_pk_bf16_f32 v131, v120, v123
	v_pk_add_f32 v[120:121], v[118:119], v[110:111]
	v_pk_add_f32 v[118:119], v[114:115], v[106:107]
	v_lshl_add_u64 v[126:127], s[2:3], 0, v[126:127]
	v_pk_add_f32 v[114:115], v[112:113], v[104:105]
	v_lshl_add_u64 v[168:169], v[158:159], 1, v[126:127]
	v_mul_f32_e32 v112, 0xbfb8aa3b, v114
	v_cvt_pk_bf16_f32 v132, v122, v125
	v_cvt_pk_bf16_f32 v133, v128, v129
	global_store_dwordx4 v[168:169], v[130:133], off sc1
	s_and_saveexec_b64 s[2:3], vcc
	s_xor_b64 s[2:3], exec, s[2:3]
	s_cbranch_execz .LBB0_1942
	v_exp_f32_e32 v112, v112
	v_mul_f32_e32 v116, 0x3f1b4598, v116
	v_add_f32_e32 v112, 1.0, v112
	v_rcp_f32_e32 v112, v112
	s_nop 0
	v_mul_f32_e32 v114, 0x3f1b4598, v112

; __device__ __forceinline__ unsigned cvt_pk_bf16(float lo, float hi) { unsigned r; asm volatile("v_cvt_pk_bf16_f32 %0, %1, %2" : "=v"(r) : "v"(lo), "v"(hi)); return r; }
; __device__ __forceinline__ float sigmoidf_(float x) { return __builtin_amdgcn_rcpf(1.f + __expf(-x)); }
;     __device__ __forceinline__ void operator()(const f32x4 (&acc)[2][2][4][2], const Unit& u, int wr, int wc, int fr, int fq) const {
;     ...
;             if (MODE == 2) { if (c < 1024) { kind = 3; b0 = *(const f32x4*)(p0 + c); b1 = *(const f32x4*)(p0 + c + 4); } else { kind = 2; b0 = *(const f32x4*)(p1 + c - 1024); b1 = *(const f32x4*)(p1 + c - 1024 + 4); } }
; #pragma unroll
;             for (int ai = 0; ai < 2; ++ai)
; #pragma unroll
;                 for (int m = 0; m < 4; ++m) { bf16_t* rowp = O + (size_t)(row0 + ai * HALF + m * 16) * ldc + c;
;                     f32x4 v0, v1;
;                     if (MODE == 3) { const float rstd = rs[ai * 4 + m]; v0 = acc[ai][bj][m][0] * rstd + b0; v1 = acc[ai][bj][m][1] * rstd + b1; }
;                     else { v0 = acc[ai][bj][m][0] + b0; v1 = acc[ai][bj][m][1] + b1; }
;                     if (MODE == 1 || MODE == 2) {
; #pragma unroll
;                         for (int e = 0; e < 4; ++e) {
;                             if (kind == 1) { v0[e] = 2.f * sigmoidf_(2.f * v0[e]) - 1.f; v1[e] = 2.f * sigmoidf_(2.f * v1[e]) - 1.f; }
;                             else if (kind == 2) { v0[e] = sigmoidf_(v0[e]); v1[e] = sigmoidf_(v1[e]); }
;                             else if (kind == 3) { v0[e] = 0.60653066f * sigmoidf_(v0[e]); v1[e] = 0.60653066f * sigmoidf_(v1[e]); }
;                         }
;                     }
;                     u32x4 w; w.x = cvt_pk_bf16(v0[0], v0[1]); w.y = cvt_pk_bf16(v0[2], v0[3]); w.z = cvt_pk_bf16(v1[0], v1[1]); w.w = cvt_pk_bf16(v1[2], v1[3]);
;                     *(u32x4*)rowp = w; }
.LBB0_1954:
	s_andn2_saveexec_b64 s[2:3], s[2:3]
	v_exp_f32_e32 v118, v118
	s_nop 0
	v_add_f32_e32 v118, 1.0, v118
	v_rcp_f32_e32 v121, v118
	s_or_b64 exec, exec, s[2:3]
	v_pk_add_f32 v[100:101], v[100:101], v[108:109]
	v_or_b32_e32 v118, 32, v160
	v_mul_f32_e32 v100, 0xbfb8aa3b, v100
	v_exp_f32_e32 v100, v100
	v_ashrrev_i32_e32 v119, 31, v118
	v_readlane_b32 s2, v251, 42
	v_lshlrev_b64 v[118:119], 12, v[118:119]
	v_add_f32_e32 v100, 1.0, v100
	v_rcp_f32_e32 v100, v100
	v_readlane_b32 s3, v251, 43
	v_cvt_pk_bf16_f32 v122, v116, v113
	v_cvt_pk_bf16_f32 v123, v112, v115
	v_pk_add_f32 v[112:113], v[102:103], v[110:111]
	v_pk_add_f32 v[102:103], v[98:99], v[106:107]
	v_lshl_add_u64 v[118:119], s[2:3], 0, v[118:119]
	v_pk_add_f32 v[98:99], v[96:97], v[104:105]
	v_lshl_add_u64 v[128:129], v[158:159], 1, v[118:119]
	v_mul_f32_e32 v96, 0xbfb8aa3b, v98
	v_cvt_pk_bf16_f32 v124, v114, v117
	v_cvt_pk_bf16_f32 v125, v120, v121
	global_store_dwordx4 v[128:129], v[122:125], off sc1
	s_and_saveexec_b64 s[2:3], vcc
	s_xor_b64 s[2:3], exec, s[2:3]
	s_cbranch_execz .LBB0_1958
	v_exp_f32_e32 v96, v96
	v_mul_f32_e32 v100, 0x3f1b4598, v100
	v_add_f32_e32 v96, 1.0, v96
	v_rcp_f32_e32 v96, v96
	s_nop 0
	v_mul_f32_e32 v98, 0x3f1b4598, v96

; __device__ __forceinline__ unsigned cvt_pk_bf16(float lo, float hi) { unsigned r; asm volatile("v_cvt_pk_bf16_f32 %0, %1, %2" : "=v"(r) : "v"(lo), "v"(hi)); return r; }
; __device__ __forceinline__ float sigmoidf_(float x) { return __builtin_amdgcn_rcpf(1.f + __expf(-x)); }
;     __device__ __forceinline__ void operator()(const f32x4 (&acc)[2][2][4][2], const Unit& u, int wr, int wc, int fr, int fq) const {
;     ...
;             if (MODE == 2) { if (c < 1024) { kind = 3; b0 = *(const f32x4*)(p0 + c); b1 = *(const f32x4*)(p0 + c + 4); } else { kind = 2; b0 = *(const f32x4*)(p1 + c - 1024); b1 = *(const f32x4*)(p1 + c - 1024 + 4); } }
; #pragma unroll
;             for (int ai = 0; ai < 2; ++ai)
; #pragma unroll
;                 for (int m = 0; m < 4; ++m) { bf16_t* rowp = O + (size_t)(row0 + ai * HALF + m * 16) * ldc + c;
;                     f32x4 v0, v1;
;                     if (MODE == 3) { const float rstd = rs[ai * 4 + m]; v0 = acc[ai][bj][m][0] * rstd + b0; v1 = acc[ai][bj][m][1] * rstd + b1; }
;                     else { v0 = acc[ai][bj][m][0] + b0; v1 = acc[ai][bj][m][1] + b1; }
;                     if (MODE == 1 || MODE == 2) {
; #pragma unroll
;                         for (int e = 0; e < 4; ++e) {
;                             if (kind == 1) { v0[e] = 2.f * sigmoidf_(2.f * v0[e]) - 1.f; v1[e] = 2.f * sigmoidf_(2.f * v1[e]) - 1.f; }
;                             else if (kind == 2) { v0[e] = sigmoidf_(v0[e]); v1[e] = sigmoidf_(v1[e]); }
;                             else if (kind == 3) { v0[e] = 0.60653066f * sigmoidf_(v0[e]); v1[e] = 0.60653066f * sigmoidf_(v1[e]); }
;                         }
;                     }
;                     u32x4 w; w.x = cvt_pk_bf16(v0[0], v0[1]); w.y = cvt_pk_bf16(v0[2], v0[3]); w.z = cvt_pk_bf16(v1[0], v1[1]); w.w = cvt_pk_bf16(v1[2], v1[3]);
;                     *(u32x4*)rowp = w; }
.LBB0_1970:
	s_andn2_saveexec_b64 s[2:3], s[2:3]
	v_exp_f32_e32 v102, v102
	s_nop 0
	v_add_f32_e32 v102, 1.0, v102
	v_rcp_f32_e32 v113, v102
	s_or_b64 exec, exec, s[2:3]
	v_pk_add_f32 v[92:93], v[92:93], v[108:109]
	v_or_b32_e32 v102, 48, v160
	v_mul_f32_e32 v92, 0xbfb8aa3b, v92
	v_exp_f32_e32 v92, v92
	v_ashrrev_i32_e32 v103, 31, v102
	v_readlane_b32 s2, v251, 42
	v_lshlrev_b64 v[102:103], 12, v[102:103]
	v_add_f32_e32 v92, 1.0, v92
	v_rcp_f32_e32 v92, v92
	v_readlane_b32 s3, v251, 43
	v_cvt_pk_bf16_f32 v114, v100, v97
	v_cvt_pk_bf16_f32 v115, v96, v99
	v_pk_add_f32 v[96:97], v[94:95], v[110:111]
	v_pk_add_f32 v[94:95], v[90:91], v[106:107]
	v_lshl_add_u64 v[102:103], s[2:3], 0, v[102:103]
	v_pk_add_f32 v[90:91], v[88:89], v[104:105]
	v_lshl_add_u64 v[120:121], v[158:159], 1, v[102:103]
	v_mul_f32_e32 v88, 0xbfb8aa3b, v90
	v_cvt_pk_bf16_f32 v116, v98, v101
	v_cvt_pk_bf16_f32 v117, v112, v113
	global_store_dwordx4 v[120:121], v[114:117], off sc1
	s_and_saveexec_b64 s[2:3], vcc
	s_xor_b64 s[2:3], exec, s[2:3]
	s_cbranch_execz .LBB0_1974
	v_exp_f32_e32 v88, v88
	v_mul_f32_e32 v92, 0x3f1b4598, v92
	v_add_f32_e32 v88, 1.0, v88
	v_rcp_f32_e32 v88, v88
	s_nop 0
	v_mul_f32_e32 v90, 0x3f1b4598, v88

; __device__ __forceinline__ unsigned cvt_pk_bf16(float lo, float hi) { unsigned r; asm volatile("v_cvt_pk_bf16_f32 %0, %1, %2" : "=v"(r) : "v"(lo), "v"(hi)); return r; }
; __device__ __forceinline__ float sigmoidf_(float x) { return __builtin_amdgcn_rcpf(1.f + __expf(-x)); }
;     __device__ __forceinline__ void operator()(const f32x4 (&acc)[2][2][4][2], const Unit& u, int wr, int wc, int fr, int fq) const {
;     ...
;             if (MODE == 2) { if (c < 1024) { kind = 3; b0 = *(const f32x4*)(p0 + c); b1 = *(const f32x4*)(p0 + c + 4); } else { kind = 2; b0 = *(const f32x4*)(p1 + c - 1024); b1 = *(const f32x4*)(p1 + c - 1024 + 4); } }
; #pragma unroll
;             for (int ai = 0; ai < 2; ++ai)
; #pragma unroll
;                 for (int m = 0; m < 4; ++m) { bf16_t* rowp = O + (size_t)(row0 + ai * HALF + m * 16) * ldc + c;
;                     f32x4 v0, v1;
;                     if (MODE == 3) { const float rstd = rs[ai * 4 + m]; v0 = acc[ai][bj][m][0] * rstd + b0; v1 = acc[ai][bj][m][1] * rstd + b1; }
;                     else { v0 = acc[ai][bj][m][0] + b0; v1 = acc[ai][bj][m][1] + b1; }
;                     if (MODE == 1 || MODE == 2) {
; #pragma unroll
;                         for (int e = 0; e < 4; ++e) {
;                             if (kind == 1) { v0[e] = 2.f * sigmoidf_(2.f * v0[e]) - 1.f; v1[e] = 2.f * sigmoidf_(2.f * v1[e]) - 1.f; }
;                             else if (kind == 2) { v0[e] = sigmoidf_(v0[e]); v1[e] = sigmoidf_(v1[e]); }
;                             else if (kind == 3) { v0[e] = 0.60653066f * sigmoidf_(v0[e]); v1[e] = 0.60653066f * sigmoidf_(v1[e]); }
;                         }
;                     }
;                     u32x4 w; w.x = cvt_pk_bf16(v0[0], v0[1]); w.y = cvt_pk_bf16(v0[2], v0[3]); w.z = cvt_pk_bf16(v1[0], v1[1]); w.w = cvt_pk_bf16(v1[2], v1[3]);
;                     *(u32x4*)rowp = w; }
.LBB0_1986:
	s_andn2_saveexec_b64 s[2:3], s[2:3]
	v_exp_f32_e32 v94, v94
	s_nop 0
	v_add_f32_e32 v94, 1.0, v94
	v_rcp_f32_e32 v97, v94
	s_or_b64 exec, exec, s[2:3]
	v_pk_add_f32 v[84:85], v[84:85], v[108:109]
	v_readlane_b32 s2, v251, 42
	v_mul_f32_e32 v84, 0xbfb8aa3b, v84
	v_exp_f32_e32 v84, v84
	v_lshlrev_b64 v[94:95], 12, v[160:161]
	v_readlane_b32 s3, v251, 43
	v_cvt_pk_bf16_f32 v98, v92, v89
	v_add_f32_e32 v84, 1.0, v84
	v_rcp_f32_e32 v84, v84
	v_lshl_add_u64 v[94:95], s[2:3], 0, v[94:95]
	s_mov_b64 s[2:3], 0x80000
	v_lshl_add_u64 v[94:95], v[94:95], 0, s[2:3]
	v_cvt_pk_bf16_f32 v99, v88, v91
	v_pk_add_f32 v[88:89], v[86:87], v[110:111]
	v_pk_add_f32 v[86:87], v[82:83], v[106:107]
	v_pk_add_f32 v[82:83], v[80:81], v[104:105]
	v_lshl_add_u64 v[112:113], v[158:159], 1, v[94:95]
	v_mul_f32_e32 v80, 0xbfb8aa3b, v82
	v_cvt_pk_bf16_f32 v100, v90, v93
	v_cvt_pk_bf16_f32 v101, v96, v97
	global_store_dwordx4 v[112:113], v[98:101], off sc1
	s_and_saveexec_b64 s[2:3], vcc
	s_xor_b64 s[2:3], exec, s[2:3]
	s_cbranch_execz .LBB0_1990
	v_exp_f32_e32 v80, v80
	v_mul_f32_e32 v84, 0x3f1b4598, v84
	v_add_f32_e32 v80, 1.0, v80
	v_rcp_f32_e32 v80, v80
	s_nop 0
	v_mul_f32_e32 v82, 0x3f1b4598, v80

; __device__ __forceinline__ unsigned cvt_pk_bf16(float lo, float hi) { unsigned r; asm volatile("v_cvt_pk_bf16_f32 %0, %1, %2" : "=v"(r) : "v"(lo), "v"(hi)); return r; }
; __device__ __forceinline__ float sigmoidf_(float x) { return __builtin_amdgcn_rcpf(1.f + __expf(-x)); }
;     __device__ __forceinline__ void operator()(const f32x4 (&acc)[2][2][4][2], const Unit& u, int wr, int wc, int fr, int fq) const {
;     ...
;             if (MODE == 2) { if (c < 1024) { kind = 3; b0 = *(const f32x4*)(p0 + c); b1 = *(const f32x4*)(p0 + c + 4); } else { kind = 2; b0 = *(const f32x4*)(p1 + c - 1024); b1 = *(const f32x4*)(p1 + c - 1024 + 4); } }
; #pragma unroll
;             for (int ai = 0; ai < 2; ++ai)
; #pragma unroll
;                 for (int m = 0; m < 4; ++m) { bf16_t* rowp = O + (size_t)(row0 + ai * HALF + m * 16) * ldc + c;
;                     f32x4 v0, v1;
;                     if (MODE == 3) { const float rstd = rs[ai * 4 + m]; v0 = acc[ai][bj][m][0] * rstd + b0; v1 = acc[ai][bj][m][1] * rstd + b1; }
;                     else { v0 = acc[ai][bj][m][0] + b0; v1 = acc[ai][bj][m][1] + b1; }
;                     if (MODE == 1 || MODE == 2) {
; #pragma unroll
;                         for (int e = 0; e < 4; ++e) {
;                             if (kind == 1) { v0[e] = 2.f * sigmoidf_(2.f * v0[e]) - 1.f; v1[e] = 2.f * sigmoidf_(2.f * v1[e]) - 1.f; }
;                             else if (kind == 2) { v0[e] = sigmoidf_(v0[e]); v1[e] = sigmoidf_(v1[e]); }
;                             else if (kind == 3) { v0[e] = 0.60653066f * sigmoidf_(v0[e]); v1[e] = 0.60653066f * sigmoidf_(v1[e]); }
;                         }
;                     }
;                     u32x4 w; w.x = cvt_pk_bf16(v0[0], v0[1]); w.y = cvt_pk_bf16(v0[2], v0[3]); w.z = cvt_pk_bf16(v1[0], v1[1]); w.w = cvt_pk_bf16(v1[2], v1[3]);
;                     *(u32x4*)rowp = w; }
.LBB0_2002:
	s_andn2_saveexec_b64 s[2:3], s[2:3]
	v_exp_f32_e32 v86, v86
	s_nop 0
	v_add_f32_e32 v86, 1.0, v86
	v_rcp_f32_e32 v89, v86
	s_or_b64 exec, exec, s[2:3]
	v_pk_add_f32 v[76:77], v[76:77], v[108:109]
	v_readlane_b32 s2, v251, 42
	v_mul_f32_e32 v76, 0xbfb8aa3b, v76
	v_exp_f32_e32 v76, v76
	v_lshlrev_b64 v[86:87], 12, v[160:161]
	v_readlane_b32 s3, v251, 43
	v_cvt_pk_bf16_f32 v90, v84, v81
	v_add_f32_e32 v76, 1.0, v76
	v_rcp_f32_e32 v76, v76
	v_lshl_add_u64 v[86:87], s[2:3], 0, v[86:87]
	s_mov_b64 s[2:3], 0x90000
	v_lshl_add_u64 v[86:87], v[86:87], 0, s[2:3]
	v_cvt_pk_bf16_f32 v91, v80, v83
	v_pk_add_f32 v[80:81], v[78:79], v[110:111]
	v_pk_add_f32 v[78:79], v[74:75], v[106:107]
	v_pk_add_f32 v[74:75], v[72:73], v[104:105]
	v_lshl_add_u64 v[96:97], v[158:159], 1, v[86:87]
	v_mul_f32_e32 v72, 0xbfb8aa3b, v74
	v_cvt_pk_bf16_f32 v92, v82, v85
	v_cvt_pk_bf16_f32 v93, v88, v89
	global_store_dwordx4 v[96:97], v[90:93], off sc1
	s_and_saveexec_b64 s[2:3], vcc
	s_xor_b64 s[2:3], exec, s[2:3]
	s_cbranch_execz .LBB0_2006
	v_exp_f32_e32 v72, v72
	v_mul_f32_e32 v76, 0x3f1b4598, v76
	v_add_f32_e32 v72, 1.0, v72
	v_rcp_f32_e32 v72, v72
	s_nop 0
	v_mul_f32_e32 v74, 0x3f1b4598, v72

; __device__ __forceinline__ unsigned cvt_pk_bf16(float lo, float hi) { unsigned r; asm volatile("v_cvt_pk_bf16_f32 %0, %1, %2" : "=v"(r) : "v"(lo), "v"(hi)); return r; }
; __device__ __forceinline__ float sigmoidf_(float x) { return __builtin_amdgcn_rcpf(1.f + __expf(-x)); }
;     __device__ __forceinline__ void operator()(const f32x4 (&acc)[2][2][4][2], const Unit& u, int wr, int wc, int fr, int fq) const {
;     ...
;             if (MODE == 2) { if (c < 1024) { kind = 3; b0 = *(const f32x4*)(p0 + c); b1 = *(const f32x4*)(p0 + c + 4); } else { kind = 2; b0 = *(const f32x4*)(p1 + c - 1024); b1 = *(const f32x4*)(p1 + c - 1024 + 4); } }
; #pragma unroll
;             for (int ai = 0; ai < 2; ++ai)
; #pragma unroll
;                 for (int m = 0; m < 4; ++m) { bf16_t* rowp = O + (size_t)(row0 + ai * HALF + m * 16) * ldc + c;
;                     f32x4 v0, v1;
;                     if (MODE == 3) { const float rstd = rs[ai * 4 + m]; v0 = acc[ai][bj][m][0] * rstd + b0; v1 = acc[ai][bj][m][1] * rstd + b1; }
;                     else { v0 = acc[ai][bj][m][0] + b0; v1 = acc[ai][bj][m][1] + b1; }
;                     if (MODE == 1 || MODE == 2) {
; #pragma unroll
;                         for (int e = 0; e < 4; ++e) {
;                             if (kind == 1) { v0[e] = 2.f * sigmoidf_(2.f * v0[e]) - 1.f; v1[e] = 2.f * sigmoidf_(2.f * v1[e]) - 1.f; }
;                             else if (kind == 2) { v0[e] = sigmoidf_(v0[e]); v1[e] = sigmoidf_(v1[e]); }
;                             else if (kind == 3) { v0[e] = 0.60653066f * sigmoidf_(v0[e]); v1[e] = 0.60653066f * sigmoidf_(v1[e]); }
;                         }
;                     }
;                     u32x4 w; w.x = cvt_pk_bf16(v0[0], v0[1]); w.y = cvt_pk_bf16(v0[2], v0[3]); w.z = cvt_pk_bf16(v1[0], v1[1]); w.w = cvt_pk_bf16(v1[2], v1[3]);
;                     *(u32x4*)rowp = w; }
.LBB0_2018:
	s_andn2_saveexec_b64 s[2:3], s[2:3]
	v_exp_f32_e32 v78, v78
	s_nop 0
	v_add_f32_e32 v78, 1.0, v78
	v_rcp_f32_e32 v81, v78
	s_or_b64 exec, exec, s[2:3]
	v_pk_add_f32 v[68:69], v[68:69], v[108:109]
	v_readlane_b32 s2, v251, 42
	v_mul_f32_e32 v68, 0xbfb8aa3b, v68
	v_exp_f32_e32 v68, v68
	v_lshlrev_b64 v[78:79], 12, v[160:161]
	v_readlane_b32 s3, v251, 43
	v_cvt_pk_bf16_f32 v82, v76, v73
	v_add_f32_e32 v68, 1.0, v68
	v_rcp_f32_e32 v68, v68
	v_lshl_add_u64 v[78:79], s[2:3], 0, v[78:79]
	s_mov_b64 s[2:3], 0xa0000
	v_lshl_add_u64 v[78:79], v[78:79], 0, s[2:3]
	v_cvt_pk_bf16_f32 v83, v72, v75
	v_pk_add_f32 v[72:73], v[70:71], v[110:111]
	v_pk_add_f32 v[70:71], v[66:67], v[106:107]
	v_pk_add_f32 v[66:67], v[64:65], v[104:105]
	v_lshl_add_u64 v[88:89], v[158:159], 1, v[78:79]
	v_mul_f32_e32 v64, 0xbfb8aa3b, v66
	v_cvt_pk_bf16_f32 v84, v74, v77
	v_cvt_pk_bf16_f32 v85, v80, v81
	global_store_dwordx4 v[88:89], v[82:85], off sc1
	s_and_saveexec_b64 s[2:3], vcc
	s_xor_b64 s[2:3], exec, s[2:3]
	s_cbranch_execz .LBB0_2022
	v_exp_f32_e32 v64, v64
	v_mul_f32_e32 v68, 0x3f1b4598, v68
	v_add_f32_e32 v64, 1.0, v64
	v_rcp_f32_e32 v64, v64
	s_nop 0
	v_mul_f32_e32 v66, 0x3f1b4598, v64

; __device__ __forceinline__ unsigned cvt_pk_bf16(float lo, float hi) { unsigned r; asm volatile("v_cvt_pk_bf16_f32 %0, %1, %2" : "=v"(r) : "v"(lo), "v"(hi)); return r; }
; __device__ __forceinline__ float sigmoidf_(float x) { return __builtin_amdgcn_rcpf(1.f + __expf(-x)); }
;     __device__ __forceinline__ void operator()(const f32x4 (&acc)[2][2][4][2], const Unit& u, int wr, int wc, int fr, int fq) const {
;     ...
;             if (MODE == 3) { b0 = *(const f32x4*)(p1 + (size_t)(u.pm >> 4) * ldc + c); b1 = *(const f32x4*)(p1 + (size_t)(u.pm >> 4) * ldc + c + 4); }
;             if (MODE == 2) { if (c < 1024) { kind = 3; b0 = *(const f32x4*)(p0 + c); b1 = *(const f32x4*)(p0 + c + 4); } else { kind = 2; b0 = *(const f32x4*)(p1 + c - 1024); b1 = *(const f32x4*)(p1 + c - 1024 + 4); } }
; #pragma unroll
;             for (int ai = 0; ai < 2; ++ai)
; #pragma unroll
;                 for (int m = 0; m < 4; ++m) { bf16_t* rowp = O + (size_t)(row0 + ai * HALF + m * 16) * ldc + c;
;                     f32x4 v0, v1;
;                     if (MODE == 3) { const float rstd = rs[ai * 4 + m]; v0 = acc[ai][bj][m][0] * rstd + b0; v1 = acc[ai][bj][m][1] * rstd + b1; }
;                     else { v0 = acc[ai][bj][m][0] + b0; v1 = acc[ai][bj][m][1] + b1; }
;                     if (MODE == 1 || MODE == 2) {
; #pragma unroll
;                         for (int e = 0; e < 4; ++e) {
;                             if (kind == 1) { v0[e] = 2.f * sigmoidf_(2.f * v0[e]) - 1.f; v1[e] = 2.f * sigmoidf_(2.f * v1[e]) - 1.f; }
;                             else if (kind == 2) { v0[e] = sigmoidf_(v0[e]); v1[e] = sigmoidf_(v1[e]); }
;                             else if (kind == 3) { v0[e] = 0.60653066f * sigmoidf_(v0[e]); v1[e] = 0.60653066f * sigmoidf_(v1[e]); }
;                         }
;                     }
;                     u32x4 w; w.x = cvt_pk_bf16(v0[0], v0[1]); w.y = cvt_pk_bf16(v0[2], v0[3]); w.z = cvt_pk_bf16(v1[0], v1[1]); w.w = cvt_pk_bf16(v1[2], v1[3]);
;                     *(u32x4*)rowp = w; }
.LBB0_2034:
	s_andn2_saveexec_b64 s[2:3], s[2:3]
	v_exp_f32_e32 v71, v72
	s_nop 0
	v_add_f32_e32 v71, 1.0, v71
	v_rcp_f32_e32 v71, v71
	s_or_b64 exec, exec, s[2:3]
	v_readlane_b32 s2, v251, 42
	v_lshlrev_b64 v[72:73], 12, v[160:161]
	v_readlane_b32 s3, v251, 43
	v_cvt_pk_bf16_f32 v74, v68, v65
	v_cvt_pk_bf16_f32 v75, v64, v67
	v_cvt_pk_bf16_f32 v76, v66, v69
	v_cvt_pk_bf16_f32 v77, v70, v71
	s_nop 1
	v_lshl_add_u64 v[72:73], s[2:3], 0, v[72:73]
	s_mov_b64 s[2:3], 0xb0000
	v_lshl_add_u64 v[72:73], v[72:73], 0, s[2:3]
	s_movk_i32 s2, 0xf200
	v_lshl_add_u64 v[80:81], v[158:159], 1, v[72:73]
	s_mov_b32 s3, -1
	global_store_dwordx4 v[80:81], v[74:77], off sc1
	v_lshl_add_u64 v[64:65], v[154:155], 0, s[2:3]
	s_mov_b64 s[2:3], 0x200
	v_or_b32_e32 v74, 0x80, v144
	v_lshl_add_u64 v[66:67], v[156:157], 0, s[2:3]
	v_cmp_lt_i32_e64 s[2:3], s53, v74
	v_cmp_gt_i32_e32 vcc, s40, v74
	s_nop 0
	v_cndmask_b32_e64 v65, v67, v65, s[2:3]
	v_cndmask_b32_e64 v64, v66, v64, s[2:3]
	global_load_dwordx4 v[68:71], v[64:65], off
	s_nop 0
	global_load_dwordx4 v[64:67], v[64:65], off offset:16
	s_waitcnt vmcnt(0)
	v_pk_add_f32 v[60:61], v[60:61], v[68:69]
	s_nop 0
	v_mul_f32_e32 v60, 0xbfb8aa3b, v60
	v_exp_f32_e32 v60, v60
	v_pk_add_f32 v[76:77], v[62:63], v[70:71]
	v_pk_add_f32 v[62:63], v[58:59], v[66:67]
	v_pk_add_f32 v[58:59], v[56:57], v[64:65]
	v_add_f32_e32 v60, 1.0, v60
	v_rcp_f32_e32 v60, v60
	v_mul_f32_e32 v56, 0xbfb8aa3b, v58
	s_and_saveexec_b64 s[34:35], vcc
	s_xor_b64 s[34:35], exec, s[34:35]
	s_cbranch_execz .LBB0_2038
	v_exp_f32_e32 v56, v56
	v_mul_f32_e32 v60, 0x3f1b4598, v60
	v_add_f32_e32 v56, 1.0, v56
	v_rcp_f32_e32 v56, v56
	s_nop 0
	v_mul_f32_e32 v58, 0x3f1b4598, v56

; __device__ __forceinline__ unsigned cvt_pk_bf16(float lo, float hi) { unsigned r; asm volatile("v_cvt_pk_bf16_f32 %0, %1, %2" : "=v"(r) : "v"(lo), "v"(hi)); return r; }
; __device__ __forceinline__ float sigmoidf_(float x) { return __builtin_amdgcn_rcpf(1.f + __expf(-x)); }
;     __device__ __forceinline__ void operator()(const f32x4 (&acc)[2][2][4][2], const Unit& u, int wr, int wc, int fr, int fq) const {
;     ...
;             if (MODE == 2) { if (c < 1024) { kind = 3; b0 = *(const f32x4*)(p0 + c); b1 = *(const f32x4*)(p0 + c + 4); } else { kind = 2; b0 = *(const f32x4*)(p1 + c - 1024); b1 = *(const f32x4*)(p1 + c - 1024 + 4); } }
; #pragma unroll
;             for (int ai = 0; ai < 2; ++ai)
; #pragma unroll
;                 for (int m = 0; m < 4; ++m) { bf16_t* rowp = O + (size_t)(row0 + ai * HALF + m * 16) * ldc + c;
;                     f32x4 v0, v1;
;                     if (MODE == 3) { const float rstd = rs[ai * 4 + m]; v0 = acc[ai][bj][m][0] * rstd + b0; v1 = acc[ai][bj][m][1] * rstd + b1; }
;                     else { v0 = acc[ai][bj][m][0] + b0; v1 = acc[ai][bj][m][1] + b1; }
;                     if (MODE == 1 || MODE == 2) {
; #pragma unroll
;                         for (int e = 0; e < 4; ++e) {
;                             if (kind == 1) { v0[e] = 2.f * sigmoidf_(2.f * v0[e]) - 1.f; v1[e] = 2.f * sigmoidf_(2.f * v1[e]) - 1.f; }
;                             else if (kind == 2) { v0[e] = sigmoidf_(v0[e]); v1[e] = sigmoidf_(v1[e]); }
;                             else if (kind == 3) { v0[e] = 0.60653066f * sigmoidf_(v0[e]); v1[e] = 0.60653066f * sigmoidf_(v1[e]); }
;                         }
;                     }
;                     u32x4 w; w.x = cvt_pk_bf16(v0[0], v0[1]); w.y = cvt_pk_bf16(v0[2], v0[3]); w.z = cvt_pk_bf16(v1[0], v1[1]); w.w = cvt_pk_bf16(v1[2], v1[3]);
;                     *(u32x4*)rowp = w; }
.LBB0_2050:
	s_andn2_saveexec_b64 s[34:35], s[34:35]
	v_exp_f32_e32 v63, v75
	s_nop 0
	v_add_f32_e32 v63, 1.0, v63
	v_rcp_f32_e32 v63, v63
	s_or_b64 exec, exec, s[34:35]
	v_pk_add_f32 v[52:53], v[52:53], v[68:69]
	v_ashrrev_i32_e32 v75, 31, v74
	v_mul_f32_e32 v52, 0xbfb8aa3b, v52
	v_exp_f32_e32 v52, v52
	v_cndmask_b32_e64 v75, v75, 0, s[2:3]
	v_cvt_pk_bf16_f32 v80, v60, v57
	v_cvt_pk_bf16_f32 v81, v56, v59
	v_add_f32_e32 v52, 1.0, v52
	v_rcp_f32_e32 v52, v52
	v_pk_add_f32 v[56:57], v[54:55], v[70:71]
	v_pk_add_f32 v[54:55], v[50:51], v[66:67]
	v_pk_add_f32 v[50:51], v[48:49], v[64:65]
	v_lshl_add_u64 v[76:77], v[74:75], 1, v[134:135]
	v_mul_f32_e32 v48, 0xbfb8aa3b, v50
	v_cvt_pk_bf16_f32 v82, v58, v61
	v_cvt_pk_bf16_f32 v83, v62, v63
	global_store_dwordx4 v[76:77], v[80:83], off sc1
	s_and_saveexec_b64 s[2:3], vcc
	s_xor_b64 s[2:3], exec, s[2:3]
	s_cbranch_execz .LBB0_2054
	v_exp_f32_e32 v48, v48
	v_mul_f32_e32 v52, 0x3f1b4598, v52
	v_add_f32_e32 v48, 1.0, v48
	v_rcp_f32_e32 v48, v48
	s_nop 0
	v_mul_f32_e32 v50, 0x3f1b4598, v48

; __device__ __forceinline__ unsigned cvt_pk_bf16(float lo, float hi) { unsigned r; asm volatile("v_cvt_pk_bf16_f32 %0, %1, %2" : "=v"(r) : "v"(lo), "v"(hi)); return r; }
; __device__ __forceinline__ float sigmoidf_(float x) { return __builtin_amdgcn_rcpf(1.f + __expf(-x)); }
;     __device__ __forceinline__ void operator()(const f32x4 (&acc)[2][2][4][2], const Unit& u, int wr, int wc, int fr, int fq) const {
;     ...
;             if (MODE == 2) { if (c < 1024) { kind = 3; b0 = *(const f32x4*)(p0 + c); b1 = *(const f32x4*)(p0 + c + 4); } else { kind = 2; b0 = *(const f32x4*)(p1 + c - 1024); b1 = *(const f32x4*)(p1 + c - 1024 + 4); } }
; #pragma unroll
;             for (int ai = 0; ai < 2; ++ai)
; #pragma unroll
;                 for (int m = 0; m < 4; ++m) { bf16_t* rowp = O + (size_t)(row0 + ai * HALF + m * 16) * ldc + c;
;                     f32x4 v0, v1;
;                     if (MODE == 3) { const float rstd = rs[ai * 4 + m]; v0 = acc[ai][bj][m][0] * rstd + b0; v1 = acc[ai][bj][m][1] * rstd + b1; }
;                     else { v0 = acc[ai][bj][m][0] + b0; v1 = acc[ai][bj][m][1] + b1; }
;                     if (MODE == 1 || MODE == 2) {
; #pragma unroll
;                         for (int e = 0; e < 4; ++e) {
;                             if (kind == 1) { v0[e] = 2.f * sigmoidf_(2.f * v0[e]) - 1.f; v1[e] = 2.f * sigmoidf_(2.f * v1[e]) - 1.f; }
;                             else if (kind == 2) { v0[e] = sigmoidf_(v0[e]); v1[e] = sigmoidf_(v1[e]); }
;                             else if (kind == 3) { v0[e] = 0.60653066f * sigmoidf_(v0[e]); v1[e] = 0.60653066f * sigmoidf_(v1[e]); }
;                         }
;                     }
;                     u32x4 w; w.x = cvt_pk_bf16(v0[0], v0[1]); w.y = cvt_pk_bf16(v0[2], v0[3]); w.z = cvt_pk_bf16(v1[0], v1[1]); w.w = cvt_pk_bf16(v1[2], v1[3]);
;                     *(u32x4*)rowp = w; }
.LBB0_2066:
	s_andn2_saveexec_b64 s[2:3], s[2:3]
	v_exp_f32_e32 v55, v56
	s_nop 0
	v_add_f32_e32 v55, 1.0, v55
	v_rcp_f32_e32 v55, v55
	s_or_b64 exec, exec, s[2:3]
	v_pk_add_f32 v[44:45], v[44:45], v[68:69]
	v_cvt_pk_bf16_f32 v56, v52, v49
	v_cvt_pk_bf16_f32 v57, v48, v51
	v_pk_add_f32 v[48:49], v[46:47], v[70:71]
	v_mul_f32_e32 v44, 0xbfb8aa3b, v44
	v_exp_f32_e32 v44, v44
	v_pk_add_f32 v[46:47], v[42:43], v[66:67]
	v_pk_add_f32 v[42:43], v[40:41], v[64:65]
	v_lshl_add_u64 v[60:61], v[74:75], 1, v[126:127]
	v_add_f32_e32 v44, 1.0, v44
	v_rcp_f32_e32 v44, v44
	v_mul_f32_e32 v40, 0xbfb8aa3b, v42
	v_cvt_pk_bf16_f32 v58, v50, v53
	v_cvt_pk_bf16_f32 v59, v54, v55
	global_store_dwordx4 v[60:61], v[56:59], off sc1
	s_and_saveexec_b64 s[2:3], vcc
	s_xor_b64 s[2:3], exec, s[2:3]
	s_cbranch_execz .LBB0_2070
	v_exp_f32_e32 v40, v40
	v_mul_f32_e32 v44, 0x3f1b4598, v44
	v_add_f32_e32 v40, 1.0, v40
	v_rcp_f32_e32 v40, v40
	s_nop 0
	v_mul_f32_e32 v42, 0x3f1b4598, v40

; __device__ __forceinline__ unsigned cvt_pk_bf16(float lo, float hi) { unsigned r; asm volatile("v_cvt_pk_bf16_f32 %0, %1, %2" : "=v"(r) : "v"(lo), "v"(hi)); return r; }
; __device__ __forceinline__ float sigmoidf_(float x) { return __builtin_amdgcn_rcpf(1.f + __expf(-x)); }
;     __device__ __forceinline__ void operator()(const f32x4 (&acc)[2][2][4][2], const Unit& u, int wr, int wc, int fr, int fq) const {
;     ...
;             if (MODE == 2) { if (c < 1024) { kind = 3; b0 = *(const f32x4*)(p0 + c); b1 = *(const f32x4*)(p0 + c + 4); } else { kind = 2; b0 = *(const f32x4*)(p1 + c - 1024); b1 = *(const f32x4*)(p1 + c - 1024 + 4); } }
; #pragma unroll
;             for (int ai = 0; ai < 2; ++ai)
; #pragma unroll
;                 for (int m = 0; m < 4; ++m) { bf16_t* rowp = O + (size_t)(row0 + ai * HALF + m * 16) * ldc + c;
;                     f32x4 v0, v1;
;                     if (MODE == 3) { const float rstd = rs[ai * 4 + m]; v0 = acc[ai][bj][m][0] * rstd + b0; v1 = acc[ai][bj][m][1] * rstd + b1; }
;                     else { v0 = acc[ai][bj][m][0] + b0; v1 = acc[ai][bj][m][1] + b1; }
;                     if (MODE == 1 || MODE == 2) {
; #pragma unroll
;                         for (int e = 0; e < 4; ++e) {
;                             if (kind == 1) { v0[e] = 2.f * sigmoidf_(2.f * v0[e]) - 1.f; v1[e] = 2.f * sigmoidf_(2.f * v1[e]) - 1.f; }
;                             else if (kind == 2) { v0[e] = sigmoidf_(v0[e]); v1[e] = sigmoidf_(v1[e]); }
;                             else if (kind == 3) { v0[e] = 0.60653066f * sigmoidf_(v0[e]); v1[e] = 0.60653066f * sigmoidf_(v1[e]); }
;                         }
;                     }
;                     u32x4 w; w.x = cvt_pk_bf16(v0[0], v0[1]); w.y = cvt_pk_bf16(v0[2], v0[3]); w.z = cvt_pk_bf16(v1[0], v1[1]); w.w = cvt_pk_bf16(v1[2], v1[3]);
;                     *(u32x4*)rowp = w; }
.LBB0_2082:
	s_andn2_saveexec_b64 s[2:3], s[2:3]
	v_exp_f32_e32 v47, v48
	s_nop 0
	v_add_f32_e32 v47, 1.0, v47
	v_rcp_f32_e32 v47, v47
	s_or_b64 exec, exec, s[2:3]
	v_pk_add_f32 v[36:37], v[36:37], v[68:69]
	v_cvt_pk_bf16_f32 v48, v44, v41
	v_cvt_pk_bf16_f32 v49, v40, v43
	v_pk_add_f32 v[40:41], v[38:39], v[70:71]
	v_mul_f32_e32 v36, 0xbfb8aa3b, v36
	v_exp_f32_e32 v36, v36
	v_pk_add_f32 v[38:39], v[34:35], v[66:67]
	v_pk_add_f32 v[34:35], v[32:33], v[64:65]
	v_lshl_add_u64 v[52:53], v[74:75], 1, v[118:119]
	v_add_f32_e32 v36, 1.0, v36
	v_rcp_f32_e32 v36, v36
	v_mul_f32_e32 v32, 0xbfb8aa3b, v34
	v_cvt_pk_bf16_f32 v50, v42, v45
	v_cvt_pk_bf16_f32 v51, v46, v47
	global_store_dwordx4 v[52:53], v[48:51], off sc1
	s_and_saveexec_b64 s[2:3], vcc
	s_xor_b64 s[2:3], exec, s[2:3]
	s_cbranch_execz .LBB0_2086
	v_exp_f32_e32 v32, v32
	v_mul_f32_e32 v36, 0x3f1b4598, v36
	v_add_f32_e32 v32, 1.0, v32
	v_rcp_f32_e32 v32, v32
	s_nop 0
	v_mul_f32_e32 v34, 0x3f1b4598, v32

; __device__ __forceinline__ unsigned cvt_pk_bf16(float lo, float hi) { unsigned r; asm volatile("v_cvt_pk_bf16_f32 %0, %1, %2" : "=v"(r) : "v"(lo), "v"(hi)); return r; }
; __device__ __forceinline__ float sigmoidf_(float x) { return __builtin_amdgcn_rcpf(1.f + __expf(-x)); }
;     __device__ __forceinline__ void operator()(const f32x4 (&acc)[2][2][4][2], const Unit& u, int wr, int wc, int fr, int fq) const {
;     ...
;             if (MODE == 2) { if (c < 1024) { kind = 3; b0 = *(const f32x4*)(p0 + c); b1 = *(const f32x4*)(p0 + c + 4); } else { kind = 2; b0 = *(const f32x4*)(p1 + c - 1024); b1 = *(const f32x4*)(p1 + c - 1024 + 4); } }
; #pragma unroll
;             for (int ai = 0; ai < 2; ++ai)
; #pragma unroll
;                 for (int m = 0; m < 4; ++m) { bf16_t* rowp = O + (size_t)(row0 + ai * HALF + m * 16) * ldc + c;
;                     f32x4 v0, v1;
;                     if (MODE == 3) { const float rstd = rs[ai * 4 + m]; v0 = acc[ai][bj][m][0] * rstd + b0; v1 = acc[ai][bj][m][1] * rstd + b1; }
;                     else { v0 = acc[ai][bj][m][0] + b0; v1 = acc[ai][bj][m][1] + b1; }
;                     if (MODE == 1 || MODE == 2) {
; #pragma unroll
;                         for (int e = 0; e < 4; ++e) {
;                             if (kind == 1) { v0[e] = 2.f * sigmoidf_(2.f * v0[e]) - 1.f; v1[e] = 2.f * sigmoidf_(2.f * v1[e]) - 1.f; }
;                             else if (kind == 2) { v0[e] = sigmoidf_(v0[e]); v1[e] = sigmoidf_(v1[e]); }
;                             else if (kind == 3) { v0[e] = 0.60653066f * sigmoidf_(v0[e]); v1[e] = 0.60653066f * sigmoidf_(v1[e]); }
;                         }
;                     }
;                     u32x4 w; w.x = cvt_pk_bf16(v0[0], v0[1]); w.y = cvt_pk_bf16(v0[2], v0[3]); w.z = cvt_pk_bf16(v1[0], v1[1]); w.w = cvt_pk_bf16(v1[2], v1[3]);
;                     *(u32x4*)rowp = w; }
.LBB0_2098:
	s_andn2_saveexec_b64 s[2:3], s[2:3]
	v_exp_f32_e32 v39, v40
	s_nop 0
	v_add_f32_e32 v39, 1.0, v39
	v_rcp_f32_e32 v39, v39
	s_or_b64 exec, exec, s[2:3]
	v_pk_add_f32 v[28:29], v[28:29], v[68:69]
	v_cvt_pk_bf16_f32 v40, v36, v33
	v_cvt_pk_bf16_f32 v41, v32, v35
	v_pk_add_f32 v[32:33], v[30:31], v[70:71]
	v_mul_f32_e32 v28, 0xbfb8aa3b, v28
	v_exp_f32_e32 v28, v28
	v_pk_add_f32 v[30:31], v[26:27], v[66:67]
	v_pk_add_f32 v[26:27], v[24:25], v[64:65]
	v_lshl_add_u64 v[44:45], v[74:75], 1, v[102:103]
	v_add_f32_e32 v28, 1.0, v28
	v_rcp_f32_e32 v28, v28
	v_mul_f32_e32 v24, 0xbfb8aa3b, v26
	v_cvt_pk_bf16_f32 v42, v34, v37
	v_cvt_pk_bf16_f32 v43, v38, v39
	global_store_dwordx4 v[44:45], v[40:43], off sc1
	s_and_saveexec_b64 s[2:3], vcc
	s_xor_b64 s[2:3], exec, s[2:3]
	s_cbranch_execz .LBB0_2102
	v_exp_f32_e32 v24, v24
	v_mul_f32_e32 v28, 0x3f1b4598, v28
	v_add_f32_e32 v24, 1.0, v24
	v_rcp_f32_e32 v24, v24
	s_nop 0
	v_mul_f32_e32 v26, 0x3f1b4598, v24

; __device__ __forceinline__ unsigned cvt_pk_bf16(float lo, float hi) { unsigned r; asm volatile("v_cvt_pk_bf16_f32 %0, %1, %2" : "=v"(r) : "v"(lo), "v"(hi)); return r; }
; __device__ __forceinline__ float sigmoidf_(float x) { return __builtin_amdgcn_rcpf(1.f + __expf(-x)); }
;     __device__ __forceinline__ void operator()(const f32x4 (&acc)[2][2][4][2], const Unit& u, int wr, int wc, int fr, int fq) const {
;     ...
;             if (MODE == 2) { if (c < 1024) { kind = 3; b0 = *(const f32x4*)(p0 + c); b1 = *(const f32x4*)(p0 + c + 4); } else { kind = 2; b0 = *(const f32x4*)(p1 + c - 1024); b1 = *(const f32x4*)(p1 + c - 1024 + 4); } }
; #pragma unroll
;             for (int ai = 0; ai < 2; ++ai)
; #pragma unroll
;                 for (int m = 0; m < 4; ++m) { bf16_t* rowp = O + (size_t)(row0 + ai * HALF + m * 16) * ldc + c;
;                     f32x4 v0, v1;
;                     if (MODE == 3) { const float rstd = rs[ai * 4 + m]; v0 = acc[ai][bj][m][0] * rstd + b0; v1 = acc[ai][bj][m][1] * rstd + b1; }
;                     else { v0 = acc[ai][bj][m][0] + b0; v1 = acc[ai][bj][m][1] + b1; }
;                     if (MODE == 1 || MODE == 2) {
; #pragma unroll
;                         for (int e = 0; e < 4; ++e) {
;                             if (kind == 1) { v0[e] = 2.f * sigmoidf_(2.f * v0[e]) - 1.f; v1[e] = 2.f * sigmoidf_(2.f * v1[e]) - 1.f; }
;                             else if (kind == 2) { v0[e] = sigmoidf_(v0[e]); v1[e] = sigmoidf_(v1[e]); }
;                             else if (kind == 3) { v0[e] = 0.60653066f * sigmoidf_(v0[e]); v1[e] = 0.60653066f * sigmoidf_(v1[e]); }
;                         }
;                     }
;                     u32x4 w; w.x = cvt_pk_bf16(v0[0], v0[1]); w.y = cvt_pk_bf16(v0[2], v0[3]); w.z = cvt_pk_bf16(v1[0], v1[1]); w.w = cvt_pk_bf16(v1[2], v1[3]);
;                     *(u32x4*)rowp = w; }
.LBB0_2114:
	s_andn2_saveexec_b64 s[2:3], s[2:3]
	v_exp_f32_e32 v31, v32
	s_nop 0
	v_add_f32_e32 v31, 1.0, v31
	v_rcp_f32_e32 v31, v31
	s_or_b64 exec, exec, s[2:3]
	v_pk_add_f32 v[20:21], v[20:21], v[68:69]
	v_cvt_pk_bf16_f32 v32, v28, v25
	v_cvt_pk_bf16_f32 v33, v24, v27
	v_pk_add_f32 v[24:25], v[22:23], v[70:71]
	v_mul_f32_e32 v20, 0xbfb8aa3b, v20
	v_exp_f32_e32 v20, v20
	v_pk_add_f32 v[22:23], v[18:19], v[66:67]
	v_pk_add_f32 v[18:19], v[16:17], v[64:65]
	v_lshl_add_u64 v[36:37], v[74:75], 1, v[94:95]
	v_add_f32_e32 v20, 1.0, v20
	v_rcp_f32_e32 v20, v20
	v_mul_f32_e32 v16, 0xbfb8aa3b, v18
	v_cvt_pk_bf16_f32 v34, v26, v29
	v_cvt_pk_bf16_f32 v35, v30, v31
	global_store_dwordx4 v[36:37], v[32:35], off sc1
	s_and_saveexec_b64 s[2:3], vcc
	s_xor_b64 s[2:3], exec, s[2:3]
	s_cbranch_execz .LBB0_2118
	v_exp_f32_e32 v16, v16
	v_mul_f32_e32 v20, 0x3f1b4598, v20
	v_add_f32_e32 v16, 1.0, v16
	v_rcp_f32_e32 v16, v16
	s_nop 0
	v_mul_f32_e32 v18, 0x3f1b4598, v16

; __device__ __forceinline__ unsigned cvt_pk_bf16(float lo, float hi) { unsigned r; asm volatile("v_cvt_pk_bf16_f32 %0, %1, %2" : "=v"(r) : "v"(lo), "v"(hi)); return r; }
; __device__ __forceinline__ float sigmoidf_(float x) { return __builtin_amdgcn_rcpf(1.f + __expf(-x)); }
;     __device__ __forceinline__ void operator()(const f32x4 (&acc)[2][2][4][2], const Unit& u, int wr, int wc, int fr, int fq) const {
;     ...
;             if (MODE == 2) { if (c < 1024) { kind = 3; b0 = *(const f32x4*)(p0 + c); b1 = *(const f32x4*)(p0 + c + 4); } else { kind = 2; b0 = *(const f32x4*)(p1 + c - 1024); b1 = *(const f32x4*)(p1 + c - 1024 + 4); } }
; #pragma unroll
;             for (int ai = 0; ai < 2; ++ai)
; #pragma unroll
;                 for (int m = 0; m < 4; ++m) { bf16_t* rowp = O + (size_t)(row0 + ai * HALF + m * 16) * ldc + c;
;                     f32x4 v0, v1;
;                     if (MODE == 3) { const float rstd = rs[ai * 4 + m]; v0 = acc[ai][bj][m][0] * rstd + b0; v1 = acc[ai][bj][m][1] * rstd + b1; }
;                     else { v0 = acc[ai][bj][m][0] + b0; v1 = acc[ai][bj][m][1] + b1; }
;                     if (MODE == 1 || MODE == 2) {
; #pragma unroll
;                         for (int e = 0; e < 4; ++e) {
;                             if (kind == 1) { v0[e] = 2.f * sigmoidf_(2.f * v0[e]) - 1.f; v1[e] = 2.f * sigmoidf_(2.f * v1[e]) - 1.f; }
;                             else if (kind == 2) { v0[e] = sigmoidf_(v0[e]); v1[e] = sigmoidf_(v1[e]); }
;                             else if (kind == 3) { v0[e] = 0.60653066f * sigmoidf_(v0[e]); v1[e] = 0.60653066f * sigmoidf_(v1[e]); }
;                         }
;                     }
;                     u32x4 w; w.x = cvt_pk_bf16(v0[0], v0[1]); w.y = cvt_pk_bf16(v0[2], v0[3]); w.z = cvt_pk_bf16(v1[0], v1[1]); w.w = cvt_pk_bf16(v1[2], v1[3]);
;                     *(u32x4*)rowp = w; }
.LBB0_2130:
	s_andn2_saveexec_b64 s[2:3], s[2:3]
	v_exp_f32_e32 v23, v24
	s_nop 0
	v_add_f32_e32 v23, 1.0, v23
	v_rcp_f32_e32 v23, v23
	s_or_b64 exec, exec, s[2:3]
	v_pk_add_f32 v[12:13], v[12:13], v[68:69]
	v_cvt_pk_bf16_f32 v24, v20, v17
	v_cvt_pk_bf16_f32 v25, v16, v19
	v_pk_add_f32 v[16:17], v[14:15], v[70:71]
	v_mul_f32_e32 v12, 0xbfb8aa3b, v12
	v_exp_f32_e32 v12, v12
	v_pk_add_f32 v[14:15], v[10:11], v[66:67]
	v_pk_add_f32 v[10:11], v[8:9], v[64:65]
	v_lshl_add_u64 v[28:29], v[74:75], 1, v[86:87]
	v_add_f32_e32 v12, 1.0, v12
	v_rcp_f32_e32 v12, v12
	v_mul_f32_e32 v8, 0xbfb8aa3b, v10
	v_cvt_pk_bf16_f32 v26, v18, v21
	v_cvt_pk_bf16_f32 v27, v22, v23
	global_store_dwordx4 v[28:29], v[24:27], off sc1
	s_and_saveexec_b64 s[2:3], vcc
	s_xor_b64 s[2:3], exec, s[2:3]
	s_cbranch_execz .LBB0_2134
	v_exp_f32_e32 v8, v8
	v_mul_f32_e32 v12, 0x3f1b4598, v12
	v_add_f32_e32 v8, 1.0, v8
	v_rcp_f32_e32 v8, v8
	s_nop 0
	v_mul_f32_e32 v10, 0x3f1b4598, v8

; __device__ __forceinline__ unsigned cvt_pk_bf16(float lo, float hi) { unsigned r; asm volatile("v_cvt_pk_bf16_f32 %0, %1, %2" : "=v"(r) : "v"(lo), "v"(hi)); return r; }
; __device__ __forceinline__ float sigmoidf_(float x) { return __builtin_amdgcn_rcpf(1.f + __expf(-x)); }
;     __device__ __forceinline__ void operator()(const f32x4 (&acc)[2][2][4][2], const Unit& u, int wr, int wc, int fr, int fq) const {
;     ...
;             if (MODE == 2) { if (c < 1024) { kind = 3; b0 = *(const f32x4*)(p0 + c); b1 = *(const f32x4*)(p0 + c + 4); } else { kind = 2; b0 = *(const f32x4*)(p1 + c - 1024); b1 = *(const f32x4*)(p1 + c - 1024 + 4); } }
; #pragma unroll
;             for (int ai = 0; ai < 2; ++ai)
; #pragma unroll
;                 for (int m = 0; m < 4; ++m) { bf16_t* rowp = O + (size_t)(row0 + ai * HALF + m * 16) * ldc + c;
;                     f32x4 v0, v1;
;                     if (MODE == 3) { const float rstd = rs[ai * 4 + m]; v0 = acc[ai][bj][m][0] * rstd + b0; v1 = acc[ai][bj][m][1] * rstd + b1; }
;                     else { v0 = acc[ai][bj][m][0] + b0; v1 = acc[ai][bj][m][1] + b1; }
;                     if (MODE == 1 || MODE == 2) {
; #pragma unroll
;                         for (int e = 0; e < 4; ++e) {
;                             if (kind == 1) { v0[e] = 2.f * sigmoidf_(2.f * v0[e]) - 1.f; v1[e] = 2.f * sigmoidf_(2.f * v1[e]) - 1.f; }
;                             else if (kind == 2) { v0[e] = sigmoidf_(v0[e]); v1[e] = sigmoidf_(v1[e]); }
;                             else if (kind == 3) { v0[e] = 0.60653066f * sigmoidf_(v0[e]); v1[e] = 0.60653066f * sigmoidf_(v1[e]); }
;                         }
;                     }
;                     u32x4 w; w.x = cvt_pk_bf16(v0[0], v0[1]); w.y = cvt_pk_bf16(v0[2], v0[3]); w.z = cvt_pk_bf16(v1[0], v1[1]); w.w = cvt_pk_bf16(v1[2], v1[3]);
;                     *(u32x4*)rowp = w; }
.LBB0_2146:
	s_andn2_saveexec_b64 s[2:3], s[2:3]
	v_exp_f32_e32 v15, v16
	s_nop 0
	v_add_f32_e32 v15, 1.0, v15
	v_rcp_f32_e32 v15, v15
	s_or_b64 exec, exec, s[2:3]
	v_pk_add_f32 v[4:5], v[4:5], v[68:69]
	v_cvt_pk_bf16_f32 v16, v12, v9
	v_cvt_pk_bf16_f32 v17, v8, v11
	v_pk_add_f32 v[8:9], v[6:7], v[70:71]
	v_mul_f32_e32 v4, 0xbfb8aa3b, v4
	v_exp_f32_e32 v4, v4
	v_pk_add_f32 v[6:7], v[2:3], v[66:67]
	v_pk_add_f32 v[2:3], v[0:1], v[64:65]
	v_lshl_add_u64 v[20:21], v[74:75], 1, v[78:79]
	v_add_f32_e32 v4, 1.0, v4
	v_rcp_f32_e32 v4, v4
	v_mul_f32_e32 v1, 0xbfb8aa3b, v2
	v_cvt_pk_bf16_f32 v18, v10, v13
	v_cvt_pk_bf16_f32 v19, v14, v15
	global_store_dwordx4 v[20:21], v[16:19], off sc1
	s_and_saveexec_b64 s[2:3], vcc
	s_xor_b64 s[2:3], exec, s[2:3]
	s_cbranch_execz .LBB0_2150
	v_exp_f32_e32 v0, v1
	v_mul_f32_e32 v4, 0x3f1b4598, v4
	v_add_f32_e32 v0, 1.0, v0
	v_rcp_f32_e32 v0, v0
	s_nop 0
	v_mul_f32_e32 v0, 0x3f1b4598, v0

; template <class Epi, class Sched, bool ALIGN_EPI = false, bool SP2 = false>
; __device__ __forceinline__ void gemm_phase(PG8_LAS unsigned char* lds, const Gemm g, const Sched& S, const Epi& E) {
;     ...
;         if constexpr (ALIGN_EPI) { if (wr == 0) PG8_BAR; }
;         if constexpr (!Epi::AFTER_DRAIN) { E(acc, cur, wr, wc, fr, fq); S.done(cur); }
;         if (!has_next) break;
; #pragma unroll
;         for (int a = 0; a < 2; ++a)
; #pragma unroll
;             for (int b = 0; b < 2; ++b)
; #pragma unroll
;                 for (int m = 0; m < 4; ++m)
; #pragma unroll
;                     for (int n = 0; n < 2; ++n) acc[a][b][m][n] = (f32x4){0.f, 0.f, 0.f, 0.f};
;         cur = nxt; cA = nA; cB = nB; ++ui;
;         if constexpr (ALIGN_EPI) { if (wr == 1) PG8_BAR; }
;     __device__ __forceinline__ void operator()(const f32x4 (&acc)[2][2][4][2], const Unit& u, int wr, int wc, int fr, int fq) const {
;     ...
;             if (MODE == 2) { if (c < 1024) { kind = 3; b0 = *(const f32x4*)(p0 + c); b1 = *(const f32x4*)(p0 + c + 4); } else { kind = 2; b0 = *(const f32x4*)(p1 + c - 1024); b1 = *(const f32x4*)(p1 + c - 1024 + 4); } }
; #pragma unroll
;             for (int ai = 0; ai < 2; ++ai)
; #pragma unroll
;                 for (int m = 0; m < 4; ++m) { bf16_t* rowp = O + (size_t)(row0 + ai * HALF + m * 16) * ldc + c;
;                     f32x4 v0, v1;
;                     if (MODE == 3) { const float rstd = rs[ai * 4 + m]; v0 = acc[ai][bj][m][0] * rstd + b0; v1 = acc[ai][bj][m][1] * rstd + b1; }
;                     else { v0 = acc[ai][bj][m][0] + b0; v1 = acc[ai][bj][m][1] + b1; }
;                     if (MODE == 1 || MODE == 2) {
; #pragma unroll
;                         for (int e = 0; e < 4; ++e) {
;                             if (kind == 1) { v0[e] = 2.f * sigmoidf_(2.f * v0[e]) - 1.f; v1[e] = 2.f * sigmoidf_(2.f * v1[e]) - 1.f; }
;                             else if (kind == 2) { v0[e] = sigmoidf_(v0[e]); v1[e] = sigmoidf_(v1[e]); }
;                             else if (kind == 3) { v0[e] = 0.60653066f * sigmoidf_(v0[e]); v1[e] = 0.60653066f * sigmoidf_(v1[e]); }
;                         }
;                     }
;                     u32x4 w; w.x = cvt_pk_bf16(v0[0], v0[1]); w.y = cvt_pk_bf16(v0[2], v0[3]); w.z = cvt_pk_bf16(v1[0], v1[1]); w.w = cvt_pk_bf16(v1[2], v1[3]);
;                     *(u32x4*)rowp = w; }
.LBB0_2162:
	s_andn2_saveexec_b64 s[2:3], s[2:3]
	v_exp_f32_e32 v7, v8
	s_nop 0
	v_add_f32_e32 v7, 1.0, v7
	v_rcp_f32_e32 v7, v7
	s_or_b64 exec, exec, s[2:3]
	v_lshl_add_u64 v[12:13], v[74:75], 1, v[72:73]
	s_and_b64 vcc, exec, s[0:1]
	s_mov_b64 s[0:1], -1
	v_cvt_pk_bf16_f32 v8, v4, v1
	v_cvt_pk_bf16_f32 v9, v2, v3
	v_cvt_pk_bf16_f32 v10, v0, v5
	v_cvt_pk_bf16_f32 v11, v6, v7
	global_store_dwordx4 v[12:13], v[8:11], off sc1
	s_cbranch_vccnz .LBB0_1892
	s_andn2_b64 vcc, exec, s[20:21]
	s_cbranch_vccnz .LBB0_1891
	s_barrier
	s_branch .LBB0_1891

; __device__ __forceinline__ unsigned cvt_pk_bf16(float lo, float hi) { unsigned r; asm volatile("v_cvt_pk_bf16_f32 %0, %1, %2" : "=v"(r) : "v"(lo), "v"(hi)); return r; }
; __device__ __forceinline__ float sigmoidf_(float x) { return __builtin_amdgcn_rcpf(1.f + __expf(-x)); }
;     __device__ __forceinline__ void operator()(const f32x4 (&acc)[2][2][4][2], const Unit& u, int wr, int wc, int fr, int fq) const {
;     ...
;             for (int ai = 0; ai < 2; ++ai)
; #pragma unroll
;                 for (int m = 0; m < 4; ++m) { bf16_t* rowp = O + (size_t)(row0 + ai * HALF + m * 16) * ldc + c;
;                     f32x4 v0, v1;
;                     if (MODE == 3) { const float rstd = rs[ai * 4 + m]; v0 = acc[ai][bj][m][0] * rstd + b0; v1 = acc[ai][bj][m][1] * rstd + b1; }
;                     else { v0 = acc[ai][bj][m][0] + b0; v1 = acc[ai][bj][m][1] + b1; }
;                     if (MODE == 1 || MODE == 2) {
; #pragma unroll
;                         for (int e = 0; e < 4; ++e) {
;                             if (kind == 1) { v0[e] = 2.f * sigmoidf_(2.f * v0[e]) - 1.f; v1[e] = 2.f * sigmoidf_(2.f * v1[e]) - 1.f; }
;                             else if (kind == 2) { v0[e] = sigmoidf_(v0[e]); v1[e] = sigmoidf_(v1[e]); }
;                             else if (kind == 3) { v0[e] = 0.60653066f * sigmoidf_(v0[e]); v1[e] = 0.60653066f * sigmoidf_(v1[e]); }
;                         }
;                     }
;                     u32x4 w; w.x = cvt_pk_bf16(v0[0], v0[1]); w.y = cvt_pk_bf16(v0[2], v0[3]); w.z = cvt_pk_bf16(v1[0], v1[1]); w.w = cvt_pk_bf16(v1[2], v1[3]);
;                     *(u32x4*)rowp = w; }
.LBB0_2309:
	v_lshl_add_u32 v62, s45, 8, v162
	v_lshl_or_b32 v68, s51, 8, v164
	v_ashrrev_i32_e32 v63, 31, v62
	v_readlane_b32 s28, v251, 42
	v_ashrrev_i32_e32 v69, 31, v68
	v_lshlrev_b64 v[70:71], 12, v[62:63]
	v_readlane_b32 s29, v251, 43
	v_lshlrev_b64 v[76:77], 1, v[68:69]
	v_cvt_pk_bf16_f32 v68, v124, v125
	v_cvt_pk_bf16_f32 v69, v126, v127
	s_nop 0
	v_lshl_add_u64 v[70:71], s[28:29], 0, v[70:71]
	v_lshl_add_u64 v[78:79], v[70:71], 0, v[76:77]
	v_cvt_pk_bf16_f32 v70, v120, v121
	v_cvt_pk_bf16_f32 v71, v122, v123
	global_store_dwordx4 v[78:79], v[68:71], off sc1
	s_nop 1
	v_or_b32_e32 v68, 16, v62
	v_ashrrev_i32_e32 v69, 31, v68
	v_lshlrev_b64 v[68:69], 12, v[68:69]
	v_lshl_add_u64 v[68:69], s[28:29], 0, v[68:69]
	v_lshl_add_u64 v[84:85], v[68:69], 0, v[76:77]
	v_cvt_pk_bf16_f32 v68, v116, v117
	v_cvt_pk_bf16_f32 v69, v118, v119
	v_cvt_pk_bf16_f32 v70, v112, v113
	v_cvt_pk_bf16_f32 v71, v114, v115
	global_store_dwordx4 v[84:85], v[68:71], off sc1
	s_nop 1
	v_or_b32_e32 v68, 32, v62
	v_ashrrev_i32_e32 v69, 31, v68
	v_or_b32_e32 v62, 48, v62
	v_lshlrev_b64 v[68:69], 12, v[68:69]
	v_ashrrev_i32_e32 v63, 31, v62
	v_lshl_add_u64 v[68:69], s[28:29], 0, v[68:69]
	v_lshlrev_b64 v[62:63], 12, v[62:63]
	v_lshl_add_u64 v[86:87], v[68:69], 0, v[76:77]
	v_cvt_pk_bf16_f32 v68, v108, v109
	v_lshl_add_u64 v[62:63], s[28:29], 0, v[62:63]
	s_mov_b64 s[28:29], 0x80000
	v_cvt_pk_bf16_f32 v69, v110, v111
	v_cvt_pk_bf16_f32 v70, v104, v105
	v_cvt_pk_bf16_f32 v71, v106, v107
	global_store_dwordx4 v[86:87], v[68:71], off sc1
	v_lshl_add_u64 v[62:63], v[62:63], 0, v[76:77]
	v_lshl_add_u64 v[76:77], v[78:79], 0, s[28:29]
	v_cvt_pk_bf16_f32 v68, v100, v101
	s_mov_b32 s28, 0x80000
	v_cvt_pk_bf16_f32 v69, v102, v103
	v_cvt_pk_bf16_f32 v70, v96, v97
	v_cvt_pk_bf16_f32 v71, v98, v99
	global_store_dwordx4 v[62:63], v[68:71], off sc1
	s_nop 1
	v_cvt_pk_bf16_f32 v68, v88, v89
	v_add_co_u32_e32 v88, vcc, s28, v78
	s_mov_b64 s[28:29], 0x90000
	s_nop 0
	v_addc_co_u32_e32 v89, vcc, 0, v79, vcc
	v_cvt_pk_bf16_f32 v69, v90, v91
	v_cvt_pk_bf16_f32 v70, v154, v155
	v_cvt_pk_bf16_f32 v71, v146, v147
	global_store_dwordx4 v[88:89], v[68:71], off sc1
	v_lshl_add_u64 v[88:89], v[78:79], 0, s[28:29]
	s_mov_b32 s28, 0x90000
	v_cvt_pk_bf16_f32 v68, v80, v81
	v_cvt_pk_bf16_f32 v69, v74, v75
	v_add_co_u32_e32 v74, vcc, s28, v78
	s_mov_b64 s[28:29], 0xa0000
	s_nop 0
	v_addc_co_u32_e32 v75, vcc, 0, v79, vcc
	v_cvt_pk_bf16_f32 v70, v156, v157
	v_cvt_pk_bf16_f32 v71, v148, v149
	global_store_dwordx4 v[74:75], v[68:71], off sc1
	v_lshl_add_u64 v[74:75], v[78:79], 0, s[28:29]
	s_mov_b32 s28, 0xa0000
	v_cvt_pk_bf16_f32 v68, v82, v83
	v_cvt_pk_bf16_f32 v69, v66, v67
	v_add_co_u32_e32 v66, vcc, s28, v78
	v_cvt_pk_bf16_f32 v70, v158, v159
	v_cvt_pk_bf16_f32 v71, v150, v151
	s_mov_b64 s[28:29], 0xb0000
	s_nop 0
	v_addc_co_u32_e32 v67, vcc, 0, v79, vcc
	global_store_dwordx4 v[66:67], v[68:71], off sc1
	v_cvt_pk_bf16_f32 v66, v144, v145
	v_cvt_pk_bf16_f32 v67, v72, v73
	s_nop 1
	v_lshl_add_u64 v[70:71], v[78:79], 0, s[28:29]
	s_mov_b32 s28, 0xb0000
	v_add_co_u32_e32 v72, vcc, s28, v78
	v_cvt_pk_bf16_f32 v68, v160, v161
	v_cvt_pk_bf16_f32 v69, v152, v153
	s_nop 1
	v_addc_co_u32_e32 v73, vcc, 0, v79, vcc
	global_store_dwordx4 v[72:73], v[66:69], off sc1
	s_and_b64 vcc, exec, s[0:1]
	s_mov_b64 s[0:1], -1
	v_cvt_pk_bf16_f32 v66, v34, v35
	v_cvt_pk_bf16_f32 v67, v32, v33
	v_cvt_pk_bf16_f32 v68, v48, v49
	v_cvt_pk_bf16_f32 v69, v40, v41
	global_store_dwordx4 v[78:79], v[66:69], off offset:256 sc1
	v_cvt_pk_bf16_f32 v32, v50, v51
	v_cvt_pk_bf16_f32 v33, v42, v43
	v_cvt_pk_bf16_f32 v34, v64, v65
	v_cvt_pk_bf16_f32 v35, v56, v57
	global_store_dwordx4 v[84:85], v[32:35], off offset:256 sc1
	s_nop 1
	v_cvt_pk_bf16_f32 v32, v60, v61
	v_cvt_pk_bf16_f32 v33, v58, v59
	v_cvt_pk_bf16_f32 v34, v52, v53
	v_cvt_pk_bf16_f32 v35, v54, v55
	global_store_dwordx4 v[86:87], v[32:35], off offset:256 sc1
	s_nop 1
	v_cvt_pk_bf16_f32 v32, v44, v45
	v_cvt_pk_bf16_f32 v33, v46, v47
	v_cvt_pk_bf16_f32 v34, v36, v37
	v_cvt_pk_bf16_f32 v35, v38, v39
	global_store_dwordx4 v[62:63], v[32:35], off offset:256 sc1
	v_cvt_pk_bf16_f32 v28, v28, v29
	v_cvt_pk_bf16_f32 v29, v30, v31
	v_cvt_pk_bf16_f32 v30, v24, v25
	v_cvt_pk_bf16_f32 v31, v26, v27
	global_store_dwordx4 v[76:77], v[28:31], off offset:256 sc1
	v_cvt_pk_bf16_f32 v20, v20, v21
	v_cvt_pk_bf16_f32 v21, v22, v23
	v_cvt_pk_bf16_f32 v22, v16, v17
	v_cvt_pk_bf16_f32 v23, v18, v19
	global_store_dwordx4 v[88:89], v[20:23], off offset:256 sc1
	v_cvt_pk_bf16_f32 v12, v12, v13
	v_cvt_pk_bf16_f32 v13, v14, v15
	v_cvt_pk_bf16_f32 v14, v8, v9
	v_cvt_pk_bf16_f32 v15, v10, v11
	global_store_dwordx4 v[74:75], v[12:15], off offset:256 sc1
	v_cvt_pk_bf16_f32 v4, v4, v5
	v_cvt_pk_bf16_f32 v5, v6, v7
	v_cvt_pk_bf16_f32 v6, v0, v1
	v_cvt_pk_bf16_f32 v7, v2, v3
	global_store_dwordx4 v[70:71], v[4:7], off offset:256 sc1
	s_cbranch_vccnz .LBB0_2292
	s_andn2_b64 vcc, exec, s[14:15]
	s_cbranch_vccnz .LBB0_2291
	s_barrier
	s_branch .LBB0_2291

; __device__ __forceinline__ unsigned cvt_pk_bf16(float lo, float hi) { unsigned r; asm volatile("v_cvt_pk_bf16_f32 %0, %1, %2" : "=v"(r) : "v"(lo), "v"(hi)); return r; }
;     __device__ __forceinline__ void operator()(const f32x4 (&acc)[2][2][4][2], const Unit& u, int wr, int wc, int fr, int fq) const {
;         const int row0 = u.pm * BM + wr * 64 + fr, col0 = u.pn * BM + wc * 32 + 4 * fq;
;         const float* gp = gate + (size_t)(u.pm >> 4) * NMOD;
;         f32x4 gv[2][2], sv[2][2];
; #pragma unroll
;         for (int bj = 0; bj < 2; ++bj)
; #pragma unroll
;             for (int n = 0; n < 2; ++n) { gv[bj][n] = *(const f32x4*)(gp + col0 + bj * HALF + n * 16) * (HALFSC ? 0.5f : 1.0f);
;                 if (FOLD) sv[bj][n] = *(const f32x4*)(scn + (size_t)(u.pm >> 4) * NMOD + col0 + bj * HALF + n * 16) + 1.0f; }
; #pragma unroll
;         for (int ai = 0; ai < 2; ++ai)
; #pragma unroll
;             for (int m = 0; m < 4; ++m) { const int row = row0 + ai * HALF + m * 16; const size_t off = (size_t)row * D + col0;
;                 float ssq = 0.f;
; #pragma unroll
;                 for (int bj = 0; bj < 2; ++bj)
; #pragma unroll
;                     for (int n = 0; n < 2; ++n) { const f32x4 bs = *(const f32x4*)(base + off + bj * HALF + n * 16);
;                         const f32x4 o = bs + gv[bj][n] * acc[ai][bj][m][n];
;                         *(f32x4*)(out + off + bj * HALF + n * 16) = o;
;                         if (FOLD) { ssq += (o.x * o.x + o.y * o.y) + (o.z * o.z + o.w * o.w); const f32x4 q = o * sv[bj][n];
;                             u32x2 w; w.x = cvt_pk_bf16(q.x, q.y); w.y = cvt_pk_bf16(q.z, q.w); *(u32x2*)(U2 + off + bj * HALF + n * 16) = w; } }
;                 if (FOLD) { ssq += __shfl_xor(ssq, 16); ssq += __shfl_xor(ssq, 32);
;                     if (fq == 0) part[(size_t)row * 16 + (u.pn & 3) * 4 + wc] = ssq; } }
.LBB0_2445:
	s_ashr_i32 s6, s14, 4
	v_lshl_or_b32 v160, s58, 8, v170
	s_mul_i32 s34, s6, 0x9000
	s_mul_hi_i32 s27, s6, 0x9000
	s_add_u32 s6, s45, s34
	v_ashrrev_i32_e32 v161, 31, v160
	v_lshl_add_u32 v162, s14, 8, v168
	s_addc_u32 s7, s46, s27
	v_lshlrev_b64 v[96:97], 2, v[160:161]
	v_ashrrev_i32_e32 v163, 31, v162
	v_lshl_add_u64 v[98:99], s[6:7], 0, v[96:97]
	s_add_u32 s6, s47, s34
	v_lshlrev_b64 v[104:105], 10, v[162:163]
	v_readlane_b32 s60, v248, 0
	v_lshl_add_u64 v[104:105], v[104:105], 0, v[160:161]
	v_readlane_b32 s66, v248, 6
	v_readlane_b32 s67, v248, 7
	s_addc_u32 s7, s48, s27
	v_lshl_add_u64 v[186:187], s[6:7], 0, v[96:97]
	v_lshl_add_u64 v[194:195], v[104:105], 2, s[66:67]
	global_load_dwordx4 v[100:103], v[98:99], off
	global_load_dwordx4 v[174:177], v[186:187], off
	global_load_dwordx4 v[164:167], v[194:195], off
	v_readlane_b32 s6, v249, 43
	v_readlane_b32 s7, v249, 44
	v_readlane_b32 s61, v248, 1
	v_readlane_b32 s62, v248, 2
	v_lshl_add_u64 v[196:197], v[104:105], 1, s[6:7]
	global_load_dwordx4 v[108:111], v[98:99], off offset:64
	global_load_dwordx4 v[104:107], v[98:99], off offset:512
	s_nop 0
	global_load_dwordx4 v[96:99], v[98:99], off offset:576
	s_nop 0
	global_load_dwordx4 v[178:181], v[186:187], off offset:64
	global_load_dwordx4 v[182:185], v[186:187], off offset:512
	s_nop 0
	global_load_dwordx4 v[186:189], v[186:187], off offset:576
	global_load_dwordx4 v[236:239], v[194:195], off offset:64
	global_load_dwordx4 v[240:243], v[194:195], off offset:512
	global_load_dwordx4 v[244:247], v[194:195], off offset:576
	s_lshl_b32 s6, s58, 2
	s_and_b32 s27, s6, 12
	v_readlane_b32 s63, v248, 3
	v_readlane_b32 s64, v248, 4
	v_readlane_b32 s65, v248, 5
	s_waitcnt vmcnt(3)
	v_pk_fma_f32 v[192:193], v[142:143], v[102:103], v[166:167]
	v_pk_fma_f32 v[190:191], v[140:141], v[100:101], v[164:165]
	v_pk_add_f32 v[166:167], v[174:175], 1.0 op_sel_hi:[1,0]
	v_pk_add_f32 v[164:165], v[176:177], 1.0 op_sel_hi:[1,0]
	v_pk_mul_f32 v[142:143], v[166:167], v[190:191]
	global_store_dwordx4 v[194:195], v[190:193], off sc1
	v_pk_mul_f32 v[140:141], v[164:165], v[192:193]
	v_cvt_pk_bf16_f32 v142, v142, v143
	s_nop 0
	v_cvt_pk_bf16_f32 v143, v140, v141
	global_store_dwordx2 v[196:197], v[142:143], off
	v_pk_add_f32 v[142:143], v[178:179], 1.0 op_sel_hi:[1,0]
	v_pk_add_f32 v[140:141], v[180:181], 1.0 op_sel_hi:[1,0]
	v_mul_f32_e32 v191, v191, v191
	v_mul_f32_e32 v193, v193, v193
	v_fmac_f32_e32 v191, v190, v190
	v_fmac_f32_e32 v193, v192, v192
	s_waitcnt vmcnt(4)
	v_pk_fma_f32 v[174:175], v[136:137], v[108:109], v[236:237]
	v_pk_fma_f32 v[176:177], v[138:139], v[110:111], v[238:239]
	v_pk_mul_f32 v[138:139], v[142:143], v[174:175]
	global_store_dwordx4 v[194:195], v[174:177], off offset:64 sc1
	v_pk_mul_f32 v[136:137], v[140:141], v[176:177]
	v_cvt_pk_bf16_f32 v138, v138, v139
	s_nop 0
	v_cvt_pk_bf16_f32 v139, v136, v137
	global_store_dwordx2 v[196:197], v[138:139], off offset:32
	v_pk_add_f32 v[138:139], v[182:183], 1.0 op_sel_hi:[1,0]
	v_pk_add_f32 v[136:137], v[184:185], 1.0 op_sel_hi:[1,0]
	v_mul_f32_e32 v175, v175, v175
	v_mul_f32_e32 v177, v177, v177
	v_fmac_f32_e32 v175, v174, v174
	v_fmac_f32_e32 v177, v176, v176
	v_add_f32_e32 v174, v175, v177
	s_waitcnt vmcnt(5)
	v_pk_fma_f32 v[178:179], v[132:133], v[104:105], v[240:241]
	v_pk_fma_f32 v[180:181], v[134:135], v[106:107], v[242:243]
	v_pk_mul_f32 v[134:135], v[138:139], v[178:179]
	global_store_dwordx4 v[194:195], v[178:181], off offset:512 sc1
	v_pk_mul_f32 v[132:133], v[136:137], v[180:181]
	v_cvt_pk_bf16_f32 v134, v134, v135
	v_mul_f32_e32 v175, v179, v179
	v_cvt_pk_bf16_f32 v135, v132, v133
	global_store_dwordx2 v[196:197], v[134:135], off offset:256
	v_mul_f32_e32 v176, v181, v181
	v_pk_add_f32 v[132:133], v[186:187], 1.0 op_sel_hi:[1,0]
	v_add_f32_e32 v186, v191, v193
	v_fmac_f32_e32 v175, v178, v178
	v_fmac_f32_e32 v176, v180, v180
	v_add_f32_e32 v174, v186, v174
	v_add_f32_e32 v175, v175, v176
	v_add_f32_e32 v178, v174, v175
	v_pk_add_f32 v[134:135], v[188:189], 1.0 op_sel_hi:[1,0]
	s_waitcnt vmcnt(6)
	v_pk_fma_f32 v[176:177], v[130:131], v[98:99], v[246:247]
	v_pk_fma_f32 v[174:175], v[128:129], v[96:97], v[244:245]
	v_mul_f32_e32 v129, v177, v177
	v_mul_f32_e32 v128, v175, v175
	v_fmac_f32_e32 v128, v174, v174
	v_fmac_f32_e32 v129, v176, v176
	v_add_f32_e32 v128, v128, v129
	v_add_f32_e32 v128, v178, v128
	ds_bpermute_b32 v129, v207, v128
	global_store_dwordx4 v[194:195], v[174:177], off offset:576 sc1
	v_pk_mul_f32 v[130:131], v[134:135], v[176:177]
	s_waitcnt lgkmcnt(0)
	v_add_f32_e32 v128, v128, v129
	ds_bpermute_b32 v129, v208, v128
	v_pk_mul_f32 v[174:175], v[132:133], v[174:175]
	s_nop 0
	v_cvt_pk_bf16_f32 v174, v174, v175
	v_cvt_pk_bf16_f32 v175, v130, v131
	global_store_dwordx2 v[196:197], v[174:175], off offset:288
	s_and_saveexec_b64 s[6:7], s[0:1]
	s_cbranch_execz .LBB0_2447
	v_readlane_b32 s34, v249, 31
	v_lshlrev_b64 v[130:131], 6, v[162:163]
	v_readlane_b32 s35, v249, 32
	s_lshl_b32 s14, s27, 2
	s_waitcnt lgkmcnt(0)
	v_add_f32_e32 v128, v128, v129
	v_lshl_add_u64 v[130:131], s[34:35], 0, v[130:131]
	v_lshl_add_u64 v[130:131], v[130:131], 0, s[14:15]
	s_lshl_b32 s14, s49, 2
	v_lshl_add_u64 v[130:131], v[130:131], 0, s[14:15]
	global_store_dword v[130:131], v128, off
; __device__ __forceinline__ unsigned cvt_pk_bf16(float lo, float hi) { unsigned r; asm volatile("v_cvt_pk_bf16_f32 %0, %1, %2" : "=v"(r) : "v"(lo), "v"(hi)); return r; }
;     __device__ __forceinline__ void operator()(const f32x4 (&acc)[2][2][4][2], const Unit& u, int wr, int wc, int fr, int fq) const {
;         const int row0 = u.pm * BM + wr * 64 + fr, col0 = u.pn * BM + wc * 32 + 4 * fq;
;         const float* gp = gate + (size_t)(u.pm >> 4) * NMOD;
;         f32x4 gv[2][2], sv[2][2];
; #pragma unroll
;         for (int bj = 0; bj < 2; ++bj)
; #pragma unroll
;             for (int n = 0; n < 2; ++n) { gv[bj][n] = *(const f32x4*)(gp + col0 + bj * HALF + n * 16) * (HALFSC ? 0.5f : 1.0f);
;                 if (FOLD) sv[bj][n] = *(const f32x4*)(scn + (size_t)(u.pm >> 4) * NMOD + col0 + bj * HALF + n * 16) + 1.0f; }
; #pragma unroll
;         for (int ai = 0; ai < 2; ++ai)
; #pragma unroll
;             for (int m = 0; m < 4; ++m) { const int row = row0 + ai * HALF + m * 16; const size_t off = (size_t)row * D + col0;
;                 float ssq = 0.f;
; #pragma unroll
;                 for (int bj = 0; bj < 2; ++bj)
; #pragma unroll
;                     for (int n = 0; n < 2; ++n) { const f32x4 bs = *(const f32x4*)(base + off + bj * HALF + n * 16);
;                         const f32x4 o = bs + gv[bj][n] * acc[ai][bj][m][n];
;                         *(f32x4*)(out + off + bj * HALF + n * 16) = o;
;                         if (FOLD) { ssq += (o.x * o.x + o.y * o.y) + (o.z * o.z + o.w * o.w); const f32x4 q = o * sv[bj][n];
;                             u32x2 w; w.x = cvt_pk_bf16(q.x, q.y); w.y = cvt_pk_bf16(q.z, q.w); *(u32x2*)(U2 + off + bj * HALF + n * 16) = w; } }
;                 if (FOLD) { ssq += __shfl_xor(ssq, 16); ssq += __shfl_xor(ssq, 32);
;                     if (fq == 0) part[(size_t)row * 16 + (u.pn & 3) * 4 + wc] = ssq; } }
.LBB0_2447:
	s_or_b64 exec, exec, s[6:7]
	v_or_b32_e32 v128, 16, v162
	s_waitcnt lgkmcnt(0)
	v_ashrrev_i32_e32 v129, 31, v128
	v_lshlrev_b64 v[130:131], 10, v[128:129]
	v_readlane_b32 s60, v248, 0
	v_lshl_add_u64 v[130:131], v[130:131], 0, v[160:161]
	v_readlane_b32 s66, v248, 6
	v_readlane_b32 s67, v248, 7
	v_readlane_b32 s6, v249, 43
	v_readlane_b32 s7, v249, 44
	v_lshl_add_u64 v[178:179], v[130:131], 2, s[66:67]
	global_load_dwordx4 v[236:239], v[178:179], off
	global_load_dwordx4 v[240:243], v[178:179], off offset:64
	global_load_dwordx4 v[244:247], v[178:179], off offset:512
	global_load_dwordx4 v[174:177], v[178:179], off offset:576
	v_lshl_add_u64 v[130:131], v[130:131], 1, s[6:7]
	v_readlane_b32 s61, v248, 1
	v_readlane_b32 s62, v248, 2
	v_readlane_b32 s63, v248, 3
	v_readlane_b32 s64, v248, 4
	v_readlane_b32 s65, v248, 5
	s_waitcnt vmcnt(3)
	v_pk_fma_f32 v[124:125], v[124:125], v[100:101], v[236:237]
	v_pk_fma_f32 v[126:127], v[126:127], v[102:103], v[238:239]
	v_pk_mul_f32 v[238:239], v[166:167], v[124:125]
	global_store_dwordx4 v[178:179], v[124:127], off sc1
	v_pk_mul_f32 v[236:237], v[164:165], v[126:127]
	v_cvt_pk_bf16_f32 v238, v238, v239
	s_nop 0
	v_cvt_pk_bf16_f32 v239, v236, v237
	global_store_dwordx2 v[130:131], v[238:239], off
	v_mul_f32_e32 v125, v125, v125
	v_mul_f32_e32 v127, v127, v127
	v_fmac_f32_e32 v125, v124, v124
	v_fmac_f32_e32 v127, v126, v126
	v_add_f32_e32 v124, v125, v127
	s_waitcnt vmcnt(4)
	v_pk_fma_f32 v[120:121], v[120:121], v[108:109], v[240:241]
	v_pk_fma_f32 v[122:123], v[122:123], v[110:111], v[242:243]
	v_pk_mul_f32 v[242:243], v[142:143], v[120:121]
	global_store_dwordx4 v[178:179], v[120:123], off offset:64 sc1
	v_pk_mul_f32 v[240:241], v[140:141], v[122:123]
	v_cvt_pk_bf16_f32 v242, v242, v243
	s_nop 0
	v_cvt_pk_bf16_f32 v243, v240, v241
	global_store_dwordx2 v[130:131], v[242:243], off offset:32
	v_mul_f32_e32 v121, v121, v121
	v_mul_f32_e32 v123, v123, v123
	v_fmac_f32_e32 v121, v120, v120
	v_fmac_f32_e32 v123, v122, v122
	v_add_f32_e32 v120, v121, v123
	v_add_f32_e32 v120, v124, v120
	s_waitcnt vmcnt(5)
	v_pk_fma_f32 v[116:117], v[116:117], v[104:105], v[244:245]
	v_pk_fma_f32 v[118:119], v[118:119], v[106:107], v[246:247]
	v_pk_mul_f32 v[246:247], v[138:139], v[116:117]
	global_store_dwordx4 v[178:179], v[116:119], off offset:512 sc1
	v_pk_mul_f32 v[244:245], v[136:137], v[118:119]
	v_cvt_pk_bf16_f32 v246, v246, v247
	s_nop 0
	v_cvt_pk_bf16_f32 v247, v244, v245
	global_store_dwordx2 v[130:131], v[246:247], off offset:256
	v_mul_f32_e32 v117, v117, v117
	v_mul_f32_e32 v119, v119, v119
	v_fmac_f32_e32 v117, v116, v116
	v_fmac_f32_e32 v119, v118, v118
	v_add_f32_e32 v116, v117, v119
	v_add_f32_e32 v118, v120, v116
	s_waitcnt vmcnt(6)
	v_pk_fma_f32 v[116:117], v[114:115], v[98:99], v[176:177]
	v_pk_fma_f32 v[114:115], v[112:113], v[96:97], v[174:175]
	v_mul_f32_e32 v113, v117, v117
	v_mul_f32_e32 v112, v115, v115
	v_fmac_f32_e32 v112, v114, v114
	v_fmac_f32_e32 v113, v116, v116
	v_add_f32_e32 v112, v112, v113
	v_add_f32_e32 v112, v118, v112
	ds_bpermute_b32 v113, v207, v112
	global_store_dwordx4 v[178:179], v[114:117], off offset:576 sc1
	s_waitcnt lgkmcnt(0)
	v_add_f32_e32 v112, v112, v113
	ds_bpermute_b32 v113, v208, v112
	v_pk_mul_f32 v[114:115], v[132:133], v[114:115]
	v_pk_mul_f32 v[116:117], v[134:135], v[116:117]
	v_cvt_pk_bf16_f32 v114, v114, v115
	s_nop 0
	v_cvt_pk_bf16_f32 v115, v116, v117
	global_store_dwordx2 v[130:131], v[114:115], off offset:288
	s_and_saveexec_b64 s[6:7], s[0:1]
	s_cbranch_execz .LBB0_2449
	v_readlane_b32 s34, v249, 31
	v_lshlrev_b64 v[114:115], 6, v[128:129]
	v_readlane_b32 s35, v249, 32
	s_lshl_b32 s14, s27, 2
	s_waitcnt lgkmcnt(0)
	v_add_f32_e32 v112, v112, v113
	v_lshl_add_u64 v[114:115], s[34:35], 0, v[114:115]
	v_lshl_add_u64 v[114:115], v[114:115], 0, s[14:15]
	s_lshl_b32 s14, s49, 2
	v_lshl_add_u64 v[114:115], v[114:115], 0, s[14:15]
	global_store_dword v[114:115], v112, off
.LBB0_2449:
	s_or_b64 exec, exec, s[6:7]
	v_or_b32_e32 v112, 32, v162
	s_waitcnt lgkmcnt(0)
	v_ashrrev_i32_e32 v113, 31, v112
	v_lshlrev_b64 v[114:115], 10, v[112:113]
	v_readlane_b32 s60, v248, 0
	v_lshl_add_u64 v[118:119], v[114:115], 0, v[160:161]
	v_readlane_b32 s66, v248, 6
	v_readlane_b32 s67, v248, 7
	v_readlane_b32 s6, v249, 43
	v_readlane_b32 s7, v249, 44
	v_lshl_add_u64 v[120:121], v[118:119], 2, s[66:67]
	global_load_dwordx4 v[236:239], v[120:121], off
	global_load_dwordx4 v[240:243], v[120:121], off offset:64
	global_load_dwordx4 v[244:247], v[120:121], off offset:512
	global_load_dwordx4 v[114:117], v[120:121], off offset:576
	v_lshl_add_u64 v[118:119], v[118:119], 1, s[6:7]
	v_readlane_b32 s61, v248, 1
	v_readlane_b32 s62, v248, 2
	v_readlane_b32 s63, v248, 3
	v_readlane_b32 s64, v248, 4
	v_readlane_b32 s65, v248, 5
	s_waitcnt vmcnt(3)
	v_pk_fma_f32 v[92:93], v[92:93], v[100:101], v[236:237]
	v_pk_fma_f32 v[94:95], v[94:95], v[102:103], v[238:239]
	v_pk_mul_f32 v[238:239], v[166:167], v[92:93]
	global_store_dwordx4 v[120:121], v[92:95], off sc1
	v_pk_mul_f32 v[236:237], v[164:165], v[94:95]
	v_cvt_pk_bf16_f32 v238, v238, v239
	s_nop 0
	v_cvt_pk_bf16_f32 v239, v236, v237
	global_store_dwordx2 v[118:119], v[238:239], off
	v_mul_f32_e32 v93, v93, v93
	v_mul_f32_e32 v95, v95, v95
	v_fmac_f32_e32 v93, v92, v92
	v_fmac_f32_e32 v95, v94, v94
	v_add_f32_e32 v92, v93, v95
	s_waitcnt vmcnt(4)
; __device__ __forceinline__ unsigned cvt_pk_bf16(float lo, float hi) { unsigned r; asm volatile("v_cvt_pk_bf16_f32 %0, %1, %2" : "=v"(r) : "v"(lo), "v"(hi)); return r; }
;     __device__ __forceinline__ void operator()(const f32x4 (&acc)[2][2][4][2], const Unit& u, int wr, int wc, int fr, int fq) const {
;         const int row0 = u.pm * BM + wr * 64 + fr, col0 = u.pn * BM + wc * 32 + 4 * fq;
;         const float* gp = gate + (size_t)(u.pm >> 4) * NMOD;
;         f32x4 gv[2][2], sv[2][2];
; #pragma unroll
;         for (int bj = 0; bj < 2; ++bj)
; #pragma unroll
;             for (int n = 0; n < 2; ++n) { gv[bj][n] = *(const f32x4*)(gp + col0 + bj * HALF + n * 16) * (HALFSC ? 0.5f : 1.0f);
;                 if (FOLD) sv[bj][n] = *(const f32x4*)(scn + (size_t)(u.pm >> 4) * NMOD + col0 + bj * HALF + n * 16) + 1.0f; }
; #pragma unroll
;         for (int ai = 0; ai < 2; ++ai)
; #pragma unroll
;             for (int m = 0; m < 4; ++m) { const int row = row0 + ai * HALF + m * 16; const size_t off = (size_t)row * D + col0;
;                 float ssq = 0.f;
; #pragma unroll
;                 for (int bj = 0; bj < 2; ++bj)
; #pragma unroll
;                     for (int n = 0; n < 2; ++n) { const f32x4 bs = *(const f32x4*)(base + off + bj * HALF + n * 16);
;                         const f32x4 o = bs + gv[bj][n] * acc[ai][bj][m][n];
;                         *(f32x4*)(out + off + bj * HALF + n * 16) = o;
;                         if (FOLD) { ssq += (o.x * o.x + o.y * o.y) + (o.z * o.z + o.w * o.w); const f32x4 q = o * sv[bj][n];
;                             u32x2 w; w.x = cvt_pk_bf16(q.x, q.y); w.y = cvt_pk_bf16(q.z, q.w); *(u32x2*)(U2 + off + bj * HALF + n * 16) = w; } }
;                 if (FOLD) { ssq += __shfl_xor(ssq, 16); ssq += __shfl_xor(ssq, 32);
;                     if (fq == 0) part[(size_t)row * 16 + (u.pn & 3) * 4 + wc] = ssq; } }
	v_pk_fma_f32 v[88:89], v[88:89], v[108:109], v[240:241]
	v_pk_fma_f32 v[90:91], v[90:91], v[110:111], v[242:243]
	v_pk_mul_f32 v[242:243], v[142:143], v[88:89]
	global_store_dwordx4 v[120:121], v[88:91], off offset:64 sc1
	v_pk_mul_f32 v[240:241], v[140:141], v[90:91]
	v_cvt_pk_bf16_f32 v242, v242, v243
	s_nop 0
	v_cvt_pk_bf16_f32 v243, v240, v241
	global_store_dwordx2 v[118:119], v[242:243], off offset:32
	v_mul_f32_e32 v89, v89, v89
	v_mul_f32_e32 v91, v91, v91
	v_fmac_f32_e32 v89, v88, v88
	v_fmac_f32_e32 v91, v90, v90
	v_add_f32_e32 v88, v89, v91
	v_add_f32_e32 v88, v92, v88
	s_waitcnt vmcnt(5)
	v_pk_fma_f32 v[84:85], v[84:85], v[104:105], v[244:245]
	v_pk_fma_f32 v[86:87], v[86:87], v[106:107], v[246:247]
	v_pk_mul_f32 v[246:247], v[138:139], v[84:85]
	global_store_dwordx4 v[120:121], v[84:87], off offset:512 sc1
	v_pk_mul_f32 v[244:245], v[136:137], v[86:87]
	v_cvt_pk_bf16_f32 v246, v246, v247
	s_nop 0
	v_cvt_pk_bf16_f32 v247, v244, v245
	global_store_dwordx2 v[118:119], v[246:247], off offset:256
	v_mul_f32_e32 v85, v85, v85
	v_mul_f32_e32 v87, v87, v87
	v_fmac_f32_e32 v85, v84, v84
	v_fmac_f32_e32 v87, v86, v86
	v_add_f32_e32 v84, v85, v87
	v_add_f32_e32 v86, v88, v84
	s_waitcnt vmcnt(6)
	v_pk_fma_f32 v[84:85], v[82:83], v[98:99], v[116:117]
	v_pk_fma_f32 v[82:83], v[80:81], v[96:97], v[114:115]
	v_mul_f32_e32 v81, v85, v85
	v_mul_f32_e32 v80, v83, v83
	v_fmac_f32_e32 v80, v82, v82
	v_fmac_f32_e32 v81, v84, v84
	v_add_f32_e32 v80, v80, v81
	v_add_f32_e32 v80, v86, v80
	ds_bpermute_b32 v81, v207, v80
	global_store_dwordx4 v[120:121], v[82:85], off offset:576 sc1
	s_waitcnt lgkmcnt(0)
	v_add_f32_e32 v80, v80, v81
	ds_bpermute_b32 v81, v208, v80
	v_pk_mul_f32 v[82:83], v[132:133], v[82:83]
	v_pk_mul_f32 v[84:85], v[134:135], v[84:85]
	v_cvt_pk_bf16_f32 v82, v82, v83
	s_nop 0
	v_cvt_pk_bf16_f32 v83, v84, v85
	global_store_dwordx2 v[118:119], v[82:83], off offset:288
	s_and_saveexec_b64 s[6:7], s[0:1]
	s_cbranch_execz .LBB0_2451
	v_readlane_b32 s34, v249, 31
	v_lshlrev_b64 v[82:83], 6, v[112:113]
	v_readlane_b32 s35, v249, 32
	s_lshl_b32 s14, s27, 2
	s_waitcnt lgkmcnt(0)
	v_add_f32_e32 v80, v80, v81
	v_lshl_add_u64 v[82:83], s[34:35], 0, v[82:83]
	v_lshl_add_u64 v[82:83], v[82:83], 0, s[14:15]
	s_lshl_b32 s14, s49, 2
	v_lshl_add_u64 v[82:83], v[82:83], 0, s[14:15]
	global_store_dword v[82:83], v80, off
.LBB0_2451:
	s_or_b64 exec, exec, s[6:7]
	v_or_b32_e32 v80, 48, v162
	s_waitcnt lgkmcnt(0)
	v_ashrrev_i32_e32 v81, 31, v80
	v_lshlrev_b64 v[82:83], 10, v[80:81]
	v_readlane_b32 s60, v248, 0
	v_lshl_add_u64 v[86:87], v[82:83], 0, v[160:161]
	v_readlane_b32 s66, v248, 6
	v_readlane_b32 s67, v248, 7
	v_readlane_b32 s6, v249, 43
	v_readlane_b32 s7, v249, 44
	v_lshl_add_u64 v[88:89], v[86:87], 2, s[66:67]
	global_load_dwordx4 v[236:239], v[88:89], off
	global_load_dwordx4 v[240:243], v[88:89], off offset:64
	global_load_dwordx4 v[244:247], v[88:89], off offset:512
	global_load_dwordx4 v[82:85], v[88:89], off offset:576
	v_lshl_add_u64 v[86:87], v[86:87], 1, s[6:7]
	v_readlane_b32 s61, v248, 1
	v_readlane_b32 s62, v248, 2
	v_readlane_b32 s63, v248, 3
	v_readlane_b32 s64, v248, 4
	v_readlane_b32 s65, v248, 5
	s_waitcnt vmcnt(3)
	v_pk_fma_f32 v[76:77], v[76:77], v[100:101], v[236:237]
	v_pk_fma_f32 v[78:79], v[78:79], v[102:103], v[238:239]
	v_pk_mul_f32 v[238:239], v[166:167], v[76:77]
	global_store_dwordx4 v[88:89], v[76:79], off sc1
	v_pk_mul_f32 v[236:237], v[164:165], v[78:79]
	v_cvt_pk_bf16_f32 v238, v238, v239
	s_nop 0
	v_cvt_pk_bf16_f32 v239, v236, v237
	global_store_dwordx2 v[86:87], v[238:239], off
	v_mul_f32_e32 v77, v77, v77
	v_mul_f32_e32 v79, v79, v79
	v_fmac_f32_e32 v77, v76, v76
	v_fmac_f32_e32 v79, v78, v78
	v_add_f32_e32 v76, v77, v79
	s_waitcnt vmcnt(4)
	v_pk_fma_f32 v[72:73], v[72:73], v[108:109], v[240:241]
	v_pk_fma_f32 v[74:75], v[74:75], v[110:111], v[242:243]
	v_pk_mul_f32 v[242:243], v[142:143], v[72:73]
	global_store_dwordx4 v[88:89], v[72:75], off offset:64 sc1
	v_pk_mul_f32 v[240:241], v[140:141], v[74:75]
	v_cvt_pk_bf16_f32 v242, v242, v243
	s_nop 0
	v_cvt_pk_bf16_f32 v243, v240, v241
	global_store_dwordx2 v[86:87], v[242:243], off offset:32
	v_mul_f32_e32 v73, v73, v73
	v_mul_f32_e32 v75, v75, v75
	v_fmac_f32_e32 v73, v72, v72
	v_fmac_f32_e32 v75, v74, v74
	v_add_f32_e32 v72, v73, v75
	v_add_f32_e32 v72, v76, v72
	s_waitcnt vmcnt(5)
	v_pk_fma_f32 v[68:69], v[68:69], v[104:105], v[244:245]
	v_pk_fma_f32 v[70:71], v[70:71], v[106:107], v[246:247]
	v_pk_mul_f32 v[246:247], v[138:139], v[68:69]
	global_store_dwordx4 v[88:89], v[68:71], off offset:512 sc1
	v_pk_mul_f32 v[244:245], v[136:137], v[70:71]
	v_cvt_pk_bf16_f32 v246, v246, v247
	s_nop 0
	v_cvt_pk_bf16_f32 v247, v244, v245
	global_store_dwordx2 v[86:87], v[246:247], off offset:256
	v_mul_f32_e32 v69, v69, v69
	v_mul_f32_e32 v71, v71, v71
	v_fmac_f32_e32 v69, v68, v68
	v_fmac_f32_e32 v71, v70, v70
	v_add_f32_e32 v68, v69, v71
	v_add_f32_e32 v70, v72, v68
	s_waitcnt vmcnt(6)
	v_pk_fma_f32 v[68:69], v[66:67], v[98:99], v[84:85]
	v_pk_fma_f32 v[66:67], v[64:65], v[96:97], v[82:83]
	v_mul_f32_e32 v65, v69, v69
	v_mul_f32_e32 v64, v67, v67
	v_fmac_f32_e32 v64, v66, v66
	v_fmac_f32_e32 v65, v68, v68
	v_add_f32_e32 v64, v64, v65
	v_add_f32_e32 v64, v70, v64
	ds_bpermute_b32 v65, v207, v64
	global_store_dwordx4 v[88:89], v[66:69], off offset:576 sc1
	s_waitcnt lgkmcnt(0)
	v_add_f32_e32 v64, v64, v65
	ds_bpermute_b32 v65, v208, v64
	v_pk_mul_f32 v[66:67], v[132:133], v[66:67]
	v_pk_mul_f32 v[68:69], v[134:135], v[68:69]
	v_cvt_pk_bf16_f32 v66, v66, v67
	s_nop 0
	v_cvt_pk_bf16_f32 v67, v68, v69
	global_store_dwordx2 v[86:87], v[66:67], off offset:288
	s_and_saveexec_b64 s[6:7], s[0:1]
	s_cbranch_execz .LBB0_2453
	v_readlane_b32 s34, v249, 31
	v_lshlrev_b64 v[66:67], 6, v[80:81]
	v_readlane_b32 s35, v249, 32
	s_lshl_b32 s14, s27, 2
	s_waitcnt lgkmcnt(0)
	v_add_f32_e32 v64, v64, v65
	v_lshl_add_u64 v[66:67], s[34:35], 0, v[66:67]
	v_lshl_add_u64 v[66:67], v[66:67], 0, s[14:15]
	s_lshl_b32 s14, s49, 2
	v_lshl_add_u64 v[66:67], v[66:67], 0, s[14:15]
	global_store_dword v[66:67], v64, off
; __device__ __forceinline__ unsigned cvt_pk_bf16(float lo, float hi) { unsigned r; asm volatile("v_cvt_pk_bf16_f32 %0, %1, %2" : "=v"(r) : "v"(lo), "v"(hi)); return r; }
;     __device__ __forceinline__ void operator()(const f32x4 (&acc)[2][2][4][2], const Unit& u, int wr, int wc, int fr, int fq) const {
;         const int row0 = u.pm * BM + wr * 64 + fr, col0 = u.pn * BM + wc * 32 + 4 * fq;
;         const float* gp = gate + (size_t)(u.pm >> 4) * NMOD;
;         f32x4 gv[2][2], sv[2][2];
; #pragma unroll
;         for (int bj = 0; bj < 2; ++bj)
; #pragma unroll
;             for (int n = 0; n < 2; ++n) { gv[bj][n] = *(const f32x4*)(gp + col0 + bj * HALF + n * 16) * (HALFSC ? 0.5f : 1.0f);
;                 if (FOLD) sv[bj][n] = *(const f32x4*)(scn + (size_t)(u.pm >> 4) * NMOD + col0 + bj * HALF + n * 16) + 1.0f; }
; #pragma unroll
;         for (int ai = 0; ai < 2; ++ai)
; #pragma unroll
;             for (int m = 0; m < 4; ++m) { const int row = row0 + ai * HALF + m * 16; const size_t off = (size_t)row * D + col0;
;                 float ssq = 0.f;
; #pragma unroll
;                 for (int bj = 0; bj < 2; ++bj)
; #pragma unroll
;                     for (int n = 0; n < 2; ++n) { const f32x4 bs = *(const f32x4*)(base + off + bj * HALF + n * 16);
;                         const f32x4 o = bs + gv[bj][n] * acc[ai][bj][m][n];
;                         *(f32x4*)(out + off + bj * HALF + n * 16) = o;
;                         if (FOLD) { ssq += (o.x * o.x + o.y * o.y) + (o.z * o.z + o.w * o.w); const f32x4 q = o * sv[bj][n];
;                             u32x2 w; w.x = cvt_pk_bf16(q.x, q.y); w.y = cvt_pk_bf16(q.z, q.w); *(u32x2*)(U2 + off + bj * HALF + n * 16) = w; } }
;                 if (FOLD) { ssq += __shfl_xor(ssq, 16); ssq += __shfl_xor(ssq, 32);
;                     if (fq == 0) part[(size_t)row * 16 + (u.pn & 3) * 4 + wc] = ssq; } }
.LBB0_2453:
	s_or_b64 exec, exec, s[6:7]
	v_add_u32_e32 v64, 0x80, v162
	s_waitcnt lgkmcnt(0)
	v_ashrrev_i32_e32 v65, 31, v64
	v_lshlrev_b64 v[66:67], 10, v[64:65]
	v_readlane_b32 s60, v248, 0
	v_lshl_add_u64 v[70:71], v[66:67], 0, v[160:161]
	v_readlane_b32 s66, v248, 6
	v_readlane_b32 s67, v248, 7
	v_readlane_b32 s6, v249, 43
	v_readlane_b32 s7, v249, 44
	v_lshl_add_u64 v[72:73], v[70:71], 2, s[66:67]
	global_load_dwordx4 v[236:239], v[72:73], off
	global_load_dwordx4 v[240:243], v[72:73], off offset:64
	global_load_dwordx4 v[244:247], v[72:73], off offset:512
	global_load_dwordx4 v[66:69], v[72:73], off offset:576
	v_lshl_add_u64 v[70:71], v[70:71], 1, s[6:7]
	v_readlane_b32 s61, v248, 1
	v_readlane_b32 s62, v248, 2
	v_readlane_b32 s63, v248, 3
	v_readlane_b32 s64, v248, 4
	v_readlane_b32 s65, v248, 5
	s_waitcnt vmcnt(3)
	v_pk_fma_f32 v[60:61], v[60:61], v[100:101], v[236:237]
	v_pk_fma_f32 v[62:63], v[62:63], v[102:103], v[238:239]
	v_pk_mul_f32 v[238:239], v[166:167], v[60:61]
	global_store_dwordx4 v[72:73], v[60:63], off sc1
	v_pk_mul_f32 v[236:237], v[164:165], v[62:63]
	v_cvt_pk_bf16_f32 v238, v238, v239
	s_nop 0
	v_cvt_pk_bf16_f32 v239, v236, v237
	global_store_dwordx2 v[70:71], v[238:239], off
	v_mul_f32_e32 v61, v61, v61
	v_mul_f32_e32 v63, v63, v63
	v_fmac_f32_e32 v61, v60, v60
	v_fmac_f32_e32 v63, v62, v62
	v_add_f32_e32 v60, v61, v63
	s_waitcnt vmcnt(4)
	v_pk_fma_f32 v[56:57], v[56:57], v[108:109], v[240:241]
	v_pk_fma_f32 v[58:59], v[58:59], v[110:111], v[242:243]
	v_pk_mul_f32 v[242:243], v[142:143], v[56:57]
	global_store_dwordx4 v[72:73], v[56:59], off offset:64 sc1
	v_pk_mul_f32 v[240:241], v[140:141], v[58:59]
	v_cvt_pk_bf16_f32 v242, v242, v243
	s_nop 0
	v_cvt_pk_bf16_f32 v243, v240, v241
	global_store_dwordx2 v[70:71], v[242:243], off offset:32
	v_mul_f32_e32 v57, v57, v57
	v_mul_f32_e32 v59, v59, v59
	v_fmac_f32_e32 v57, v56, v56
	v_fmac_f32_e32 v59, v58, v58
	v_add_f32_e32 v56, v57, v59
	v_add_f32_e32 v56, v60, v56
	s_waitcnt vmcnt(5)
	v_pk_fma_f32 v[52:53], v[52:53], v[104:105], v[244:245]
	v_pk_fma_f32 v[54:55], v[54:55], v[106:107], v[246:247]
	v_pk_mul_f32 v[246:247], v[138:139], v[52:53]
	global_store_dwordx4 v[72:73], v[52:55], off offset:512 sc1
	v_pk_mul_f32 v[244:245], v[136:137], v[54:55]
	v_cvt_pk_bf16_f32 v246, v246, v247
	s_nop 0
	v_cvt_pk_bf16_f32 v247, v244, v245
	global_store_dwordx2 v[70:71], v[246:247], off offset:256
	v_mul_f32_e32 v53, v53, v53
	v_mul_f32_e32 v55, v55, v55
	v_fmac_f32_e32 v53, v52, v52
	v_fmac_f32_e32 v55, v54, v54
	v_add_f32_e32 v52, v53, v55
	v_add_f32_e32 v54, v56, v52
	s_waitcnt vmcnt(6)
	v_pk_fma_f32 v[52:53], v[50:51], v[98:99], v[68:69]
	v_pk_fma_f32 v[50:51], v[48:49], v[96:97], v[66:67]
	v_mul_f32_e32 v49, v53, v53
	v_mul_f32_e32 v48, v51, v51
	v_fmac_f32_e32 v48, v50, v50
	v_fmac_f32_e32 v49, v52, v52
	v_add_f32_e32 v48, v48, v49
	v_add_f32_e32 v48, v54, v48
	ds_bpermute_b32 v49, v207, v48
	global_store_dwordx4 v[72:73], v[50:53], off offset:576 sc1
	s_waitcnt lgkmcnt(0)
	v_add_f32_e32 v48, v48, v49
	ds_bpermute_b32 v49, v208, v48
	v_pk_mul_f32 v[50:51], v[132:133], v[50:51]
	v_pk_mul_f32 v[52:53], v[134:135], v[52:53]
	v_cvt_pk_bf16_f32 v50, v50, v51
	s_nop 0
	v_cvt_pk_bf16_f32 v51, v52, v53
	global_store_dwordx2 v[70:71], v[50:51], off offset:288
	s_and_saveexec_b64 s[6:7], s[0:1]
	s_cbranch_execz .LBB0_2455
	v_readlane_b32 s34, v249, 31
	v_lshlrev_b64 v[50:51], 6, v[64:65]
	v_readlane_b32 s35, v249, 32
	s_lshl_b32 s14, s27, 2
	s_waitcnt lgkmcnt(0)
	v_add_f32_e32 v48, v48, v49
	v_lshl_add_u64 v[50:51], s[34:35], 0, v[50:51]
	v_lshl_add_u64 v[50:51], v[50:51], 0, s[14:15]
	s_lshl_b32 s14, s49, 2
	v_lshl_add_u64 v[50:51], v[50:51], 0, s[14:15]
	global_store_dword v[50:51], v48, off
.LBB0_2455:
	s_or_b64 exec, exec, s[6:7]
	v_add_u32_e32 v48, 0x90, v162
	s_waitcnt lgkmcnt(0)
	v_ashrrev_i32_e32 v49, 31, v48
	v_lshlrev_b64 v[50:51], 10, v[48:49]
	v_readlane_b32 s60, v248, 0
	v_lshl_add_u64 v[54:55], v[50:51], 0, v[160:161]
	v_readlane_b32 s66, v248, 6
	v_readlane_b32 s67, v248, 7
	v_readlane_b32 s6, v249, 43
	v_readlane_b32 s7, v249, 44
	v_lshl_add_u64 v[56:57], v[54:55], 2, s[66:67]
	global_load_dwordx4 v[236:239], v[56:57], off
	global_load_dwordx4 v[240:243], v[56:57], off offset:64
	global_load_dwordx4 v[244:247], v[56:57], off offset:512
	global_load_dwordx4 v[50:53], v[56:57], off offset:576
	v_lshl_add_u64 v[54:55], v[54:55], 1, s[6:7]
	v_readlane_b32 s61, v248, 1
	v_readlane_b32 s62, v248, 2
	v_readlane_b32 s63, v248, 3
	v_readlane_b32 s64, v248, 4
	v_readlane_b32 s65, v248, 5
	s_waitcnt vmcnt(3)
	v_pk_fma_f32 v[44:45], v[44:45], v[100:101], v[236:237]
	v_pk_fma_f32 v[46:47], v[46:47], v[102:103], v[238:239]
	v_pk_mul_f32 v[238:239], v[166:167], v[44:45]
	global_store_dwordx4 v[56:57], v[44:47], off sc1
	v_pk_mul_f32 v[236:237], v[164:165], v[46:47]
	v_cvt_pk_bf16_f32 v238, v238, v239
	s_nop 0
	v_cvt_pk_bf16_f32 v239, v236, v237
	global_store_dwordx2 v[54:55], v[238:239], off
	v_mul_f32_e32 v45, v45, v45
	v_mul_f32_e32 v47, v47, v47
	v_fmac_f32_e32 v45, v44, v44
	v_fmac_f32_e32 v47, v46, v46
	v_add_f32_e32 v44, v45, v47
	s_waitcnt vmcnt(4)
	v_pk_fma_f32 v[40:41], v[40:41], v[108:109], v[240:241]
	v_pk_fma_f32 v[42:43], v[42:43], v[110:111], v[242:243]
	v_pk_mul_f32 v[242:243], v[142:143], v[40:41]
	global_store_dwordx4 v[56:57], v[40:43], off offset:64 sc1
	v_pk_mul_f32 v[240:241], v[140:141], v[42:43]
	v_cvt_pk_bf16_f32 v242, v242, v243
	s_nop 0
	v_cvt_pk_bf16_f32 v243, v240, v241
	global_store_dwordx2 v[54:55], v[242:243], off offset:32
	v_mul_f32_e32 v41, v41, v41
	v_mul_f32_e32 v43, v43, v43
	v_fmac_f32_e32 v41, v40, v40
	v_fmac_f32_e32 v43, v42, v42
	v_add_f32_e32 v40, v41, v43
	v_add_f32_e32 v40, v44, v40
	s_waitcnt vmcnt(5)
; __device__ __forceinline__ unsigned cvt_pk_bf16(float lo, float hi) { unsigned r; asm volatile("v_cvt_pk_bf16_f32 %0, %1, %2" : "=v"(r) : "v"(lo), "v"(hi)); return r; }
;     __device__ __forceinline__ void operator()(const f32x4 (&acc)[2][2][4][2], const Unit& u, int wr, int wc, int fr, int fq) const {
;         const int row0 = u.pm * BM + wr * 64 + fr, col0 = u.pn * BM + wc * 32 + 4 * fq;
;         const float* gp = gate + (size_t)(u.pm >> 4) * NMOD;
;         f32x4 gv[2][2], sv[2][2];
; #pragma unroll
;         for (int bj = 0; bj < 2; ++bj)
; #pragma unroll
;             for (int n = 0; n < 2; ++n) { gv[bj][n] = *(const f32x4*)(gp + col0 + bj * HALF + n * 16) * (HALFSC ? 0.5f : 1.0f);
;                 if (FOLD) sv[bj][n] = *(const f32x4*)(scn + (size_t)(u.pm >> 4) * NMOD + col0 + bj * HALF + n * 16) + 1.0f; }
; #pragma unroll
;         for (int ai = 0; ai < 2; ++ai)
; #pragma unroll
;             for (int m = 0; m < 4; ++m) { const int row = row0 + ai * HALF + m * 16; const size_t off = (size_t)row * D + col0;
;                 float ssq = 0.f;
; #pragma unroll
;                 for (int bj = 0; bj < 2; ++bj)
; #pragma unroll
;                     for (int n = 0; n < 2; ++n) { const f32x4 bs = *(const f32x4*)(base + off + bj * HALF + n * 16);
;                         const f32x4 o = bs + gv[bj][n] * acc[ai][bj][m][n];
;                         *(f32x4*)(out + off + bj * HALF + n * 16) = o;
;                         if (FOLD) { ssq += (o.x * o.x + o.y * o.y) + (o.z * o.z + o.w * o.w); const f32x4 q = o * sv[bj][n];
;                             u32x2 w; w.x = cvt_pk_bf16(q.x, q.y); w.y = cvt_pk_bf16(q.z, q.w); *(u32x2*)(U2 + off + bj * HALF + n * 16) = w; } }
;                 if (FOLD) { ssq += __shfl_xor(ssq, 16); ssq += __shfl_xor(ssq, 32);
;                     if (fq == 0) part[(size_t)row * 16 + (u.pn & 3) * 4 + wc] = ssq; } }
	v_pk_fma_f32 v[36:37], v[36:37], v[104:105], v[244:245]
	v_pk_fma_f32 v[38:39], v[38:39], v[106:107], v[246:247]
	v_pk_mul_f32 v[246:247], v[138:139], v[36:37]
	global_store_dwordx4 v[56:57], v[36:39], off offset:512 sc1
	v_pk_mul_f32 v[244:245], v[136:137], v[38:39]
	v_cvt_pk_bf16_f32 v246, v246, v247
	s_nop 0
	v_cvt_pk_bf16_f32 v247, v244, v245
	global_store_dwordx2 v[54:55], v[246:247], off offset:256
	v_mul_f32_e32 v37, v37, v37
	v_mul_f32_e32 v39, v39, v39
	v_fmac_f32_e32 v37, v36, v36
	v_fmac_f32_e32 v39, v38, v38
	v_add_f32_e32 v36, v37, v39
	v_add_f32_e32 v38, v40, v36
	s_waitcnt vmcnt(6)
	v_pk_fma_f32 v[36:37], v[34:35], v[98:99], v[52:53]
	v_pk_fma_f32 v[34:35], v[32:33], v[96:97], v[50:51]
	v_mul_f32_e32 v33, v37, v37
	v_mul_f32_e32 v32, v35, v35
	v_fmac_f32_e32 v32, v34, v34
	v_fmac_f32_e32 v33, v36, v36
	v_add_f32_e32 v32, v32, v33
	v_add_f32_e32 v32, v38, v32
	ds_bpermute_b32 v33, v207, v32
	global_store_dwordx4 v[56:57], v[34:37], off offset:576 sc1
	s_waitcnt lgkmcnt(0)
	v_add_f32_e32 v32, v32, v33
	ds_bpermute_b32 v33, v208, v32
	v_pk_mul_f32 v[34:35], v[132:133], v[34:35]
	v_pk_mul_f32 v[36:37], v[134:135], v[36:37]
	v_cvt_pk_bf16_f32 v34, v34, v35
	s_nop 0
	v_cvt_pk_bf16_f32 v35, v36, v37
	global_store_dwordx2 v[54:55], v[34:35], off offset:288
	s_and_saveexec_b64 s[6:7], s[0:1]
	s_cbranch_execz .LBB0_2457
	v_readlane_b32 s34, v249, 31
	v_lshlrev_b64 v[34:35], 6, v[48:49]
	v_readlane_b32 s35, v249, 32
	s_lshl_b32 s14, s27, 2
	s_waitcnt lgkmcnt(0)
	v_add_f32_e32 v32, v32, v33
	v_lshl_add_u64 v[34:35], s[34:35], 0, v[34:35]
	v_lshl_add_u64 v[34:35], v[34:35], 0, s[14:15]
	s_lshl_b32 s14, s49, 2
	v_lshl_add_u64 v[34:35], v[34:35], 0, s[14:15]
	global_store_dword v[34:35], v32, off
.LBB0_2457:
	s_or_b64 exec, exec, s[6:7]
	v_add_u32_e32 v32, 0xa0, v162
	s_waitcnt lgkmcnt(0)
	v_ashrrev_i32_e32 v33, 31, v32
	v_lshlrev_b64 v[34:35], 10, v[32:33]
	v_readlane_b32 s60, v248, 0
	v_lshl_add_u64 v[38:39], v[34:35], 0, v[160:161]
	v_readlane_b32 s66, v248, 6
	v_readlane_b32 s67, v248, 7
	v_readlane_b32 s6, v249, 43
	v_readlane_b32 s7, v249, 44
	v_lshl_add_u64 v[40:41], v[38:39], 2, s[66:67]
	global_load_dwordx4 v[236:239], v[40:41], off
	global_load_dwordx4 v[240:243], v[40:41], off offset:64
	global_load_dwordx4 v[244:247], v[40:41], off offset:512
	global_load_dwordx4 v[34:37], v[40:41], off offset:576
	v_lshl_add_u64 v[38:39], v[38:39], 1, s[6:7]
	v_readlane_b32 s61, v248, 1
	v_readlane_b32 s62, v248, 2
	v_readlane_b32 s63, v248, 3
	v_readlane_b32 s64, v248, 4
	v_readlane_b32 s65, v248, 5
	s_waitcnt vmcnt(3)
	v_pk_fma_f32 v[28:29], v[28:29], v[100:101], v[236:237]
	v_pk_fma_f32 v[30:31], v[30:31], v[102:103], v[238:239]
	v_pk_mul_f32 v[238:239], v[166:167], v[28:29]
	global_store_dwordx4 v[40:41], v[28:31], off sc1
	v_pk_mul_f32 v[236:237], v[164:165], v[30:31]
	v_cvt_pk_bf16_f32 v238, v238, v239
	s_nop 0
	v_cvt_pk_bf16_f32 v239, v236, v237
	global_store_dwordx2 v[38:39], v[238:239], off
	v_mul_f32_e32 v29, v29, v29
	v_mul_f32_e32 v31, v31, v31
	v_fmac_f32_e32 v29, v28, v28
	v_fmac_f32_e32 v31, v30, v30
	v_add_f32_e32 v28, v29, v31
	s_waitcnt vmcnt(4)
	v_pk_fma_f32 v[24:25], v[24:25], v[108:109], v[240:241]
	v_pk_fma_f32 v[26:27], v[26:27], v[110:111], v[242:243]
	v_pk_mul_f32 v[242:243], v[142:143], v[24:25]
	global_store_dwordx4 v[40:41], v[24:27], off offset:64 sc1
	v_pk_mul_f32 v[240:241], v[140:141], v[26:27]
	v_cvt_pk_bf16_f32 v242, v242, v243
	s_nop 0
	v_cvt_pk_bf16_f32 v243, v240, v241
	global_store_dwordx2 v[38:39], v[242:243], off offset:32
	v_mul_f32_e32 v25, v25, v25
	v_mul_f32_e32 v27, v27, v27
	v_fmac_f32_e32 v25, v24, v24
	v_fmac_f32_e32 v27, v26, v26
	v_add_f32_e32 v24, v25, v27
	v_add_f32_e32 v24, v28, v24
	s_waitcnt vmcnt(5)
	v_pk_fma_f32 v[20:21], v[20:21], v[104:105], v[244:245]
	v_pk_fma_f32 v[22:23], v[22:23], v[106:107], v[246:247]
	v_pk_mul_f32 v[246:247], v[138:139], v[20:21]
	global_store_dwordx4 v[40:41], v[20:23], off offset:512 sc1
	v_pk_mul_f32 v[244:245], v[136:137], v[22:23]
	v_cvt_pk_bf16_f32 v246, v246, v247
	s_nop 0
	v_cvt_pk_bf16_f32 v247, v244, v245
	global_store_dwordx2 v[38:39], v[246:247], off offset:256
	v_mul_f32_e32 v21, v21, v21
	v_mul_f32_e32 v23, v23, v23
	v_fmac_f32_e32 v21, v20, v20
	v_fmac_f32_e32 v23, v22, v22
	v_add_f32_e32 v20, v21, v23
	v_add_f32_e32 v22, v24, v20
	s_waitcnt vmcnt(6)
	v_pk_fma_f32 v[20:21], v[18:19], v[98:99], v[36:37]
	v_pk_fma_f32 v[18:19], v[16:17], v[96:97], v[34:35]
	v_mul_f32_e32 v17, v21, v21
	v_mul_f32_e32 v16, v19, v19
	v_fmac_f32_e32 v16, v18, v18
	v_fmac_f32_e32 v17, v20, v20
	v_add_f32_e32 v16, v16, v17
	v_add_f32_e32 v16, v22, v16
	ds_bpermute_b32 v17, v207, v16
	global_store_dwordx4 v[40:41], v[18:21], off offset:576 sc1
	s_waitcnt lgkmcnt(0)
	v_add_f32_e32 v16, v16, v17
	ds_bpermute_b32 v17, v208, v16
	v_pk_mul_f32 v[18:19], v[132:133], v[18:19]
	v_pk_mul_f32 v[20:21], v[134:135], v[20:21]
	v_cvt_pk_bf16_f32 v18, v18, v19
	s_nop 0
	v_cvt_pk_bf16_f32 v19, v20, v21
	global_store_dwordx2 v[38:39], v[18:19], off offset:288
	s_and_saveexec_b64 s[6:7], s[0:1]
	s_cbranch_execz .LBB0_2459
	v_readlane_b32 s34, v249, 31
	v_lshlrev_b64 v[18:19], 6, v[32:33]
	v_readlane_b32 s35, v249, 32
	s_lshl_b32 s14, s27, 2
	s_waitcnt lgkmcnt(0)
	v_add_f32_e32 v16, v16, v17
	v_lshl_add_u64 v[18:19], s[34:35], 0, v[18:19]
	v_lshl_add_u64 v[18:19], v[18:19], 0, s[14:15]
	s_lshl_b32 s14, s49, 2
	v_lshl_add_u64 v[18:19], v[18:19], 0, s[14:15]
	global_store_dword v[18:19], v16, off
; __device__ __forceinline__ unsigned cvt_pk_bf16(float lo, float hi) { unsigned r; asm volatile("v_cvt_pk_bf16_f32 %0, %1, %2" : "=v"(r) : "v"(lo), "v"(hi)); return r; }
;     __device__ __forceinline__ void operator()(const f32x4 (&acc)[2][2][4][2], const Unit& u, int wr, int wc, int fr, int fq) const {
;         const int row0 = u.pm * BM + wr * 64 + fr, col0 = u.pn * BM + wc * 32 + 4 * fq;
;         const float* gp = gate + (size_t)(u.pm >> 4) * NMOD;
;         f32x4 gv[2][2], sv[2][2];
; #pragma unroll
;         for (int bj = 0; bj < 2; ++bj)
; #pragma unroll
;             for (int n = 0; n < 2; ++n) { gv[bj][n] = *(const f32x4*)(gp + col0 + bj * HALF + n * 16) * (HALFSC ? 0.5f : 1.0f);
;                 if (FOLD) sv[bj][n] = *(const f32x4*)(scn + (size_t)(u.pm >> 4) * NMOD + col0 + bj * HALF + n * 16) + 1.0f; }
; #pragma unroll
;         for (int ai = 0; ai < 2; ++ai)
; #pragma unroll
;             for (int m = 0; m < 4; ++m) { const int row = row0 + ai * HALF + m * 16; const size_t off = (size_t)row * D + col0;
;                 float ssq = 0.f;
; #pragma unroll
;                 for (int bj = 0; bj < 2; ++bj)
; #pragma unroll
;                     for (int n = 0; n < 2; ++n) { const f32x4 bs = *(const f32x4*)(base + off + bj * HALF + n * 16);
;                         const f32x4 o = bs + gv[bj][n] * acc[ai][bj][m][n];
;                         *(f32x4*)(out + off + bj * HALF + n * 16) = o;
;                         if (FOLD) { ssq += (o.x * o.x + o.y * o.y) + (o.z * o.z + o.w * o.w); const f32x4 q = o * sv[bj][n];
;                             u32x2 w; w.x = cvt_pk_bf16(q.x, q.y); w.y = cvt_pk_bf16(q.z, q.w); *(u32x2*)(U2 + off + bj * HALF + n * 16) = w; } }
;                 if (FOLD) { ssq += __shfl_xor(ssq, 16); ssq += __shfl_xor(ssq, 32);
;                     if (fq == 0) part[(size_t)row * 16 + (u.pn & 3) * 4 + wc] = ssq; } }
.LBB0_2459:
	s_or_b64 exec, exec, s[6:7]
	v_add_u32_e32 v16, 0xb0, v162
	s_waitcnt lgkmcnt(0)
	v_ashrrev_i32_e32 v17, 31, v16
	v_lshlrev_b64 v[18:19], 10, v[16:17]
	v_readlane_b32 s60, v248, 0
	v_lshl_add_u64 v[22:23], v[18:19], 0, v[160:161]
	v_readlane_b32 s66, v248, 6
	v_readlane_b32 s67, v248, 7
	v_readlane_b32 s6, v249, 43
	v_readlane_b32 s7, v249, 44
	v_lshl_add_u64 v[24:25], v[22:23], 2, s[66:67]
	global_load_dwordx4 v[236:239], v[24:25], off
	global_load_dwordx4 v[240:243], v[24:25], off offset:64
	global_load_dwordx4 v[244:247], v[24:25], off offset:512
	global_load_dwordx4 v[18:21], v[24:25], off offset:576
	v_lshl_add_u64 v[22:23], v[22:23], 1, s[6:7]
	v_readlane_b32 s61, v248, 1
	v_readlane_b32 s62, v248, 2
	v_readlane_b32 s63, v248, 3
	v_readlane_b32 s64, v248, 4
	v_readlane_b32 s65, v248, 5
	s_waitcnt vmcnt(3)
	v_pk_fma_f32 v[12:13], v[12:13], v[100:101], v[236:237]
	v_pk_fma_f32 v[14:15], v[14:15], v[102:103], v[238:239]
	v_pk_mul_f32 v[238:239], v[166:167], v[12:13]
	global_store_dwordx4 v[24:25], v[12:15], off sc1
	v_pk_mul_f32 v[236:237], v[164:165], v[14:15]
	v_cvt_pk_bf16_f32 v238, v238, v239
	s_nop 0
	v_cvt_pk_bf16_f32 v239, v236, v237
	global_store_dwordx2 v[22:23], v[238:239], off
	v_mul_f32_e32 v13, v13, v13
	v_mul_f32_e32 v15, v15, v15
	v_fmac_f32_e32 v13, v12, v12
	v_fmac_f32_e32 v15, v14, v14
	v_add_f32_e32 v12, v13, v15
	s_waitcnt vmcnt(4)
	v_pk_fma_f32 v[8:9], v[8:9], v[108:109], v[240:241]
	v_pk_fma_f32 v[10:11], v[10:11], v[110:111], v[242:243]
	v_pk_mul_f32 v[242:243], v[142:143], v[8:9]
	global_store_dwordx4 v[24:25], v[8:11], off offset:64 sc1
	v_pk_mul_f32 v[240:241], v[140:141], v[10:11]
	v_cvt_pk_bf16_f32 v242, v242, v243
	s_nop 0
	v_cvt_pk_bf16_f32 v243, v240, v241
	global_store_dwordx2 v[22:23], v[242:243], off offset:32
	v_mul_f32_e32 v9, v9, v9
	v_mul_f32_e32 v11, v11, v11
	v_fmac_f32_e32 v9, v8, v8
	v_fmac_f32_e32 v11, v10, v10
	v_add_f32_e32 v8, v9, v11
	v_add_f32_e32 v8, v12, v8
	s_waitcnt vmcnt(5)
	v_pk_fma_f32 v[4:5], v[4:5], v[104:105], v[244:245]
	v_pk_fma_f32 v[6:7], v[6:7], v[106:107], v[246:247]
	v_pk_mul_f32 v[246:247], v[138:139], v[4:5]
	global_store_dwordx4 v[24:25], v[4:7], off offset:512 sc1
	v_pk_mul_f32 v[244:245], v[136:137], v[6:7]
	v_cvt_pk_bf16_f32 v246, v246, v247
	s_nop 0
	v_cvt_pk_bf16_f32 v247, v244, v245
	global_store_dwordx2 v[22:23], v[246:247], off offset:256
	v_mul_f32_e32 v5, v5, v5
	v_mul_f32_e32 v7, v7, v7
	v_fmac_f32_e32 v5, v4, v4
	v_fmac_f32_e32 v7, v6, v6
	v_add_f32_e32 v4, v5, v7
	v_add_f32_e32 v6, v8, v4
	s_waitcnt vmcnt(6)
	v_pk_fma_f32 v[4:5], v[2:3], v[98:99], v[20:21]
	v_pk_fma_f32 v[2:3], v[0:1], v[96:97], v[18:19]
	v_mul_f32_e32 v1, v5, v5
	v_mul_f32_e32 v0, v3, v3
	v_fmac_f32_e32 v0, v2, v2
	v_fmac_f32_e32 v1, v4, v4
	v_add_f32_e32 v0, v0, v1
	v_add_f32_e32 v0, v6, v0
	ds_bpermute_b32 v1, v207, v0
	global_store_dwordx4 v[24:25], v[2:5], off offset:576 sc1
	s_waitcnt lgkmcnt(0)
	v_add_f32_e32 v0, v0, v1
	ds_bpermute_b32 v1, v208, v0
	v_pk_mul_f32 v[2:3], v[132:133], v[2:3]
	v_pk_mul_f32 v[4:5], v[134:135], v[4:5]
	v_cvt_pk_bf16_f32 v2, v2, v3
	s_nop 0
	v_cvt_pk_bf16_f32 v3, v4, v5
	global_store_dwordx2 v[22:23], v[2:3], off offset:288
	s_and_saveexec_b64 s[6:7], s[0:1]
	s_cbranch_execz .LBB0_2461
	v_readlane_b32 s34, v249, 31
	v_lshlrev_b64 v[2:3], 6, v[16:17]
	v_readlane_b32 s35, v249, 32
	s_lshl_b32 s14, s27, 2
	s_waitcnt lgkmcnt(0)
	v_add_f32_e32 v0, v0, v1
	v_lshl_add_u64 v[2:3], s[34:35], 0, v[2:3]
	v_lshl_add_u64 v[2:3], v[2:3], 0, s[14:15]
	s_lshl_b32 s14, s49, 2
	v_lshl_add_u64 v[2:3], v[2:3], 0, s[14:15]
	global_store_dword v[2:3], v0, off

; __device__ __forceinline__ unsigned cvt_pk_bf16(float lo, float hi) { unsigned r; asm volatile("v_cvt_pk_bf16_f32 %0, %1, %2" : "=v"(r) : "v"(lo), "v"(hi)); return r; }
;     __device__ __forceinline__ void operator()(const f32x4 (&acc)[2][2][4][2], const Unit& u, int wr, int wc, int fr, int fq) const {
;         const int row0 = u.pm * BM + wr * 64 + fr, col0 = u.pn * BM + wc * 32 + 4 * fq;
;         const float* gp = gate + (size_t)(u.pm >> 4) * NMOD;
;         f32x4 gv[2][2], sv[2][2];
; #pragma unroll
;         for (int bj = 0; bj < 2; ++bj)
; #pragma unroll
;             for (int n = 0; n < 2; ++n) { gv[bj][n] = *(const f32x4*)(gp + col0 + bj * HALF + n * 16) * (HALFSC ? 0.5f : 1.0f);
;                 if (FOLD) sv[bj][n] = *(const f32x4*)(scn + (size_t)(u.pm >> 4) * NMOD + col0 + bj * HALF + n * 16) + 1.0f; }
; #pragma unroll
;         for (int ai = 0; ai < 2; ++ai)
; #pragma unroll
;             for (int m = 0; m < 4; ++m) { const int row = row0 + ai * HALF + m * 16; const size_t off = (size_t)row * D + col0;
;                 float ssq = 0.f;
; #pragma unroll
;                 for (int bj = 0; bj < 2; ++bj)
; #pragma unroll
;                     for (int n = 0; n < 2; ++n) { const f32x4 bs = *(const f32x4*)(base + off + bj * HALF + n * 16);
;                         const f32x4 o = bs + gv[bj][n] * acc[ai][bj][m][n];
;                         *(f32x4*)(out + off + bj * HALF + n * 16) = o;
;                         if (FOLD) { ssq += (o.x * o.x + o.y * o.y) + (o.z * o.z + o.w * o.w); const f32x4 q = o * sv[bj][n];
;                             u32x2 w; w.x = cvt_pk_bf16(q.x, q.y); w.y = cvt_pk_bf16(q.z, q.w); *(u32x2*)(U2 + off + bj * HALF + n * 16) = w; } }
;                 if (FOLD) { ssq += __shfl_xor(ssq, 16); ssq += __shfl_xor(ssq, 32);
;                     if (fq == 0) part[(size_t)row * 16 + (u.pn & 3) * 4 + wc] = ssq; } }
.LBB0_2613:
	s_ashr_i32 s22, s46, 4
	v_lshl_or_b32 v144, s47, 8, v166
	s_mul_hi_i32 s23, s22, 0x9000
	s_mul_i32 s22, s22, 0x9000
	s_add_u32 s22, s36, s22
	v_ashrrev_i32_e32 v145, 31, v144
	s_addc_u32 s23, s37, s23
	v_lshlrev_b64 v[162:163], 2, v[144:145]
	v_lshl_add_u64 v[160:161], s[22:23], 0, v[162:163]
	global_load_dwordx4 v[176:179], v[160:161], off
	global_load_dwordx4 v[180:183], v[160:161], off offset:64
	global_load_dwordx4 v[184:187], v[160:161], off offset:512
	global_load_dwordx4 v[144:147], v[160:161], off offset:576
	v_lshl_add_u32 v174, s46, 8, v164
	v_readlane_b32 s48, v248, 0
	v_ashrrev_i32_e32 v175, 31, v174
	v_readlane_b32 s54, v248, 6
	v_readlane_b32 s55, v248, 7
	s_mov_b64 s[22:23], s[54:55]
	v_readlane_b32 s49, v248, 1
	v_readlane_b32 s50, v248, 2
	v_readlane_b32 s51, v248, 3
	v_readlane_b32 s52, v248, 4
	v_readlane_b32 s53, v248, 5
	s_waitcnt vmcnt(3)
	v_pk_mul_f32 v[156:157], v[178:179], 0.5 op_sel_hi:[1,0]
	v_pk_mul_f32 v[158:159], v[176:177], 0.5 op_sel_hi:[1,0]
	s_waitcnt vmcnt(2)
	v_pk_mul_f32 v[152:153], v[182:183], 0.5 op_sel_hi:[1,0]
	v_pk_mul_f32 v[154:155], v[180:181], 0.5 op_sel_hi:[1,0]
	s_waitcnt vmcnt(1)
	v_pk_mul_f32 v[148:149], v[186:187], 0.5 op_sel_hi:[1,0]
	v_pk_mul_f32 v[150:151], v[184:185], 0.5 op_sel_hi:[1,0]
	v_lshlrev_b64 v[160:161], 12, v[174:175]
	v_lshl_add_u64 v[160:161], s[22:23], 0, v[160:161]
	v_lshl_add_u64 v[160:161], v[160:161], 0, v[162:163]
	global_load_dwordx4 v[216:219], v[160:161], off
	global_load_dwordx4 v[220:223], v[160:161], off offset:64
	global_load_dwordx4 v[236:239], v[160:161], off offset:512
	global_load_dwordx4 v[240:243], v[160:161], off offset:576
	s_waitcnt vmcnt(3)
	v_pk_mul_f32 v[146:147], v[146:147], 0.5 op_sel_hi:[1,0]
	v_pk_mul_f32 v[144:145], v[144:145], 0.5 op_sel_hi:[1,0]
	v_pk_fma_f32 v[126:127], v[126:127], v[156:157], v[218:219]
	v_pk_fma_f32 v[124:125], v[124:125], v[158:159], v[216:217]
	global_store_dwordx4 v[160:161], v[124:127], off sc1
	s_waitcnt vmcnt(3)
	v_pk_fma_f32 v[122:123], v[122:123], v[152:153], v[222:223]
	v_pk_fma_f32 v[120:121], v[120:121], v[154:155], v[220:221]
	global_store_dwordx4 v[160:161], v[120:123], off offset:64 sc1
	s_waitcnt vmcnt(3)
	v_pk_fma_f32 v[118:119], v[118:119], v[148:149], v[238:239]
	v_pk_fma_f32 v[116:117], v[116:117], v[150:151], v[236:237]
	global_store_dwordx4 v[160:161], v[116:119], off offset:512 sc1
	s_waitcnt vmcnt(3)
	v_pk_fma_f32 v[114:115], v[114:115], v[146:147], v[242:243]
	v_pk_fma_f32 v[112:113], v[112:113], v[144:145], v[240:241]
	global_store_dwordx4 v[160:161], v[112:115], off offset:576 sc1
	s_nop 1
	v_or_b32_e32 v112, 16, v174
	v_ashrrev_i32_e32 v113, 31, v112
	v_lshlrev_b64 v[112:113], 12, v[112:113]
	v_lshl_add_u64 v[112:113], s[22:23], 0, v[112:113]
	v_lshl_add_u64 v[116:117], v[112:113], 0, v[162:163]
	global_load_dwordx4 v[216:219], v[116:117], off
	global_load_dwordx4 v[220:223], v[116:117], off offset:64
	global_load_dwordx4 v[236:239], v[116:117], off offset:512
	global_load_dwordx4 v[240:243], v[116:117], off offset:576
	s_waitcnt vmcnt(3)
	v_pk_fma_f32 v[110:111], v[110:111], v[156:157], v[218:219]
	v_pk_fma_f32 v[108:109], v[108:109], v[158:159], v[216:217]
	global_store_dwordx4 v[116:117], v[108:111], off sc1
	s_waitcnt vmcnt(3)
	v_pk_fma_f32 v[106:107], v[106:107], v[152:153], v[222:223]
	v_pk_fma_f32 v[104:105], v[104:105], v[154:155], v[220:221]
	global_store_dwordx4 v[116:117], v[104:107], off offset:64 sc1
	s_waitcnt vmcnt(3)
	v_pk_fma_f32 v[102:103], v[102:103], v[148:149], v[238:239]
	v_pk_fma_f32 v[100:101], v[100:101], v[150:151], v[236:237]
	global_store_dwordx4 v[116:117], v[100:103], off offset:512 sc1
	s_waitcnt vmcnt(3)
	v_pk_fma_f32 v[98:99], v[98:99], v[146:147], v[242:243]
	v_pk_fma_f32 v[96:97], v[96:97], v[144:145], v[240:241]
	global_store_dwordx4 v[116:117], v[96:99], off offset:576 sc1
	s_nop 1
	v_or_b32_e32 v96, 32, v174
	v_ashrrev_i32_e32 v97, 31, v96
	v_lshlrev_b64 v[96:97], 12, v[96:97]
	v_lshl_add_u64 v[96:97], s[22:23], 0, v[96:97]
	v_lshl_add_u64 v[100:101], v[96:97], 0, v[162:163]
	global_load_dwordx4 v[216:219], v[100:101], off
	global_load_dwordx4 v[220:223], v[100:101], off offset:64
	global_load_dwordx4 v[236:239], v[100:101], off offset:512
	global_load_dwordx4 v[240:243], v[100:101], off offset:576
	s_waitcnt vmcnt(3)
	v_pk_fma_f32 v[94:95], v[94:95], v[156:157], v[218:219]
	v_pk_fma_f32 v[92:93], v[92:93], v[158:159], v[216:217]
	global_store_dwordx4 v[100:101], v[92:95], off sc1
	s_waitcnt vmcnt(3)
	v_pk_fma_f32 v[90:91], v[90:91], v[152:153], v[222:223]
	v_pk_fma_f32 v[88:89], v[88:89], v[154:155], v[220:221]
	global_store_dwordx4 v[100:101], v[88:91], off offset:64 sc1
	s_waitcnt vmcnt(3)
	v_pk_fma_f32 v[86:87], v[86:87], v[148:149], v[238:239]
	v_pk_fma_f32 v[84:85], v[84:85], v[150:151], v[236:237]
	global_store_dwordx4 v[100:101], v[84:87], off offset:512 sc1
	s_waitcnt vmcnt(3)
	v_pk_fma_f32 v[82:83], v[82:83], v[146:147], v[242:243]
	v_pk_fma_f32 v[80:81], v[80:81], v[144:145], v[240:241]
	global_store_dwordx4 v[100:101], v[80:83], off offset:576 sc1
	s_nop 1
	v_or_b32_e32 v80, 48, v174
	v_ashrrev_i32_e32 v81, 31, v80
	v_lshlrev_b64 v[80:81], 12, v[80:81]
	v_lshl_add_u64 v[80:81], s[22:23], 0, v[80:81]
	v_lshl_add_u64 v[84:85], v[80:81], 0, v[162:163]
	global_load_dwordx4 v[216:219], v[84:85], off
	global_load_dwordx4 v[220:223], v[84:85], off offset:64
	global_load_dwordx4 v[236:239], v[84:85], off offset:512
	global_load_dwordx4 v[240:243], v[84:85], off offset:576
	s_mov_b64 s[22:23], 0x80000
	s_waitcnt vmcnt(3)
; __device__ __forceinline__ unsigned cvt_pk_bf16(float lo, float hi) { unsigned r; asm volatile("v_cvt_pk_bf16_f32 %0, %1, %2" : "=v"(r) : "v"(lo), "v"(hi)); return r; }
;     __device__ __forceinline__ void operator()(const f32x4 (&acc)[2][2][4][2], const Unit& u, int wr, int wc, int fr, int fq) const {
;         const int row0 = u.pm * BM + wr * 64 + fr, col0 = u.pn * BM + wc * 32 + 4 * fq;
;         const float* gp = gate + (size_t)(u.pm >> 4) * NMOD;
;         f32x4 gv[2][2], sv[2][2];
; #pragma unroll
;         for (int bj = 0; bj < 2; ++bj)
; #pragma unroll
;             for (int n = 0; n < 2; ++n) { gv[bj][n] = *(const f32x4*)(gp + col0 + bj * HALF + n * 16) * (HALFSC ? 0.5f : 1.0f);
;                 if (FOLD) sv[bj][n] = *(const f32x4*)(scn + (size_t)(u.pm >> 4) * NMOD + col0 + bj * HALF + n * 16) + 1.0f; }
; #pragma unroll
;         for (int ai = 0; ai < 2; ++ai)
; #pragma unroll
;             for (int m = 0; m < 4; ++m) { const int row = row0 + ai * HALF + m * 16; const size_t off = (size_t)row * D + col0;
;                 float ssq = 0.f;
; #pragma unroll
;                 for (int bj = 0; bj < 2; ++bj)
; #pragma unroll
;                     for (int n = 0; n < 2; ++n) { const f32x4 bs = *(const f32x4*)(base + off + bj * HALF + n * 16);
;                         const f32x4 o = bs + gv[bj][n] * acc[ai][bj][m][n];
;                         *(f32x4*)(out + off + bj * HALF + n * 16) = o;
;                         if (FOLD) { ssq += (o.x * o.x + o.y * o.y) + (o.z * o.z + o.w * o.w); const f32x4 q = o * sv[bj][n];
;                             u32x2 w; w.x = cvt_pk_bf16(q.x, q.y); w.y = cvt_pk_bf16(q.z, q.w); *(u32x2*)(U2 + off + bj * HALF + n * 16) = w; } }
;                 if (FOLD) { ssq += __shfl_xor(ssq, 16); ssq += __shfl_xor(ssq, 32);
;                     if (fq == 0) part[(size_t)row * 16 + (u.pn & 3) * 4 + wc] = ssq; } }
	v_pk_fma_f32 v[78:79], v[78:79], v[156:157], v[218:219]
	v_pk_fma_f32 v[76:77], v[76:77], v[158:159], v[216:217]
	global_store_dwordx4 v[84:85], v[76:79], off sc1
	s_waitcnt vmcnt(3)
	v_pk_fma_f32 v[74:75], v[74:75], v[152:153], v[222:223]
	v_pk_fma_f32 v[72:73], v[72:73], v[154:155], v[220:221]
	global_store_dwordx4 v[84:85], v[72:75], off offset:64 sc1
	s_waitcnt vmcnt(3)
	v_pk_fma_f32 v[70:71], v[70:71], v[148:149], v[238:239]
	v_pk_fma_f32 v[68:69], v[68:69], v[150:151], v[236:237]
	global_store_dwordx4 v[84:85], v[68:71], off offset:512 sc1
	s_waitcnt vmcnt(3)
	v_pk_fma_f32 v[64:65], v[64:65], v[144:145], v[240:241]
	v_lshl_add_u64 v[68:69], v[160:161], 0, s[22:23]
	s_mov_b32 s22, 0x80000
	v_pk_fma_f32 v[66:67], v[66:67], v[146:147], v[242:243]
	v_add_co_u32_e32 v70, vcc, s22, v160
	global_store_dwordx4 v[84:85], v[64:67], off offset:576 sc1
	s_nop 0
	v_addc_co_u32_e32 v71, vcc, 0, v161, vcc
	global_load_dwordx4 v[216:219], v[70:71], off
	global_load_dwordx4 v[220:223], v[68:69], off offset:64
	global_load_dwordx4 v[236:239], v[68:69], off offset:512
	global_load_dwordx4 v[240:243], v[68:69], off offset:576
	s_mov_b64 s[22:23], 0x90000
	s_waitcnt vmcnt(3)
	v_pk_fma_f32 v[62:63], v[62:63], v[156:157], v[218:219]
	v_pk_fma_f32 v[60:61], v[60:61], v[158:159], v[216:217]
	global_store_dwordx4 v[70:71], v[60:63], off sc1
	s_waitcnt vmcnt(3)
	v_pk_fma_f32 v[58:59], v[58:59], v[152:153], v[222:223]
	v_pk_fma_f32 v[56:57], v[56:57], v[154:155], v[220:221]
	global_store_dwordx4 v[68:69], v[56:59], off offset:64 sc1
	s_waitcnt vmcnt(3)
	v_pk_fma_f32 v[54:55], v[54:55], v[148:149], v[238:239]
	v_pk_fma_f32 v[52:53], v[52:53], v[150:151], v[236:237]
	global_store_dwordx4 v[68:69], v[52:55], off offset:512 sc1
	s_waitcnt vmcnt(3)
	v_pk_fma_f32 v[50:51], v[50:51], v[146:147], v[242:243]
	v_pk_fma_f32 v[48:49], v[48:49], v[144:145], v[240:241]
	global_store_dwordx4 v[68:69], v[48:51], off offset:576 sc1
	s_nop 1
	v_lshl_add_u64 v[48:49], v[160:161], 0, s[22:23]
	s_mov_b32 s22, 0x90000
	v_add_co_u32_e32 v54, vcc, s22, v160
	s_mov_b64 s[22:23], 0xa0000
	s_nop 0
	v_addc_co_u32_e32 v55, vcc, 0, v161, vcc
	global_load_dwordx4 v[216:219], v[54:55], off
	global_load_dwordx4 v[220:223], v[48:49], off offset:64
	global_load_dwordx4 v[236:239], v[48:49], off offset:512
	global_load_dwordx4 v[240:243], v[48:49], off offset:576
	s_waitcnt vmcnt(3)
	v_pk_fma_f32 v[46:47], v[46:47], v[156:157], v[218:219]
	v_pk_fma_f32 v[44:45], v[44:45], v[158:159], v[216:217]
	global_store_dwordx4 v[54:55], v[44:47], off sc1
	s_waitcnt vmcnt(3)
	v_pk_fma_f32 v[42:43], v[42:43], v[152:153], v[222:223]
	v_pk_fma_f32 v[40:41], v[40:41], v[154:155], v[220:221]
	global_store_dwordx4 v[48:49], v[40:43], off offset:64 sc1
	s_waitcnt vmcnt(3)
	v_pk_fma_f32 v[38:39], v[38:39], v[148:149], v[238:239]
	v_pk_fma_f32 v[36:37], v[36:37], v[150:151], v[236:237]
	global_store_dwordx4 v[48:49], v[36:39], off offset:512 sc1
	s_waitcnt vmcnt(3)
	v_pk_fma_f32 v[32:33], v[32:33], v[144:145], v[240:241]
	v_lshl_add_u64 v[36:37], v[160:161], 0, s[22:23]
	s_mov_b32 s22, 0xa0000
	v_pk_fma_f32 v[34:35], v[34:35], v[146:147], v[242:243]
	v_add_co_u32_e32 v38, vcc, s22, v160
	global_store_dwordx4 v[48:49], v[32:35], off offset:576 sc1
	s_nop 0
	v_addc_co_u32_e32 v39, vcc, 0, v161, vcc
	global_load_dwordx4 v[216:219], v[38:39], off
	global_load_dwordx4 v[220:223], v[36:37], off offset:64
	global_load_dwordx4 v[236:239], v[36:37], off offset:512
	global_load_dwordx4 v[240:243], v[36:37], off offset:576
	s_mov_b64 s[22:23], 0xb0000
	s_waitcnt vmcnt(3)
	v_pk_fma_f32 v[30:31], v[30:31], v[156:157], v[218:219]
	v_pk_fma_f32 v[28:29], v[28:29], v[158:159], v[216:217]
	global_store_dwordx4 v[38:39], v[28:31], off sc1
	s_waitcnt vmcnt(3)
	v_pk_fma_f32 v[26:27], v[26:27], v[152:153], v[222:223]
	v_pk_fma_f32 v[24:25], v[24:25], v[154:155], v[220:221]
	global_store_dwordx4 v[36:37], v[24:27], off offset:64 sc1
	s_waitcnt vmcnt(3)
	v_pk_fma_f32 v[22:23], v[22:23], v[148:149], v[238:239]
	v_pk_fma_f32 v[20:21], v[20:21], v[150:151], v[236:237]
	global_store_dwordx4 v[36:37], v[20:23], off offset:512 sc1
	s_waitcnt vmcnt(3)
	v_pk_fma_f32 v[18:19], v[18:19], v[146:147], v[242:243]
	v_pk_fma_f32 v[16:17], v[16:17], v[144:145], v[240:241]
	global_store_dwordx4 v[36:37], v[16:19], off offset:576 sc1
	s_nop 1
	v_lshl_add_u64 v[16:17], v[160:161], 0, s[22:23]
	s_mov_b32 s22, 0xb0000
	v_add_co_u32_e32 v22, vcc, s22, v160
	s_mov_b64 s[22:23], -1
	s_nop 0
	v_addc_co_u32_e32 v23, vcc, 0, v161, vcc
	global_load_dwordx4 v[216:219], v[22:23], off
	global_load_dwordx4 v[220:223], v[16:17], off offset:64
	global_load_dwordx4 v[236:239], v[16:17], off offset:512
	global_load_dwordx4 v[240:243], v[16:17], off offset:576
	s_and_b64 vcc, exec, s[0:1]
	s_waitcnt vmcnt(3)
	v_pk_fma_f32 v[14:15], v[14:15], v[156:157], v[218:219]
	v_pk_fma_f32 v[12:13], v[12:13], v[158:159], v[216:217]
	global_store_dwordx4 v[22:23], v[12:15], off sc1
	s_waitcnt vmcnt(3)
	v_pk_fma_f32 v[10:11], v[10:11], v[152:153], v[222:223]
	v_pk_fma_f32 v[8:9], v[8:9], v[154:155], v[220:221]
	global_store_dwordx4 v[16:17], v[8:11], off offset:64 sc1
	s_waitcnt vmcnt(3)
	v_pk_fma_f32 v[6:7], v[6:7], v[148:149], v[238:239]
	v_pk_fma_f32 v[4:5], v[4:5], v[150:151], v[236:237]
	global_store_dwordx4 v[16:17], v[4:7], off offset:512 sc1
	s_waitcnt vmcnt(3)
	v_pk_fma_f32 v[2:3], v[2:3], v[146:147], v[242:243]
	v_pk_fma_f32 v[0:1], v[0:1], v[144:145], v[240:241]
	global_store_dwordx4 v[16:17], v[0:3], off offset:576 sc1
	s_cbranch_vccnz .LBB0_2597
	s_andn2_b64 vcc, exec, s[10:11]
	s_cbranch_vccnz .LBB0_2596
	s_barrier
	s_branch .LBB0_2596
